# packed row-pair forward substitution (v_pk_fma_f32) + V-transpose LDS image skewed 8B per 8 rows in both attention variants (removes 16-way ds_write_b16 bank conflicts)
# speedup vs baseline: 1.0441x; 1.0104x over previous
.LBB0_428:
	s_or_b64 exec, exec, s[22:23]
	s_waitcnt lgkmcnt(0)
	v_mul_f32_e32 v26, v14, v19
	v_mul_f32_e32 v6, v6, v26
	v_mul_f32_e32 v26, v14, v21
	v_cndmask_b32_e32 v6, 0, v6, vcc
	v_mul_f32_e32 v7, v7, v26
	v_cmp_lt_i32_e32 vcc, v20, v13
	v_mul_f32_e32 v20, v14, v22
	v_mul_f32_e32 v8, v8, v20
	v_cndmask_b32_e32 v7, 0, v7, vcc
	v_cmp_lt_i32_e32 vcc, v25, v13
	v_mul_f32_e32 v20, v3, v21
	v_mul_f32_e32 v21, v2, v19
	v_mul_lo_u32 v2, v13, s54
	v_mul_f32_e32 v25, v14, v24
	v_cndmask_b32_e32 v8, 0, v8, vcc
	v_mul_f32_e32 v4, v4, v22
	v_add_u32_e32 v19, s60, v2
	v_lshlrev_b32_e32 v22, 2, v18
	s_ashr_i32 s7, s6, 31
	v_mul_f32_e32 v9, v9, v25
	v_cmp_lt_i32_e32 vcc, v23, v13
	v_lshlrev_b32_e32 v23, 2, v11
	s_lshl_b64 s[4:5], s[6:7], 13
	v_cndmask_b32_e32 v9, 0, v9, vcc
	v_add3_u32 v19, v19, v22, v23
	s_add_u32 s4, s45, s4
	v_lshlrev_b32_e32 v2, 6, v13
	v_mul_f32_e32 v5, v5, v24
	v_lshrrev_b32_e32 v157, 7, v100
	v_bfe_u32 v158, v100, 1, 3
	v_lshl_or_b32 v157, v157, 3, v158
	v_mul_u32_u24_e32 v157, 0x220, v157
	v_and_b32_e32 v158, 1, v100
	v_lshl_add_u32 v157, v158, 2, v157
	v_bfe_u32 v158, v100, 6, 1
	v_lshl_add_u32 v157, v158, 8, v157
	v_bfe_u32 v158, v100, 4, 2
	v_lshl_add_u32 v157, v158, 5, v157
	v_add_u32_e32 v157, 0x19000, v157
	ds_write2_b32 v157, v6, v7 offset0:0 offset1:2
	ds_write2_b32 v157, v8, v9 offset0:4 offset1:6
	v_and_b32_sdwa v6, v4, v130 dst_sel:DWORD dst_unused:UNUSED_PAD src0_sel:WORD_1 src1_sel:DWORD
	s_addc_u32 s5, s46, s5
	v_ashrrev_i32_e32 v3, 31, v2
	v_add3_u32 v4, v4, v6, s56
	v_and_b32_sdwa v6, v5, v130 dst_sel:DWORD dst_unused:UNUSED_PAD src0_sel:WORD_1 src1_sel:DWORD
	v_and_b32_sdwa v8, v20, v130 dst_sel:DWORD dst_unused:UNUSED_PAD src0_sel:WORD_1 src1_sel:DWORD
	v_lshl_add_u64 v[2:3], v[2:3], 1, s[4:5]
	v_lshlrev_b32_e32 v96, 1, v18
	v_and_b32_sdwa v7, v21, v130 dst_sel:DWORD dst_unused:UNUSED_PAD src0_sel:WORD_1 src1_sel:DWORD
	v_add3_u32 v5, v5, v6, s56
	v_add3_u32 v6, v20, v8, s56
	v_lshl_add_u64 v[2:3], v[2:3], 0, v[96:97]
	v_add3_u32 v7, v21, v7, s56
	v_and_b32_e32 v5, 0xffff0000, v5
	v_and_b32_e32 v6, 0xffff0000, v6
	v_lshlrev_b32_e32 v96, 1, v11
	v_or_b32_sdwa v5, v5, v4 dst_sel:DWORD dst_unused:UNUSED_PAD src0_sel:DWORD src1_sel:WORD_1
	v_or_b32_sdwa v4, v6, v7 dst_sel:DWORD dst_unused:UNUSED_PAD src0_sel:DWORD src1_sel:WORD_1
	v_lshl_add_u64 v[8:9], v[2:3], 0, v[96:97]
	global_store_dwordx2 v[8:9], v[4:5], off
	v_cmp_lt_i32_e32 vcc, v17, v1
	v_or_b32_e32 v11, 16, v11
	v_mov_b32_e32 v1, 0
	v_mov_b32_e32 v2, 0
	v_mov_b32_e32 v3, 0
	v_mov_b32_e32 v4, 0
	v_mov_b32_e32 v5, 0
	v_mov_b32_e32 v6, 0
	v_mov_b32_e32 v7, 0
	s_and_saveexec_b64 s[4:5], vcc
	s_cbranch_execz .LBB0_430
	v_or_b32_e32 v0, v11, v16
	v_mad_u32_u24 v12, v0, s54, v12
	ds_read_b128 v[0:3], v12 offset:17408
	ds_read_b128 v[4:7], v10 offset:17408
	ds_read_b128 v[20:23], v10 offset:17472
	ds_read_b128 v[24:27], v12 offset:17472
	ds_read_b128 v[28:31], v10
	ds_read_b128 v[32:35], v10 offset:64
	s_waitcnt lgkmcnt(4)
	v_mfma_f32_16x16x32_bf16 v[4:7], v[0:3], v[4:7], 0
	s_waitcnt lgkmcnt(2)
	v_mfma_f32_16x16x32_bf16 v[4:7], v[24:27], v[20:23], v[4:7]
	ds_read_b128 v[20:23], v12 offset:17536
	s_waitcnt lgkmcnt(2)
	v_mfma_f32_16x16x32_bf16 v[0:3], v[0:3], v[28:31], 0
	s_waitcnt lgkmcnt(1)
	v_mfma_f32_16x16x32_bf16 v[0:3], v[24:27], v[32:35], v[0:3]
	ds_read_b128 v[24:27], v10 offset:17536
	ds_read_b128 v[28:31], v10 offset:17600
	ds_read_b128 v[32:35], v12 offset:17600
	s_waitcnt lgkmcnt(2)
	v_mfma_f32_16x16x32_bf16 v[4:7], v[20:23], v[24:27], v[4:7]
	ds_read_b128 v[24:27], v10 offset:128
	ds_read_b128 v[36:39], v10 offset:192
	s_waitcnt lgkmcnt(1)
	v_mfma_f32_16x16x32_bf16 v[0:3], v[20:23], v[24:27], v[0:3]
	v_mfma_f32_16x16x32_bf16 v[4:7], v[32:35], v[28:31], v[4:7]
	s_waitcnt lgkmcnt(0)
	v_mfma_f32_16x16x32_bf16 v[0:3], v[32:35], v[36:39], v[0:3]

.LBB0_438:
	s_or_b64 exec, exec, s[22:23]
	v_mul_f32_e32 v15, v14, v10
	v_mul_f32_e32 v4, v4, v15
	v_mul_f32_e32 v15, v14, v11
	v_cndmask_b32_e32 v4, 0, v4, vcc
	v_mul_f32_e32 v5, v5, v15
	v_cmp_lt_i32_e32 vcc, v12, v13
	v_mul_f32_e32 v12, v14, v20
	v_mul_f32_e32 v6, v6, v12
	v_cndmask_b32_e32 v5, 0, v5, vcc
	v_cmp_lt_i32_e32 vcc, v18, v13
	v_mul_f32_e32 v0, v0, v10
	v_mul_f32_e32 v10, v14, v17
	v_cndmask_b32_e32 v6, 0, v6, vcc
	v_mul_f32_e32 v7, v7, v10
	v_cmp_lt_i32_e32 vcc, v16, v13
	v_mul_f32_e32 v2, v2, v20
	v_mul_f32_e32 v1, v1, v11
	v_cndmask_b32_e32 v7, 0, v7, vcc
	v_mul_f32_e32 v3, v3, v17
	v_lshrrev_b32_e32 v157, 7, v100
	v_bfe_u32 v158, v100, 1, 3
	v_lshl_or_b32 v157, v157, 3, v158
	v_mul_u32_u24_e32 v157, 0x220, v157
	v_and_b32_e32 v158, 1, v100
	v_lshl_add_u32 v157, v158, 2, v157
	v_bfe_u32 v158, v100, 6, 1
	v_lshl_add_u32 v157, v158, 8, v157
	v_bfe_u32 v158, v100, 4, 2
	v_lshl_add_u32 v157, v158, 5, v157
	v_add_u32_e32 v157, 0x19000, v157
	ds_write2_b32 v157, v4, v5 offset0:32 offset1:34
	ds_write2_b32 v157, v6, v7 offset0:36 offset1:38
	v_and_b32_sdwa v4, v2, v130 dst_sel:DWORD dst_unused:UNUSED_PAD src0_sel:WORD_1 src1_sel:DWORD
	v_and_b32_sdwa v5, v0, v130 dst_sel:DWORD dst_unused:UNUSED_PAD src0_sel:WORD_1 src1_sel:DWORD
	v_add3_u32 v0, v0, v5, s56
	v_add3_u32 v2, v2, v4, s56
	v_and_b32_sdwa v4, v3, v130 dst_sel:DWORD dst_unused:UNUSED_PAD src0_sel:WORD_1 src1_sel:DWORD
	v_and_b32_sdwa v5, v1, v130 dst_sel:DWORD dst_unused:UNUSED_PAD src0_sel:WORD_1 src1_sel:DWORD
	v_add3_u32 v3, v3, v4, s56
	v_add3_u32 v1, v1, v5, s56
	v_and_b32_e32 v3, 0xffff0000, v3
	v_and_b32_e32 v4, 0xffff0000, v1
	s_movk_i32 s4, 0xff
	v_or_b32_sdwa v1, v3, v2 dst_sel:DWORD dst_unused:UNUSED_PAD src0_sel:DWORD src1_sel:WORD_1
	v_or_b32_sdwa v0, v4, v0 dst_sel:DWORD dst_unused:UNUSED_PAD src0_sel:DWORD src1_sel:WORD_1
	v_cmp_lt_i32_e32 vcc, s4, v100
	global_store_dwordx2 v[8:9], v[0:1], off offset:32
	s_waitcnt lgkmcnt(0)
	s_barrier
	s_and_saveexec_b64 s[4:5], vcc
	s_xor_b64 s[4:5], exec, s[4:5]
	s_cbranch_execz .LBB0_442
	v_lshlrev_b32_e32 v0, 4, v100
	v_add_u32_e32 v18, 0xffffff00, v100
	v_and_b32_e32 v96, 0xf0, v0
	v_add_u32_e32 v4, 0, v96
	v_lshrrev_b32_e32 v5, 4, v18
	v_mad_u64_u32 v[0:1], s[10:11], v5, s54, v[4:5]
	v_mov_b32_e32 v2, s61
	v_lshl_add_u32 v1, v5, 2, s59
	ds_read_b32 v19, v2
	ds_read_b32 v6, v1
	ds_read_b128 v[0:3], v0
	s_lshl_b64 s[22:23], s[6:7], 14
	v_readlane_b32 s10, v245, 16
	s_add_u32 s10, s10, s22
	s_waitcnt lgkmcnt(1)
	v_mul_f32_e32 v6, 0x3fb8aa3b, v6
	v_exp_f32_e32 v6, v6
	s_waitcnt lgkmcnt(0)
	v_lshlrev_b32_e32 v9, 16, v1
	v_lshlrev_b32_e32 v8, 16, v0
	v_and_b32_e32 v1, 0xffff0000, v1
	v_and_b32_e32 v0, 0xffff0000, v0
	v_lshlrev_b32_e32 v13, 16, v3
	v_lshlrev_b32_e32 v12, 16, v2
	v_and_b32_e32 v3, 0xffff0000, v3
	v_and_b32_e32 v2, 0xffff0000, v2
	v_pk_mul_f32 v[0:1], v[6:7], v[0:1] op_sel_hi:[0,1]
	v_pk_mul_f32 v[2:3], v[6:7], v[2:3] op_sel_hi:[0,1]
	v_pk_mul_f32 v[8:9], v[6:7], v[8:9] op_sel_hi:[0,1]
	v_pk_mul_f32 v[12:13], v[6:7], v[12:13] op_sel_hi:[0,1]
	v_bfe_u32 v6, v3, 16, 1
	v_bfe_u32 v7, v2, 16, 1
	v_bfe_u32 v14, v1, 16, 1
	v_bfe_u32 v15, v0, 16, 1
	v_add3_u32 v15, v0, v15, s56
	v_add3_u32 v14, v1, v14, s56
	v_add3_u32 v0, v2, v7, s56
	v_add3_u32 v1, v3, v6, s56
	v_bfe_u32 v2, v8, 16, 1
	v_bfe_u32 v3, v9, 16, 1
	v_bfe_u32 v6, v12, 16, 1
	v_bfe_u32 v7, v13, 16, 1
	v_readlane_b32 s11, v245, 17
	v_add3_u32 v7, v13, v7, s56
	v_add3_u32 v6, v12, v6, s56
	v_add3_u32 v3, v9, v3, s56
	v_add3_u32 v2, v8, v2, s56
	s_addc_u32 s11, s11, s23
	v_lshrrev_b32_e32 v12, 16, v2
	v_lshrrev_b32_e32 v13, 16, v3
	v_lshrrev_b32_e32 v2, 16, v6
	v_lshrrev_b32_e32 v3, 16, v7
	v_lshrrev_b32_e32 v16, 4, v100
	v_lshl_add_u64 v[10:11], s[10:11], 0, v[96:97]
	v_and_or_b32 v3, v1, s53, v3
	v_and_or_b32 v2, v0, s53, v2
	v_mad_u64_u32 v[0:1], s[10:11], v16, s54, v[4:5]
	v_lshl_add_u32 v1, v16, 2, s59
	ds_read_b128 v[6:9], v0
	ds_read_b32 v17, v1
	v_lshlrev_b32_e32 v96, 8, v5
	v_and_or_b32 v1, v14, s53, v13
	v_and_or_b32 v0, v15, s53, v12
	v_lshl_add_u64 v[12:13], v[10:11], 0, v[96:97]
	s_waitcnt lgkmcnt(0)
	v_mul_f32_e32 v5, 0x3fb8aa3b, v17
	v_exp_f32_e32 v14, v5
	global_store_dwordx4 v[12:13], v[0:3], off
	v_lshlrev_b32_e32 v96, 8, v16
	v_and_b32_e32 v21, 0x7f, v100
	v_lshlrev_b32_e32 v1, 16, v7
	v_lshlrev_b32_e32 v0, 16, v6
	v_and_b32_e32 v3, 0xffff0000, v7
	v_and_b32_e32 v2, 0xffff0000, v6
	v_lshlrev_b32_e32 v7, 16, v9
	v_lshlrev_b32_e32 v6, 16, v8
	v_and_b32_e32 v9, 0xffff0000, v9
	v_and_b32_e32 v8, 0xffff0000, v8
	v_pk_mul_f32 v[2:3], v[14:15], v[2:3] op_sel_hi:[0,1]
	v_pk_mul_f32 v[8:9], v[14:15], v[8:9] op_sel_hi:[0,1]
	v_pk_mul_f32 v[0:1], v[14:15], v[0:1] op_sel_hi:[0,1]
	v_pk_mul_f32 v[6:7], v[14:15], v[6:7] op_sel_hi:[0,1]
	v_bfe_u32 v5, v9, 16, 1
	v_bfe_u32 v13, v3, 16, 1
	v_add3_u32 v13, v3, v13, s56
	v_add3_u32 v3, v9, v5, s56
	v_bfe_u32 v5, v0, 16, 1
	v_bfe_u32 v9, v6, 16, 1
	v_bfe_u32 v12, v8, 16, 1
	v_bfe_u32 v14, v2, 16, 1
	v_add3_u32 v6, v6, v9, s56
	v_add3_u32 v0, v0, v5, s56
	v_add3_u32 v14, v2, v14, s56
	v_add3_u32 v2, v8, v12, s56
	v_bfe_u32 v8, v1, 16, 1
	v_bfe_u32 v12, v7, 16, 1
	v_lshrrev_b32_e32 v5, 16, v0
	v_lshrrev_b32_e32 v0, 16, v6
	v_add3_u32 v7, v7, v12, s56
	v_add3_u32 v1, v1, v8, s56
	v_and_or_b32 v2, v2, s53, v0
	v_add_u32_e32 v0, 0x100, v100
	v_lshrrev_b32_e32 v12, 16, v1
	v_lshrrev_b32_e32 v1, 16, v7
	v_lshrrev_b32_e32 v15, 4, v0
	v_and_or_b32 v3, v3, s53, v1
	v_mad_u64_u32 v[0:1], s[10:11], v15, s54, v[4:5]
	v_lshl_add_u32 v1, v15, 2, s59
	ds_read_b128 v[6:9], v0
	ds_read_b32 v17, v1
	v_and_or_b32 v0, v14, s53, v5
	v_and_or_b32 v1, v13, s53, v12
	v_lshl_add_u64 v[12:13], v[10:11], 0, v[96:97]
	global_store_dwordx4 v[12:13], v[0:3], off
	s_waitcnt lgkmcnt(0)
	v_mul_f32_e32 v5, 0x3fb8aa3b, v17
	v_exp_f32_e32 v14, v5
	v_lshlrev_b32_e32 v1, 16, v7
	v_lshlrev_b32_e32 v0, 16, v6
	v_and_b32_e32 v3, 0xffff0000, v7
	v_and_b32_e32 v2, 0xffff0000, v6
	v_lshlrev_b32_e32 v7, 16, v9
	v_lshlrev_b32_e32 v6, 16, v8
	v_and_b32_e32 v9, 0xffff0000, v9
	v_and_b32_e32 v8, 0xffff0000, v8
	v_pk_mul_f32 v[2:3], v[14:15], v[2:3] op_sel_hi:[0,1]
	v_pk_mul_f32 v[8:9], v[14:15], v[8:9] op_sel_hi:[0,1]
	v_pk_mul_f32 v[6:7], v[14:15], v[6:7] op_sel_hi:[0,1]
	v_bfe_u32 v5, v9, 16, 1
	v_bfe_u32 v13, v3, 16, 1
	v_pk_mul_f32 v[0:1], v[14:15], v[0:1] op_sel_hi:[0,1]
	v_add3_u32 v13, v3, v13, s56
	v_add3_u32 v3, v9, v5, s56
	v_bfe_u32 v9, v6, 16, 1
	v_bfe_u32 v12, v8, 16, 1
	v_bfe_u32 v14, v2, 16, 1
	v_bfe_u32 v5, v0, 16, 1
	v_add3_u32 v6, v6, v9, s56
	v_add3_u32 v14, v2, v14, s56
	v_add3_u32 v2, v8, v12, s56
	v_add3_u32 v0, v0, v5, s56
	v_lshrrev_b32_e32 v5, 16, v6
	v_and_or_b32 v2, v2, s53, v5
	v_add_u32_e32 v5, 0x200, v100
	v_lshrrev_b32_e32 v16, 4, v5
	v_mad_u64_u32 v[4:5], s[10:11], v16, s54, v[4:5]
	v_lshl_add_u32 v5, v16, 2, s59
	ds_read_b32 v17, v5
	v_bfe_u32 v8, v1, 16, 1
	v_bfe_u32 v12, v7, 16, 1
	v_add3_u32 v1, v1, v8, s56
	v_lshrrev_b32_e32 v20, 2, v18
	v_add3_u32 v7, v7, v12, s56
	v_lshrrev_b32_e32 v1, 16, v1
	v_and_b32_e32 v22, 0x3fffffe0, v20
	v_lshl_add_u32 v8, v21, 2, 0
	v_lshrrev_b32_e32 v6, 16, v7
	v_and_or_b32 v1, v13, s53, v1
	v_mad_u64_u32 v[12:13], s[10:11], v22, s57, v[8:9]
	v_and_or_b32 v3, v3, s53, v6
	ds_read_b128 v[4:7], v4
	ds_read_b32 v9, v12 offset:50656
	s_waitcnt lgkmcnt(2)
	v_mul_f32_e32 v13, 0x3fb8aa3b, v17
	v_exp_f32_e32 v24, v13
	v_lshrrev_b32_e32 v0, 16, v0
	v_lshlrev_b32_e32 v96, 8, v15
	v_and_or_b32 v0, v14, s53, v0
	v_lshl_add_u64 v[14:15], v[10:11], 0, v[96:97]
	global_store_dwordx4 v[14:15], v[0:3], off
	v_lshlrev_b32_e32 v96, 8, v16
	v_readlane_b32 s10, v245, 14
	s_waitcnt lgkmcnt(1)
	v_lshlrev_b32_e32 v1, 16, v5
	v_lshlrev_b32_e32 v0, 16, v4
	v_and_b32_e32 v3, 0xffff0000, v5
	v_and_b32_e32 v2, 0xffff0000, v4
	v_lshlrev_b32_e32 v5, 16, v7
	v_lshlrev_b32_e32 v4, 16, v6
	v_and_b32_e32 v7, 0xffff0000, v7
	v_and_b32_e32 v6, 0xffff0000, v6
	v_pk_mul_f32 v[2:3], v[24:25], v[2:3] op_sel_hi:[0,1]
	v_pk_mul_f32 v[6:7], v[24:25], v[6:7] op_sel_hi:[0,1]
	v_pk_mul_f32 v[0:1], v[24:25], v[0:1] op_sel_hi:[0,1]
	v_pk_mul_f32 v[4:5], v[24:25], v[4:5] op_sel_hi:[0,1]
	v_bfe_u32 v13, v7, 16, 1
	v_bfe_u32 v14, v6, 16, 1
	v_bfe_u32 v15, v3, 16, 1
	v_bfe_u32 v17, v2, 16, 1
	v_add3_u32 v17, v2, v17, s56
	v_add3_u32 v15, v3, v15, s56
	v_add3_u32 v2, v6, v14, s56
	v_add3_u32 v3, v7, v13, s56
	v_bfe_u32 v6, v0, 16, 1
	v_bfe_u32 v7, v1, 16, 1
	v_bfe_u32 v13, v4, 16, 1
	v_bfe_u32 v14, v5, 16, 1
	v_add3_u32 v5, v5, v14, s56
	v_add3_u32 v4, v4, v13, s56
	v_add3_u32 v1, v1, v7, s56
	v_add3_u32 v0, v0, v6, s56
	v_lshrrev_b32_e32 v0, 16, v0
	v_lshrrev_b32_e32 v1, 16, v1
	v_lshrrev_b32_e32 v4, 16, v4
	v_lshrrev_b32_e32 v5, 16, v5
	v_and_or_b32 v3, v3, s53, v5
	v_and_or_b32 v2, v2, s53, v4
	v_and_or_b32 v1, v15, s53, v1
	v_and_or_b32 v0, v17, s53, v0
	v_lshl_add_u64 v[4:5], v[10:11], 0, v[96:97]
	v_lshl_add_u32 v13, v22, 2, s59
	global_store_dwordx4 v[4:5], v[0:3], off
	ds_read_b128 v[0:3], v13
	v_add_u32_e32 v6, 0x8800, v12
	ds_read2_b32 v[6:7], v6 offset1:132
	ds_read_b128 v[14:17], v13 offset:16
	s_add_u32 s10, s10, s22
	v_readlane_b32 s11, v245, 15
	s_waitcnt lgkmcnt(2)
	v_sub_f32_e32 v1, v19, v1
	v_mul_f32_e32 v1, 0x3fb8aa3b, v1
	s_addc_u32 s11, s11, s23
	v_lshlrev_b32_e32 v96, 7, v21
	v_exp_f32_e32 v10, v1
	v_add_u32_e32 v1, 0x8c00, v12
	v_lshl_add_u64 v[4:5], s[10:11], 0, v[96:97]
	v_lshlrev_b32_e32 v96, 1, v22
	ds_read2_b32 v[22:23], v1 offset0:8 offset1:140
	v_sub_f32_e32 v1, v19, v2
	v_sub_f32_e32 v2, v19, v3
	s_waitcnt lgkmcnt(1)
	v_sub_f32_e32 v15, v19, v15
	v_mul_f32_e32 v2, 0x3fb8aa3b, v2
	v_mul_f32_e32 v15, 0x3fb8aa3b, v15
	v_exp_f32_e32 v11, v2
	v_add_u32_e32 v2, 0x9000, v12
	v_exp_f32_e32 v24, v15
	v_add_u32_e32 v15, 0x9400, v12
	ds_read2_b32 v[2:3], v2 offset0:16 offset1:148
	ds_read2_b32 v[26:27], v15 offset0:24 offset1:156
	v_sub_f32_e32 v15, v19, v16
	v_sub_f32_e32 v16, v19, v17
	v_sub_f32_e32 v0, v19, v0
	v_sub_f32_e32 v14, v19, v14
	v_mul_f32_e32 v16, 0x3fb8aa3b, v16
	v_mul_f32_e32 v0, 0x3fb8aa3b, v0
	v_mul_f32_e32 v1, 0x3fb8aa3b, v1
	v_mul_f32_e32 v14, 0x3fb8aa3b, v14
	v_mul_f32_e32 v15, 0x3fb8aa3b, v15
	v_exp_f32_e32 v25, v16
	v_exp_f32_e32 v0, v0
	v_exp_f32_e32 v1, v1
	v_exp_f32_e32 v14, v14
	v_exp_f32_e32 v15, v15
	s_waitcnt lgkmcnt(2)
	v_mov_b32_e32 v17, v22
	v_mov_b32_e32 v22, v7
	v_mov_b32_e32 v16, v6
	v_pk_mul_f32 v[6:7], v[22:23], v[10:11]
	s_waitcnt lgkmcnt(0)
	v_mov_b32_e32 v11, v26
	v_mov_b32_e32 v26, v3
	v_mov_b32_e32 v10, v2
	v_pk_mul_f32 v[2:3], v[26:27], v[24:25]
	v_pk_mul_f32 v[0:1], v[16:17], v[0:1]
	v_pk_mul_f32 v[10:11], v[10:11], v[14:15]
	v_bfe_u32 v14, v3, 16, 1
	v_bfe_u32 v15, v2, 16, 1
	v_bfe_u32 v16, v7, 16, 1
	v_bfe_u32 v17, v6, 16, 1
	v_add3_u32 v6, v6, v17, s56
	v_add3_u32 v7, v7, v16, s56
	v_add3_u32 v2, v2, v15, s56
	v_add3_u32 v3, v3, v14, s56
	v_bfe_u32 v14, v0, 16, 1
	v_bfe_u32 v15, v1, 16, 1
	v_bfe_u32 v16, v10, 16, 1
	v_bfe_u32 v17, v11, 16, 1
	v_add3_u32 v11, v11, v17, s56
	v_add3_u32 v10, v10, v16, s56
	v_add3_u32 v1, v1, v15, s56
	v_add3_u32 v0, v0, v14, s56
	v_lshrrev_b32_e32 v0, 16, v0
	v_lshrrev_b32_e32 v1, 16, v1
	v_lshrrev_b32_e32 v10, 16, v10
	v_lshrrev_b32_e32 v11, 16, v11
	v_lshl_add_u64 v[4:5], v[4:5], 0, v[96:97]
	v_and_or_b32 v3, v3, s53, v11
	v_and_or_b32 v2, v2, s53, v10
	v_and_or_b32 v1, v7, s53, v1
	v_and_or_b32 v0, v6, s53, v0
	global_store_dwordx4 v[4:5], v[0:3], off
	v_add_u32_e32 v6, 0x9800, v12
	ds_read_b128 v[0:3], v13 offset:32
	ds_read2_b32 v[6:7], v6 offset0:32 offset1:164
	ds_read_b128 v[14:17], v13 offset:48
	ds_read_b128 v[22:25], v13 offset:64
	ds_read_b128 v[26:29], v13 offset:80
	s_waitcnt lgkmcnt(4)
	v_sub_f32_e32 v1, v19, v1
	v_mul_f32_e32 v1, 0x3fb8aa3b, v1
	v_exp_f32_e32 v10, v1
	v_add_u32_e32 v1, 0x9c00, v12
	ds_read2_b32 v[30:31], v1 offset0:40 offset1:172
	v_sub_f32_e32 v1, v19, v2
	v_sub_f32_e32 v2, v19, v3
	s_waitcnt lgkmcnt(3)
	v_sub_f32_e32 v15, v19, v15
	v_mul_f32_e32 v2, 0x3fb8aa3b, v2
	v_mul_f32_e32 v15, 0x3fb8aa3b, v15
	v_exp_f32_e32 v11, v2
	v_add_u32_e32 v2, 0xa000, v12
	v_exp_f32_e32 v32, v15
	v_add_u32_e32 v15, 0xa400, v12
	ds_read2_b32 v[2:3], v2 offset0:48 offset1:180
	ds_read2_b32 v[34:35], v15 offset0:56 offset1:188
	v_sub_f32_e32 v15, v19, v16
	v_sub_f32_e32 v16, v19, v17
	v_sub_f32_e32 v0, v19, v0
	v_sub_f32_e32 v14, v19, v14
	v_mul_f32_e32 v16, 0x3fb8aa3b, v16
	v_mul_f32_e32 v0, 0x3fb8aa3b, v0
	v_mul_f32_e32 v1, 0x3fb8aa3b, v1
	v_mul_f32_e32 v14, 0x3fb8aa3b, v14
	v_mul_f32_e32 v15, 0x3fb8aa3b, v15
	v_exp_f32_e32 v33, v16
	v_exp_f32_e32 v0, v0
	v_exp_f32_e32 v1, v1
	v_exp_f32_e32 v14, v14
	v_exp_f32_e32 v15, v15
	s_waitcnt lgkmcnt(2)
	v_mov_b32_e32 v17, v30
	v_mov_b32_e32 v30, v7
	v_mov_b32_e32 v16, v6
	v_pk_mul_f32 v[6:7], v[30:31], v[10:11]
	s_waitcnt lgkmcnt(0)
	v_mov_b32_e32 v11, v34
	v_mov_b32_e32 v34, v3
	v_mov_b32_e32 v10, v2
	v_pk_mul_f32 v[2:3], v[34:35], v[32:33]
	v_pk_mul_f32 v[0:1], v[16:17], v[0:1]
	v_pk_mul_f32 v[10:11], v[10:11], v[14:15]
	v_bfe_u32 v14, v3, 16, 1
	v_bfe_u32 v15, v2, 16, 1
	v_bfe_u32 v16, v7, 16, 1
	v_bfe_u32 v17, v6, 16, 1
	v_add3_u32 v6, v6, v17, s56
	v_add3_u32 v7, v7, v16, s56
	v_add3_u32 v2, v2, v15, s56
	v_add3_u32 v3, v3, v14, s56
	v_bfe_u32 v14, v0, 16, 1
	v_bfe_u32 v15, v1, 16, 1
	v_bfe_u32 v16, v10, 16, 1
	v_bfe_u32 v17, v11, 16, 1
	v_add3_u32 v11, v11, v17, s56
	v_add3_u32 v10, v10, v16, s56
	v_add3_u32 v1, v1, v15, s56
	v_add3_u32 v0, v0, v14, s56
	v_lshrrev_b32_e32 v0, 16, v0
	v_lshrrev_b32_e32 v1, 16, v1
	v_lshrrev_b32_e32 v10, 16, v10
	v_lshrrev_b32_e32 v11, 16, v11
	v_and_or_b32 v3, v3, s53, v11
	v_and_or_b32 v2, v2, s53, v10
	v_and_or_b32 v1, v7, s53, v1
	v_and_or_b32 v0, v6, s53, v0
	global_store_dwordx4 v[4:5], v[0:3], off offset:16
	v_sub_f32_e32 v17, v19, v27
	v_mul_f32_e32 v17, 0x3fb8aa3b, v17
	v_sub_f32_e32 v3, v19, v23
	v_mul_f32_e32 v3, 0x3fb8aa3b, v3
	v_add_u32_e32 v0, 0xa800, v12
	v_exp_f32_e32 v6, v3
	v_add_u32_e32 v3, 0xac00, v12
	ds_read2_b32 v[0:1], v0 offset0:64 offset1:196
	v_sub_f32_e32 v2, v19, v22
	ds_read2_b32 v[10:11], v3 offset0:72 offset1:204
	v_sub_f32_e32 v7, v19, v25
	v_add_u32_e32 v14, 0xb000, v12
	v_exp_f32_e32 v22, v17
	v_add_u32_e32 v17, 0xb400, v12
	v_sub_f32_e32 v3, v19, v24
	v_mul_f32_e32 v7, 0x3fb8aa3b, v7
	ds_read2_b32 v[14:15], v14 offset0:80 offset1:212
	ds_read2_b32 v[24:25], v17 offset0:88 offset1:220
	v_sub_f32_e32 v21, v19, v29
	v_exp_f32_e32 v7, v7
	v_sub_f32_e32 v16, v19, v26
	v_sub_f32_e32 v17, v19, v28
	v_mul_f32_e32 v21, 0x3fb8aa3b, v21
	v_mul_f32_e32 v2, 0x3fb8aa3b, v2
	v_mul_f32_e32 v3, 0x3fb8aa3b, v3
	v_mul_f32_e32 v16, 0x3fb8aa3b, v16
	v_mul_f32_e32 v17, 0x3fb8aa3b, v17
	v_exp_f32_e32 v23, v21
	v_exp_f32_e32 v2, v2
	v_exp_f32_e32 v3, v3
	v_exp_f32_e32 v16, v16
	v_exp_f32_e32 v17, v17
	s_waitcnt lgkmcnt(2)
	v_mov_b32_e32 v27, v10
	v_mov_b32_e32 v10, v1
	v_mov_b32_e32 v26, v0
	v_pk_mul_f32 v[0:1], v[10:11], v[6:7]
	s_waitcnt lgkmcnt(0)
	v_mov_b32_e32 v7, v24
	v_mov_b32_e32 v24, v15
	v_mov_b32_e32 v6, v14
	v_pk_mul_f32 v[10:11], v[24:25], v[22:23]
	v_pk_mul_f32 v[2:3], v[26:27], v[2:3]
	v_pk_mul_f32 v[6:7], v[6:7], v[16:17]
	v_bfe_u32 v14, v11, 16, 1
	v_bfe_u32 v15, v10, 16, 1
	v_bfe_u32 v16, v1, 16, 1
	v_bfe_u32 v17, v0, 16, 1
	ds_read_b128 v[22:25], v13 offset:96
	v_add3_u32 v0, v0, v17, s56
	v_add3_u32 v1, v1, v16, s56
	v_add3_u32 v10, v10, v15, s56
	v_add3_u32 v11, v11, v14, s56
	v_bfe_u32 v14, v2, 16, 1
	v_bfe_u32 v15, v3, 16, 1
	v_bfe_u32 v16, v6, 16, 1
	v_bfe_u32 v17, v7, 16, 1
	v_add3_u32 v7, v7, v17, s56
	v_add3_u32 v6, v6, v16, s56
	v_add3_u32 v3, v3, v15, s56
	v_add3_u32 v2, v2, v14, s56
	v_lshrrev_b32_e32 v14, 16, v2
	v_lshrrev_b32_e32 v15, 16, v3
	v_lshrrev_b32_e32 v2, 16, v6
	v_lshrrev_b32_e32 v3, 16, v7
	v_and_or_b32 v3, v11, s53, v3
	v_and_or_b32 v2, v10, s53, v2
	v_and_or_b32 v1, v1, s53, v15
	v_and_or_b32 v0, v0, s53, v14
	global_store_dwordx4 v[4:5], v[0:3], off offset:32
	v_cmp_eq_u32_e32 vcc, 0, v18
	s_waitcnt lgkmcnt(0)
	v_sub_f32_e32 v3, v19, v22
	v_mul_f32_e32 v3, 0x3fb8aa3b, v3
	v_exp_f32_e32 v16, v3
	v_sub_f32_e32 v3, v19, v23
	v_mul_f32_e32 v3, 0x3fb8aa3b, v3
	v_add_u32_e32 v0, 0xb800, v12
	v_exp_f32_e32 v10, v3
	v_add_u32_e32 v3, 0xbc00, v12
	ds_read2_b32 v[6:7], v0 offset0:96 offset1:228
	ds_read_b96 v[0:2], v13 offset:112
	ds_read2_b32 v[14:15], v3 offset0:104 offset1:236
	v_sub_f32_e32 v3, v19, v24
	v_mul_f32_e32 v3, 0x3fb8aa3b, v3
	v_exp_f32_e32 v17, v3
	v_sub_f32_e32 v3, v19, v25
	v_mul_f32_e32 v3, 0x3fb8aa3b, v3
	v_exp_f32_e32 v11, v3
	v_add_u32_e32 v3, 0xc000, v12
	ds_read2_b32 v[12:13], v3 offset0:112 offset1:244
	v_or_b32_e32 v3, 31, v20
	v_mad_u64_u32 v[20:21], s[10:11], v3, s57, v[8:9]
	v_lshl_add_u32 v8, v3, 2, s59
	ds_read_b32 v3, v20 offset:34816
	ds_read_b32 v8, v8
	s_waitcnt lgkmcnt(4)
	v_sub_f32_e32 v1, v19, v1
	v_mul_f32_e32 v1, 0x3fb8aa3b, v1
	v_exp_f32_e32 v20, v1
	v_sub_f32_e32 v1, v19, v2
	s_waitcnt lgkmcnt(0)
	v_sub_f32_e32 v2, v19, v8
	v_sub_f32_e32 v0, v19, v0
	v_mul_f32_e32 v2, 0x3fb8aa3b, v2
	v_mul_f32_e32 v0, 0x3fb8aa3b, v0
	v_mul_f32_e32 v1, 0x3fb8aa3b, v1
	v_exp_f32_e32 v21, v2
	v_exp_f32_e32 v0, v0
	v_exp_f32_e32 v1, v1
	v_mov_b32_e32 v23, v14
	v_mov_b32_e32 v14, v7
	v_mov_b32_e32 v2, v13
	v_mov_b32_e32 v22, v6
	v_pk_mul_f32 v[6:7], v[14:15], v[10:11]
	v_mov_b32_e32 v8, v12
	v_pk_mul_f32 v[2:3], v[2:3], v[20:21]
	v_pk_mul_f32 v[16:17], v[22:23], v[16:17]
	v_pk_mul_f32 v[0:1], v[8:9], v[0:1]
	v_bfe_u32 v8, v3, 16, 1
	v_bfe_u32 v9, v2, 16, 1
	v_bfe_u32 v10, v7, 16, 1
	v_bfe_u32 v11, v6, 16, 1
	v_add3_u32 v6, v6, v11, s56
	v_add3_u32 v7, v7, v10, s56
	v_add3_u32 v2, v2, v9, s56
	v_add3_u32 v3, v3, v8, s56
	v_bfe_u32 v8, v16, 16, 1
	v_bfe_u32 v9, v17, 16, 1
	v_bfe_u32 v10, v0, 16, 1
	v_bfe_u32 v11, v1, 16, 1
	v_add3_u32 v1, v1, v11, s56
	v_add3_u32 v0, v0, v10, s56
	v_add3_u32 v9, v17, v9, s56
	v_add3_u32 v8, v16, v8, s56
	v_lshrrev_b32_e32 v8, 16, v8
	v_lshrrev_b32_e32 v9, 16, v9
	v_lshrrev_b32_e32 v0, 16, v0
	v_lshrrev_b32_e32 v1, 16, v1
	v_and_or_b32 v3, v3, s53, v1
	v_and_or_b32 v2, v2, s53, v0
	v_and_or_b32 v1, v7, s53, v9
	v_and_or_b32 v0, v6, s53, v8
	global_store_dwordx4 v[4:5], v[0:3], off offset:48
	s_and_saveexec_b64 s[22:23], vcc
	s_cbranch_execz .LBB0_441
	v_mul_f32_e32 v0, 0x3fb8aa3b, v19
	v_exp_f32_e32 v0, v0
	s_lshl_b64 s[10:11], s[6:7], 2
	v_readlane_b32 s20, v245, 18
	s_add_u32 s10, s20, s10
	v_readlane_b32 s20, v245, 19
	s_addc_u32 s11, s20, s11
	global_store_dword v97, v0, s[10:11]

.LBB0_442:
	s_andn2_saveexec_b64 s[4:5], s[4:5]
	s_cbranch_execz .LBB0_392
	v_lshlrev_b32_e32 v76, 2, v100
	v_add_u32_e32 v77, 0x10c00, v76
	v_add_u32_e32 v76, 0x8600, v76
	s_movk_i32 s7, 0x80
	v_cmp_gt_u32_e64 s[24:25], s7, v100
	v_mov_b32_e32 v78, 0x19000
	v_mov_b32_e32 v79, 0x1d500
	v_readfirstlane_b32 s7, v100
	v_cndmask_b32_e64 v77, v76, v77, s[24:25]
	ds_read_b32 v160, v77 offset:0
	ds_read_b32 v161, v77 offset:528
	ds_read_b32 v162, v77 offset:1056
	ds_read_b32 v163, v77 offset:1584
	ds_read_b32 v164, v77 offset:2112
	ds_read_b32 v165, v77 offset:2640
	ds_read_b32 v166, v77 offset:3168
	ds_read_b32 v167, v77 offset:3696
	ds_read_b32 v168, v77 offset:4224
	ds_read_b32 v169, v77 offset:4752
	ds_read_b32 v170, v77 offset:5280
	ds_read_b32 v171, v77 offset:5808
	ds_read_b32 v172, v77 offset:6336
	ds_read_b32 v173, v77 offset:6864
	ds_read_b32 v174, v77 offset:7392
	ds_read_b32 v175, v77 offset:7920
	ds_read_b32 v176, v77 offset:8448
	ds_read_b32 v177, v77 offset:8976
	ds_read_b32 v178, v77 offset:9504
	ds_read_b32 v179, v77 offset:10032
	ds_read_b32 v180, v77 offset:10560
	ds_read_b32 v181, v77 offset:11088
	ds_read_b32 v182, v77 offset:11616
	ds_read_b32 v183, v77 offset:12144
	ds_read_b32 v184, v77 offset:12672
	ds_read_b32 v185, v77 offset:13200
	ds_read_b32 v186, v77 offset:13728
	ds_read_b32 v187, v77 offset:14256
	ds_read_b32 v188, v77 offset:14784
	ds_read_b32 v189, v77 offset:15312
	ds_read_b32 v190, v77 offset:15840
	ds_read_b32 v191, v77 offset:16368
	ds_read_b32 v192, v77 offset:16896
	ds_read_b32 v193, v77 offset:17424
	ds_read_b32 v194, v77 offset:17952
	ds_read_b32 v195, v77 offset:18480
	ds_read_b32 v196, v77 offset:19008
	ds_read_b32 v197, v77 offset:19536
	ds_read_b32 v198, v77 offset:20064
	ds_read_b32 v199, v77 offset:20592
	ds_read_b32 v200, v77 offset:21120
	ds_read_b32 v201, v77 offset:21648
	ds_read_b32 v202, v77 offset:22176
	ds_read_b32 v203, v77 offset:22704
	ds_read_b32 v204, v77 offset:23232
	ds_read_b32 v205, v77 offset:23760
	ds_read_b32 v206, v77 offset:24288
	ds_read_b32 v207, v77 offset:24816
	ds_read_b32 v208, v77 offset:25344
	ds_read_b32 v209, v77 offset:25872
	ds_read_b32 v210, v77 offset:26400
	ds_read_b32 v211, v77 offset:26928
	ds_read_b32 v212, v77 offset:27456
	ds_read_b32 v213, v77 offset:27984
	ds_read_b32 v214, v77 offset:28512
	ds_read_b32 v215, v77 offset:29040
	ds_read_b32 v216, v77 offset:29568
	ds_read_b32 v217, v77 offset:30096
	ds_read_b32 v218, v77 offset:30624
	ds_read_b32 v219, v77 offset:31152
	ds_read_b32 v220, v77 offset:31680
	ds_read_b32 v221, v77 offset:32208
	ds_read_b32 v222, v77 offset:32736
	ds_read_b32 v223, v77 offset:33264
	ds_read_b128 v[0:3], v79 offset:0
	ds_read_b128 v[4:7], v79 offset:16
	ds_read_b128 v[8:11], v79 offset:32
	ds_read_b128 v[12:15], v79 offset:48
	ds_read_b128 v[16:19], v79 offset:64
	ds_read_b128 v[20:23], v79 offset:80
	ds_read_b128 v[24:27], v79 offset:96
	ds_read_b128 v[28:31], v79 offset:112
	s_cmpk_lt_u32 s7, 0x80
	s_cbranch_scc1 .Lgsolve_noexp0
	ds_read_b128 v[32:35], v79 offset:256
	ds_read_b128 v[36:39], v79 offset:272
	ds_read_b128 v[40:43], v79 offset:288
	ds_read_b128 v[44:47], v79 offset:304
	ds_read_b128 v[48:51], v79 offset:320
	ds_read_b128 v[52:55], v79 offset:336
	ds_read_b128 v[56:59], v79 offset:352
	ds_read_b128 v[60:63], v79 offset:368
	s_waitcnt lgkmcnt(0)
	v_mul_f32_e32 v32, 0x3fb8aa3b, v32
	v_mul_f32_e32 v33, 0x3fb8aa3b, v33
	v_mul_f32_e32 v34, 0x3fb8aa3b, v34
	v_mul_f32_e32 v35, 0x3fb8aa3b, v35
	v_mul_f32_e32 v36, 0x3fb8aa3b, v36
	v_mul_f32_e32 v37, 0x3fb8aa3b, v37
	v_mul_f32_e32 v38, 0x3fb8aa3b, v38
	v_mul_f32_e32 v39, 0x3fb8aa3b, v39
	v_mul_f32_e32 v40, 0x3fb8aa3b, v40
	v_mul_f32_e32 v41, 0x3fb8aa3b, v41
	v_mul_f32_e32 v42, 0x3fb8aa3b, v42
	v_mul_f32_e32 v43, 0x3fb8aa3b, v43
	v_mul_f32_e32 v44, 0x3fb8aa3b, v44
	v_mul_f32_e32 v45, 0x3fb8aa3b, v45
	v_mul_f32_e32 v46, 0x3fb8aa3b, v46
	v_mul_f32_e32 v47, 0x3fb8aa3b, v47
	v_mul_f32_e32 v48, 0x3fb8aa3b, v48
	v_mul_f32_e32 v49, 0x3fb8aa3b, v49
	v_mul_f32_e32 v50, 0x3fb8aa3b, v50
	v_mul_f32_e32 v51, 0x3fb8aa3b, v51
	v_mul_f32_e32 v52, 0x3fb8aa3b, v52
	v_mul_f32_e32 v53, 0x3fb8aa3b, v53
	v_mul_f32_e32 v54, 0x3fb8aa3b, v54
	v_mul_f32_e32 v55, 0x3fb8aa3b, v55
	v_mul_f32_e32 v56, 0x3fb8aa3b, v56
	v_mul_f32_e32 v57, 0x3fb8aa3b, v57
	v_mul_f32_e32 v58, 0x3fb8aa3b, v58
	v_mul_f32_e32 v59, 0x3fb8aa3b, v59
	v_mul_f32_e32 v60, 0x3fb8aa3b, v60
	v_mul_f32_e32 v61, 0x3fb8aa3b, v61
	v_mul_f32_e32 v62, 0x3fb8aa3b, v62
	v_mul_f32_e32 v63, 0x3fb8aa3b, v63
	v_exp_f32_e32 v32, v32
	v_exp_f32_e32 v33, v33
	v_exp_f32_e32 v34, v34
	v_exp_f32_e32 v35, v35
	v_exp_f32_e32 v36, v36
	v_exp_f32_e32 v37, v37
	v_exp_f32_e32 v38, v38
	v_exp_f32_e32 v39, v39
	v_exp_f32_e32 v40, v40
	v_exp_f32_e32 v41, v41
	v_exp_f32_e32 v42, v42
	v_exp_f32_e32 v43, v43
	v_exp_f32_e32 v44, v44
	v_exp_f32_e32 v45, v45
	v_exp_f32_e32 v46, v46
	v_exp_f32_e32 v47, v47
	v_exp_f32_e32 v48, v48
	v_exp_f32_e32 v49, v49
	v_exp_f32_e32 v50, v50
	v_exp_f32_e32 v51, v51
	v_exp_f32_e32 v52, v52
	v_exp_f32_e32 v53, v53
	v_exp_f32_e32 v54, v54
	v_exp_f32_e32 v55, v55
	v_exp_f32_e32 v56, v56
	v_exp_f32_e32 v57, v57
	v_exp_f32_e32 v58, v58
	v_exp_f32_e32 v59, v59
	v_exp_f32_e32 v60, v60
	v_exp_f32_e32 v61, v61
	v_exp_f32_e32 v62, v62
	v_exp_f32_e32 v63, v63
	s_nop 0
	v_pk_mul_f32 v[0:1], v[0:1], v[32:33]
	v_pk_mul_f32 v[2:3], v[2:3], v[34:35]
	v_pk_mul_f32 v[4:5], v[4:5], v[36:37]
	v_pk_mul_f32 v[6:7], v[6:7], v[38:39]
	v_pk_mul_f32 v[8:9], v[8:9], v[40:41]
	v_pk_mul_f32 v[10:11], v[10:11], v[42:43]
	v_pk_mul_f32 v[12:13], v[12:13], v[44:45]
	v_pk_mul_f32 v[14:15], v[14:15], v[46:47]
	v_pk_mul_f32 v[16:17], v[16:17], v[48:49]
	v_pk_mul_f32 v[18:19], v[18:19], v[50:51]
	v_pk_mul_f32 v[20:21], v[20:21], v[52:53]
	v_pk_mul_f32 v[22:23], v[22:23], v[54:55]
	v_pk_mul_f32 v[24:25], v[24:25], v[56:57]
	v_pk_mul_f32 v[26:27], v[26:27], v[58:59]
	v_pk_mul_f32 v[28:29], v[28:29], v[60:61]
	v_pk_mul_f32 v[30:31], v[30:31], v[62:63]
.Lgsolve_noexp0:
	s_waitcnt lgkmcnt(0)
	v_pk_mul_f32 v[160:161], v[160:161], v[0:1]
	v_pk_mul_f32 v[162:163], v[162:163], v[2:3]
	v_pk_mul_f32 v[164:165], v[164:165], v[4:5]
	v_pk_mul_f32 v[166:167], v[166:167], v[6:7]
	v_pk_mul_f32 v[168:169], v[168:169], v[8:9]
	v_pk_mul_f32 v[170:171], v[170:171], v[10:11]
	v_pk_mul_f32 v[172:173], v[172:173], v[12:13]
	v_pk_mul_f32 v[174:175], v[174:175], v[14:15]
	v_pk_mul_f32 v[176:177], v[176:177], v[16:17]
	v_pk_mul_f32 v[178:179], v[178:179], v[18:19]
	v_pk_mul_f32 v[180:181], v[180:181], v[20:21]
	v_pk_mul_f32 v[182:183], v[182:183], v[22:23]
	v_pk_mul_f32 v[184:185], v[184:185], v[24:25]
	v_pk_mul_f32 v[186:187], v[186:187], v[26:27]
	v_pk_mul_f32 v[188:189], v[188:189], v[28:29]
	v_pk_mul_f32 v[190:191], v[190:191], v[30:31]
	ds_read_b128 v[0:3], v79 offset:128
	ds_read_b128 v[4:7], v79 offset:144
	ds_read_b128 v[8:11], v79 offset:160
	ds_read_b128 v[12:15], v79 offset:176
	ds_read_b128 v[16:19], v79 offset:192
	ds_read_b128 v[20:23], v79 offset:208
	ds_read_b128 v[24:27], v79 offset:224
	ds_read_b128 v[28:31], v79 offset:240
	s_cmpk_lt_u32 s7, 0x80
	s_cbranch_scc1 .Lgsolve_noexp1
	ds_read_b128 v[32:35], v79 offset:384
	ds_read_b128 v[36:39], v79 offset:400
	ds_read_b128 v[40:43], v79 offset:416
	ds_read_b128 v[44:47], v79 offset:432
	ds_read_b128 v[48:51], v79 offset:448
	ds_read_b128 v[52:55], v79 offset:464
	ds_read_b128 v[56:59], v79 offset:480
	ds_read_b128 v[60:63], v79 offset:496
	s_waitcnt lgkmcnt(0)
	v_mul_f32_e32 v32, 0x3fb8aa3b, v32
	v_mul_f32_e32 v33, 0x3fb8aa3b, v33
	v_mul_f32_e32 v34, 0x3fb8aa3b, v34
	v_mul_f32_e32 v35, 0x3fb8aa3b, v35
	v_mul_f32_e32 v36, 0x3fb8aa3b, v36
	v_mul_f32_e32 v37, 0x3fb8aa3b, v37
	v_mul_f32_e32 v38, 0x3fb8aa3b, v38
	v_mul_f32_e32 v39, 0x3fb8aa3b, v39
	v_mul_f32_e32 v40, 0x3fb8aa3b, v40
	v_mul_f32_e32 v41, 0x3fb8aa3b, v41
	v_mul_f32_e32 v42, 0x3fb8aa3b, v42
	v_mul_f32_e32 v43, 0x3fb8aa3b, v43
	v_mul_f32_e32 v44, 0x3fb8aa3b, v44
	v_mul_f32_e32 v45, 0x3fb8aa3b, v45
	v_mul_f32_e32 v46, 0x3fb8aa3b, v46
	v_mul_f32_e32 v47, 0x3fb8aa3b, v47
	v_mul_f32_e32 v48, 0x3fb8aa3b, v48
	v_mul_f32_e32 v49, 0x3fb8aa3b, v49
	v_mul_f32_e32 v50, 0x3fb8aa3b, v50
	v_mul_f32_e32 v51, 0x3fb8aa3b, v51
	v_mul_f32_e32 v52, 0x3fb8aa3b, v52
	v_mul_f32_e32 v53, 0x3fb8aa3b, v53
	v_mul_f32_e32 v54, 0x3fb8aa3b, v54
	v_mul_f32_e32 v55, 0x3fb8aa3b, v55
	v_mul_f32_e32 v56, 0x3fb8aa3b, v56
	v_mul_f32_e32 v57, 0x3fb8aa3b, v57
	v_mul_f32_e32 v58, 0x3fb8aa3b, v58
	v_mul_f32_e32 v59, 0x3fb8aa3b, v59
	v_mul_f32_e32 v60, 0x3fb8aa3b, v60
	v_mul_f32_e32 v61, 0x3fb8aa3b, v61
	v_mul_f32_e32 v62, 0x3fb8aa3b, v62
	v_mul_f32_e32 v63, 0x3fb8aa3b, v63
	v_exp_f32_e32 v32, v32
	v_exp_f32_e32 v33, v33
	v_exp_f32_e32 v34, v34
	v_exp_f32_e32 v35, v35
	v_exp_f32_e32 v36, v36
	v_exp_f32_e32 v37, v37
	v_exp_f32_e32 v38, v38
	v_exp_f32_e32 v39, v39
	v_exp_f32_e32 v40, v40
	v_exp_f32_e32 v41, v41
	v_exp_f32_e32 v42, v42
	v_exp_f32_e32 v43, v43
	v_exp_f32_e32 v44, v44
	v_exp_f32_e32 v45, v45
	v_exp_f32_e32 v46, v46
	v_exp_f32_e32 v47, v47
	v_exp_f32_e32 v48, v48
	v_exp_f32_e32 v49, v49
	v_exp_f32_e32 v50, v50
	v_exp_f32_e32 v51, v51
	v_exp_f32_e32 v52, v52
	v_exp_f32_e32 v53, v53
	v_exp_f32_e32 v54, v54
	v_exp_f32_e32 v55, v55
	v_exp_f32_e32 v56, v56
	v_exp_f32_e32 v57, v57
	v_exp_f32_e32 v58, v58
	v_exp_f32_e32 v59, v59
	v_exp_f32_e32 v60, v60
	v_exp_f32_e32 v61, v61
	v_exp_f32_e32 v62, v62
	v_exp_f32_e32 v63, v63
	s_nop 0
	v_pk_mul_f32 v[0:1], v[0:1], v[32:33]
	v_pk_mul_f32 v[2:3], v[2:3], v[34:35]
	v_pk_mul_f32 v[4:5], v[4:5], v[36:37]
	v_pk_mul_f32 v[6:7], v[6:7], v[38:39]
	v_pk_mul_f32 v[8:9], v[8:9], v[40:41]
	v_pk_mul_f32 v[10:11], v[10:11], v[42:43]
	v_pk_mul_f32 v[12:13], v[12:13], v[44:45]
	v_pk_mul_f32 v[14:15], v[14:15], v[46:47]
	v_pk_mul_f32 v[16:17], v[16:17], v[48:49]
	v_pk_mul_f32 v[18:19], v[18:19], v[50:51]
	v_pk_mul_f32 v[20:21], v[20:21], v[52:53]
	v_pk_mul_f32 v[22:23], v[22:23], v[54:55]
	v_pk_mul_f32 v[24:25], v[24:25], v[56:57]
	v_pk_mul_f32 v[26:27], v[26:27], v[58:59]
	v_pk_mul_f32 v[28:29], v[28:29], v[60:61]
	v_pk_mul_f32 v[30:31], v[30:31], v[62:63]
.Lgsolve_noexp1:
	s_waitcnt lgkmcnt(0)
	v_pk_mul_f32 v[192:193], v[192:193], v[0:1]
	v_pk_mul_f32 v[194:195], v[194:195], v[2:3]
	v_pk_mul_f32 v[196:197], v[196:197], v[4:5]
	v_pk_mul_f32 v[198:199], v[198:199], v[6:7]
	v_pk_mul_f32 v[200:201], v[200:201], v[8:9]
	v_pk_mul_f32 v[202:203], v[202:203], v[10:11]
	v_pk_mul_f32 v[204:205], v[204:205], v[12:13]
	v_pk_mul_f32 v[206:207], v[206:207], v[14:15]
	v_pk_mul_f32 v[208:209], v[208:209], v[16:17]
	v_pk_mul_f32 v[210:211], v[210:211], v[18:19]
	v_pk_mul_f32 v[212:213], v[212:213], v[20:21]
	v_pk_mul_f32 v[214:215], v[214:215], v[22:23]
	v_pk_mul_f32 v[216:217], v[216:217], v[24:25]
	v_pk_mul_f32 v[218:219], v[218:219], v[26:27]
	v_pk_mul_f32 v[220:221], v[220:221], v[28:29]
	v_pk_mul_f32 v[222:223], v[222:223], v[30:31]
	ds_read_b128 v[64:67], v78 offset:0
	ds_read_b128 v[68:71], v78 offset:544
	ds_read_b128 v[72:75], v78 offset:560
	ds_read_b128 v[0:3], v78 offset:1088
	ds_read_b128 v[4:7], v78 offset:1104
	ds_read_b128 v[8:11], v78 offset:1632
	ds_read_b128 v[12:15], v78 offset:1648
	ds_read_b128 v[16:19], v78 offset:2176
	ds_read_b128 v[20:23], v78 offset:2192
	ds_read_b128 v[24:27], v78 offset:2720
	ds_read_b128 v[28:31], v78 offset:2736
	ds_read_b128 v[32:35], v78 offset:3264
	ds_read_b128 v[36:39], v78 offset:3280
	ds_read_b128 v[40:43], v78 offset:3808
	ds_read_b128 v[44:47], v78 offset:3824
	s_waitcnt lgkmcnt(14)
	v_pk_fma_f32 v[160:161], v[64:65], v[160:161], v[160:161] op_sel_hi:[1,0,1] neg_lo:[1,0,0] neg_hi:[1,0,0]
	s_waitcnt lgkmcnt(13)
	v_pk_fma_f32 v[162:163], v[68:69], v[160:161], v[162:163] op_sel_hi:[1,0,1] neg_lo:[1,0,0] neg_hi:[1,0,0]
	v_pk_fma_f32 v[162:163], v[70:71], v[160:161], v[162:163] op_sel:[0,1,0] op_sel_hi:[1,1,1] neg_lo:[1,0,0] neg_hi:[1,0,0]
	s_waitcnt lgkmcnt(12)
	v_pk_fma_f32 v[162:163], v[72:73], v[162:163], v[162:163] op_sel_hi:[1,0,1] neg_lo:[1,0,0] neg_hi:[1,0,0]
	ds_read_b128 v[64:67], v78 offset:1120
	ds_read_b128 v[68:71], v78 offset:1664
	ds_read_b128 v[72:75], v78 offset:1680
	ds_read_b128 v[48:51], v78 offset:4352
	ds_read_b128 v[52:55], v78 offset:4368
	ds_read_b128 v[56:59], v78 offset:4896
	ds_read_b128 v[60:63], v78 offset:4912
	s_waitcnt lgkmcnt(15)
	v_pk_fma_f32 v[164:165], v[0:1], v[160:161], v[164:165] op_sel_hi:[1,0,1] neg_lo:[1,0,0] neg_hi:[1,0,0]
	v_pk_fma_f32 v[166:167], v[8:9], v[160:161], v[166:167] op_sel_hi:[1,0,1] neg_lo:[1,0,0] neg_hi:[1,0,0]
	v_pk_fma_f32 v[164:165], v[2:3], v[160:161], v[164:165] op_sel:[0,1,0] op_sel_hi:[1,1,1] neg_lo:[1,0,0] neg_hi:[1,0,0]
	v_pk_fma_f32 v[166:167], v[10:11], v[160:161], v[166:167] op_sel:[0,1,0] op_sel_hi:[1,1,1] neg_lo:[1,0,0] neg_hi:[1,0,0]
	v_pk_fma_f32 v[164:165], v[4:5], v[162:163], v[164:165] op_sel_hi:[1,0,1] neg_lo:[1,0,0] neg_hi:[1,0,0]
	v_pk_fma_f32 v[166:167], v[12:13], v[162:163], v[166:167] op_sel_hi:[1,0,1] neg_lo:[1,0,0] neg_hi:[1,0,0]
	v_pk_fma_f32 v[164:165], v[6:7], v[162:163], v[164:165] op_sel:[0,1,0] op_sel_hi:[1,1,1] neg_lo:[1,0,0] neg_hi:[1,0,0]
	v_pk_fma_f32 v[166:167], v[14:15], v[162:163], v[166:167] op_sel:[0,1,0] op_sel_hi:[1,1,1] neg_lo:[1,0,0] neg_hi:[1,0,0]
	ds_read_b128 v[0:3], v78 offset:5440
	ds_read_b128 v[4:7], v78 offset:5456
	ds_read_b128 v[8:11], v78 offset:5984
	ds_read_b128 v[12:15], v78 offset:6000
	s_waitcnt lgkmcnt(15)
	v_pk_fma_f32 v[168:169], v[16:17], v[160:161], v[168:169] op_sel_hi:[1,0,1] neg_lo:[1,0,0] neg_hi:[1,0,0]
	v_pk_fma_f32 v[170:171], v[24:25], v[160:161], v[170:171] op_sel_hi:[1,0,1] neg_lo:[1,0,0] neg_hi:[1,0,0]
	s_waitcnt lgkmcnt(10)
	v_pk_fma_f32 v[164:165], v[64:65], v[164:165], v[164:165] op_sel_hi:[1,0,1] neg_lo:[1,0,0] neg_hi:[1,0,0]
	v_pk_fma_f32 v[168:169], v[18:19], v[160:161], v[168:169] op_sel:[0,1,0] op_sel_hi:[1,1,1] neg_lo:[1,0,0] neg_hi:[1,0,0]
	v_pk_fma_f32 v[170:171], v[26:27], v[160:161], v[170:171] op_sel:[0,1,0] op_sel_hi:[1,1,1] neg_lo:[1,0,0] neg_hi:[1,0,0]
	s_waitcnt lgkmcnt(9)
	v_pk_fma_f32 v[166:167], v[68:69], v[164:165], v[166:167] op_sel_hi:[1,0,1] neg_lo:[1,0,0] neg_hi:[1,0,0]
	v_pk_fma_f32 v[168:169], v[20:21], v[162:163], v[168:169] op_sel_hi:[1,0,1] neg_lo:[1,0,0] neg_hi:[1,0,0]
	v_pk_fma_f32 v[170:171], v[28:29], v[162:163], v[170:171] op_sel_hi:[1,0,1] neg_lo:[1,0,0] neg_hi:[1,0,0]
	v_pk_fma_f32 v[166:167], v[70:71], v[164:165], v[166:167] op_sel:[0,1,0] op_sel_hi:[1,1,1] neg_lo:[1,0,0] neg_hi:[1,0,0]
	v_pk_fma_f32 v[168:169], v[22:23], v[162:163], v[168:169] op_sel:[0,1,0] op_sel_hi:[1,1,1] neg_lo:[1,0,0] neg_hi:[1,0,0]
	v_pk_fma_f32 v[170:171], v[30:31], v[162:163], v[170:171] op_sel:[0,1,0] op_sel_hi:[1,1,1] neg_lo:[1,0,0] neg_hi:[1,0,0]
	s_waitcnt lgkmcnt(8)
	v_pk_fma_f32 v[166:167], v[72:73], v[166:167], v[166:167] op_sel_hi:[1,0,1] neg_lo:[1,0,0] neg_hi:[1,0,0]
	ds_read_b128 v[16:19], v78 offset:6528
	ds_read_b128 v[20:23], v78 offset:6544
	ds_read_b128 v[24:27], v78 offset:7072
	ds_read_b128 v[28:31], v78 offset:7088
	s_waitcnt lgkmcnt(15)
	v_pk_fma_f32 v[172:173], v[32:33], v[160:161], v[172:173] op_sel_hi:[1,0,1] neg_lo:[1,0,0] neg_hi:[1,0,0]
	v_pk_fma_f32 v[174:175], v[40:41], v[160:161], v[174:175] op_sel_hi:[1,0,1] neg_lo:[1,0,0] neg_hi:[1,0,0]
	v_pk_fma_f32 v[172:173], v[34:35], v[160:161], v[172:173] op_sel:[0,1,0] op_sel_hi:[1,1,1] neg_lo:[1,0,0] neg_hi:[1,0,0]
	v_pk_fma_f32 v[174:175], v[42:43], v[160:161], v[174:175] op_sel:[0,1,0] op_sel_hi:[1,1,1] neg_lo:[1,0,0] neg_hi:[1,0,0]
	v_pk_fma_f32 v[172:173], v[36:37], v[162:163], v[172:173] op_sel_hi:[1,0,1] neg_lo:[1,0,0] neg_hi:[1,0,0]
	v_pk_fma_f32 v[174:175], v[44:45], v[162:163], v[174:175] op_sel_hi:[1,0,1] neg_lo:[1,0,0] neg_hi:[1,0,0]
	v_pk_fma_f32 v[172:173], v[38:39], v[162:163], v[172:173] op_sel:[0,1,0] op_sel_hi:[1,1,1] neg_lo:[1,0,0] neg_hi:[1,0,0]
	v_pk_fma_f32 v[174:175], v[46:47], v[162:163], v[174:175] op_sel:[0,1,0] op_sel_hi:[1,1,1] neg_lo:[1,0,0] neg_hi:[1,0,0]
	ds_read_b128 v[32:35], v78 offset:7616
	ds_read_b128 v[36:39], v78 offset:7632
	ds_read_b128 v[40:43], v78 offset:8160
	ds_read_b128 v[44:47], v78 offset:8176
	s_waitcnt lgkmcnt(12)
	v_pk_fma_f32 v[176:177], v[48:49], v[160:161], v[176:177] op_sel_hi:[1,0,1] neg_lo:[1,0,0] neg_hi:[1,0,0]
	v_pk_fma_f32 v[178:179], v[56:57], v[160:161], v[178:179] op_sel_hi:[1,0,1] neg_lo:[1,0,0] neg_hi:[1,0,0]
	v_pk_fma_f32 v[176:177], v[50:51], v[160:161], v[176:177] op_sel:[0,1,0] op_sel_hi:[1,1,1] neg_lo:[1,0,0] neg_hi:[1,0,0]
	v_pk_fma_f32 v[178:179], v[58:59], v[160:161], v[178:179] op_sel:[0,1,0] op_sel_hi:[1,1,1] neg_lo:[1,0,0] neg_hi:[1,0,0]
	v_pk_fma_f32 v[176:177], v[52:53], v[162:163], v[176:177] op_sel_hi:[1,0,1] neg_lo:[1,0,0] neg_hi:[1,0,0]
	v_pk_fma_f32 v[178:179], v[60:61], v[162:163], v[178:179] op_sel_hi:[1,0,1] neg_lo:[1,0,0] neg_hi:[1,0,0]
	v_pk_fma_f32 v[176:177], v[54:55], v[162:163], v[176:177] op_sel:[0,1,0] op_sel_hi:[1,1,1] neg_lo:[1,0,0] neg_hi:[1,0,0]
	v_pk_fma_f32 v[178:179], v[62:63], v[162:163], v[178:179] op_sel:[0,1,0] op_sel_hi:[1,1,1] neg_lo:[1,0,0] neg_hi:[1,0,0]
	ds_read_b128 v[48:51], v78 offset:8704
	ds_read_b128 v[52:55], v78 offset:8720
	ds_read_b128 v[56:59], v78 offset:9248
	ds_read_b128 v[60:63], v78 offset:9264
	s_waitcnt lgkmcnt(12)
	v_pk_fma_f32 v[180:181], v[0:1], v[160:161], v[180:181] op_sel_hi:[1,0,1] neg_lo:[1,0,0] neg_hi:[1,0,0]
	v_pk_fma_f32 v[182:183], v[8:9], v[160:161], v[182:183] op_sel_hi:[1,0,1] neg_lo:[1,0,0] neg_hi:[1,0,0]
	v_pk_fma_f32 v[180:181], v[2:3], v[160:161], v[180:181] op_sel:[0,1,0] op_sel_hi:[1,1,1] neg_lo:[1,0,0] neg_hi:[1,0,0]
	v_pk_fma_f32 v[182:183], v[10:11], v[160:161], v[182:183] op_sel:[0,1,0] op_sel_hi:[1,1,1] neg_lo:[1,0,0] neg_hi:[1,0,0]
	v_pk_fma_f32 v[180:181], v[4:5], v[162:163], v[180:181] op_sel_hi:[1,0,1] neg_lo:[1,0,0] neg_hi:[1,0,0]
	v_pk_fma_f32 v[182:183], v[12:13], v[162:163], v[182:183] op_sel_hi:[1,0,1] neg_lo:[1,0,0] neg_hi:[1,0,0]
	v_pk_fma_f32 v[180:181], v[6:7], v[162:163], v[180:181] op_sel:[0,1,0] op_sel_hi:[1,1,1] neg_lo:[1,0,0] neg_hi:[1,0,0]
	v_pk_fma_f32 v[182:183], v[14:15], v[162:163], v[182:183] op_sel:[0,1,0] op_sel_hi:[1,1,1] neg_lo:[1,0,0] neg_hi:[1,0,0]
	ds_read_b128 v[0:3], v78 offset:9792
	ds_read_b128 v[4:7], v78 offset:9808
	ds_read_b128 v[8:11], v78 offset:10336
	ds_read_b128 v[12:15], v78 offset:10352
	s_waitcnt lgkmcnt(12)
	v_pk_fma_f32 v[184:185], v[16:17], v[160:161], v[184:185] op_sel_hi:[1,0,1] neg_lo:[1,0,0] neg_hi:[1,0,0]
	v_pk_fma_f32 v[186:187], v[24:25], v[160:161], v[186:187] op_sel_hi:[1,0,1] neg_lo:[1,0,0] neg_hi:[1,0,0]
	v_pk_fma_f32 v[184:185], v[18:19], v[160:161], v[184:185] op_sel:[0,1,0] op_sel_hi:[1,1,1] neg_lo:[1,0,0] neg_hi:[1,0,0]
	v_pk_fma_f32 v[186:187], v[26:27], v[160:161], v[186:187] op_sel:[0,1,0] op_sel_hi:[1,1,1] neg_lo:[1,0,0] neg_hi:[1,0,0]
	v_pk_fma_f32 v[184:185], v[20:21], v[162:163], v[184:185] op_sel_hi:[1,0,1] neg_lo:[1,0,0] neg_hi:[1,0,0]
	v_pk_fma_f32 v[186:187], v[28:29], v[162:163], v[186:187] op_sel_hi:[1,0,1] neg_lo:[1,0,0] neg_hi:[1,0,0]
	v_pk_fma_f32 v[184:185], v[22:23], v[162:163], v[184:185] op_sel:[0,1,0] op_sel_hi:[1,1,1] neg_lo:[1,0,0] neg_hi:[1,0,0]
	v_pk_fma_f32 v[186:187], v[30:31], v[162:163], v[186:187] op_sel:[0,1,0] op_sel_hi:[1,1,1] neg_lo:[1,0,0] neg_hi:[1,0,0]
	ds_read_b128 v[16:19], v78 offset:10880
	ds_read_b128 v[20:23], v78 offset:10896
	ds_read_b128 v[24:27], v78 offset:11424
	ds_read_b128 v[28:31], v78 offset:11440
	s_waitcnt lgkmcnt(12)
	v_pk_fma_f32 v[188:189], v[32:33], v[160:161], v[188:189] op_sel_hi:[1,0,1] neg_lo:[1,0,0] neg_hi:[1,0,0]
	v_pk_fma_f32 v[190:191], v[40:41], v[160:161], v[190:191] op_sel_hi:[1,0,1] neg_lo:[1,0,0] neg_hi:[1,0,0]
	v_pk_fma_f32 v[188:189], v[34:35], v[160:161], v[188:189] op_sel:[0,1,0] op_sel_hi:[1,1,1] neg_lo:[1,0,0] neg_hi:[1,0,0]
	v_pk_fma_f32 v[190:191], v[42:43], v[160:161], v[190:191] op_sel:[0,1,0] op_sel_hi:[1,1,1] neg_lo:[1,0,0] neg_hi:[1,0,0]
	v_pk_fma_f32 v[188:189], v[36:37], v[162:163], v[188:189] op_sel_hi:[1,0,1] neg_lo:[1,0,0] neg_hi:[1,0,0]
	v_pk_fma_f32 v[190:191], v[44:45], v[162:163], v[190:191] op_sel_hi:[1,0,1] neg_lo:[1,0,0] neg_hi:[1,0,0]
	v_pk_fma_f32 v[188:189], v[38:39], v[162:163], v[188:189] op_sel:[0,1,0] op_sel_hi:[1,1,1] neg_lo:[1,0,0] neg_hi:[1,0,0]
	v_pk_fma_f32 v[190:191], v[46:47], v[162:163], v[190:191] op_sel:[0,1,0] op_sel_hi:[1,1,1] neg_lo:[1,0,0] neg_hi:[1,0,0]
	ds_read_b128 v[32:35], v78 offset:11968
	ds_read_b128 v[36:39], v78 offset:11984
	ds_read_b128 v[40:43], v78 offset:12512
	ds_read_b128 v[44:47], v78 offset:12528
	s_waitcnt lgkmcnt(12)
	v_pk_fma_f32 v[192:193], v[48:49], v[160:161], v[192:193] op_sel_hi:[1,0,1] neg_lo:[1,0,0] neg_hi:[1,0,0]
	v_pk_fma_f32 v[194:195], v[56:57], v[160:161], v[194:195] op_sel_hi:[1,0,1] neg_lo:[1,0,0] neg_hi:[1,0,0]
	v_pk_fma_f32 v[192:193], v[50:51], v[160:161], v[192:193] op_sel:[0,1,0] op_sel_hi:[1,1,1] neg_lo:[1,0,0] neg_hi:[1,0,0]
	v_pk_fma_f32 v[194:195], v[58:59], v[160:161], v[194:195] op_sel:[0,1,0] op_sel_hi:[1,1,1] neg_lo:[1,0,0] neg_hi:[1,0,0]
	v_pk_fma_f32 v[192:193], v[52:53], v[162:163], v[192:193] op_sel_hi:[1,0,1] neg_lo:[1,0,0] neg_hi:[1,0,0]
	v_pk_fma_f32 v[194:195], v[60:61], v[162:163], v[194:195] op_sel_hi:[1,0,1] neg_lo:[1,0,0] neg_hi:[1,0,0]
	v_pk_fma_f32 v[192:193], v[54:55], v[162:163], v[192:193] op_sel:[0,1,0] op_sel_hi:[1,1,1] neg_lo:[1,0,0] neg_hi:[1,0,0]
	v_pk_fma_f32 v[194:195], v[62:63], v[162:163], v[194:195] op_sel:[0,1,0] op_sel_hi:[1,1,1] neg_lo:[1,0,0] neg_hi:[1,0,0]
	ds_read_b128 v[48:51], v78 offset:13056
	ds_read_b128 v[52:55], v78 offset:13072
	ds_read_b128 v[56:59], v78 offset:13600
	ds_read_b128 v[60:63], v78 offset:13616
	s_waitcnt lgkmcnt(12)
	v_pk_fma_f32 v[196:197], v[0:1], v[160:161], v[196:197] op_sel_hi:[1,0,1] neg_lo:[1,0,0] neg_hi:[1,0,0]
	v_pk_fma_f32 v[198:199], v[8:9], v[160:161], v[198:199] op_sel_hi:[1,0,1] neg_lo:[1,0,0] neg_hi:[1,0,0]
	v_pk_fma_f32 v[196:197], v[2:3], v[160:161], v[196:197] op_sel:[0,1,0] op_sel_hi:[1,1,1] neg_lo:[1,0,0] neg_hi:[1,0,0]
	v_pk_fma_f32 v[198:199], v[10:11], v[160:161], v[198:199] op_sel:[0,1,0] op_sel_hi:[1,1,1] neg_lo:[1,0,0] neg_hi:[1,0,0]
	v_pk_fma_f32 v[196:197], v[4:5], v[162:163], v[196:197] op_sel_hi:[1,0,1] neg_lo:[1,0,0] neg_hi:[1,0,0]
	v_pk_fma_f32 v[198:199], v[12:13], v[162:163], v[198:199] op_sel_hi:[1,0,1] neg_lo:[1,0,0] neg_hi:[1,0,0]
	v_pk_fma_f32 v[196:197], v[6:7], v[162:163], v[196:197] op_sel:[0,1,0] op_sel_hi:[1,1,1] neg_lo:[1,0,0] neg_hi:[1,0,0]
	v_pk_fma_f32 v[198:199], v[14:15], v[162:163], v[198:199] op_sel:[0,1,0] op_sel_hi:[1,1,1] neg_lo:[1,0,0] neg_hi:[1,0,0]
	ds_read_b128 v[0:3], v78 offset:14144
	ds_read_b128 v[4:7], v78 offset:14160
	ds_read_b128 v[8:11], v78 offset:14688
	ds_read_b128 v[12:15], v78 offset:14704
	s_waitcnt lgkmcnt(12)
	v_pk_fma_f32 v[200:201], v[16:17], v[160:161], v[200:201] op_sel_hi:[1,0,1] neg_lo:[1,0,0] neg_hi:[1,0,0]
	v_pk_fma_f32 v[202:203], v[24:25], v[160:161], v[202:203] op_sel_hi:[1,0,1] neg_lo:[1,0,0] neg_hi:[1,0,0]
	v_pk_fma_f32 v[200:201], v[18:19], v[160:161], v[200:201] op_sel:[0,1,0] op_sel_hi:[1,1,1] neg_lo:[1,0,0] neg_hi:[1,0,0]
	v_pk_fma_f32 v[202:203], v[26:27], v[160:161], v[202:203] op_sel:[0,1,0] op_sel_hi:[1,1,1] neg_lo:[1,0,0] neg_hi:[1,0,0]
	v_pk_fma_f32 v[200:201], v[20:21], v[162:163], v[200:201] op_sel_hi:[1,0,1] neg_lo:[1,0,0] neg_hi:[1,0,0]
	v_pk_fma_f32 v[202:203], v[28:29], v[162:163], v[202:203] op_sel_hi:[1,0,1] neg_lo:[1,0,0] neg_hi:[1,0,0]
	v_pk_fma_f32 v[200:201], v[22:23], v[162:163], v[200:201] op_sel:[0,1,0] op_sel_hi:[1,1,1] neg_lo:[1,0,0] neg_hi:[1,0,0]
	v_pk_fma_f32 v[202:203], v[30:31], v[162:163], v[202:203] op_sel:[0,1,0] op_sel_hi:[1,1,1] neg_lo:[1,0,0] neg_hi:[1,0,0]
	ds_read_b128 v[16:19], v78 offset:15232
	ds_read_b128 v[20:23], v78 offset:15248
	ds_read_b128 v[24:27], v78 offset:15776
	ds_read_b128 v[28:31], v78 offset:15792
	s_waitcnt lgkmcnt(12)
	v_pk_fma_f32 v[204:205], v[32:33], v[160:161], v[204:205] op_sel_hi:[1,0,1] neg_lo:[1,0,0] neg_hi:[1,0,0]
	v_pk_fma_f32 v[206:207], v[40:41], v[160:161], v[206:207] op_sel_hi:[1,0,1] neg_lo:[1,0,0] neg_hi:[1,0,0]
	v_pk_fma_f32 v[204:205], v[34:35], v[160:161], v[204:205] op_sel:[0,1,0] op_sel_hi:[1,1,1] neg_lo:[1,0,0] neg_hi:[1,0,0]
	v_pk_fma_f32 v[206:207], v[42:43], v[160:161], v[206:207] op_sel:[0,1,0] op_sel_hi:[1,1,1] neg_lo:[1,0,0] neg_hi:[1,0,0]
	v_pk_fma_f32 v[204:205], v[36:37], v[162:163], v[204:205] op_sel_hi:[1,0,1] neg_lo:[1,0,0] neg_hi:[1,0,0]
	v_pk_fma_f32 v[206:207], v[44:45], v[162:163], v[206:207] op_sel_hi:[1,0,1] neg_lo:[1,0,0] neg_hi:[1,0,0]
	v_pk_fma_f32 v[204:205], v[38:39], v[162:163], v[204:205] op_sel:[0,1,0] op_sel_hi:[1,1,1] neg_lo:[1,0,0] neg_hi:[1,0,0]
	v_pk_fma_f32 v[206:207], v[46:47], v[162:163], v[206:207] op_sel:[0,1,0] op_sel_hi:[1,1,1] neg_lo:[1,0,0] neg_hi:[1,0,0]
	ds_read_b128 v[32:35], v78 offset:16320
	ds_read_b128 v[36:39], v78 offset:16336
	ds_read_b128 v[40:43], v78 offset:16864
	ds_read_b128 v[44:47], v78 offset:16880
	s_waitcnt lgkmcnt(12)
	v_pk_fma_f32 v[208:209], v[48:49], v[160:161], v[208:209] op_sel_hi:[1,0,1] neg_lo:[1,0,0] neg_hi:[1,0,0]
	v_pk_fma_f32 v[210:211], v[56:57], v[160:161], v[210:211] op_sel_hi:[1,0,1] neg_lo:[1,0,0] neg_hi:[1,0,0]
	v_pk_fma_f32 v[208:209], v[50:51], v[160:161], v[208:209] op_sel:[0,1,0] op_sel_hi:[1,1,1] neg_lo:[1,0,0] neg_hi:[1,0,0]
	v_pk_fma_f32 v[210:211], v[58:59], v[160:161], v[210:211] op_sel:[0,1,0] op_sel_hi:[1,1,1] neg_lo:[1,0,0] neg_hi:[1,0,0]
	v_pk_fma_f32 v[208:209], v[52:53], v[162:163], v[208:209] op_sel_hi:[1,0,1] neg_lo:[1,0,0] neg_hi:[1,0,0]
	v_pk_fma_f32 v[210:211], v[60:61], v[162:163], v[210:211] op_sel_hi:[1,0,1] neg_lo:[1,0,0] neg_hi:[1,0,0]
	v_pk_fma_f32 v[208:209], v[54:55], v[162:163], v[208:209] op_sel:[0,1,0] op_sel_hi:[1,1,1] neg_lo:[1,0,0] neg_hi:[1,0,0]
	v_pk_fma_f32 v[210:211], v[62:63], v[162:163], v[210:211] op_sel:[0,1,0] op_sel_hi:[1,1,1] neg_lo:[1,0,0] neg_hi:[1,0,0]
	ds_read_b128 v[48:51], v78 offset:2208
	ds_read_b128 v[52:55], v78 offset:2224
	ds_read_b128 v[56:59], v78 offset:2752
	ds_read_b128 v[60:63], v78 offset:2768
	s_waitcnt lgkmcnt(12)
	v_pk_fma_f32 v[212:213], v[0:1], v[160:161], v[212:213] op_sel_hi:[1,0,1] neg_lo:[1,0,0] neg_hi:[1,0,0]
	v_pk_fma_f32 v[214:215], v[8:9], v[160:161], v[214:215] op_sel_hi:[1,0,1] neg_lo:[1,0,0] neg_hi:[1,0,0]
	v_pk_fma_f32 v[212:213], v[2:3], v[160:161], v[212:213] op_sel:[0,1,0] op_sel_hi:[1,1,1] neg_lo:[1,0,0] neg_hi:[1,0,0]
	v_pk_fma_f32 v[214:215], v[10:11], v[160:161], v[214:215] op_sel:[0,1,0] op_sel_hi:[1,1,1] neg_lo:[1,0,0] neg_hi:[1,0,0]
	v_pk_fma_f32 v[212:213], v[4:5], v[162:163], v[212:213] op_sel_hi:[1,0,1] neg_lo:[1,0,0] neg_hi:[1,0,0]
	v_pk_fma_f32 v[214:215], v[12:13], v[162:163], v[214:215] op_sel_hi:[1,0,1] neg_lo:[1,0,0] neg_hi:[1,0,0]
	v_pk_fma_f32 v[212:213], v[6:7], v[162:163], v[212:213] op_sel:[0,1,0] op_sel_hi:[1,1,1] neg_lo:[1,0,0] neg_hi:[1,0,0]
	v_pk_fma_f32 v[214:215], v[14:15], v[162:163], v[214:215] op_sel:[0,1,0] op_sel_hi:[1,1,1] neg_lo:[1,0,0] neg_hi:[1,0,0]
	ds_read_b128 v[0:3], v78 offset:3296
	ds_read_b128 v[4:7], v78 offset:3312
	ds_read_b128 v[8:11], v78 offset:3840
	ds_read_b128 v[12:15], v78 offset:3856
	s_waitcnt lgkmcnt(12)
	v_pk_fma_f32 v[216:217], v[16:17], v[160:161], v[216:217] op_sel_hi:[1,0,1] neg_lo:[1,0,0] neg_hi:[1,0,0]
	v_pk_fma_f32 v[218:219], v[24:25], v[160:161], v[218:219] op_sel_hi:[1,0,1] neg_lo:[1,0,0] neg_hi:[1,0,0]
	v_pk_fma_f32 v[216:217], v[18:19], v[160:161], v[216:217] op_sel:[0,1,0] op_sel_hi:[1,1,1] neg_lo:[1,0,0] neg_hi:[1,0,0]
	v_pk_fma_f32 v[218:219], v[26:27], v[160:161], v[218:219] op_sel:[0,1,0] op_sel_hi:[1,1,1] neg_lo:[1,0,0] neg_hi:[1,0,0]
	v_pk_fma_f32 v[216:217], v[20:21], v[162:163], v[216:217] op_sel_hi:[1,0,1] neg_lo:[1,0,0] neg_hi:[1,0,0]
	v_pk_fma_f32 v[218:219], v[28:29], v[162:163], v[218:219] op_sel_hi:[1,0,1] neg_lo:[1,0,0] neg_hi:[1,0,0]
	v_pk_fma_f32 v[216:217], v[22:23], v[162:163], v[216:217] op_sel:[0,1,0] op_sel_hi:[1,1,1] neg_lo:[1,0,0] neg_hi:[1,0,0]
	v_pk_fma_f32 v[218:219], v[30:31], v[162:163], v[218:219] op_sel:[0,1,0] op_sel_hi:[1,1,1] neg_lo:[1,0,0] neg_hi:[1,0,0]
	ds_read_b128 v[16:19], v78 offset:4384
	ds_read_b128 v[20:23], v78 offset:4400
	ds_read_b128 v[24:27], v78 offset:4928
	ds_read_b128 v[28:31], v78 offset:4944
	s_waitcnt lgkmcnt(12)
	v_pk_fma_f32 v[220:221], v[32:33], v[160:161], v[220:221] op_sel_hi:[1,0,1] neg_lo:[1,0,0] neg_hi:[1,0,0]
	v_pk_fma_f32 v[222:223], v[40:41], v[160:161], v[222:223] op_sel_hi:[1,0,1] neg_lo:[1,0,0] neg_hi:[1,0,0]
	v_pk_fma_f32 v[220:221], v[34:35], v[160:161], v[220:221] op_sel:[0,1,0] op_sel_hi:[1,1,1] neg_lo:[1,0,0] neg_hi:[1,0,0]
	v_pk_fma_f32 v[222:223], v[42:43], v[160:161], v[222:223] op_sel:[0,1,0] op_sel_hi:[1,1,1] neg_lo:[1,0,0] neg_hi:[1,0,0]
	v_pk_fma_f32 v[220:221], v[36:37], v[162:163], v[220:221] op_sel_hi:[1,0,1] neg_lo:[1,0,0] neg_hi:[1,0,0]
	v_pk_fma_f32 v[222:223], v[44:45], v[162:163], v[222:223] op_sel_hi:[1,0,1] neg_lo:[1,0,0] neg_hi:[1,0,0]
	v_pk_fma_f32 v[220:221], v[38:39], v[162:163], v[220:221] op_sel:[0,1,0] op_sel_hi:[1,1,1] neg_lo:[1,0,0] neg_hi:[1,0,0]
	v_pk_fma_f32 v[222:223], v[46:47], v[162:163], v[222:223] op_sel:[0,1,0] op_sel_hi:[1,1,1] neg_lo:[1,0,0] neg_hi:[1,0,0]
	ds_read_b128 v[64:67], v78 offset:2240
	ds_read_b128 v[68:71], v78 offset:2784
	ds_read_b128 v[72:75], v78 offset:2800
	ds_read_b128 v[32:35], v78 offset:5472
	ds_read_b128 v[36:39], v78 offset:5488
	ds_read_b128 v[40:43], v78 offset:6016
	ds_read_b128 v[44:47], v78 offset:6032
	s_waitcnt lgkmcnt(15)
	v_pk_fma_f32 v[168:169], v[48:49], v[164:165], v[168:169] op_sel_hi:[1,0,1] neg_lo:[1,0,0] neg_hi:[1,0,0]
	v_pk_fma_f32 v[170:171], v[56:57], v[164:165], v[170:171] op_sel_hi:[1,0,1] neg_lo:[1,0,0] neg_hi:[1,0,0]
	v_pk_fma_f32 v[168:169], v[50:51], v[164:165], v[168:169] op_sel:[0,1,0] op_sel_hi:[1,1,1] neg_lo:[1,0,0] neg_hi:[1,0,0]
	v_pk_fma_f32 v[170:171], v[58:59], v[164:165], v[170:171] op_sel:[0,1,0] op_sel_hi:[1,1,1] neg_lo:[1,0,0] neg_hi:[1,0,0]
	v_pk_fma_f32 v[168:169], v[52:53], v[166:167], v[168:169] op_sel_hi:[1,0,1] neg_lo:[1,0,0] neg_hi:[1,0,0]
	v_pk_fma_f32 v[170:171], v[60:61], v[166:167], v[170:171] op_sel_hi:[1,0,1] neg_lo:[1,0,0] neg_hi:[1,0,0]
	v_pk_fma_f32 v[168:169], v[54:55], v[166:167], v[168:169] op_sel:[0,1,0] op_sel_hi:[1,1,1] neg_lo:[1,0,0] neg_hi:[1,0,0]
	v_pk_fma_f32 v[170:171], v[62:63], v[166:167], v[170:171] op_sel:[0,1,0] op_sel_hi:[1,1,1] neg_lo:[1,0,0] neg_hi:[1,0,0]
	ds_read_b128 v[48:51], v78 offset:6560
	ds_read_b128 v[52:55], v78 offset:6576
	ds_read_b128 v[56:59], v78 offset:7104
	ds_read_b128 v[60:63], v78 offset:7120
	s_waitcnt lgkmcnt(15)
	v_pk_fma_f32 v[172:173], v[0:1], v[164:165], v[172:173] op_sel_hi:[1,0,1] neg_lo:[1,0,0] neg_hi:[1,0,0]
	v_pk_fma_f32 v[174:175], v[8:9], v[164:165], v[174:175] op_sel_hi:[1,0,1] neg_lo:[1,0,0] neg_hi:[1,0,0]
	s_waitcnt lgkmcnt(10)
	v_pk_fma_f32 v[168:169], v[64:65], v[168:169], v[168:169] op_sel_hi:[1,0,1] neg_lo:[1,0,0] neg_hi:[1,0,0]
	v_pk_fma_f32 v[172:173], v[2:3], v[164:165], v[172:173] op_sel:[0,1,0] op_sel_hi:[1,1,1] neg_lo:[1,0,0] neg_hi:[1,0,0]
	v_pk_fma_f32 v[174:175], v[10:11], v[164:165], v[174:175] op_sel:[0,1,0] op_sel_hi:[1,1,1] neg_lo:[1,0,0] neg_hi:[1,0,0]
	s_waitcnt lgkmcnt(9)
	v_pk_fma_f32 v[170:171], v[68:69], v[168:169], v[170:171] op_sel_hi:[1,0,1] neg_lo:[1,0,0] neg_hi:[1,0,0]
	v_pk_fma_f32 v[172:173], v[4:5], v[166:167], v[172:173] op_sel_hi:[1,0,1] neg_lo:[1,0,0] neg_hi:[1,0,0]
	v_pk_fma_f32 v[174:175], v[12:13], v[166:167], v[174:175] op_sel_hi:[1,0,1] neg_lo:[1,0,0] neg_hi:[1,0,0]
	v_pk_fma_f32 v[170:171], v[70:71], v[168:169], v[170:171] op_sel:[0,1,0] op_sel_hi:[1,1,1] neg_lo:[1,0,0] neg_hi:[1,0,0]
	v_pk_fma_f32 v[172:173], v[6:7], v[166:167], v[172:173] op_sel:[0,1,0] op_sel_hi:[1,1,1] neg_lo:[1,0,0] neg_hi:[1,0,0]
	v_pk_fma_f32 v[174:175], v[14:15], v[166:167], v[174:175] op_sel:[0,1,0] op_sel_hi:[1,1,1] neg_lo:[1,0,0] neg_hi:[1,0,0]
	s_waitcnt lgkmcnt(8)
	v_pk_fma_f32 v[170:171], v[72:73], v[170:171], v[170:171] op_sel_hi:[1,0,1] neg_lo:[1,0,0] neg_hi:[1,0,0]
	ds_read_b128 v[0:3], v78 offset:7648
	ds_read_b128 v[4:7], v78 offset:7664
	ds_read_b128 v[8:11], v78 offset:8192
	ds_read_b128 v[12:15], v78 offset:8208
	s_waitcnt lgkmcnt(15)
	v_pk_fma_f32 v[176:177], v[16:17], v[164:165], v[176:177] op_sel_hi:[1,0,1] neg_lo:[1,0,0] neg_hi:[1,0,0]
	v_pk_fma_f32 v[178:179], v[24:25], v[164:165], v[178:179] op_sel_hi:[1,0,1] neg_lo:[1,0,0] neg_hi:[1,0,0]
	v_pk_fma_f32 v[176:177], v[18:19], v[164:165], v[176:177] op_sel:[0,1,0] op_sel_hi:[1,1,1] neg_lo:[1,0,0] neg_hi:[1,0,0]
	v_pk_fma_f32 v[178:179], v[26:27], v[164:165], v[178:179] op_sel:[0,1,0] op_sel_hi:[1,1,1] neg_lo:[1,0,0] neg_hi:[1,0,0]
	v_pk_fma_f32 v[176:177], v[20:21], v[166:167], v[176:177] op_sel_hi:[1,0,1] neg_lo:[1,0,0] neg_hi:[1,0,0]
	v_pk_fma_f32 v[178:179], v[28:29], v[166:167], v[178:179] op_sel_hi:[1,0,1] neg_lo:[1,0,0] neg_hi:[1,0,0]
	v_pk_fma_f32 v[176:177], v[22:23], v[166:167], v[176:177] op_sel:[0,1,0] op_sel_hi:[1,1,1] neg_lo:[1,0,0] neg_hi:[1,0,0]
	v_pk_fma_f32 v[178:179], v[30:31], v[166:167], v[178:179] op_sel:[0,1,0] op_sel_hi:[1,1,1] neg_lo:[1,0,0] neg_hi:[1,0,0]
	ds_read_b128 v[16:19], v78 offset:8736
	ds_read_b128 v[20:23], v78 offset:8752
	ds_read_b128 v[24:27], v78 offset:9280
	ds_read_b128 v[28:31], v78 offset:9296
	s_waitcnt lgkmcnt(12)
	v_pk_fma_f32 v[180:181], v[32:33], v[164:165], v[180:181] op_sel_hi:[1,0,1] neg_lo:[1,0,0] neg_hi:[1,0,0]
	v_pk_fma_f32 v[182:183], v[40:41], v[164:165], v[182:183] op_sel_hi:[1,0,1] neg_lo:[1,0,0] neg_hi:[1,0,0]
	v_pk_fma_f32 v[180:181], v[34:35], v[164:165], v[180:181] op_sel:[0,1,0] op_sel_hi:[1,1,1] neg_lo:[1,0,0] neg_hi:[1,0,0]
	v_pk_fma_f32 v[182:183], v[42:43], v[164:165], v[182:183] op_sel:[0,1,0] op_sel_hi:[1,1,1] neg_lo:[1,0,0] neg_hi:[1,0,0]
	v_pk_fma_f32 v[180:181], v[36:37], v[166:167], v[180:181] op_sel_hi:[1,0,1] neg_lo:[1,0,0] neg_hi:[1,0,0]
	v_pk_fma_f32 v[182:183], v[44:45], v[166:167], v[182:183] op_sel_hi:[1,0,1] neg_lo:[1,0,0] neg_hi:[1,0,0]
	v_pk_fma_f32 v[180:181], v[38:39], v[166:167], v[180:181] op_sel:[0,1,0] op_sel_hi:[1,1,1] neg_lo:[1,0,0] neg_hi:[1,0,0]
	v_pk_fma_f32 v[182:183], v[46:47], v[166:167], v[182:183] op_sel:[0,1,0] op_sel_hi:[1,1,1] neg_lo:[1,0,0] neg_hi:[1,0,0]
	ds_read_b128 v[32:35], v78 offset:9824
	ds_read_b128 v[36:39], v78 offset:9840
	ds_read_b128 v[40:43], v78 offset:10368
	ds_read_b128 v[44:47], v78 offset:10384
	s_waitcnt lgkmcnt(12)
	v_pk_fma_f32 v[184:185], v[48:49], v[164:165], v[184:185] op_sel_hi:[1,0,1] neg_lo:[1,0,0] neg_hi:[1,0,0]
	v_pk_fma_f32 v[186:187], v[56:57], v[164:165], v[186:187] op_sel_hi:[1,0,1] neg_lo:[1,0,0] neg_hi:[1,0,0]
	v_pk_fma_f32 v[184:185], v[50:51], v[164:165], v[184:185] op_sel:[0,1,0] op_sel_hi:[1,1,1] neg_lo:[1,0,0] neg_hi:[1,0,0]
	v_pk_fma_f32 v[186:187], v[58:59], v[164:165], v[186:187] op_sel:[0,1,0] op_sel_hi:[1,1,1] neg_lo:[1,0,0] neg_hi:[1,0,0]
	v_pk_fma_f32 v[184:185], v[52:53], v[166:167], v[184:185] op_sel_hi:[1,0,1] neg_lo:[1,0,0] neg_hi:[1,0,0]
	v_pk_fma_f32 v[186:187], v[60:61], v[166:167], v[186:187] op_sel_hi:[1,0,1] neg_lo:[1,0,0] neg_hi:[1,0,0]
	v_pk_fma_f32 v[184:185], v[54:55], v[166:167], v[184:185] op_sel:[0,1,0] op_sel_hi:[1,1,1] neg_lo:[1,0,0] neg_hi:[1,0,0]
	v_pk_fma_f32 v[186:187], v[62:63], v[166:167], v[186:187] op_sel:[0,1,0] op_sel_hi:[1,1,1] neg_lo:[1,0,0] neg_hi:[1,0,0]
	ds_read_b128 v[48:51], v78 offset:10912
	ds_read_b128 v[52:55], v78 offset:10928
	ds_read_b128 v[56:59], v78 offset:11456
	ds_read_b128 v[60:63], v78 offset:11472
	s_waitcnt lgkmcnt(12)
	v_pk_fma_f32 v[188:189], v[0:1], v[164:165], v[188:189] op_sel_hi:[1,0,1] neg_lo:[1,0,0] neg_hi:[1,0,0]
	v_pk_fma_f32 v[190:191], v[8:9], v[164:165], v[190:191] op_sel_hi:[1,0,1] neg_lo:[1,0,0] neg_hi:[1,0,0]
	v_pk_fma_f32 v[188:189], v[2:3], v[164:165], v[188:189] op_sel:[0,1,0] op_sel_hi:[1,1,1] neg_lo:[1,0,0] neg_hi:[1,0,0]
	v_pk_fma_f32 v[190:191], v[10:11], v[164:165], v[190:191] op_sel:[0,1,0] op_sel_hi:[1,1,1] neg_lo:[1,0,0] neg_hi:[1,0,0]
	v_pk_fma_f32 v[188:189], v[4:5], v[166:167], v[188:189] op_sel_hi:[1,0,1] neg_lo:[1,0,0] neg_hi:[1,0,0]
	v_pk_fma_f32 v[190:191], v[12:13], v[166:167], v[190:191] op_sel_hi:[1,0,1] neg_lo:[1,0,0] neg_hi:[1,0,0]
	v_pk_fma_f32 v[188:189], v[6:7], v[166:167], v[188:189] op_sel:[0,1,0] op_sel_hi:[1,1,1] neg_lo:[1,0,0] neg_hi:[1,0,0]
	v_pk_fma_f32 v[190:191], v[14:15], v[166:167], v[190:191] op_sel:[0,1,0] op_sel_hi:[1,1,1] neg_lo:[1,0,0] neg_hi:[1,0,0]
	ds_read_b128 v[0:3], v78 offset:12000
	ds_read_b128 v[4:7], v78 offset:12016
	ds_read_b128 v[8:11], v78 offset:12544
	ds_read_b128 v[12:15], v78 offset:12560
	s_waitcnt lgkmcnt(12)
	v_pk_fma_f32 v[192:193], v[16:17], v[164:165], v[192:193] op_sel_hi:[1,0,1] neg_lo:[1,0,0] neg_hi:[1,0,0]
	v_pk_fma_f32 v[194:195], v[24:25], v[164:165], v[194:195] op_sel_hi:[1,0,1] neg_lo:[1,0,0] neg_hi:[1,0,0]
	v_pk_fma_f32 v[192:193], v[18:19], v[164:165], v[192:193] op_sel:[0,1,0] op_sel_hi:[1,1,1] neg_lo:[1,0,0] neg_hi:[1,0,0]
	v_pk_fma_f32 v[194:195], v[26:27], v[164:165], v[194:195] op_sel:[0,1,0] op_sel_hi:[1,1,1] neg_lo:[1,0,0] neg_hi:[1,0,0]
	v_pk_fma_f32 v[192:193], v[20:21], v[166:167], v[192:193] op_sel_hi:[1,0,1] neg_lo:[1,0,0] neg_hi:[1,0,0]
	v_pk_fma_f32 v[194:195], v[28:29], v[166:167], v[194:195] op_sel_hi:[1,0,1] neg_lo:[1,0,0] neg_hi:[1,0,0]
	v_pk_fma_f32 v[192:193], v[22:23], v[166:167], v[192:193] op_sel:[0,1,0] op_sel_hi:[1,1,1] neg_lo:[1,0,0] neg_hi:[1,0,0]
	v_pk_fma_f32 v[194:195], v[30:31], v[166:167], v[194:195] op_sel:[0,1,0] op_sel_hi:[1,1,1] neg_lo:[1,0,0] neg_hi:[1,0,0]
	ds_read_b128 v[16:19], v78 offset:13088
	ds_read_b128 v[20:23], v78 offset:13104
	ds_read_b128 v[24:27], v78 offset:13632
	ds_read_b128 v[28:31], v78 offset:13648
	s_waitcnt lgkmcnt(12)
	v_pk_fma_f32 v[196:197], v[32:33], v[164:165], v[196:197] op_sel_hi:[1,0,1] neg_lo:[1,0,0] neg_hi:[1,0,0]
	v_pk_fma_f32 v[198:199], v[40:41], v[164:165], v[198:199] op_sel_hi:[1,0,1] neg_lo:[1,0,0] neg_hi:[1,0,0]
	v_pk_fma_f32 v[196:197], v[34:35], v[164:165], v[196:197] op_sel:[0,1,0] op_sel_hi:[1,1,1] neg_lo:[1,0,0] neg_hi:[1,0,0]
	v_pk_fma_f32 v[198:199], v[42:43], v[164:165], v[198:199] op_sel:[0,1,0] op_sel_hi:[1,1,1] neg_lo:[1,0,0] neg_hi:[1,0,0]
	v_pk_fma_f32 v[196:197], v[36:37], v[166:167], v[196:197] op_sel_hi:[1,0,1] neg_lo:[1,0,0] neg_hi:[1,0,0]
	v_pk_fma_f32 v[198:199], v[44:45], v[166:167], v[198:199] op_sel_hi:[1,0,1] neg_lo:[1,0,0] neg_hi:[1,0,0]
	v_pk_fma_f32 v[196:197], v[38:39], v[166:167], v[196:197] op_sel:[0,1,0] op_sel_hi:[1,1,1] neg_lo:[1,0,0] neg_hi:[1,0,0]
	v_pk_fma_f32 v[198:199], v[46:47], v[166:167], v[198:199] op_sel:[0,1,0] op_sel_hi:[1,1,1] neg_lo:[1,0,0] neg_hi:[1,0,0]
	ds_read_b128 v[32:35], v78 offset:14176
	ds_read_b128 v[36:39], v78 offset:14192
	ds_read_b128 v[40:43], v78 offset:14720
	ds_read_b128 v[44:47], v78 offset:14736
	s_waitcnt lgkmcnt(12)
	v_pk_fma_f32 v[200:201], v[48:49], v[164:165], v[200:201] op_sel_hi:[1,0,1] neg_lo:[1,0,0] neg_hi:[1,0,0]
	v_pk_fma_f32 v[202:203], v[56:57], v[164:165], v[202:203] op_sel_hi:[1,0,1] neg_lo:[1,0,0] neg_hi:[1,0,0]
	v_pk_fma_f32 v[200:201], v[50:51], v[164:165], v[200:201] op_sel:[0,1,0] op_sel_hi:[1,1,1] neg_lo:[1,0,0] neg_hi:[1,0,0]
	v_pk_fma_f32 v[202:203], v[58:59], v[164:165], v[202:203] op_sel:[0,1,0] op_sel_hi:[1,1,1] neg_lo:[1,0,0] neg_hi:[1,0,0]
	v_pk_fma_f32 v[200:201], v[52:53], v[166:167], v[200:201] op_sel_hi:[1,0,1] neg_lo:[1,0,0] neg_hi:[1,0,0]
	v_pk_fma_f32 v[202:203], v[60:61], v[166:167], v[202:203] op_sel_hi:[1,0,1] neg_lo:[1,0,0] neg_hi:[1,0,0]
	v_pk_fma_f32 v[200:201], v[54:55], v[166:167], v[200:201] op_sel:[0,1,0] op_sel_hi:[1,1,1] neg_lo:[1,0,0] neg_hi:[1,0,0]
	v_pk_fma_f32 v[202:203], v[62:63], v[166:167], v[202:203] op_sel:[0,1,0] op_sel_hi:[1,1,1] neg_lo:[1,0,0] neg_hi:[1,0,0]
	ds_read_b128 v[48:51], v78 offset:15264
	ds_read_b128 v[52:55], v78 offset:15280
	ds_read_b128 v[56:59], v78 offset:15808
	ds_read_b128 v[60:63], v78 offset:15824
	s_waitcnt lgkmcnt(12)
	v_pk_fma_f32 v[204:205], v[0:1], v[164:165], v[204:205] op_sel_hi:[1,0,1] neg_lo:[1,0,0] neg_hi:[1,0,0]
	v_pk_fma_f32 v[206:207], v[8:9], v[164:165], v[206:207] op_sel_hi:[1,0,1] neg_lo:[1,0,0] neg_hi:[1,0,0]
	v_pk_fma_f32 v[204:205], v[2:3], v[164:165], v[204:205] op_sel:[0,1,0] op_sel_hi:[1,1,1] neg_lo:[1,0,0] neg_hi:[1,0,0]
	v_pk_fma_f32 v[206:207], v[10:11], v[164:165], v[206:207] op_sel:[0,1,0] op_sel_hi:[1,1,1] neg_lo:[1,0,0] neg_hi:[1,0,0]
	v_pk_fma_f32 v[204:205], v[4:5], v[166:167], v[204:205] op_sel_hi:[1,0,1] neg_lo:[1,0,0] neg_hi:[1,0,0]
	v_pk_fma_f32 v[206:207], v[12:13], v[166:167], v[206:207] op_sel_hi:[1,0,1] neg_lo:[1,0,0] neg_hi:[1,0,0]
	v_pk_fma_f32 v[204:205], v[6:7], v[166:167], v[204:205] op_sel:[0,1,0] op_sel_hi:[1,1,1] neg_lo:[1,0,0] neg_hi:[1,0,0]
	v_pk_fma_f32 v[206:207], v[14:15], v[166:167], v[206:207] op_sel:[0,1,0] op_sel_hi:[1,1,1] neg_lo:[1,0,0] neg_hi:[1,0,0]
	ds_read_b128 v[0:3], v78 offset:16352
	ds_read_b128 v[4:7], v78 offset:16368
	ds_read_b128 v[8:11], v78 offset:16896
	ds_read_b128 v[12:15], v78 offset:16912
	s_waitcnt lgkmcnt(12)
	v_pk_fma_f32 v[208:209], v[16:17], v[164:165], v[208:209] op_sel_hi:[1,0,1] neg_lo:[1,0,0] neg_hi:[1,0,0]
	v_pk_fma_f32 v[210:211], v[24:25], v[164:165], v[210:211] op_sel_hi:[1,0,1] neg_lo:[1,0,0] neg_hi:[1,0,0]
	v_pk_fma_f32 v[208:209], v[18:19], v[164:165], v[208:209] op_sel:[0,1,0] op_sel_hi:[1,1,1] neg_lo:[1,0,0] neg_hi:[1,0,0]
	v_pk_fma_f32 v[210:211], v[26:27], v[164:165], v[210:211] op_sel:[0,1,0] op_sel_hi:[1,1,1] neg_lo:[1,0,0] neg_hi:[1,0,0]
	v_pk_fma_f32 v[208:209], v[20:21], v[166:167], v[208:209] op_sel_hi:[1,0,1] neg_lo:[1,0,0] neg_hi:[1,0,0]
	v_pk_fma_f32 v[210:211], v[28:29], v[166:167], v[210:211] op_sel_hi:[1,0,1] neg_lo:[1,0,0] neg_hi:[1,0,0]
	v_pk_fma_f32 v[208:209], v[22:23], v[166:167], v[208:209] op_sel:[0,1,0] op_sel_hi:[1,1,1] neg_lo:[1,0,0] neg_hi:[1,0,0]
	v_pk_fma_f32 v[210:211], v[30:31], v[166:167], v[210:211] op_sel:[0,1,0] op_sel_hi:[1,1,1] neg_lo:[1,0,0] neg_hi:[1,0,0]
	ds_read_b128 v[16:19], v78 offset:3328
	ds_read_b128 v[20:23], v78 offset:3344
	ds_read_b128 v[24:27], v78 offset:3872
	ds_read_b128 v[28:31], v78 offset:3888
	s_waitcnt lgkmcnt(12)
	v_pk_fma_f32 v[212:213], v[32:33], v[164:165], v[212:213] op_sel_hi:[1,0,1] neg_lo:[1,0,0] neg_hi:[1,0,0]
	v_pk_fma_f32 v[214:215], v[40:41], v[164:165], v[214:215] op_sel_hi:[1,0,1] neg_lo:[1,0,0] neg_hi:[1,0,0]
	v_pk_fma_f32 v[212:213], v[34:35], v[164:165], v[212:213] op_sel:[0,1,0] op_sel_hi:[1,1,1] neg_lo:[1,0,0] neg_hi:[1,0,0]
	v_pk_fma_f32 v[214:215], v[42:43], v[164:165], v[214:215] op_sel:[0,1,0] op_sel_hi:[1,1,1] neg_lo:[1,0,0] neg_hi:[1,0,0]
	v_pk_fma_f32 v[212:213], v[36:37], v[166:167], v[212:213] op_sel_hi:[1,0,1] neg_lo:[1,0,0] neg_hi:[1,0,0]
	v_pk_fma_f32 v[214:215], v[44:45], v[166:167], v[214:215] op_sel_hi:[1,0,1] neg_lo:[1,0,0] neg_hi:[1,0,0]
	v_pk_fma_f32 v[212:213], v[38:39], v[166:167], v[212:213] op_sel:[0,1,0] op_sel_hi:[1,1,1] neg_lo:[1,0,0] neg_hi:[1,0,0]
	v_pk_fma_f32 v[214:215], v[46:47], v[166:167], v[214:215] op_sel:[0,1,0] op_sel_hi:[1,1,1] neg_lo:[1,0,0] neg_hi:[1,0,0]
	ds_read_b128 v[32:35], v78 offset:4416
	ds_read_b128 v[36:39], v78 offset:4432
	ds_read_b128 v[40:43], v78 offset:4960
	ds_read_b128 v[44:47], v78 offset:4976
	s_waitcnt lgkmcnt(12)
	v_pk_fma_f32 v[216:217], v[48:49], v[164:165], v[216:217] op_sel_hi:[1,0,1] neg_lo:[1,0,0] neg_hi:[1,0,0]
	v_pk_fma_f32 v[218:219], v[56:57], v[164:165], v[218:219] op_sel_hi:[1,0,1] neg_lo:[1,0,0] neg_hi:[1,0,0]
	v_pk_fma_f32 v[216:217], v[50:51], v[164:165], v[216:217] op_sel:[0,1,0] op_sel_hi:[1,1,1] neg_lo:[1,0,0] neg_hi:[1,0,0]
	v_pk_fma_f32 v[218:219], v[58:59], v[164:165], v[218:219] op_sel:[0,1,0] op_sel_hi:[1,1,1] neg_lo:[1,0,0] neg_hi:[1,0,0]
	v_pk_fma_f32 v[216:217], v[52:53], v[166:167], v[216:217] op_sel_hi:[1,0,1] neg_lo:[1,0,0] neg_hi:[1,0,0]
	v_pk_fma_f32 v[218:219], v[60:61], v[166:167], v[218:219] op_sel_hi:[1,0,1] neg_lo:[1,0,0] neg_hi:[1,0,0]
	v_pk_fma_f32 v[216:217], v[54:55], v[166:167], v[216:217] op_sel:[0,1,0] op_sel_hi:[1,1,1] neg_lo:[1,0,0] neg_hi:[1,0,0]
	v_pk_fma_f32 v[218:219], v[62:63], v[166:167], v[218:219] op_sel:[0,1,0] op_sel_hi:[1,1,1] neg_lo:[1,0,0] neg_hi:[1,0,0]
	ds_read_b128 v[48:51], v78 offset:5504
	ds_read_b128 v[52:55], v78 offset:5520
	ds_read_b128 v[56:59], v78 offset:6048
	ds_read_b128 v[60:63], v78 offset:6064
	s_waitcnt lgkmcnt(12)
	v_pk_fma_f32 v[220:221], v[0:1], v[164:165], v[220:221] op_sel_hi:[1,0,1] neg_lo:[1,0,0] neg_hi:[1,0,0]
	v_pk_fma_f32 v[222:223], v[8:9], v[164:165], v[222:223] op_sel_hi:[1,0,1] neg_lo:[1,0,0] neg_hi:[1,0,0]
	v_pk_fma_f32 v[220:221], v[2:3], v[164:165], v[220:221] op_sel:[0,1,0] op_sel_hi:[1,1,1] neg_lo:[1,0,0] neg_hi:[1,0,0]
	v_pk_fma_f32 v[222:223], v[10:11], v[164:165], v[222:223] op_sel:[0,1,0] op_sel_hi:[1,1,1] neg_lo:[1,0,0] neg_hi:[1,0,0]
	v_pk_fma_f32 v[220:221], v[4:5], v[166:167], v[220:221] op_sel_hi:[1,0,1] neg_lo:[1,0,0] neg_hi:[1,0,0]
	v_pk_fma_f32 v[222:223], v[12:13], v[166:167], v[222:223] op_sel_hi:[1,0,1] neg_lo:[1,0,0] neg_hi:[1,0,0]
	v_pk_fma_f32 v[220:221], v[6:7], v[166:167], v[220:221] op_sel:[0,1,0] op_sel_hi:[1,1,1] neg_lo:[1,0,0] neg_hi:[1,0,0]
	v_pk_fma_f32 v[222:223], v[14:15], v[166:167], v[222:223] op_sel:[0,1,0] op_sel_hi:[1,1,1] neg_lo:[1,0,0] neg_hi:[1,0,0]
	ds_read_b128 v[64:67], v78 offset:3360
	ds_read_b128 v[68:71], v78 offset:3904
	ds_read_b128 v[72:75], v78 offset:3920
	ds_read_b128 v[0:3], v78 offset:6592
	ds_read_b128 v[4:7], v78 offset:6608
	ds_read_b128 v[8:11], v78 offset:7136
	ds_read_b128 v[12:15], v78 offset:7152
	s_waitcnt lgkmcnt(15)
	v_pk_fma_f32 v[172:173], v[16:17], v[168:169], v[172:173] op_sel_hi:[1,0,1] neg_lo:[1,0,0] neg_hi:[1,0,0]
	v_pk_fma_f32 v[174:175], v[24:25], v[168:169], v[174:175] op_sel_hi:[1,0,1] neg_lo:[1,0,0] neg_hi:[1,0,0]
	v_pk_fma_f32 v[172:173], v[18:19], v[168:169], v[172:173] op_sel:[0,1,0] op_sel_hi:[1,1,1] neg_lo:[1,0,0] neg_hi:[1,0,0]
	v_pk_fma_f32 v[174:175], v[26:27], v[168:169], v[174:175] op_sel:[0,1,0] op_sel_hi:[1,1,1] neg_lo:[1,0,0] neg_hi:[1,0,0]
	v_pk_fma_f32 v[172:173], v[20:21], v[170:171], v[172:173] op_sel_hi:[1,0,1] neg_lo:[1,0,0] neg_hi:[1,0,0]
	v_pk_fma_f32 v[174:175], v[28:29], v[170:171], v[174:175] op_sel_hi:[1,0,1] neg_lo:[1,0,0] neg_hi:[1,0,0]
	v_pk_fma_f32 v[172:173], v[22:23], v[170:171], v[172:173] op_sel:[0,1,0] op_sel_hi:[1,1,1] neg_lo:[1,0,0] neg_hi:[1,0,0]
	v_pk_fma_f32 v[174:175], v[30:31], v[170:171], v[174:175] op_sel:[0,1,0] op_sel_hi:[1,1,1] neg_lo:[1,0,0] neg_hi:[1,0,0]
	ds_read_b128 v[16:19], v78 offset:7680
	ds_read_b128 v[20:23], v78 offset:7696
	ds_read_b128 v[24:27], v78 offset:8224
	ds_read_b128 v[28:31], v78 offset:8240
	s_waitcnt lgkmcnt(15)
	v_pk_fma_f32 v[176:177], v[32:33], v[168:169], v[176:177] op_sel_hi:[1,0,1] neg_lo:[1,0,0] neg_hi:[1,0,0]
	v_pk_fma_f32 v[178:179], v[40:41], v[168:169], v[178:179] op_sel_hi:[1,0,1] neg_lo:[1,0,0] neg_hi:[1,0,0]
	s_waitcnt lgkmcnt(10)
	v_pk_fma_f32 v[172:173], v[64:65], v[172:173], v[172:173] op_sel_hi:[1,0,1] neg_lo:[1,0,0] neg_hi:[1,0,0]
	v_pk_fma_f32 v[176:177], v[34:35], v[168:169], v[176:177] op_sel:[0,1,0] op_sel_hi:[1,1,1] neg_lo:[1,0,0] neg_hi:[1,0,0]
	v_pk_fma_f32 v[178:179], v[42:43], v[168:169], v[178:179] op_sel:[0,1,0] op_sel_hi:[1,1,1] neg_lo:[1,0,0] neg_hi:[1,0,0]
	s_waitcnt lgkmcnt(9)
	v_pk_fma_f32 v[174:175], v[68:69], v[172:173], v[174:175] op_sel_hi:[1,0,1] neg_lo:[1,0,0] neg_hi:[1,0,0]
	v_pk_fma_f32 v[176:177], v[36:37], v[170:171], v[176:177] op_sel_hi:[1,0,1] neg_lo:[1,0,0] neg_hi:[1,0,0]
	v_pk_fma_f32 v[178:179], v[44:45], v[170:171], v[178:179] op_sel_hi:[1,0,1] neg_lo:[1,0,0] neg_hi:[1,0,0]
	v_pk_fma_f32 v[174:175], v[70:71], v[172:173], v[174:175] op_sel:[0,1,0] op_sel_hi:[1,1,1] neg_lo:[1,0,0] neg_hi:[1,0,0]
	v_pk_fma_f32 v[176:177], v[38:39], v[170:171], v[176:177] op_sel:[0,1,0] op_sel_hi:[1,1,1] neg_lo:[1,0,0] neg_hi:[1,0,0]
	v_pk_fma_f32 v[178:179], v[46:47], v[170:171], v[178:179] op_sel:[0,1,0] op_sel_hi:[1,1,1] neg_lo:[1,0,0] neg_hi:[1,0,0]
	s_waitcnt lgkmcnt(8)
	v_pk_fma_f32 v[174:175], v[72:73], v[174:175], v[174:175] op_sel_hi:[1,0,1] neg_lo:[1,0,0] neg_hi:[1,0,0]
	ds_read_b128 v[32:35], v78 offset:8768
	ds_read_b128 v[36:39], v78 offset:8784
	ds_read_b128 v[40:43], v78 offset:9312
	ds_read_b128 v[44:47], v78 offset:9328
	s_waitcnt lgkmcnt(15)
	v_pk_fma_f32 v[180:181], v[48:49], v[168:169], v[180:181] op_sel_hi:[1,0,1] neg_lo:[1,0,0] neg_hi:[1,0,0]
	v_pk_fma_f32 v[182:183], v[56:57], v[168:169], v[182:183] op_sel_hi:[1,0,1] neg_lo:[1,0,0] neg_hi:[1,0,0]
	v_pk_fma_f32 v[180:181], v[50:51], v[168:169], v[180:181] op_sel:[0,1,0] op_sel_hi:[1,1,1] neg_lo:[1,0,0] neg_hi:[1,0,0]
	v_pk_fma_f32 v[182:183], v[58:59], v[168:169], v[182:183] op_sel:[0,1,0] op_sel_hi:[1,1,1] neg_lo:[1,0,0] neg_hi:[1,0,0]
	v_pk_fma_f32 v[180:181], v[52:53], v[170:171], v[180:181] op_sel_hi:[1,0,1] neg_lo:[1,0,0] neg_hi:[1,0,0]
	v_pk_fma_f32 v[182:183], v[60:61], v[170:171], v[182:183] op_sel_hi:[1,0,1] neg_lo:[1,0,0] neg_hi:[1,0,0]
	v_pk_fma_f32 v[180:181], v[54:55], v[170:171], v[180:181] op_sel:[0,1,0] op_sel_hi:[1,1,1] neg_lo:[1,0,0] neg_hi:[1,0,0]
	v_pk_fma_f32 v[182:183], v[62:63], v[170:171], v[182:183] op_sel:[0,1,0] op_sel_hi:[1,1,1] neg_lo:[1,0,0] neg_hi:[1,0,0]
	ds_read_b128 v[48:51], v78 offset:9856
	ds_read_b128 v[52:55], v78 offset:9872
	ds_read_b128 v[56:59], v78 offset:10400
	ds_read_b128 v[60:63], v78 offset:10416
	s_waitcnt lgkmcnt(12)
	v_pk_fma_f32 v[184:185], v[0:1], v[168:169], v[184:185] op_sel_hi:[1,0,1] neg_lo:[1,0,0] neg_hi:[1,0,0]
	v_pk_fma_f32 v[186:187], v[8:9], v[168:169], v[186:187] op_sel_hi:[1,0,1] neg_lo:[1,0,0] neg_hi:[1,0,0]
	v_pk_fma_f32 v[184:185], v[2:3], v[168:169], v[184:185] op_sel:[0,1,0] op_sel_hi:[1,1,1] neg_lo:[1,0,0] neg_hi:[1,0,0]
	v_pk_fma_f32 v[186:187], v[10:11], v[168:169], v[186:187] op_sel:[0,1,0] op_sel_hi:[1,1,1] neg_lo:[1,0,0] neg_hi:[1,0,0]
	v_pk_fma_f32 v[184:185], v[4:5], v[170:171], v[184:185] op_sel_hi:[1,0,1] neg_lo:[1,0,0] neg_hi:[1,0,0]
	v_pk_fma_f32 v[186:187], v[12:13], v[170:171], v[186:187] op_sel_hi:[1,0,1] neg_lo:[1,0,0] neg_hi:[1,0,0]
	v_pk_fma_f32 v[184:185], v[6:7], v[170:171], v[184:185] op_sel:[0,1,0] op_sel_hi:[1,1,1] neg_lo:[1,0,0] neg_hi:[1,0,0]
	v_pk_fma_f32 v[186:187], v[14:15], v[170:171], v[186:187] op_sel:[0,1,0] op_sel_hi:[1,1,1] neg_lo:[1,0,0] neg_hi:[1,0,0]
	ds_read_b128 v[0:3], v78 offset:10944
	ds_read_b128 v[4:7], v78 offset:10960
	ds_read_b128 v[8:11], v78 offset:11488
	ds_read_b128 v[12:15], v78 offset:11504
	s_waitcnt lgkmcnt(12)
	v_pk_fma_f32 v[188:189], v[16:17], v[168:169], v[188:189] op_sel_hi:[1,0,1] neg_lo:[1,0,0] neg_hi:[1,0,0]
	v_pk_fma_f32 v[190:191], v[24:25], v[168:169], v[190:191] op_sel_hi:[1,0,1] neg_lo:[1,0,0] neg_hi:[1,0,0]
	v_pk_fma_f32 v[188:189], v[18:19], v[168:169], v[188:189] op_sel:[0,1,0] op_sel_hi:[1,1,1] neg_lo:[1,0,0] neg_hi:[1,0,0]
	v_pk_fma_f32 v[190:191], v[26:27], v[168:169], v[190:191] op_sel:[0,1,0] op_sel_hi:[1,1,1] neg_lo:[1,0,0] neg_hi:[1,0,0]
	v_pk_fma_f32 v[188:189], v[20:21], v[170:171], v[188:189] op_sel_hi:[1,0,1] neg_lo:[1,0,0] neg_hi:[1,0,0]
	v_pk_fma_f32 v[190:191], v[28:29], v[170:171], v[190:191] op_sel_hi:[1,0,1] neg_lo:[1,0,0] neg_hi:[1,0,0]
	v_pk_fma_f32 v[188:189], v[22:23], v[170:171], v[188:189] op_sel:[0,1,0] op_sel_hi:[1,1,1] neg_lo:[1,0,0] neg_hi:[1,0,0]
	v_pk_fma_f32 v[190:191], v[30:31], v[170:171], v[190:191] op_sel:[0,1,0] op_sel_hi:[1,1,1] neg_lo:[1,0,0] neg_hi:[1,0,0]
	ds_read_b128 v[16:19], v78 offset:12032
	ds_read_b128 v[20:23], v78 offset:12048
	ds_read_b128 v[24:27], v78 offset:12576
	ds_read_b128 v[28:31], v78 offset:12592
	s_waitcnt lgkmcnt(12)
	v_pk_fma_f32 v[192:193], v[32:33], v[168:169], v[192:193] op_sel_hi:[1,0,1] neg_lo:[1,0,0] neg_hi:[1,0,0]
	v_pk_fma_f32 v[194:195], v[40:41], v[168:169], v[194:195] op_sel_hi:[1,0,1] neg_lo:[1,0,0] neg_hi:[1,0,0]
	v_pk_fma_f32 v[192:193], v[34:35], v[168:169], v[192:193] op_sel:[0,1,0] op_sel_hi:[1,1,1] neg_lo:[1,0,0] neg_hi:[1,0,0]
	v_pk_fma_f32 v[194:195], v[42:43], v[168:169], v[194:195] op_sel:[0,1,0] op_sel_hi:[1,1,1] neg_lo:[1,0,0] neg_hi:[1,0,0]
	v_pk_fma_f32 v[192:193], v[36:37], v[170:171], v[192:193] op_sel_hi:[1,0,1] neg_lo:[1,0,0] neg_hi:[1,0,0]
	v_pk_fma_f32 v[194:195], v[44:45], v[170:171], v[194:195] op_sel_hi:[1,0,1] neg_lo:[1,0,0] neg_hi:[1,0,0]
	v_pk_fma_f32 v[192:193], v[38:39], v[170:171], v[192:193] op_sel:[0,1,0] op_sel_hi:[1,1,1] neg_lo:[1,0,0] neg_hi:[1,0,0]
	v_pk_fma_f32 v[194:195], v[46:47], v[170:171], v[194:195] op_sel:[0,1,0] op_sel_hi:[1,1,1] neg_lo:[1,0,0] neg_hi:[1,0,0]
	ds_read_b128 v[32:35], v78 offset:13120
	ds_read_b128 v[36:39], v78 offset:13136
	ds_read_b128 v[40:43], v78 offset:13664
	ds_read_b128 v[44:47], v78 offset:13680
	s_waitcnt lgkmcnt(12)
	v_pk_fma_f32 v[196:197], v[48:49], v[168:169], v[196:197] op_sel_hi:[1,0,1] neg_lo:[1,0,0] neg_hi:[1,0,0]
	v_pk_fma_f32 v[198:199], v[56:57], v[168:169], v[198:199] op_sel_hi:[1,0,1] neg_lo:[1,0,0] neg_hi:[1,0,0]
	v_pk_fma_f32 v[196:197], v[50:51], v[168:169], v[196:197] op_sel:[0,1,0] op_sel_hi:[1,1,1] neg_lo:[1,0,0] neg_hi:[1,0,0]
	v_pk_fma_f32 v[198:199], v[58:59], v[168:169], v[198:199] op_sel:[0,1,0] op_sel_hi:[1,1,1] neg_lo:[1,0,0] neg_hi:[1,0,0]
	v_pk_fma_f32 v[196:197], v[52:53], v[170:171], v[196:197] op_sel_hi:[1,0,1] neg_lo:[1,0,0] neg_hi:[1,0,0]
	v_pk_fma_f32 v[198:199], v[60:61], v[170:171], v[198:199] op_sel_hi:[1,0,1] neg_lo:[1,0,0] neg_hi:[1,0,0]
	v_pk_fma_f32 v[196:197], v[54:55], v[170:171], v[196:197] op_sel:[0,1,0] op_sel_hi:[1,1,1] neg_lo:[1,0,0] neg_hi:[1,0,0]
	v_pk_fma_f32 v[198:199], v[62:63], v[170:171], v[198:199] op_sel:[0,1,0] op_sel_hi:[1,1,1] neg_lo:[1,0,0] neg_hi:[1,0,0]
	ds_read_b128 v[48:51], v78 offset:14208
	ds_read_b128 v[52:55], v78 offset:14224
	ds_read_b128 v[56:59], v78 offset:14752
	ds_read_b128 v[60:63], v78 offset:14768
	s_waitcnt lgkmcnt(12)
	v_pk_fma_f32 v[200:201], v[0:1], v[168:169], v[200:201] op_sel_hi:[1,0,1] neg_lo:[1,0,0] neg_hi:[1,0,0]
	v_pk_fma_f32 v[202:203], v[8:9], v[168:169], v[202:203] op_sel_hi:[1,0,1] neg_lo:[1,0,0] neg_hi:[1,0,0]
	v_pk_fma_f32 v[200:201], v[2:3], v[168:169], v[200:201] op_sel:[0,1,0] op_sel_hi:[1,1,1] neg_lo:[1,0,0] neg_hi:[1,0,0]
	v_pk_fma_f32 v[202:203], v[10:11], v[168:169], v[202:203] op_sel:[0,1,0] op_sel_hi:[1,1,1] neg_lo:[1,0,0] neg_hi:[1,0,0]
	v_pk_fma_f32 v[200:201], v[4:5], v[170:171], v[200:201] op_sel_hi:[1,0,1] neg_lo:[1,0,0] neg_hi:[1,0,0]
	v_pk_fma_f32 v[202:203], v[12:13], v[170:171], v[202:203] op_sel_hi:[1,0,1] neg_lo:[1,0,0] neg_hi:[1,0,0]
	v_pk_fma_f32 v[200:201], v[6:7], v[170:171], v[200:201] op_sel:[0,1,0] op_sel_hi:[1,1,1] neg_lo:[1,0,0] neg_hi:[1,0,0]
	v_pk_fma_f32 v[202:203], v[14:15], v[170:171], v[202:203] op_sel:[0,1,0] op_sel_hi:[1,1,1] neg_lo:[1,0,0] neg_hi:[1,0,0]
	ds_read_b128 v[0:3], v78 offset:15296
	ds_read_b128 v[4:7], v78 offset:15312
	ds_read_b128 v[8:11], v78 offset:15840
	ds_read_b128 v[12:15], v78 offset:15856
	s_waitcnt lgkmcnt(12)
	v_pk_fma_f32 v[204:205], v[16:17], v[168:169], v[204:205] op_sel_hi:[1,0,1] neg_lo:[1,0,0] neg_hi:[1,0,0]
	v_pk_fma_f32 v[206:207], v[24:25], v[168:169], v[206:207] op_sel_hi:[1,0,1] neg_lo:[1,0,0] neg_hi:[1,0,0]
	v_pk_fma_f32 v[204:205], v[18:19], v[168:169], v[204:205] op_sel:[0,1,0] op_sel_hi:[1,1,1] neg_lo:[1,0,0] neg_hi:[1,0,0]
	v_pk_fma_f32 v[206:207], v[26:27], v[168:169], v[206:207] op_sel:[0,1,0] op_sel_hi:[1,1,1] neg_lo:[1,0,0] neg_hi:[1,0,0]
	v_pk_fma_f32 v[204:205], v[20:21], v[170:171], v[204:205] op_sel_hi:[1,0,1] neg_lo:[1,0,0] neg_hi:[1,0,0]
	v_pk_fma_f32 v[206:207], v[28:29], v[170:171], v[206:207] op_sel_hi:[1,0,1] neg_lo:[1,0,0] neg_hi:[1,0,0]
	v_pk_fma_f32 v[204:205], v[22:23], v[170:171], v[204:205] op_sel:[0,1,0] op_sel_hi:[1,1,1] neg_lo:[1,0,0] neg_hi:[1,0,0]
	v_pk_fma_f32 v[206:207], v[30:31], v[170:171], v[206:207] op_sel:[0,1,0] op_sel_hi:[1,1,1] neg_lo:[1,0,0] neg_hi:[1,0,0]
	ds_read_b128 v[16:19], v78 offset:16384
	ds_read_b128 v[20:23], v78 offset:16400
	ds_read_b128 v[24:27], v78 offset:16928
	ds_read_b128 v[28:31], v78 offset:16944
	s_waitcnt lgkmcnt(12)
	v_pk_fma_f32 v[208:209], v[32:33], v[168:169], v[208:209] op_sel_hi:[1,0,1] neg_lo:[1,0,0] neg_hi:[1,0,0]
	v_pk_fma_f32 v[210:211], v[40:41], v[168:169], v[210:211] op_sel_hi:[1,0,1] neg_lo:[1,0,0] neg_hi:[1,0,0]
	v_pk_fma_f32 v[208:209], v[34:35], v[168:169], v[208:209] op_sel:[0,1,0] op_sel_hi:[1,1,1] neg_lo:[1,0,0] neg_hi:[1,0,0]
	v_pk_fma_f32 v[210:211], v[42:43], v[168:169], v[210:211] op_sel:[0,1,0] op_sel_hi:[1,1,1] neg_lo:[1,0,0] neg_hi:[1,0,0]
	v_pk_fma_f32 v[208:209], v[36:37], v[170:171], v[208:209] op_sel_hi:[1,0,1] neg_lo:[1,0,0] neg_hi:[1,0,0]
	v_pk_fma_f32 v[210:211], v[44:45], v[170:171], v[210:211] op_sel_hi:[1,0,1] neg_lo:[1,0,0] neg_hi:[1,0,0]
	v_pk_fma_f32 v[208:209], v[38:39], v[170:171], v[208:209] op_sel:[0,1,0] op_sel_hi:[1,1,1] neg_lo:[1,0,0] neg_hi:[1,0,0]
	v_pk_fma_f32 v[210:211], v[46:47], v[170:171], v[210:211] op_sel:[0,1,0] op_sel_hi:[1,1,1] neg_lo:[1,0,0] neg_hi:[1,0,0]
	ds_read_b128 v[32:35], v78 offset:4448
	ds_read_b128 v[36:39], v78 offset:4464
	ds_read_b128 v[40:43], v78 offset:4992
	ds_read_b128 v[44:47], v78 offset:5008
	s_waitcnt lgkmcnt(12)
	v_pk_fma_f32 v[212:213], v[48:49], v[168:169], v[212:213] op_sel_hi:[1,0,1] neg_lo:[1,0,0] neg_hi:[1,0,0]
	v_pk_fma_f32 v[214:215], v[56:57], v[168:169], v[214:215] op_sel_hi:[1,0,1] neg_lo:[1,0,0] neg_hi:[1,0,0]
	v_pk_fma_f32 v[212:213], v[50:51], v[168:169], v[212:213] op_sel:[0,1,0] op_sel_hi:[1,1,1] neg_lo:[1,0,0] neg_hi:[1,0,0]
	v_pk_fma_f32 v[214:215], v[58:59], v[168:169], v[214:215] op_sel:[0,1,0] op_sel_hi:[1,1,1] neg_lo:[1,0,0] neg_hi:[1,0,0]
	v_pk_fma_f32 v[212:213], v[52:53], v[170:171], v[212:213] op_sel_hi:[1,0,1] neg_lo:[1,0,0] neg_hi:[1,0,0]
	v_pk_fma_f32 v[214:215], v[60:61], v[170:171], v[214:215] op_sel_hi:[1,0,1] neg_lo:[1,0,0] neg_hi:[1,0,0]
	v_pk_fma_f32 v[212:213], v[54:55], v[170:171], v[212:213] op_sel:[0,1,0] op_sel_hi:[1,1,1] neg_lo:[1,0,0] neg_hi:[1,0,0]
	v_pk_fma_f32 v[214:215], v[62:63], v[170:171], v[214:215] op_sel:[0,1,0] op_sel_hi:[1,1,1] neg_lo:[1,0,0] neg_hi:[1,0,0]
	ds_read_b128 v[48:51], v78 offset:5536
	ds_read_b128 v[52:55], v78 offset:5552
	ds_read_b128 v[56:59], v78 offset:6080
	ds_read_b128 v[60:63], v78 offset:6096
	s_waitcnt lgkmcnt(12)
	v_pk_fma_f32 v[216:217], v[0:1], v[168:169], v[216:217] op_sel_hi:[1,0,1] neg_lo:[1,0,0] neg_hi:[1,0,0]
	v_pk_fma_f32 v[218:219], v[8:9], v[168:169], v[218:219] op_sel_hi:[1,0,1] neg_lo:[1,0,0] neg_hi:[1,0,0]
	v_pk_fma_f32 v[216:217], v[2:3], v[168:169], v[216:217] op_sel:[0,1,0] op_sel_hi:[1,1,1] neg_lo:[1,0,0] neg_hi:[1,0,0]
	v_pk_fma_f32 v[218:219], v[10:11], v[168:169], v[218:219] op_sel:[0,1,0] op_sel_hi:[1,1,1] neg_lo:[1,0,0] neg_hi:[1,0,0]
	v_pk_fma_f32 v[216:217], v[4:5], v[170:171], v[216:217] op_sel_hi:[1,0,1] neg_lo:[1,0,0] neg_hi:[1,0,0]
	v_pk_fma_f32 v[218:219], v[12:13], v[170:171], v[218:219] op_sel_hi:[1,0,1] neg_lo:[1,0,0] neg_hi:[1,0,0]
	v_pk_fma_f32 v[216:217], v[6:7], v[170:171], v[216:217] op_sel:[0,1,0] op_sel_hi:[1,1,1] neg_lo:[1,0,0] neg_hi:[1,0,0]
	v_pk_fma_f32 v[218:219], v[14:15], v[170:171], v[218:219] op_sel:[0,1,0] op_sel_hi:[1,1,1] neg_lo:[1,0,0] neg_hi:[1,0,0]
	ds_read_b128 v[0:3], v78 offset:6624
	ds_read_b128 v[4:7], v78 offset:6640
	ds_read_b128 v[8:11], v78 offset:7168
	ds_read_b128 v[12:15], v78 offset:7184
	s_waitcnt lgkmcnt(12)
	v_pk_fma_f32 v[220:221], v[16:17], v[168:169], v[220:221] op_sel_hi:[1,0,1] neg_lo:[1,0,0] neg_hi:[1,0,0]
	v_pk_fma_f32 v[222:223], v[24:25], v[168:169], v[222:223] op_sel_hi:[1,0,1] neg_lo:[1,0,0] neg_hi:[1,0,0]
	v_pk_fma_f32 v[220:221], v[18:19], v[168:169], v[220:221] op_sel:[0,1,0] op_sel_hi:[1,1,1] neg_lo:[1,0,0] neg_hi:[1,0,0]
	v_pk_fma_f32 v[222:223], v[26:27], v[168:169], v[222:223] op_sel:[0,1,0] op_sel_hi:[1,1,1] neg_lo:[1,0,0] neg_hi:[1,0,0]
	v_pk_fma_f32 v[220:221], v[20:21], v[170:171], v[220:221] op_sel_hi:[1,0,1] neg_lo:[1,0,0] neg_hi:[1,0,0]
	v_pk_fma_f32 v[222:223], v[28:29], v[170:171], v[222:223] op_sel_hi:[1,0,1] neg_lo:[1,0,0] neg_hi:[1,0,0]
	v_pk_fma_f32 v[220:221], v[22:23], v[170:171], v[220:221] op_sel:[0,1,0] op_sel_hi:[1,1,1] neg_lo:[1,0,0] neg_hi:[1,0,0]
	v_pk_fma_f32 v[222:223], v[30:31], v[170:171], v[222:223] op_sel:[0,1,0] op_sel_hi:[1,1,1] neg_lo:[1,0,0] neg_hi:[1,0,0]
	ds_read_b128 v[64:67], v78 offset:4480
	ds_read_b128 v[68:71], v78 offset:5024
	ds_read_b128 v[72:75], v78 offset:5040
	ds_read_b128 v[16:19], v78 offset:7712
	ds_read_b128 v[20:23], v78 offset:7728
	ds_read_b128 v[24:27], v78 offset:8256
	ds_read_b128 v[28:31], v78 offset:8272
	s_waitcnt lgkmcnt(15)
	v_pk_fma_f32 v[176:177], v[32:33], v[172:173], v[176:177] op_sel_hi:[1,0,1] neg_lo:[1,0,0] neg_hi:[1,0,0]
	v_pk_fma_f32 v[178:179], v[40:41], v[172:173], v[178:179] op_sel_hi:[1,0,1] neg_lo:[1,0,0] neg_hi:[1,0,0]
	v_pk_fma_f32 v[176:177], v[34:35], v[172:173], v[176:177] op_sel:[0,1,0] op_sel_hi:[1,1,1] neg_lo:[1,0,0] neg_hi:[1,0,0]
	v_pk_fma_f32 v[178:179], v[42:43], v[172:173], v[178:179] op_sel:[0,1,0] op_sel_hi:[1,1,1] neg_lo:[1,0,0] neg_hi:[1,0,0]
	v_pk_fma_f32 v[176:177], v[36:37], v[174:175], v[176:177] op_sel_hi:[1,0,1] neg_lo:[1,0,0] neg_hi:[1,0,0]
	v_pk_fma_f32 v[178:179], v[44:45], v[174:175], v[178:179] op_sel_hi:[1,0,1] neg_lo:[1,0,0] neg_hi:[1,0,0]
	v_pk_fma_f32 v[176:177], v[38:39], v[174:175], v[176:177] op_sel:[0,1,0] op_sel_hi:[1,1,1] neg_lo:[1,0,0] neg_hi:[1,0,0]
	v_pk_fma_f32 v[178:179], v[46:47], v[174:175], v[178:179] op_sel:[0,1,0] op_sel_hi:[1,1,1] neg_lo:[1,0,0] neg_hi:[1,0,0]
	ds_read_b128 v[32:35], v78 offset:8800
	ds_read_b128 v[36:39], v78 offset:8816
	ds_read_b128 v[40:43], v78 offset:9344
	ds_read_b128 v[44:47], v78 offset:9360
	s_waitcnt lgkmcnt(15)
	v_pk_fma_f32 v[180:181], v[48:49], v[172:173], v[180:181] op_sel_hi:[1,0,1] neg_lo:[1,0,0] neg_hi:[1,0,0]
	v_pk_fma_f32 v[182:183], v[56:57], v[172:173], v[182:183] op_sel_hi:[1,0,1] neg_lo:[1,0,0] neg_hi:[1,0,0]
	s_waitcnt lgkmcnt(10)
	v_pk_fma_f32 v[176:177], v[64:65], v[176:177], v[176:177] op_sel_hi:[1,0,1] neg_lo:[1,0,0] neg_hi:[1,0,0]
	v_pk_fma_f32 v[180:181], v[50:51], v[172:173], v[180:181] op_sel:[0,1,0] op_sel_hi:[1,1,1] neg_lo:[1,0,0] neg_hi:[1,0,0]
	v_pk_fma_f32 v[182:183], v[58:59], v[172:173], v[182:183] op_sel:[0,1,0] op_sel_hi:[1,1,1] neg_lo:[1,0,0] neg_hi:[1,0,0]
	s_waitcnt lgkmcnt(9)
	v_pk_fma_f32 v[178:179], v[68:69], v[176:177], v[178:179] op_sel_hi:[1,0,1] neg_lo:[1,0,0] neg_hi:[1,0,0]
	v_pk_fma_f32 v[180:181], v[52:53], v[174:175], v[180:181] op_sel_hi:[1,0,1] neg_lo:[1,0,0] neg_hi:[1,0,0]
	v_pk_fma_f32 v[182:183], v[60:61], v[174:175], v[182:183] op_sel_hi:[1,0,1] neg_lo:[1,0,0] neg_hi:[1,0,0]
	v_pk_fma_f32 v[178:179], v[70:71], v[176:177], v[178:179] op_sel:[0,1,0] op_sel_hi:[1,1,1] neg_lo:[1,0,0] neg_hi:[1,0,0]
	v_pk_fma_f32 v[180:181], v[54:55], v[174:175], v[180:181] op_sel:[0,1,0] op_sel_hi:[1,1,1] neg_lo:[1,0,0] neg_hi:[1,0,0]
	v_pk_fma_f32 v[182:183], v[62:63], v[174:175], v[182:183] op_sel:[0,1,0] op_sel_hi:[1,1,1] neg_lo:[1,0,0] neg_hi:[1,0,0]
	s_waitcnt lgkmcnt(8)
	v_pk_fma_f32 v[178:179], v[72:73], v[178:179], v[178:179] op_sel_hi:[1,0,1] neg_lo:[1,0,0] neg_hi:[1,0,0]
	ds_read_b128 v[48:51], v78 offset:9888
	ds_read_b128 v[52:55], v78 offset:9904
	ds_read_b128 v[56:59], v78 offset:10432
	ds_read_b128 v[60:63], v78 offset:10448
	s_waitcnt lgkmcnt(15)
	v_pk_fma_f32 v[184:185], v[0:1], v[172:173], v[184:185] op_sel_hi:[1,0,1] neg_lo:[1,0,0] neg_hi:[1,0,0]
	v_pk_fma_f32 v[186:187], v[8:9], v[172:173], v[186:187] op_sel_hi:[1,0,1] neg_lo:[1,0,0] neg_hi:[1,0,0]
	v_pk_fma_f32 v[184:185], v[2:3], v[172:173], v[184:185] op_sel:[0,1,0] op_sel_hi:[1,1,1] neg_lo:[1,0,0] neg_hi:[1,0,0]
	v_pk_fma_f32 v[186:187], v[10:11], v[172:173], v[186:187] op_sel:[0,1,0] op_sel_hi:[1,1,1] neg_lo:[1,0,0] neg_hi:[1,0,0]
	v_pk_fma_f32 v[184:185], v[4:5], v[174:175], v[184:185] op_sel_hi:[1,0,1] neg_lo:[1,0,0] neg_hi:[1,0,0]
	v_pk_fma_f32 v[186:187], v[12:13], v[174:175], v[186:187] op_sel_hi:[1,0,1] neg_lo:[1,0,0] neg_hi:[1,0,0]
	v_pk_fma_f32 v[184:185], v[6:7], v[174:175], v[184:185] op_sel:[0,1,0] op_sel_hi:[1,1,1] neg_lo:[1,0,0] neg_hi:[1,0,0]
	v_pk_fma_f32 v[186:187], v[14:15], v[174:175], v[186:187] op_sel:[0,1,0] op_sel_hi:[1,1,1] neg_lo:[1,0,0] neg_hi:[1,0,0]
	ds_read_b128 v[0:3], v78 offset:10976
	ds_read_b128 v[4:7], v78 offset:10992
	ds_read_b128 v[8:11], v78 offset:11520
	ds_read_b128 v[12:15], v78 offset:11536
	s_waitcnt lgkmcnt(12)
	v_pk_fma_f32 v[188:189], v[16:17], v[172:173], v[188:189] op_sel_hi:[1,0,1] neg_lo:[1,0,0] neg_hi:[1,0,0]
	v_pk_fma_f32 v[190:191], v[24:25], v[172:173], v[190:191] op_sel_hi:[1,0,1] neg_lo:[1,0,0] neg_hi:[1,0,0]
	v_pk_fma_f32 v[188:189], v[18:19], v[172:173], v[188:189] op_sel:[0,1,0] op_sel_hi:[1,1,1] neg_lo:[1,0,0] neg_hi:[1,0,0]
	v_pk_fma_f32 v[190:191], v[26:27], v[172:173], v[190:191] op_sel:[0,1,0] op_sel_hi:[1,1,1] neg_lo:[1,0,0] neg_hi:[1,0,0]
	v_pk_fma_f32 v[188:189], v[20:21], v[174:175], v[188:189] op_sel_hi:[1,0,1] neg_lo:[1,0,0] neg_hi:[1,0,0]
	v_pk_fma_f32 v[190:191], v[28:29], v[174:175], v[190:191] op_sel_hi:[1,0,1] neg_lo:[1,0,0] neg_hi:[1,0,0]
	v_pk_fma_f32 v[188:189], v[22:23], v[174:175], v[188:189] op_sel:[0,1,0] op_sel_hi:[1,1,1] neg_lo:[1,0,0] neg_hi:[1,0,0]
	v_pk_fma_f32 v[190:191], v[30:31], v[174:175], v[190:191] op_sel:[0,1,0] op_sel_hi:[1,1,1] neg_lo:[1,0,0] neg_hi:[1,0,0]
	ds_read_b128 v[16:19], v78 offset:12064
	ds_read_b128 v[20:23], v78 offset:12080
	ds_read_b128 v[24:27], v78 offset:12608
	ds_read_b128 v[28:31], v78 offset:12624
	s_waitcnt lgkmcnt(12)
	v_pk_fma_f32 v[192:193], v[32:33], v[172:173], v[192:193] op_sel_hi:[1,0,1] neg_lo:[1,0,0] neg_hi:[1,0,0]
	v_pk_fma_f32 v[194:195], v[40:41], v[172:173], v[194:195] op_sel_hi:[1,0,1] neg_lo:[1,0,0] neg_hi:[1,0,0]
	v_pk_fma_f32 v[192:193], v[34:35], v[172:173], v[192:193] op_sel:[0,1,0] op_sel_hi:[1,1,1] neg_lo:[1,0,0] neg_hi:[1,0,0]
	v_pk_fma_f32 v[194:195], v[42:43], v[172:173], v[194:195] op_sel:[0,1,0] op_sel_hi:[1,1,1] neg_lo:[1,0,0] neg_hi:[1,0,0]
	v_pk_fma_f32 v[192:193], v[36:37], v[174:175], v[192:193] op_sel_hi:[1,0,1] neg_lo:[1,0,0] neg_hi:[1,0,0]
	v_pk_fma_f32 v[194:195], v[44:45], v[174:175], v[194:195] op_sel_hi:[1,0,1] neg_lo:[1,0,0] neg_hi:[1,0,0]
	v_pk_fma_f32 v[192:193], v[38:39], v[174:175], v[192:193] op_sel:[0,1,0] op_sel_hi:[1,1,1] neg_lo:[1,0,0] neg_hi:[1,0,0]
	v_pk_fma_f32 v[194:195], v[46:47], v[174:175], v[194:195] op_sel:[0,1,0] op_sel_hi:[1,1,1] neg_lo:[1,0,0] neg_hi:[1,0,0]
	ds_read_b128 v[32:35], v78 offset:13152
	ds_read_b128 v[36:39], v78 offset:13168
	ds_read_b128 v[40:43], v78 offset:13696
	ds_read_b128 v[44:47], v78 offset:13712
	s_waitcnt lgkmcnt(12)
	v_pk_fma_f32 v[196:197], v[48:49], v[172:173], v[196:197] op_sel_hi:[1,0,1] neg_lo:[1,0,0] neg_hi:[1,0,0]
	v_pk_fma_f32 v[198:199], v[56:57], v[172:173], v[198:199] op_sel_hi:[1,0,1] neg_lo:[1,0,0] neg_hi:[1,0,0]
	v_pk_fma_f32 v[196:197], v[50:51], v[172:173], v[196:197] op_sel:[0,1,0] op_sel_hi:[1,1,1] neg_lo:[1,0,0] neg_hi:[1,0,0]
	v_pk_fma_f32 v[198:199], v[58:59], v[172:173], v[198:199] op_sel:[0,1,0] op_sel_hi:[1,1,1] neg_lo:[1,0,0] neg_hi:[1,0,0]
	v_pk_fma_f32 v[196:197], v[52:53], v[174:175], v[196:197] op_sel_hi:[1,0,1] neg_lo:[1,0,0] neg_hi:[1,0,0]
	v_pk_fma_f32 v[198:199], v[60:61], v[174:175], v[198:199] op_sel_hi:[1,0,1] neg_lo:[1,0,0] neg_hi:[1,0,0]
	v_pk_fma_f32 v[196:197], v[54:55], v[174:175], v[196:197] op_sel:[0,1,0] op_sel_hi:[1,1,1] neg_lo:[1,0,0] neg_hi:[1,0,0]
	v_pk_fma_f32 v[198:199], v[62:63], v[174:175], v[198:199] op_sel:[0,1,0] op_sel_hi:[1,1,1] neg_lo:[1,0,0] neg_hi:[1,0,0]
	ds_read_b128 v[48:51], v78 offset:14240
	ds_read_b128 v[52:55], v78 offset:14256
	ds_read_b128 v[56:59], v78 offset:14784
	ds_read_b128 v[60:63], v78 offset:14800
	s_waitcnt lgkmcnt(12)
	v_pk_fma_f32 v[200:201], v[0:1], v[172:173], v[200:201] op_sel_hi:[1,0,1] neg_lo:[1,0,0] neg_hi:[1,0,0]
	v_pk_fma_f32 v[202:203], v[8:9], v[172:173], v[202:203] op_sel_hi:[1,0,1] neg_lo:[1,0,0] neg_hi:[1,0,0]
	v_pk_fma_f32 v[200:201], v[2:3], v[172:173], v[200:201] op_sel:[0,1,0] op_sel_hi:[1,1,1] neg_lo:[1,0,0] neg_hi:[1,0,0]
	v_pk_fma_f32 v[202:203], v[10:11], v[172:173], v[202:203] op_sel:[0,1,0] op_sel_hi:[1,1,1] neg_lo:[1,0,0] neg_hi:[1,0,0]
	v_pk_fma_f32 v[200:201], v[4:5], v[174:175], v[200:201] op_sel_hi:[1,0,1] neg_lo:[1,0,0] neg_hi:[1,0,0]
	v_pk_fma_f32 v[202:203], v[12:13], v[174:175], v[202:203] op_sel_hi:[1,0,1] neg_lo:[1,0,0] neg_hi:[1,0,0]
	v_pk_fma_f32 v[200:201], v[6:7], v[174:175], v[200:201] op_sel:[0,1,0] op_sel_hi:[1,1,1] neg_lo:[1,0,0] neg_hi:[1,0,0]
	v_pk_fma_f32 v[202:203], v[14:15], v[174:175], v[202:203] op_sel:[0,1,0] op_sel_hi:[1,1,1] neg_lo:[1,0,0] neg_hi:[1,0,0]
	ds_read_b128 v[0:3], v78 offset:15328
	ds_read_b128 v[4:7], v78 offset:15344
	ds_read_b128 v[8:11], v78 offset:15872
	ds_read_b128 v[12:15], v78 offset:15888
	s_waitcnt lgkmcnt(12)
	v_pk_fma_f32 v[204:205], v[16:17], v[172:173], v[204:205] op_sel_hi:[1,0,1] neg_lo:[1,0,0] neg_hi:[1,0,0]
	v_pk_fma_f32 v[206:207], v[24:25], v[172:173], v[206:207] op_sel_hi:[1,0,1] neg_lo:[1,0,0] neg_hi:[1,0,0]
	v_pk_fma_f32 v[204:205], v[18:19], v[172:173], v[204:205] op_sel:[0,1,0] op_sel_hi:[1,1,1] neg_lo:[1,0,0] neg_hi:[1,0,0]
	v_pk_fma_f32 v[206:207], v[26:27], v[172:173], v[206:207] op_sel:[0,1,0] op_sel_hi:[1,1,1] neg_lo:[1,0,0] neg_hi:[1,0,0]
	v_pk_fma_f32 v[204:205], v[20:21], v[174:175], v[204:205] op_sel_hi:[1,0,1] neg_lo:[1,0,0] neg_hi:[1,0,0]
	v_pk_fma_f32 v[206:207], v[28:29], v[174:175], v[206:207] op_sel_hi:[1,0,1] neg_lo:[1,0,0] neg_hi:[1,0,0]
	v_pk_fma_f32 v[204:205], v[22:23], v[174:175], v[204:205] op_sel:[0,1,0] op_sel_hi:[1,1,1] neg_lo:[1,0,0] neg_hi:[1,0,0]
	v_pk_fma_f32 v[206:207], v[30:31], v[174:175], v[206:207] op_sel:[0,1,0] op_sel_hi:[1,1,1] neg_lo:[1,0,0] neg_hi:[1,0,0]
	ds_read_b128 v[16:19], v78 offset:16416
	ds_read_b128 v[20:23], v78 offset:16432
	ds_read_b128 v[24:27], v78 offset:16960
	ds_read_b128 v[28:31], v78 offset:16976
	s_waitcnt lgkmcnt(12)
	v_pk_fma_f32 v[208:209], v[32:33], v[172:173], v[208:209] op_sel_hi:[1,0,1] neg_lo:[1,0,0] neg_hi:[1,0,0]
	v_pk_fma_f32 v[210:211], v[40:41], v[172:173], v[210:211] op_sel_hi:[1,0,1] neg_lo:[1,0,0] neg_hi:[1,0,0]
	v_pk_fma_f32 v[208:209], v[34:35], v[172:173], v[208:209] op_sel:[0,1,0] op_sel_hi:[1,1,1] neg_lo:[1,0,0] neg_hi:[1,0,0]
	v_pk_fma_f32 v[210:211], v[42:43], v[172:173], v[210:211] op_sel:[0,1,0] op_sel_hi:[1,1,1] neg_lo:[1,0,0] neg_hi:[1,0,0]
	v_pk_fma_f32 v[208:209], v[36:37], v[174:175], v[208:209] op_sel_hi:[1,0,1] neg_lo:[1,0,0] neg_hi:[1,0,0]
	v_pk_fma_f32 v[210:211], v[44:45], v[174:175], v[210:211] op_sel_hi:[1,0,1] neg_lo:[1,0,0] neg_hi:[1,0,0]
	v_pk_fma_f32 v[208:209], v[38:39], v[174:175], v[208:209] op_sel:[0,1,0] op_sel_hi:[1,1,1] neg_lo:[1,0,0] neg_hi:[1,0,0]
	v_pk_fma_f32 v[210:211], v[46:47], v[174:175], v[210:211] op_sel:[0,1,0] op_sel_hi:[1,1,1] neg_lo:[1,0,0] neg_hi:[1,0,0]
	ds_read_b128 v[32:35], v78 offset:5568
	ds_read_b128 v[36:39], v78 offset:5584
	ds_read_b128 v[40:43], v78 offset:6112
	ds_read_b128 v[44:47], v78 offset:6128
	s_waitcnt lgkmcnt(12)
	v_pk_fma_f32 v[212:213], v[48:49], v[172:173], v[212:213] op_sel_hi:[1,0,1] neg_lo:[1,0,0] neg_hi:[1,0,0]
	v_pk_fma_f32 v[214:215], v[56:57], v[172:173], v[214:215] op_sel_hi:[1,0,1] neg_lo:[1,0,0] neg_hi:[1,0,0]
	v_pk_fma_f32 v[212:213], v[50:51], v[172:173], v[212:213] op_sel:[0,1,0] op_sel_hi:[1,1,1] neg_lo:[1,0,0] neg_hi:[1,0,0]
	v_pk_fma_f32 v[214:215], v[58:59], v[172:173], v[214:215] op_sel:[0,1,0] op_sel_hi:[1,1,1] neg_lo:[1,0,0] neg_hi:[1,0,0]
	v_pk_fma_f32 v[212:213], v[52:53], v[174:175], v[212:213] op_sel_hi:[1,0,1] neg_lo:[1,0,0] neg_hi:[1,0,0]
	v_pk_fma_f32 v[214:215], v[60:61], v[174:175], v[214:215] op_sel_hi:[1,0,1] neg_lo:[1,0,0] neg_hi:[1,0,0]
	v_pk_fma_f32 v[212:213], v[54:55], v[174:175], v[212:213] op_sel:[0,1,0] op_sel_hi:[1,1,1] neg_lo:[1,0,0] neg_hi:[1,0,0]
	v_pk_fma_f32 v[214:215], v[62:63], v[174:175], v[214:215] op_sel:[0,1,0] op_sel_hi:[1,1,1] neg_lo:[1,0,0] neg_hi:[1,0,0]
	ds_read_b128 v[48:51], v78 offset:6656
	ds_read_b128 v[52:55], v78 offset:6672
	ds_read_b128 v[56:59], v78 offset:7200
	ds_read_b128 v[60:63], v78 offset:7216
	s_waitcnt lgkmcnt(12)
	v_pk_fma_f32 v[216:217], v[0:1], v[172:173], v[216:217] op_sel_hi:[1,0,1] neg_lo:[1,0,0] neg_hi:[1,0,0]
	v_pk_fma_f32 v[218:219], v[8:9], v[172:173], v[218:219] op_sel_hi:[1,0,1] neg_lo:[1,0,0] neg_hi:[1,0,0]
	v_pk_fma_f32 v[216:217], v[2:3], v[172:173], v[216:217] op_sel:[0,1,0] op_sel_hi:[1,1,1] neg_lo:[1,0,0] neg_hi:[1,0,0]
	v_pk_fma_f32 v[218:219], v[10:11], v[172:173], v[218:219] op_sel:[0,1,0] op_sel_hi:[1,1,1] neg_lo:[1,0,0] neg_hi:[1,0,0]
	v_pk_fma_f32 v[216:217], v[4:5], v[174:175], v[216:217] op_sel_hi:[1,0,1] neg_lo:[1,0,0] neg_hi:[1,0,0]
	v_pk_fma_f32 v[218:219], v[12:13], v[174:175], v[218:219] op_sel_hi:[1,0,1] neg_lo:[1,0,0] neg_hi:[1,0,0]
	v_pk_fma_f32 v[216:217], v[6:7], v[174:175], v[216:217] op_sel:[0,1,0] op_sel_hi:[1,1,1] neg_lo:[1,0,0] neg_hi:[1,0,0]
	v_pk_fma_f32 v[218:219], v[14:15], v[174:175], v[218:219] op_sel:[0,1,0] op_sel_hi:[1,1,1] neg_lo:[1,0,0] neg_hi:[1,0,0]
	ds_read_b128 v[0:3], v78 offset:7744
	ds_read_b128 v[4:7], v78 offset:7760
	ds_read_b128 v[8:11], v78 offset:8288
	ds_read_b128 v[12:15], v78 offset:8304
	s_waitcnt lgkmcnt(12)
	v_pk_fma_f32 v[220:221], v[16:17], v[172:173], v[220:221] op_sel_hi:[1,0,1] neg_lo:[1,0,0] neg_hi:[1,0,0]
	v_pk_fma_f32 v[222:223], v[24:25], v[172:173], v[222:223] op_sel_hi:[1,0,1] neg_lo:[1,0,0] neg_hi:[1,0,0]
	v_pk_fma_f32 v[220:221], v[18:19], v[172:173], v[220:221] op_sel:[0,1,0] op_sel_hi:[1,1,1] neg_lo:[1,0,0] neg_hi:[1,0,0]
	v_pk_fma_f32 v[222:223], v[26:27], v[172:173], v[222:223] op_sel:[0,1,0] op_sel_hi:[1,1,1] neg_lo:[1,0,0] neg_hi:[1,0,0]
	v_pk_fma_f32 v[220:221], v[20:21], v[174:175], v[220:221] op_sel_hi:[1,0,1] neg_lo:[1,0,0] neg_hi:[1,0,0]
	v_pk_fma_f32 v[222:223], v[28:29], v[174:175], v[222:223] op_sel_hi:[1,0,1] neg_lo:[1,0,0] neg_hi:[1,0,0]
	v_pk_fma_f32 v[220:221], v[22:23], v[174:175], v[220:221] op_sel:[0,1,0] op_sel_hi:[1,1,1] neg_lo:[1,0,0] neg_hi:[1,0,0]
	v_pk_fma_f32 v[222:223], v[30:31], v[174:175], v[222:223] op_sel:[0,1,0] op_sel_hi:[1,1,1] neg_lo:[1,0,0] neg_hi:[1,0,0]
	ds_read_b128 v[64:67], v78 offset:5600
	ds_read_b128 v[68:71], v78 offset:6144
	ds_read_b128 v[72:75], v78 offset:6160
	ds_read_b128 v[16:19], v78 offset:8832
	ds_read_b128 v[20:23], v78 offset:8848
	ds_read_b128 v[24:27], v78 offset:9376
	ds_read_b128 v[28:31], v78 offset:9392
	s_waitcnt lgkmcnt(15)
	v_pk_fma_f32 v[180:181], v[32:33], v[176:177], v[180:181] op_sel_hi:[1,0,1] neg_lo:[1,0,0] neg_hi:[1,0,0]
	v_pk_fma_f32 v[182:183], v[40:41], v[176:177], v[182:183] op_sel_hi:[1,0,1] neg_lo:[1,0,0] neg_hi:[1,0,0]
	v_pk_fma_f32 v[180:181], v[34:35], v[176:177], v[180:181] op_sel:[0,1,0] op_sel_hi:[1,1,1] neg_lo:[1,0,0] neg_hi:[1,0,0]
	v_pk_fma_f32 v[182:183], v[42:43], v[176:177], v[182:183] op_sel:[0,1,0] op_sel_hi:[1,1,1] neg_lo:[1,0,0] neg_hi:[1,0,0]
	v_pk_fma_f32 v[180:181], v[36:37], v[178:179], v[180:181] op_sel_hi:[1,0,1] neg_lo:[1,0,0] neg_hi:[1,0,0]
	v_pk_fma_f32 v[182:183], v[44:45], v[178:179], v[182:183] op_sel_hi:[1,0,1] neg_lo:[1,0,0] neg_hi:[1,0,0]
	v_pk_fma_f32 v[180:181], v[38:39], v[178:179], v[180:181] op_sel:[0,1,0] op_sel_hi:[1,1,1] neg_lo:[1,0,0] neg_hi:[1,0,0]
	v_pk_fma_f32 v[182:183], v[46:47], v[178:179], v[182:183] op_sel:[0,1,0] op_sel_hi:[1,1,1] neg_lo:[1,0,0] neg_hi:[1,0,0]
	ds_read_b128 v[32:35], v78 offset:9920
	ds_read_b128 v[36:39], v78 offset:9936
	ds_read_b128 v[40:43], v78 offset:10464
	ds_read_b128 v[44:47], v78 offset:10480
	s_waitcnt lgkmcnt(15)
	v_pk_fma_f32 v[184:185], v[48:49], v[176:177], v[184:185] op_sel_hi:[1,0,1] neg_lo:[1,0,0] neg_hi:[1,0,0]
	v_pk_fma_f32 v[186:187], v[56:57], v[176:177], v[186:187] op_sel_hi:[1,0,1] neg_lo:[1,0,0] neg_hi:[1,0,0]
	s_waitcnt lgkmcnt(10)
	v_pk_fma_f32 v[180:181], v[64:65], v[180:181], v[180:181] op_sel_hi:[1,0,1] neg_lo:[1,0,0] neg_hi:[1,0,0]
	v_pk_fma_f32 v[184:185], v[50:51], v[176:177], v[184:185] op_sel:[0,1,0] op_sel_hi:[1,1,1] neg_lo:[1,0,0] neg_hi:[1,0,0]
	v_pk_fma_f32 v[186:187], v[58:59], v[176:177], v[186:187] op_sel:[0,1,0] op_sel_hi:[1,1,1] neg_lo:[1,0,0] neg_hi:[1,0,0]
	s_waitcnt lgkmcnt(9)
	v_pk_fma_f32 v[182:183], v[68:69], v[180:181], v[182:183] op_sel_hi:[1,0,1] neg_lo:[1,0,0] neg_hi:[1,0,0]
	v_pk_fma_f32 v[184:185], v[52:53], v[178:179], v[184:185] op_sel_hi:[1,0,1] neg_lo:[1,0,0] neg_hi:[1,0,0]
	v_pk_fma_f32 v[186:187], v[60:61], v[178:179], v[186:187] op_sel_hi:[1,0,1] neg_lo:[1,0,0] neg_hi:[1,0,0]
	v_pk_fma_f32 v[182:183], v[70:71], v[180:181], v[182:183] op_sel:[0,1,0] op_sel_hi:[1,1,1] neg_lo:[1,0,0] neg_hi:[1,0,0]
	v_pk_fma_f32 v[184:185], v[54:55], v[178:179], v[184:185] op_sel:[0,1,0] op_sel_hi:[1,1,1] neg_lo:[1,0,0] neg_hi:[1,0,0]
	v_pk_fma_f32 v[186:187], v[62:63], v[178:179], v[186:187] op_sel:[0,1,0] op_sel_hi:[1,1,1] neg_lo:[1,0,0] neg_hi:[1,0,0]
	s_waitcnt lgkmcnt(8)
	v_pk_fma_f32 v[182:183], v[72:73], v[182:183], v[182:183] op_sel_hi:[1,0,1] neg_lo:[1,0,0] neg_hi:[1,0,0]
	ds_read_b128 v[48:51], v78 offset:11008
	ds_read_b128 v[52:55], v78 offset:11024
	ds_read_b128 v[56:59], v78 offset:11552
	ds_read_b128 v[60:63], v78 offset:11568
	s_waitcnt lgkmcnt(15)
	v_pk_fma_f32 v[188:189], v[0:1], v[176:177], v[188:189] op_sel_hi:[1,0,1] neg_lo:[1,0,0] neg_hi:[1,0,0]
	v_pk_fma_f32 v[190:191], v[8:9], v[176:177], v[190:191] op_sel_hi:[1,0,1] neg_lo:[1,0,0] neg_hi:[1,0,0]
	v_pk_fma_f32 v[188:189], v[2:3], v[176:177], v[188:189] op_sel:[0,1,0] op_sel_hi:[1,1,1] neg_lo:[1,0,0] neg_hi:[1,0,0]
	v_pk_fma_f32 v[190:191], v[10:11], v[176:177], v[190:191] op_sel:[0,1,0] op_sel_hi:[1,1,1] neg_lo:[1,0,0] neg_hi:[1,0,0]
	v_pk_fma_f32 v[188:189], v[4:5], v[178:179], v[188:189] op_sel_hi:[1,0,1] neg_lo:[1,0,0] neg_hi:[1,0,0]
	v_pk_fma_f32 v[190:191], v[12:13], v[178:179], v[190:191] op_sel_hi:[1,0,1] neg_lo:[1,0,0] neg_hi:[1,0,0]
	v_pk_fma_f32 v[188:189], v[6:7], v[178:179], v[188:189] op_sel:[0,1,0] op_sel_hi:[1,1,1] neg_lo:[1,0,0] neg_hi:[1,0,0]
	v_pk_fma_f32 v[190:191], v[14:15], v[178:179], v[190:191] op_sel:[0,1,0] op_sel_hi:[1,1,1] neg_lo:[1,0,0] neg_hi:[1,0,0]
	ds_read_b128 v[0:3], v78 offset:12096
	ds_read_b128 v[4:7], v78 offset:12112
	ds_read_b128 v[8:11], v78 offset:12640
	ds_read_b128 v[12:15], v78 offset:12656
	s_waitcnt lgkmcnt(12)
	v_pk_fma_f32 v[192:193], v[16:17], v[176:177], v[192:193] op_sel_hi:[1,0,1] neg_lo:[1,0,0] neg_hi:[1,0,0]
	v_pk_fma_f32 v[194:195], v[24:25], v[176:177], v[194:195] op_sel_hi:[1,0,1] neg_lo:[1,0,0] neg_hi:[1,0,0]
	v_pk_fma_f32 v[192:193], v[18:19], v[176:177], v[192:193] op_sel:[0,1,0] op_sel_hi:[1,1,1] neg_lo:[1,0,0] neg_hi:[1,0,0]
	v_pk_fma_f32 v[194:195], v[26:27], v[176:177], v[194:195] op_sel:[0,1,0] op_sel_hi:[1,1,1] neg_lo:[1,0,0] neg_hi:[1,0,0]
	v_pk_fma_f32 v[192:193], v[20:21], v[178:179], v[192:193] op_sel_hi:[1,0,1] neg_lo:[1,0,0] neg_hi:[1,0,0]
	v_pk_fma_f32 v[194:195], v[28:29], v[178:179], v[194:195] op_sel_hi:[1,0,1] neg_lo:[1,0,0] neg_hi:[1,0,0]
	v_pk_fma_f32 v[192:193], v[22:23], v[178:179], v[192:193] op_sel:[0,1,0] op_sel_hi:[1,1,1] neg_lo:[1,0,0] neg_hi:[1,0,0]
	v_pk_fma_f32 v[194:195], v[30:31], v[178:179], v[194:195] op_sel:[0,1,0] op_sel_hi:[1,1,1] neg_lo:[1,0,0] neg_hi:[1,0,0]
	ds_read_b128 v[16:19], v78 offset:13184
	ds_read_b128 v[20:23], v78 offset:13200
	ds_read_b128 v[24:27], v78 offset:13728
	ds_read_b128 v[28:31], v78 offset:13744
	s_waitcnt lgkmcnt(12)
	v_pk_fma_f32 v[196:197], v[32:33], v[176:177], v[196:197] op_sel_hi:[1,0,1] neg_lo:[1,0,0] neg_hi:[1,0,0]
	v_pk_fma_f32 v[198:199], v[40:41], v[176:177], v[198:199] op_sel_hi:[1,0,1] neg_lo:[1,0,0] neg_hi:[1,0,0]
	v_pk_fma_f32 v[196:197], v[34:35], v[176:177], v[196:197] op_sel:[0,1,0] op_sel_hi:[1,1,1] neg_lo:[1,0,0] neg_hi:[1,0,0]
	v_pk_fma_f32 v[198:199], v[42:43], v[176:177], v[198:199] op_sel:[0,1,0] op_sel_hi:[1,1,1] neg_lo:[1,0,0] neg_hi:[1,0,0]
	v_pk_fma_f32 v[196:197], v[36:37], v[178:179], v[196:197] op_sel_hi:[1,0,1] neg_lo:[1,0,0] neg_hi:[1,0,0]
	v_pk_fma_f32 v[198:199], v[44:45], v[178:179], v[198:199] op_sel_hi:[1,0,1] neg_lo:[1,0,0] neg_hi:[1,0,0]
	v_pk_fma_f32 v[196:197], v[38:39], v[178:179], v[196:197] op_sel:[0,1,0] op_sel_hi:[1,1,1] neg_lo:[1,0,0] neg_hi:[1,0,0]
	v_pk_fma_f32 v[198:199], v[46:47], v[178:179], v[198:199] op_sel:[0,1,0] op_sel_hi:[1,1,1] neg_lo:[1,0,0] neg_hi:[1,0,0]
	ds_read_b128 v[32:35], v78 offset:14272
	ds_read_b128 v[36:39], v78 offset:14288
	ds_read_b128 v[40:43], v78 offset:14816
	ds_read_b128 v[44:47], v78 offset:14832
	s_waitcnt lgkmcnt(12)
	v_pk_fma_f32 v[200:201], v[48:49], v[176:177], v[200:201] op_sel_hi:[1,0,1] neg_lo:[1,0,0] neg_hi:[1,0,0]
	v_pk_fma_f32 v[202:203], v[56:57], v[176:177], v[202:203] op_sel_hi:[1,0,1] neg_lo:[1,0,0] neg_hi:[1,0,0]
	v_pk_fma_f32 v[200:201], v[50:51], v[176:177], v[200:201] op_sel:[0,1,0] op_sel_hi:[1,1,1] neg_lo:[1,0,0] neg_hi:[1,0,0]
	v_pk_fma_f32 v[202:203], v[58:59], v[176:177], v[202:203] op_sel:[0,1,0] op_sel_hi:[1,1,1] neg_lo:[1,0,0] neg_hi:[1,0,0]
	v_pk_fma_f32 v[200:201], v[52:53], v[178:179], v[200:201] op_sel_hi:[1,0,1] neg_lo:[1,0,0] neg_hi:[1,0,0]
	v_pk_fma_f32 v[202:203], v[60:61], v[178:179], v[202:203] op_sel_hi:[1,0,1] neg_lo:[1,0,0] neg_hi:[1,0,0]
	v_pk_fma_f32 v[200:201], v[54:55], v[178:179], v[200:201] op_sel:[0,1,0] op_sel_hi:[1,1,1] neg_lo:[1,0,0] neg_hi:[1,0,0]
	v_pk_fma_f32 v[202:203], v[62:63], v[178:179], v[202:203] op_sel:[0,1,0] op_sel_hi:[1,1,1] neg_lo:[1,0,0] neg_hi:[1,0,0]
	ds_read_b128 v[48:51], v78 offset:15360
	ds_read_b128 v[52:55], v78 offset:15376
	ds_read_b128 v[56:59], v78 offset:15904
	ds_read_b128 v[60:63], v78 offset:15920
	s_waitcnt lgkmcnt(12)
	v_pk_fma_f32 v[204:205], v[0:1], v[176:177], v[204:205] op_sel_hi:[1,0,1] neg_lo:[1,0,0] neg_hi:[1,0,0]
	v_pk_fma_f32 v[206:207], v[8:9], v[176:177], v[206:207] op_sel_hi:[1,0,1] neg_lo:[1,0,0] neg_hi:[1,0,0]
	v_pk_fma_f32 v[204:205], v[2:3], v[176:177], v[204:205] op_sel:[0,1,0] op_sel_hi:[1,1,1] neg_lo:[1,0,0] neg_hi:[1,0,0]
	v_pk_fma_f32 v[206:207], v[10:11], v[176:177], v[206:207] op_sel:[0,1,0] op_sel_hi:[1,1,1] neg_lo:[1,0,0] neg_hi:[1,0,0]
	v_pk_fma_f32 v[204:205], v[4:5], v[178:179], v[204:205] op_sel_hi:[1,0,1] neg_lo:[1,0,0] neg_hi:[1,0,0]
	v_pk_fma_f32 v[206:207], v[12:13], v[178:179], v[206:207] op_sel_hi:[1,0,1] neg_lo:[1,0,0] neg_hi:[1,0,0]
	v_pk_fma_f32 v[204:205], v[6:7], v[178:179], v[204:205] op_sel:[0,1,0] op_sel_hi:[1,1,1] neg_lo:[1,0,0] neg_hi:[1,0,0]
	v_pk_fma_f32 v[206:207], v[14:15], v[178:179], v[206:207] op_sel:[0,1,0] op_sel_hi:[1,1,1] neg_lo:[1,0,0] neg_hi:[1,0,0]
	ds_read_b128 v[0:3], v78 offset:16448
	ds_read_b128 v[4:7], v78 offset:16464
	ds_read_b128 v[8:11], v78 offset:16992
	ds_read_b128 v[12:15], v78 offset:17008
	s_waitcnt lgkmcnt(12)
	v_pk_fma_f32 v[208:209], v[16:17], v[176:177], v[208:209] op_sel_hi:[1,0,1] neg_lo:[1,0,0] neg_hi:[1,0,0]
	v_pk_fma_f32 v[210:211], v[24:25], v[176:177], v[210:211] op_sel_hi:[1,0,1] neg_lo:[1,0,0] neg_hi:[1,0,0]
	v_pk_fma_f32 v[208:209], v[18:19], v[176:177], v[208:209] op_sel:[0,1,0] op_sel_hi:[1,1,1] neg_lo:[1,0,0] neg_hi:[1,0,0]
	v_pk_fma_f32 v[210:211], v[26:27], v[176:177], v[210:211] op_sel:[0,1,0] op_sel_hi:[1,1,1] neg_lo:[1,0,0] neg_hi:[1,0,0]
	v_pk_fma_f32 v[208:209], v[20:21], v[178:179], v[208:209] op_sel_hi:[1,0,1] neg_lo:[1,0,0] neg_hi:[1,0,0]
	v_pk_fma_f32 v[210:211], v[28:29], v[178:179], v[210:211] op_sel_hi:[1,0,1] neg_lo:[1,0,0] neg_hi:[1,0,0]
	v_pk_fma_f32 v[208:209], v[22:23], v[178:179], v[208:209] op_sel:[0,1,0] op_sel_hi:[1,1,1] neg_lo:[1,0,0] neg_hi:[1,0,0]
	v_pk_fma_f32 v[210:211], v[30:31], v[178:179], v[210:211] op_sel:[0,1,0] op_sel_hi:[1,1,1] neg_lo:[1,0,0] neg_hi:[1,0,0]
	ds_read_b128 v[16:19], v78 offset:6688
	ds_read_b128 v[20:23], v78 offset:6704
	ds_read_b128 v[24:27], v78 offset:7232
	ds_read_b128 v[28:31], v78 offset:7248
	s_waitcnt lgkmcnt(12)
	v_pk_fma_f32 v[212:213], v[32:33], v[176:177], v[212:213] op_sel_hi:[1,0,1] neg_lo:[1,0,0] neg_hi:[1,0,0]
	v_pk_fma_f32 v[214:215], v[40:41], v[176:177], v[214:215] op_sel_hi:[1,0,1] neg_lo:[1,0,0] neg_hi:[1,0,0]
	v_pk_fma_f32 v[212:213], v[34:35], v[176:177], v[212:213] op_sel:[0,1,0] op_sel_hi:[1,1,1] neg_lo:[1,0,0] neg_hi:[1,0,0]
	v_pk_fma_f32 v[214:215], v[42:43], v[176:177], v[214:215] op_sel:[0,1,0] op_sel_hi:[1,1,1] neg_lo:[1,0,0] neg_hi:[1,0,0]
	v_pk_fma_f32 v[212:213], v[36:37], v[178:179], v[212:213] op_sel_hi:[1,0,1] neg_lo:[1,0,0] neg_hi:[1,0,0]
	v_pk_fma_f32 v[214:215], v[44:45], v[178:179], v[214:215] op_sel_hi:[1,0,1] neg_lo:[1,0,0] neg_hi:[1,0,0]
	v_pk_fma_f32 v[212:213], v[38:39], v[178:179], v[212:213] op_sel:[0,1,0] op_sel_hi:[1,1,1] neg_lo:[1,0,0] neg_hi:[1,0,0]
	v_pk_fma_f32 v[214:215], v[46:47], v[178:179], v[214:215] op_sel:[0,1,0] op_sel_hi:[1,1,1] neg_lo:[1,0,0] neg_hi:[1,0,0]
	ds_read_b128 v[32:35], v78 offset:7776
	ds_read_b128 v[36:39], v78 offset:7792
	ds_read_b128 v[40:43], v78 offset:8320
	ds_read_b128 v[44:47], v78 offset:8336
	s_waitcnt lgkmcnt(12)
	v_pk_fma_f32 v[216:217], v[48:49], v[176:177], v[216:217] op_sel_hi:[1,0,1] neg_lo:[1,0,0] neg_hi:[1,0,0]
	v_pk_fma_f32 v[218:219], v[56:57], v[176:177], v[218:219] op_sel_hi:[1,0,1] neg_lo:[1,0,0] neg_hi:[1,0,0]
	v_pk_fma_f32 v[216:217], v[50:51], v[176:177], v[216:217] op_sel:[0,1,0] op_sel_hi:[1,1,1] neg_lo:[1,0,0] neg_hi:[1,0,0]
	v_pk_fma_f32 v[218:219], v[58:59], v[176:177], v[218:219] op_sel:[0,1,0] op_sel_hi:[1,1,1] neg_lo:[1,0,0] neg_hi:[1,0,0]
	v_pk_fma_f32 v[216:217], v[52:53], v[178:179], v[216:217] op_sel_hi:[1,0,1] neg_lo:[1,0,0] neg_hi:[1,0,0]
	v_pk_fma_f32 v[218:219], v[60:61], v[178:179], v[218:219] op_sel_hi:[1,0,1] neg_lo:[1,0,0] neg_hi:[1,0,0]
	v_pk_fma_f32 v[216:217], v[54:55], v[178:179], v[216:217] op_sel:[0,1,0] op_sel_hi:[1,1,1] neg_lo:[1,0,0] neg_hi:[1,0,0]
	v_pk_fma_f32 v[218:219], v[62:63], v[178:179], v[218:219] op_sel:[0,1,0] op_sel_hi:[1,1,1] neg_lo:[1,0,0] neg_hi:[1,0,0]
	ds_read_b128 v[48:51], v78 offset:8864
	ds_read_b128 v[52:55], v78 offset:8880
	ds_read_b128 v[56:59], v78 offset:9408
	ds_read_b128 v[60:63], v78 offset:9424
	s_waitcnt lgkmcnt(12)
	v_pk_fma_f32 v[220:221], v[0:1], v[176:177], v[220:221] op_sel_hi:[1,0,1] neg_lo:[1,0,0] neg_hi:[1,0,0]
	v_pk_fma_f32 v[222:223], v[8:9], v[176:177], v[222:223] op_sel_hi:[1,0,1] neg_lo:[1,0,0] neg_hi:[1,0,0]
	v_pk_fma_f32 v[220:221], v[2:3], v[176:177], v[220:221] op_sel:[0,1,0] op_sel_hi:[1,1,1] neg_lo:[1,0,0] neg_hi:[1,0,0]
	v_pk_fma_f32 v[222:223], v[10:11], v[176:177], v[222:223] op_sel:[0,1,0] op_sel_hi:[1,1,1] neg_lo:[1,0,0] neg_hi:[1,0,0]
	v_pk_fma_f32 v[220:221], v[4:5], v[178:179], v[220:221] op_sel_hi:[1,0,1] neg_lo:[1,0,0] neg_hi:[1,0,0]
	v_pk_fma_f32 v[222:223], v[12:13], v[178:179], v[222:223] op_sel_hi:[1,0,1] neg_lo:[1,0,0] neg_hi:[1,0,0]
	v_pk_fma_f32 v[220:221], v[6:7], v[178:179], v[220:221] op_sel:[0,1,0] op_sel_hi:[1,1,1] neg_lo:[1,0,0] neg_hi:[1,0,0]
	v_pk_fma_f32 v[222:223], v[14:15], v[178:179], v[222:223] op_sel:[0,1,0] op_sel_hi:[1,1,1] neg_lo:[1,0,0] neg_hi:[1,0,0]
	ds_read_b128 v[64:67], v78 offset:6720
	ds_read_b128 v[68:71], v78 offset:7264
	ds_read_b128 v[72:75], v78 offset:7280
	ds_read_b128 v[0:3], v78 offset:9952
	ds_read_b128 v[4:7], v78 offset:9968
	ds_read_b128 v[8:11], v78 offset:10496
	ds_read_b128 v[12:15], v78 offset:10512
	s_waitcnt lgkmcnt(15)
	v_pk_fma_f32 v[184:185], v[16:17], v[180:181], v[184:185] op_sel_hi:[1,0,1] neg_lo:[1,0,0] neg_hi:[1,0,0]
	v_pk_fma_f32 v[186:187], v[24:25], v[180:181], v[186:187] op_sel_hi:[1,0,1] neg_lo:[1,0,0] neg_hi:[1,0,0]
	v_pk_fma_f32 v[184:185], v[18:19], v[180:181], v[184:185] op_sel:[0,1,0] op_sel_hi:[1,1,1] neg_lo:[1,0,0] neg_hi:[1,0,0]
	v_pk_fma_f32 v[186:187], v[26:27], v[180:181], v[186:187] op_sel:[0,1,0] op_sel_hi:[1,1,1] neg_lo:[1,0,0] neg_hi:[1,0,0]
	v_pk_fma_f32 v[184:185], v[20:21], v[182:183], v[184:185] op_sel_hi:[1,0,1] neg_lo:[1,0,0] neg_hi:[1,0,0]
	v_pk_fma_f32 v[186:187], v[28:29], v[182:183], v[186:187] op_sel_hi:[1,0,1] neg_lo:[1,0,0] neg_hi:[1,0,0]
	v_pk_fma_f32 v[184:185], v[22:23], v[182:183], v[184:185] op_sel:[0,1,0] op_sel_hi:[1,1,1] neg_lo:[1,0,0] neg_hi:[1,0,0]
	v_pk_fma_f32 v[186:187], v[30:31], v[182:183], v[186:187] op_sel:[0,1,0] op_sel_hi:[1,1,1] neg_lo:[1,0,0] neg_hi:[1,0,0]
	ds_read_b128 v[16:19], v78 offset:11040
	ds_read_b128 v[20:23], v78 offset:11056
	ds_read_b128 v[24:27], v78 offset:11584
	ds_read_b128 v[28:31], v78 offset:11600
	s_waitcnt lgkmcnt(15)
	v_pk_fma_f32 v[188:189], v[32:33], v[180:181], v[188:189] op_sel_hi:[1,0,1] neg_lo:[1,0,0] neg_hi:[1,0,0]
	v_pk_fma_f32 v[190:191], v[40:41], v[180:181], v[190:191] op_sel_hi:[1,0,1] neg_lo:[1,0,0] neg_hi:[1,0,0]
	s_waitcnt lgkmcnt(10)
	v_pk_fma_f32 v[184:185], v[64:65], v[184:185], v[184:185] op_sel_hi:[1,0,1] neg_lo:[1,0,0] neg_hi:[1,0,0]
	v_pk_fma_f32 v[188:189], v[34:35], v[180:181], v[188:189] op_sel:[0,1,0] op_sel_hi:[1,1,1] neg_lo:[1,0,0] neg_hi:[1,0,0]
	v_pk_fma_f32 v[190:191], v[42:43], v[180:181], v[190:191] op_sel:[0,1,0] op_sel_hi:[1,1,1] neg_lo:[1,0,0] neg_hi:[1,0,0]
	s_waitcnt lgkmcnt(9)
	v_pk_fma_f32 v[186:187], v[68:69], v[184:185], v[186:187] op_sel_hi:[1,0,1] neg_lo:[1,0,0] neg_hi:[1,0,0]
	v_pk_fma_f32 v[188:189], v[36:37], v[182:183], v[188:189] op_sel_hi:[1,0,1] neg_lo:[1,0,0] neg_hi:[1,0,0]
	v_pk_fma_f32 v[190:191], v[44:45], v[182:183], v[190:191] op_sel_hi:[1,0,1] neg_lo:[1,0,0] neg_hi:[1,0,0]
	v_pk_fma_f32 v[186:187], v[70:71], v[184:185], v[186:187] op_sel:[0,1,0] op_sel_hi:[1,1,1] neg_lo:[1,0,0] neg_hi:[1,0,0]
	v_pk_fma_f32 v[188:189], v[38:39], v[182:183], v[188:189] op_sel:[0,1,0] op_sel_hi:[1,1,1] neg_lo:[1,0,0] neg_hi:[1,0,0]
	v_pk_fma_f32 v[190:191], v[46:47], v[182:183], v[190:191] op_sel:[0,1,0] op_sel_hi:[1,1,1] neg_lo:[1,0,0] neg_hi:[1,0,0]
	s_waitcnt lgkmcnt(8)
	v_pk_fma_f32 v[186:187], v[72:73], v[186:187], v[186:187] op_sel_hi:[1,0,1] neg_lo:[1,0,0] neg_hi:[1,0,0]
	ds_read_b128 v[32:35], v78 offset:12128
	ds_read_b128 v[36:39], v78 offset:12144
	ds_read_b128 v[40:43], v78 offset:12672
	ds_read_b128 v[44:47], v78 offset:12688
	s_waitcnt lgkmcnt(15)
	v_pk_fma_f32 v[192:193], v[48:49], v[180:181], v[192:193] op_sel_hi:[1,0,1] neg_lo:[1,0,0] neg_hi:[1,0,0]
	v_pk_fma_f32 v[194:195], v[56:57], v[180:181], v[194:195] op_sel_hi:[1,0,1] neg_lo:[1,0,0] neg_hi:[1,0,0]
	v_pk_fma_f32 v[192:193], v[50:51], v[180:181], v[192:193] op_sel:[0,1,0] op_sel_hi:[1,1,1] neg_lo:[1,0,0] neg_hi:[1,0,0]
	v_pk_fma_f32 v[194:195], v[58:59], v[180:181], v[194:195] op_sel:[0,1,0] op_sel_hi:[1,1,1] neg_lo:[1,0,0] neg_hi:[1,0,0]
	v_pk_fma_f32 v[192:193], v[52:53], v[182:183], v[192:193] op_sel_hi:[1,0,1] neg_lo:[1,0,0] neg_hi:[1,0,0]
	v_pk_fma_f32 v[194:195], v[60:61], v[182:183], v[194:195] op_sel_hi:[1,0,1] neg_lo:[1,0,0] neg_hi:[1,0,0]
	v_pk_fma_f32 v[192:193], v[54:55], v[182:183], v[192:193] op_sel:[0,1,0] op_sel_hi:[1,1,1] neg_lo:[1,0,0] neg_hi:[1,0,0]
	v_pk_fma_f32 v[194:195], v[62:63], v[182:183], v[194:195] op_sel:[0,1,0] op_sel_hi:[1,1,1] neg_lo:[1,0,0] neg_hi:[1,0,0]
	ds_read_b128 v[48:51], v78 offset:13216
	ds_read_b128 v[52:55], v78 offset:13232
	ds_read_b128 v[56:59], v78 offset:13760
	ds_read_b128 v[60:63], v78 offset:13776
	s_waitcnt lgkmcnt(12)
	v_pk_fma_f32 v[196:197], v[0:1], v[180:181], v[196:197] op_sel_hi:[1,0,1] neg_lo:[1,0,0] neg_hi:[1,0,0]
	v_pk_fma_f32 v[198:199], v[8:9], v[180:181], v[198:199] op_sel_hi:[1,0,1] neg_lo:[1,0,0] neg_hi:[1,0,0]
	v_pk_fma_f32 v[196:197], v[2:3], v[180:181], v[196:197] op_sel:[0,1,0] op_sel_hi:[1,1,1] neg_lo:[1,0,0] neg_hi:[1,0,0]
	v_pk_fma_f32 v[198:199], v[10:11], v[180:181], v[198:199] op_sel:[0,1,0] op_sel_hi:[1,1,1] neg_lo:[1,0,0] neg_hi:[1,0,0]
	v_pk_fma_f32 v[196:197], v[4:5], v[182:183], v[196:197] op_sel_hi:[1,0,1] neg_lo:[1,0,0] neg_hi:[1,0,0]
	v_pk_fma_f32 v[198:199], v[12:13], v[182:183], v[198:199] op_sel_hi:[1,0,1] neg_lo:[1,0,0] neg_hi:[1,0,0]
	v_pk_fma_f32 v[196:197], v[6:7], v[182:183], v[196:197] op_sel:[0,1,0] op_sel_hi:[1,1,1] neg_lo:[1,0,0] neg_hi:[1,0,0]
	v_pk_fma_f32 v[198:199], v[14:15], v[182:183], v[198:199] op_sel:[0,1,0] op_sel_hi:[1,1,1] neg_lo:[1,0,0] neg_hi:[1,0,0]
	ds_read_b128 v[0:3], v78 offset:14304
	ds_read_b128 v[4:7], v78 offset:14320
	ds_read_b128 v[8:11], v78 offset:14848
	ds_read_b128 v[12:15], v78 offset:14864
	s_waitcnt lgkmcnt(12)
	v_pk_fma_f32 v[200:201], v[16:17], v[180:181], v[200:201] op_sel_hi:[1,0,1] neg_lo:[1,0,0] neg_hi:[1,0,0]
	v_pk_fma_f32 v[202:203], v[24:25], v[180:181], v[202:203] op_sel_hi:[1,0,1] neg_lo:[1,0,0] neg_hi:[1,0,0]
	v_pk_fma_f32 v[200:201], v[18:19], v[180:181], v[200:201] op_sel:[0,1,0] op_sel_hi:[1,1,1] neg_lo:[1,0,0] neg_hi:[1,0,0]
	v_pk_fma_f32 v[202:203], v[26:27], v[180:181], v[202:203] op_sel:[0,1,0] op_sel_hi:[1,1,1] neg_lo:[1,0,0] neg_hi:[1,0,0]
	v_pk_fma_f32 v[200:201], v[20:21], v[182:183], v[200:201] op_sel_hi:[1,0,1] neg_lo:[1,0,0] neg_hi:[1,0,0]
	v_pk_fma_f32 v[202:203], v[28:29], v[182:183], v[202:203] op_sel_hi:[1,0,1] neg_lo:[1,0,0] neg_hi:[1,0,0]
	v_pk_fma_f32 v[200:201], v[22:23], v[182:183], v[200:201] op_sel:[0,1,0] op_sel_hi:[1,1,1] neg_lo:[1,0,0] neg_hi:[1,0,0]
	v_pk_fma_f32 v[202:203], v[30:31], v[182:183], v[202:203] op_sel:[0,1,0] op_sel_hi:[1,1,1] neg_lo:[1,0,0] neg_hi:[1,0,0]
	ds_read_b128 v[16:19], v78 offset:15392
	ds_read_b128 v[20:23], v78 offset:15408
	ds_read_b128 v[24:27], v78 offset:15936
	ds_read_b128 v[28:31], v78 offset:15952
	s_waitcnt lgkmcnt(12)
	v_pk_fma_f32 v[204:205], v[32:33], v[180:181], v[204:205] op_sel_hi:[1,0,1] neg_lo:[1,0,0] neg_hi:[1,0,0]
	v_pk_fma_f32 v[206:207], v[40:41], v[180:181], v[206:207] op_sel_hi:[1,0,1] neg_lo:[1,0,0] neg_hi:[1,0,0]
	v_pk_fma_f32 v[204:205], v[34:35], v[180:181], v[204:205] op_sel:[0,1,0] op_sel_hi:[1,1,1] neg_lo:[1,0,0] neg_hi:[1,0,0]
	v_pk_fma_f32 v[206:207], v[42:43], v[180:181], v[206:207] op_sel:[0,1,0] op_sel_hi:[1,1,1] neg_lo:[1,0,0] neg_hi:[1,0,0]
	v_pk_fma_f32 v[204:205], v[36:37], v[182:183], v[204:205] op_sel_hi:[1,0,1] neg_lo:[1,0,0] neg_hi:[1,0,0]
	v_pk_fma_f32 v[206:207], v[44:45], v[182:183], v[206:207] op_sel_hi:[1,0,1] neg_lo:[1,0,0] neg_hi:[1,0,0]
	v_pk_fma_f32 v[204:205], v[38:39], v[182:183], v[204:205] op_sel:[0,1,0] op_sel_hi:[1,1,1] neg_lo:[1,0,0] neg_hi:[1,0,0]
	v_pk_fma_f32 v[206:207], v[46:47], v[182:183], v[206:207] op_sel:[0,1,0] op_sel_hi:[1,1,1] neg_lo:[1,0,0] neg_hi:[1,0,0]
	ds_read_b128 v[32:35], v78 offset:16480
	ds_read_b128 v[36:39], v78 offset:16496
	ds_read_b128 v[40:43], v78 offset:17024
	ds_read_b128 v[44:47], v78 offset:17040
	s_waitcnt lgkmcnt(12)
	v_pk_fma_f32 v[208:209], v[48:49], v[180:181], v[208:209] op_sel_hi:[1,0,1] neg_lo:[1,0,0] neg_hi:[1,0,0]
	v_pk_fma_f32 v[210:211], v[56:57], v[180:181], v[210:211] op_sel_hi:[1,0,1] neg_lo:[1,0,0] neg_hi:[1,0,0]
	v_pk_fma_f32 v[208:209], v[50:51], v[180:181], v[208:209] op_sel:[0,1,0] op_sel_hi:[1,1,1] neg_lo:[1,0,0] neg_hi:[1,0,0]
	v_pk_fma_f32 v[210:211], v[58:59], v[180:181], v[210:211] op_sel:[0,1,0] op_sel_hi:[1,1,1] neg_lo:[1,0,0] neg_hi:[1,0,0]
	v_pk_fma_f32 v[208:209], v[52:53], v[182:183], v[208:209] op_sel_hi:[1,0,1] neg_lo:[1,0,0] neg_hi:[1,0,0]
	v_pk_fma_f32 v[210:211], v[60:61], v[182:183], v[210:211] op_sel_hi:[1,0,1] neg_lo:[1,0,0] neg_hi:[1,0,0]
	v_pk_fma_f32 v[208:209], v[54:55], v[182:183], v[208:209] op_sel:[0,1,0] op_sel_hi:[1,1,1] neg_lo:[1,0,0] neg_hi:[1,0,0]
	v_pk_fma_f32 v[210:211], v[62:63], v[182:183], v[210:211] op_sel:[0,1,0] op_sel_hi:[1,1,1] neg_lo:[1,0,0] neg_hi:[1,0,0]
	ds_read_b128 v[48:51], v78 offset:7808
	ds_read_b128 v[52:55], v78 offset:7824
	ds_read_b128 v[56:59], v78 offset:8352
	ds_read_b128 v[60:63], v78 offset:8368
	s_waitcnt lgkmcnt(12)
	v_pk_fma_f32 v[212:213], v[0:1], v[180:181], v[212:213] op_sel_hi:[1,0,1] neg_lo:[1,0,0] neg_hi:[1,0,0]
	v_pk_fma_f32 v[214:215], v[8:9], v[180:181], v[214:215] op_sel_hi:[1,0,1] neg_lo:[1,0,0] neg_hi:[1,0,0]
	v_pk_fma_f32 v[212:213], v[2:3], v[180:181], v[212:213] op_sel:[0,1,0] op_sel_hi:[1,1,1] neg_lo:[1,0,0] neg_hi:[1,0,0]
	v_pk_fma_f32 v[214:215], v[10:11], v[180:181], v[214:215] op_sel:[0,1,0] op_sel_hi:[1,1,1] neg_lo:[1,0,0] neg_hi:[1,0,0]
	v_pk_fma_f32 v[212:213], v[4:5], v[182:183], v[212:213] op_sel_hi:[1,0,1] neg_lo:[1,0,0] neg_hi:[1,0,0]
	v_pk_fma_f32 v[214:215], v[12:13], v[182:183], v[214:215] op_sel_hi:[1,0,1] neg_lo:[1,0,0] neg_hi:[1,0,0]
	v_pk_fma_f32 v[212:213], v[6:7], v[182:183], v[212:213] op_sel:[0,1,0] op_sel_hi:[1,1,1] neg_lo:[1,0,0] neg_hi:[1,0,0]
	v_pk_fma_f32 v[214:215], v[14:15], v[182:183], v[214:215] op_sel:[0,1,0] op_sel_hi:[1,1,1] neg_lo:[1,0,0] neg_hi:[1,0,0]
	ds_read_b128 v[0:3], v78 offset:8896
	ds_read_b128 v[4:7], v78 offset:8912
	ds_read_b128 v[8:11], v78 offset:9440
	ds_read_b128 v[12:15], v78 offset:9456
	s_waitcnt lgkmcnt(12)
	v_pk_fma_f32 v[216:217], v[16:17], v[180:181], v[216:217] op_sel_hi:[1,0,1] neg_lo:[1,0,0] neg_hi:[1,0,0]
	v_pk_fma_f32 v[218:219], v[24:25], v[180:181], v[218:219] op_sel_hi:[1,0,1] neg_lo:[1,0,0] neg_hi:[1,0,0]
	v_pk_fma_f32 v[216:217], v[18:19], v[180:181], v[216:217] op_sel:[0,1,0] op_sel_hi:[1,1,1] neg_lo:[1,0,0] neg_hi:[1,0,0]
	v_pk_fma_f32 v[218:219], v[26:27], v[180:181], v[218:219] op_sel:[0,1,0] op_sel_hi:[1,1,1] neg_lo:[1,0,0] neg_hi:[1,0,0]
	v_pk_fma_f32 v[216:217], v[20:21], v[182:183], v[216:217] op_sel_hi:[1,0,1] neg_lo:[1,0,0] neg_hi:[1,0,0]
	v_pk_fma_f32 v[218:219], v[28:29], v[182:183], v[218:219] op_sel_hi:[1,0,1] neg_lo:[1,0,0] neg_hi:[1,0,0]
	v_pk_fma_f32 v[216:217], v[22:23], v[182:183], v[216:217] op_sel:[0,1,0] op_sel_hi:[1,1,1] neg_lo:[1,0,0] neg_hi:[1,0,0]
	v_pk_fma_f32 v[218:219], v[30:31], v[182:183], v[218:219] op_sel:[0,1,0] op_sel_hi:[1,1,1] neg_lo:[1,0,0] neg_hi:[1,0,0]
	ds_read_b128 v[16:19], v78 offset:9984
	ds_read_b128 v[20:23], v78 offset:10000
	ds_read_b128 v[24:27], v78 offset:10528
	ds_read_b128 v[28:31], v78 offset:10544
	s_waitcnt lgkmcnt(12)
	v_pk_fma_f32 v[220:221], v[32:33], v[180:181], v[220:221] op_sel_hi:[1,0,1] neg_lo:[1,0,0] neg_hi:[1,0,0]
	v_pk_fma_f32 v[222:223], v[40:41], v[180:181], v[222:223] op_sel_hi:[1,0,1] neg_lo:[1,0,0] neg_hi:[1,0,0]
	v_pk_fma_f32 v[220:221], v[34:35], v[180:181], v[220:221] op_sel:[0,1,0] op_sel_hi:[1,1,1] neg_lo:[1,0,0] neg_hi:[1,0,0]
	v_pk_fma_f32 v[222:223], v[42:43], v[180:181], v[222:223] op_sel:[0,1,0] op_sel_hi:[1,1,1] neg_lo:[1,0,0] neg_hi:[1,0,0]
	v_pk_fma_f32 v[220:221], v[36:37], v[182:183], v[220:221] op_sel_hi:[1,0,1] neg_lo:[1,0,0] neg_hi:[1,0,0]
	v_pk_fma_f32 v[222:223], v[44:45], v[182:183], v[222:223] op_sel_hi:[1,0,1] neg_lo:[1,0,0] neg_hi:[1,0,0]
	v_pk_fma_f32 v[220:221], v[38:39], v[182:183], v[220:221] op_sel:[0,1,0] op_sel_hi:[1,1,1] neg_lo:[1,0,0] neg_hi:[1,0,0]
	v_pk_fma_f32 v[222:223], v[46:47], v[182:183], v[222:223] op_sel:[0,1,0] op_sel_hi:[1,1,1] neg_lo:[1,0,0] neg_hi:[1,0,0]
	ds_read_b128 v[64:67], v78 offset:7840
	ds_read_b128 v[68:71], v78 offset:8384
	ds_read_b128 v[72:75], v78 offset:8400
	ds_read_b128 v[32:35], v78 offset:11072
	ds_read_b128 v[36:39], v78 offset:11088
	ds_read_b128 v[40:43], v78 offset:11616
	ds_read_b128 v[44:47], v78 offset:11632
	s_waitcnt lgkmcnt(15)
	v_pk_fma_f32 v[188:189], v[48:49], v[184:185], v[188:189] op_sel_hi:[1,0,1] neg_lo:[1,0,0] neg_hi:[1,0,0]
	v_pk_fma_f32 v[190:191], v[56:57], v[184:185], v[190:191] op_sel_hi:[1,0,1] neg_lo:[1,0,0] neg_hi:[1,0,0]
	v_pk_fma_f32 v[188:189], v[50:51], v[184:185], v[188:189] op_sel:[0,1,0] op_sel_hi:[1,1,1] neg_lo:[1,0,0] neg_hi:[1,0,0]
	v_pk_fma_f32 v[190:191], v[58:59], v[184:185], v[190:191] op_sel:[0,1,0] op_sel_hi:[1,1,1] neg_lo:[1,0,0] neg_hi:[1,0,0]
	v_pk_fma_f32 v[188:189], v[52:53], v[186:187], v[188:189] op_sel_hi:[1,0,1] neg_lo:[1,0,0] neg_hi:[1,0,0]
	v_pk_fma_f32 v[190:191], v[60:61], v[186:187], v[190:191] op_sel_hi:[1,0,1] neg_lo:[1,0,0] neg_hi:[1,0,0]
	v_pk_fma_f32 v[188:189], v[54:55], v[186:187], v[188:189] op_sel:[0,1,0] op_sel_hi:[1,1,1] neg_lo:[1,0,0] neg_hi:[1,0,0]
	v_pk_fma_f32 v[190:191], v[62:63], v[186:187], v[190:191] op_sel:[0,1,0] op_sel_hi:[1,1,1] neg_lo:[1,0,0] neg_hi:[1,0,0]
	ds_read_b128 v[48:51], v78 offset:12160
	ds_read_b128 v[52:55], v78 offset:12176
	ds_read_b128 v[56:59], v78 offset:12704
	ds_read_b128 v[60:63], v78 offset:12720
	s_waitcnt lgkmcnt(15)
	v_pk_fma_f32 v[192:193], v[0:1], v[184:185], v[192:193] op_sel_hi:[1,0,1] neg_lo:[1,0,0] neg_hi:[1,0,0]
	v_pk_fma_f32 v[194:195], v[8:9], v[184:185], v[194:195] op_sel_hi:[1,0,1] neg_lo:[1,0,0] neg_hi:[1,0,0]
	s_waitcnt lgkmcnt(10)
	v_pk_fma_f32 v[188:189], v[64:65], v[188:189], v[188:189] op_sel_hi:[1,0,1] neg_lo:[1,0,0] neg_hi:[1,0,0]
	v_pk_fma_f32 v[192:193], v[2:3], v[184:185], v[192:193] op_sel:[0,1,0] op_sel_hi:[1,1,1] neg_lo:[1,0,0] neg_hi:[1,0,0]
	v_pk_fma_f32 v[194:195], v[10:11], v[184:185], v[194:195] op_sel:[0,1,0] op_sel_hi:[1,1,1] neg_lo:[1,0,0] neg_hi:[1,0,0]
	s_waitcnt lgkmcnt(9)
	v_pk_fma_f32 v[190:191], v[68:69], v[188:189], v[190:191] op_sel_hi:[1,0,1] neg_lo:[1,0,0] neg_hi:[1,0,0]
	v_pk_fma_f32 v[192:193], v[4:5], v[186:187], v[192:193] op_sel_hi:[1,0,1] neg_lo:[1,0,0] neg_hi:[1,0,0]
	v_pk_fma_f32 v[194:195], v[12:13], v[186:187], v[194:195] op_sel_hi:[1,0,1] neg_lo:[1,0,0] neg_hi:[1,0,0]
	v_pk_fma_f32 v[190:191], v[70:71], v[188:189], v[190:191] op_sel:[0,1,0] op_sel_hi:[1,1,1] neg_lo:[1,0,0] neg_hi:[1,0,0]
	v_pk_fma_f32 v[192:193], v[6:7], v[186:187], v[192:193] op_sel:[0,1,0] op_sel_hi:[1,1,1] neg_lo:[1,0,0] neg_hi:[1,0,0]
	v_pk_fma_f32 v[194:195], v[14:15], v[186:187], v[194:195] op_sel:[0,1,0] op_sel_hi:[1,1,1] neg_lo:[1,0,0] neg_hi:[1,0,0]
	s_waitcnt lgkmcnt(8)
	v_pk_fma_f32 v[190:191], v[72:73], v[190:191], v[190:191] op_sel_hi:[1,0,1] neg_lo:[1,0,0] neg_hi:[1,0,0]
	ds_read_b128 v[0:3], v78 offset:13248
	ds_read_b128 v[4:7], v78 offset:13264
	ds_read_b128 v[8:11], v78 offset:13792
	ds_read_b128 v[12:15], v78 offset:13808
	s_waitcnt lgkmcnt(15)
	v_pk_fma_f32 v[196:197], v[16:17], v[184:185], v[196:197] op_sel_hi:[1,0,1] neg_lo:[1,0,0] neg_hi:[1,0,0]
	v_pk_fma_f32 v[198:199], v[24:25], v[184:185], v[198:199] op_sel_hi:[1,0,1] neg_lo:[1,0,0] neg_hi:[1,0,0]
	v_pk_fma_f32 v[196:197], v[18:19], v[184:185], v[196:197] op_sel:[0,1,0] op_sel_hi:[1,1,1] neg_lo:[1,0,0] neg_hi:[1,0,0]
	v_pk_fma_f32 v[198:199], v[26:27], v[184:185], v[198:199] op_sel:[0,1,0] op_sel_hi:[1,1,1] neg_lo:[1,0,0] neg_hi:[1,0,0]
	v_pk_fma_f32 v[196:197], v[20:21], v[186:187], v[196:197] op_sel_hi:[1,0,1] neg_lo:[1,0,0] neg_hi:[1,0,0]
	v_pk_fma_f32 v[198:199], v[28:29], v[186:187], v[198:199] op_sel_hi:[1,0,1] neg_lo:[1,0,0] neg_hi:[1,0,0]
	v_pk_fma_f32 v[196:197], v[22:23], v[186:187], v[196:197] op_sel:[0,1,0] op_sel_hi:[1,1,1] neg_lo:[1,0,0] neg_hi:[1,0,0]
	v_pk_fma_f32 v[198:199], v[30:31], v[186:187], v[198:199] op_sel:[0,1,0] op_sel_hi:[1,1,1] neg_lo:[1,0,0] neg_hi:[1,0,0]
	ds_read_b128 v[16:19], v78 offset:14336
	ds_read_b128 v[20:23], v78 offset:14352
	ds_read_b128 v[24:27], v78 offset:14880
	ds_read_b128 v[28:31], v78 offset:14896
	s_waitcnt lgkmcnt(12)
	v_pk_fma_f32 v[200:201], v[32:33], v[184:185], v[200:201] op_sel_hi:[1,0,1] neg_lo:[1,0,0] neg_hi:[1,0,0]
	v_pk_fma_f32 v[202:203], v[40:41], v[184:185], v[202:203] op_sel_hi:[1,0,1] neg_lo:[1,0,0] neg_hi:[1,0,0]
	v_pk_fma_f32 v[200:201], v[34:35], v[184:185], v[200:201] op_sel:[0,1,0] op_sel_hi:[1,1,1] neg_lo:[1,0,0] neg_hi:[1,0,0]
	v_pk_fma_f32 v[202:203], v[42:43], v[184:185], v[202:203] op_sel:[0,1,0] op_sel_hi:[1,1,1] neg_lo:[1,0,0] neg_hi:[1,0,0]
	v_pk_fma_f32 v[200:201], v[36:37], v[186:187], v[200:201] op_sel_hi:[1,0,1] neg_lo:[1,0,0] neg_hi:[1,0,0]
	v_pk_fma_f32 v[202:203], v[44:45], v[186:187], v[202:203] op_sel_hi:[1,0,1] neg_lo:[1,0,0] neg_hi:[1,0,0]
	v_pk_fma_f32 v[200:201], v[38:39], v[186:187], v[200:201] op_sel:[0,1,0] op_sel_hi:[1,1,1] neg_lo:[1,0,0] neg_hi:[1,0,0]
	v_pk_fma_f32 v[202:203], v[46:47], v[186:187], v[202:203] op_sel:[0,1,0] op_sel_hi:[1,1,1] neg_lo:[1,0,0] neg_hi:[1,0,0]
	ds_read_b128 v[32:35], v78 offset:15424
	ds_read_b128 v[36:39], v78 offset:15440
	ds_read_b128 v[40:43], v78 offset:15968
	ds_read_b128 v[44:47], v78 offset:15984
	s_waitcnt lgkmcnt(12)
	v_pk_fma_f32 v[204:205], v[48:49], v[184:185], v[204:205] op_sel_hi:[1,0,1] neg_lo:[1,0,0] neg_hi:[1,0,0]
	v_pk_fma_f32 v[206:207], v[56:57], v[184:185], v[206:207] op_sel_hi:[1,0,1] neg_lo:[1,0,0] neg_hi:[1,0,0]
	v_pk_fma_f32 v[204:205], v[50:51], v[184:185], v[204:205] op_sel:[0,1,0] op_sel_hi:[1,1,1] neg_lo:[1,0,0] neg_hi:[1,0,0]
	v_pk_fma_f32 v[206:207], v[58:59], v[184:185], v[206:207] op_sel:[0,1,0] op_sel_hi:[1,1,1] neg_lo:[1,0,0] neg_hi:[1,0,0]
	v_pk_fma_f32 v[204:205], v[52:53], v[186:187], v[204:205] op_sel_hi:[1,0,1] neg_lo:[1,0,0] neg_hi:[1,0,0]
	v_pk_fma_f32 v[206:207], v[60:61], v[186:187], v[206:207] op_sel_hi:[1,0,1] neg_lo:[1,0,0] neg_hi:[1,0,0]
	v_pk_fma_f32 v[204:205], v[54:55], v[186:187], v[204:205] op_sel:[0,1,0] op_sel_hi:[1,1,1] neg_lo:[1,0,0] neg_hi:[1,0,0]
	v_pk_fma_f32 v[206:207], v[62:63], v[186:187], v[206:207] op_sel:[0,1,0] op_sel_hi:[1,1,1] neg_lo:[1,0,0] neg_hi:[1,0,0]
	ds_read_b128 v[48:51], v78 offset:16512
	ds_read_b128 v[52:55], v78 offset:16528
	ds_read_b128 v[56:59], v78 offset:17056
	ds_read_b128 v[60:63], v78 offset:17072
	s_waitcnt lgkmcnt(12)
	v_pk_fma_f32 v[208:209], v[0:1], v[184:185], v[208:209] op_sel_hi:[1,0,1] neg_lo:[1,0,0] neg_hi:[1,0,0]
	v_pk_fma_f32 v[210:211], v[8:9], v[184:185], v[210:211] op_sel_hi:[1,0,1] neg_lo:[1,0,0] neg_hi:[1,0,0]
	v_pk_fma_f32 v[208:209], v[2:3], v[184:185], v[208:209] op_sel:[0,1,0] op_sel_hi:[1,1,1] neg_lo:[1,0,0] neg_hi:[1,0,0]
	v_pk_fma_f32 v[210:211], v[10:11], v[184:185], v[210:211] op_sel:[0,1,0] op_sel_hi:[1,1,1] neg_lo:[1,0,0] neg_hi:[1,0,0]
	v_pk_fma_f32 v[208:209], v[4:5], v[186:187], v[208:209] op_sel_hi:[1,0,1] neg_lo:[1,0,0] neg_hi:[1,0,0]
	v_pk_fma_f32 v[210:211], v[12:13], v[186:187], v[210:211] op_sel_hi:[1,0,1] neg_lo:[1,0,0] neg_hi:[1,0,0]
	v_pk_fma_f32 v[208:209], v[6:7], v[186:187], v[208:209] op_sel:[0,1,0] op_sel_hi:[1,1,1] neg_lo:[1,0,0] neg_hi:[1,0,0]
	v_pk_fma_f32 v[210:211], v[14:15], v[186:187], v[210:211] op_sel:[0,1,0] op_sel_hi:[1,1,1] neg_lo:[1,0,0] neg_hi:[1,0,0]
	ds_read_b128 v[0:3], v78 offset:8928
	ds_read_b128 v[4:7], v78 offset:8944
	ds_read_b128 v[8:11], v78 offset:9472
	ds_read_b128 v[12:15], v78 offset:9488
	s_waitcnt lgkmcnt(12)
	v_pk_fma_f32 v[212:213], v[16:17], v[184:185], v[212:213] op_sel_hi:[1,0,1] neg_lo:[1,0,0] neg_hi:[1,0,0]
	v_pk_fma_f32 v[214:215], v[24:25], v[184:185], v[214:215] op_sel_hi:[1,0,1] neg_lo:[1,0,0] neg_hi:[1,0,0]
	v_pk_fma_f32 v[212:213], v[18:19], v[184:185], v[212:213] op_sel:[0,1,0] op_sel_hi:[1,1,1] neg_lo:[1,0,0] neg_hi:[1,0,0]
	v_pk_fma_f32 v[214:215], v[26:27], v[184:185], v[214:215] op_sel:[0,1,0] op_sel_hi:[1,1,1] neg_lo:[1,0,0] neg_hi:[1,0,0]
	v_pk_fma_f32 v[212:213], v[20:21], v[186:187], v[212:213] op_sel_hi:[1,0,1] neg_lo:[1,0,0] neg_hi:[1,0,0]
	v_pk_fma_f32 v[214:215], v[28:29], v[186:187], v[214:215] op_sel_hi:[1,0,1] neg_lo:[1,0,0] neg_hi:[1,0,0]
	v_pk_fma_f32 v[212:213], v[22:23], v[186:187], v[212:213] op_sel:[0,1,0] op_sel_hi:[1,1,1] neg_lo:[1,0,0] neg_hi:[1,0,0]
	v_pk_fma_f32 v[214:215], v[30:31], v[186:187], v[214:215] op_sel:[0,1,0] op_sel_hi:[1,1,1] neg_lo:[1,0,0] neg_hi:[1,0,0]
	ds_read_b128 v[16:19], v78 offset:10016
	ds_read_b128 v[20:23], v78 offset:10032
	ds_read_b128 v[24:27], v78 offset:10560
	ds_read_b128 v[28:31], v78 offset:10576
	s_waitcnt lgkmcnt(12)
	v_pk_fma_f32 v[216:217], v[32:33], v[184:185], v[216:217] op_sel_hi:[1,0,1] neg_lo:[1,0,0] neg_hi:[1,0,0]
	v_pk_fma_f32 v[218:219], v[40:41], v[184:185], v[218:219] op_sel_hi:[1,0,1] neg_lo:[1,0,0] neg_hi:[1,0,0]
	v_pk_fma_f32 v[216:217], v[34:35], v[184:185], v[216:217] op_sel:[0,1,0] op_sel_hi:[1,1,1] neg_lo:[1,0,0] neg_hi:[1,0,0]
	v_pk_fma_f32 v[218:219], v[42:43], v[184:185], v[218:219] op_sel:[0,1,0] op_sel_hi:[1,1,1] neg_lo:[1,0,0] neg_hi:[1,0,0]
	v_pk_fma_f32 v[216:217], v[36:37], v[186:187], v[216:217] op_sel_hi:[1,0,1] neg_lo:[1,0,0] neg_hi:[1,0,0]
	v_pk_fma_f32 v[218:219], v[44:45], v[186:187], v[218:219] op_sel_hi:[1,0,1] neg_lo:[1,0,0] neg_hi:[1,0,0]
	v_pk_fma_f32 v[216:217], v[38:39], v[186:187], v[216:217] op_sel:[0,1,0] op_sel_hi:[1,1,1] neg_lo:[1,0,0] neg_hi:[1,0,0]
	v_pk_fma_f32 v[218:219], v[46:47], v[186:187], v[218:219] op_sel:[0,1,0] op_sel_hi:[1,1,1] neg_lo:[1,0,0] neg_hi:[1,0,0]
	ds_read_b128 v[32:35], v78 offset:11104
	ds_read_b128 v[36:39], v78 offset:11120
	ds_read_b128 v[40:43], v78 offset:11648
	ds_read_b128 v[44:47], v78 offset:11664
	s_waitcnt lgkmcnt(12)
	v_pk_fma_f32 v[220:221], v[48:49], v[184:185], v[220:221] op_sel_hi:[1,0,1] neg_lo:[1,0,0] neg_hi:[1,0,0]
	v_pk_fma_f32 v[222:223], v[56:57], v[184:185], v[222:223] op_sel_hi:[1,0,1] neg_lo:[1,0,0] neg_hi:[1,0,0]
	v_pk_fma_f32 v[220:221], v[50:51], v[184:185], v[220:221] op_sel:[0,1,0] op_sel_hi:[1,1,1] neg_lo:[1,0,0] neg_hi:[1,0,0]
	v_pk_fma_f32 v[222:223], v[58:59], v[184:185], v[222:223] op_sel:[0,1,0] op_sel_hi:[1,1,1] neg_lo:[1,0,0] neg_hi:[1,0,0]
	v_pk_fma_f32 v[220:221], v[52:53], v[186:187], v[220:221] op_sel_hi:[1,0,1] neg_lo:[1,0,0] neg_hi:[1,0,0]
	v_pk_fma_f32 v[222:223], v[60:61], v[186:187], v[222:223] op_sel_hi:[1,0,1] neg_lo:[1,0,0] neg_hi:[1,0,0]
	v_pk_fma_f32 v[220:221], v[54:55], v[186:187], v[220:221] op_sel:[0,1,0] op_sel_hi:[1,1,1] neg_lo:[1,0,0] neg_hi:[1,0,0]
	v_pk_fma_f32 v[222:223], v[62:63], v[186:187], v[222:223] op_sel:[0,1,0] op_sel_hi:[1,1,1] neg_lo:[1,0,0] neg_hi:[1,0,0]
	ds_read_b128 v[64:67], v78 offset:8960
	ds_read_b128 v[68:71], v78 offset:9504
	ds_read_b128 v[72:75], v78 offset:9520
	ds_read_b128 v[48:51], v78 offset:12192
	ds_read_b128 v[52:55], v78 offset:12208
	ds_read_b128 v[56:59], v78 offset:12736
	ds_read_b128 v[60:63], v78 offset:12752
	s_waitcnt lgkmcnt(15)
	v_pk_fma_f32 v[192:193], v[0:1], v[188:189], v[192:193] op_sel_hi:[1,0,1] neg_lo:[1,0,0] neg_hi:[1,0,0]
	v_pk_fma_f32 v[194:195], v[8:9], v[188:189], v[194:195] op_sel_hi:[1,0,1] neg_lo:[1,0,0] neg_hi:[1,0,0]
	v_pk_fma_f32 v[192:193], v[2:3], v[188:189], v[192:193] op_sel:[0,1,0] op_sel_hi:[1,1,1] neg_lo:[1,0,0] neg_hi:[1,0,0]
	v_pk_fma_f32 v[194:195], v[10:11], v[188:189], v[194:195] op_sel:[0,1,0] op_sel_hi:[1,1,1] neg_lo:[1,0,0] neg_hi:[1,0,0]
	v_pk_fma_f32 v[192:193], v[4:5], v[190:191], v[192:193] op_sel_hi:[1,0,1] neg_lo:[1,0,0] neg_hi:[1,0,0]
	v_pk_fma_f32 v[194:195], v[12:13], v[190:191], v[194:195] op_sel_hi:[1,0,1] neg_lo:[1,0,0] neg_hi:[1,0,0]
	v_pk_fma_f32 v[192:193], v[6:7], v[190:191], v[192:193] op_sel:[0,1,0] op_sel_hi:[1,1,1] neg_lo:[1,0,0] neg_hi:[1,0,0]
	v_pk_fma_f32 v[194:195], v[14:15], v[190:191], v[194:195] op_sel:[0,1,0] op_sel_hi:[1,1,1] neg_lo:[1,0,0] neg_hi:[1,0,0]
	ds_read_b128 v[0:3], v78 offset:13280
	ds_read_b128 v[4:7], v78 offset:13296
	ds_read_b128 v[8:11], v78 offset:13824
	ds_read_b128 v[12:15], v78 offset:13840
	s_waitcnt lgkmcnt(15)
	v_pk_fma_f32 v[196:197], v[16:17], v[188:189], v[196:197] op_sel_hi:[1,0,1] neg_lo:[1,0,0] neg_hi:[1,0,0]
	v_pk_fma_f32 v[198:199], v[24:25], v[188:189], v[198:199] op_sel_hi:[1,0,1] neg_lo:[1,0,0] neg_hi:[1,0,0]
	s_waitcnt lgkmcnt(10)
	v_pk_fma_f32 v[192:193], v[64:65], v[192:193], v[192:193] op_sel_hi:[1,0,1] neg_lo:[1,0,0] neg_hi:[1,0,0]
	v_pk_fma_f32 v[196:197], v[18:19], v[188:189], v[196:197] op_sel:[0,1,0] op_sel_hi:[1,1,1] neg_lo:[1,0,0] neg_hi:[1,0,0]
	v_pk_fma_f32 v[198:199], v[26:27], v[188:189], v[198:199] op_sel:[0,1,0] op_sel_hi:[1,1,1] neg_lo:[1,0,0] neg_hi:[1,0,0]
	s_waitcnt lgkmcnt(9)
	v_pk_fma_f32 v[194:195], v[68:69], v[192:193], v[194:195] op_sel_hi:[1,0,1] neg_lo:[1,0,0] neg_hi:[1,0,0]
	v_pk_fma_f32 v[196:197], v[20:21], v[190:191], v[196:197] op_sel_hi:[1,0,1] neg_lo:[1,0,0] neg_hi:[1,0,0]
	v_pk_fma_f32 v[198:199], v[28:29], v[190:191], v[198:199] op_sel_hi:[1,0,1] neg_lo:[1,0,0] neg_hi:[1,0,0]
	v_pk_fma_f32 v[194:195], v[70:71], v[192:193], v[194:195] op_sel:[0,1,0] op_sel_hi:[1,1,1] neg_lo:[1,0,0] neg_hi:[1,0,0]
	v_pk_fma_f32 v[196:197], v[22:23], v[190:191], v[196:197] op_sel:[0,1,0] op_sel_hi:[1,1,1] neg_lo:[1,0,0] neg_hi:[1,0,0]
	v_pk_fma_f32 v[198:199], v[30:31], v[190:191], v[198:199] op_sel:[0,1,0] op_sel_hi:[1,1,1] neg_lo:[1,0,0] neg_hi:[1,0,0]
	s_waitcnt lgkmcnt(8)
	v_pk_fma_f32 v[194:195], v[72:73], v[194:195], v[194:195] op_sel_hi:[1,0,1] neg_lo:[1,0,0] neg_hi:[1,0,0]
	ds_read_b128 v[16:19], v78 offset:14368
	ds_read_b128 v[20:23], v78 offset:14384
	ds_read_b128 v[24:27], v78 offset:14912
	ds_read_b128 v[28:31], v78 offset:14928
	s_waitcnt lgkmcnt(15)
	v_pk_fma_f32 v[200:201], v[32:33], v[188:189], v[200:201] op_sel_hi:[1,0,1] neg_lo:[1,0,0] neg_hi:[1,0,0]
	v_pk_fma_f32 v[202:203], v[40:41], v[188:189], v[202:203] op_sel_hi:[1,0,1] neg_lo:[1,0,0] neg_hi:[1,0,0]
	v_pk_fma_f32 v[200:201], v[34:35], v[188:189], v[200:201] op_sel:[0,1,0] op_sel_hi:[1,1,1] neg_lo:[1,0,0] neg_hi:[1,0,0]
	v_pk_fma_f32 v[202:203], v[42:43], v[188:189], v[202:203] op_sel:[0,1,0] op_sel_hi:[1,1,1] neg_lo:[1,0,0] neg_hi:[1,0,0]
	v_pk_fma_f32 v[200:201], v[36:37], v[190:191], v[200:201] op_sel_hi:[1,0,1] neg_lo:[1,0,0] neg_hi:[1,0,0]
	v_pk_fma_f32 v[202:203], v[44:45], v[190:191], v[202:203] op_sel_hi:[1,0,1] neg_lo:[1,0,0] neg_hi:[1,0,0]
	v_pk_fma_f32 v[200:201], v[38:39], v[190:191], v[200:201] op_sel:[0,1,0] op_sel_hi:[1,1,1] neg_lo:[1,0,0] neg_hi:[1,0,0]
	v_pk_fma_f32 v[202:203], v[46:47], v[190:191], v[202:203] op_sel:[0,1,0] op_sel_hi:[1,1,1] neg_lo:[1,0,0] neg_hi:[1,0,0]
	ds_read_b128 v[32:35], v78 offset:15456
	ds_read_b128 v[36:39], v78 offset:15472
	ds_read_b128 v[40:43], v78 offset:16000
	ds_read_b128 v[44:47], v78 offset:16016
	s_waitcnt lgkmcnt(12)
	v_pk_fma_f32 v[204:205], v[48:49], v[188:189], v[204:205] op_sel_hi:[1,0,1] neg_lo:[1,0,0] neg_hi:[1,0,0]
	v_pk_fma_f32 v[206:207], v[56:57], v[188:189], v[206:207] op_sel_hi:[1,0,1] neg_lo:[1,0,0] neg_hi:[1,0,0]
	v_pk_fma_f32 v[204:205], v[50:51], v[188:189], v[204:205] op_sel:[0,1,0] op_sel_hi:[1,1,1] neg_lo:[1,0,0] neg_hi:[1,0,0]
	v_pk_fma_f32 v[206:207], v[58:59], v[188:189], v[206:207] op_sel:[0,1,0] op_sel_hi:[1,1,1] neg_lo:[1,0,0] neg_hi:[1,0,0]
	v_pk_fma_f32 v[204:205], v[52:53], v[190:191], v[204:205] op_sel_hi:[1,0,1] neg_lo:[1,0,0] neg_hi:[1,0,0]
	v_pk_fma_f32 v[206:207], v[60:61], v[190:191], v[206:207] op_sel_hi:[1,0,1] neg_lo:[1,0,0] neg_hi:[1,0,0]
	v_pk_fma_f32 v[204:205], v[54:55], v[190:191], v[204:205] op_sel:[0,1,0] op_sel_hi:[1,1,1] neg_lo:[1,0,0] neg_hi:[1,0,0]
	v_pk_fma_f32 v[206:207], v[62:63], v[190:191], v[206:207] op_sel:[0,1,0] op_sel_hi:[1,1,1] neg_lo:[1,0,0] neg_hi:[1,0,0]
	ds_read_b128 v[48:51], v78 offset:16544
	ds_read_b128 v[52:55], v78 offset:16560
	ds_read_b128 v[56:59], v78 offset:17088
	ds_read_b128 v[60:63], v78 offset:17104
	s_waitcnt lgkmcnt(12)
	v_pk_fma_f32 v[208:209], v[0:1], v[188:189], v[208:209] op_sel_hi:[1,0,1] neg_lo:[1,0,0] neg_hi:[1,0,0]
	v_pk_fma_f32 v[210:211], v[8:9], v[188:189], v[210:211] op_sel_hi:[1,0,1] neg_lo:[1,0,0] neg_hi:[1,0,0]
	v_pk_fma_f32 v[208:209], v[2:3], v[188:189], v[208:209] op_sel:[0,1,0] op_sel_hi:[1,1,1] neg_lo:[1,0,0] neg_hi:[1,0,0]
	v_pk_fma_f32 v[210:211], v[10:11], v[188:189], v[210:211] op_sel:[0,1,0] op_sel_hi:[1,1,1] neg_lo:[1,0,0] neg_hi:[1,0,0]
	v_pk_fma_f32 v[208:209], v[4:5], v[190:191], v[208:209] op_sel_hi:[1,0,1] neg_lo:[1,0,0] neg_hi:[1,0,0]
	v_pk_fma_f32 v[210:211], v[12:13], v[190:191], v[210:211] op_sel_hi:[1,0,1] neg_lo:[1,0,0] neg_hi:[1,0,0]
	v_pk_fma_f32 v[208:209], v[6:7], v[190:191], v[208:209] op_sel:[0,1,0] op_sel_hi:[1,1,1] neg_lo:[1,0,0] neg_hi:[1,0,0]
	v_pk_fma_f32 v[210:211], v[14:15], v[190:191], v[210:211] op_sel:[0,1,0] op_sel_hi:[1,1,1] neg_lo:[1,0,0] neg_hi:[1,0,0]
	ds_read_b128 v[0:3], v78 offset:10048
	ds_read_b128 v[4:7], v78 offset:10064
	ds_read_b128 v[8:11], v78 offset:10592
	ds_read_b128 v[12:15], v78 offset:10608
	s_waitcnt lgkmcnt(12)
	v_pk_fma_f32 v[212:213], v[16:17], v[188:189], v[212:213] op_sel_hi:[1,0,1] neg_lo:[1,0,0] neg_hi:[1,0,0]
	v_pk_fma_f32 v[214:215], v[24:25], v[188:189], v[214:215] op_sel_hi:[1,0,1] neg_lo:[1,0,0] neg_hi:[1,0,0]
	v_pk_fma_f32 v[212:213], v[18:19], v[188:189], v[212:213] op_sel:[0,1,0] op_sel_hi:[1,1,1] neg_lo:[1,0,0] neg_hi:[1,0,0]
	v_pk_fma_f32 v[214:215], v[26:27], v[188:189], v[214:215] op_sel:[0,1,0] op_sel_hi:[1,1,1] neg_lo:[1,0,0] neg_hi:[1,0,0]
	v_pk_fma_f32 v[212:213], v[20:21], v[190:191], v[212:213] op_sel_hi:[1,0,1] neg_lo:[1,0,0] neg_hi:[1,0,0]
	v_pk_fma_f32 v[214:215], v[28:29], v[190:191], v[214:215] op_sel_hi:[1,0,1] neg_lo:[1,0,0] neg_hi:[1,0,0]
	v_pk_fma_f32 v[212:213], v[22:23], v[190:191], v[212:213] op_sel:[0,1,0] op_sel_hi:[1,1,1] neg_lo:[1,0,0] neg_hi:[1,0,0]
	v_pk_fma_f32 v[214:215], v[30:31], v[190:191], v[214:215] op_sel:[0,1,0] op_sel_hi:[1,1,1] neg_lo:[1,0,0] neg_hi:[1,0,0]
	ds_read_b128 v[16:19], v78 offset:11136
	ds_read_b128 v[20:23], v78 offset:11152
	ds_read_b128 v[24:27], v78 offset:11680
	ds_read_b128 v[28:31], v78 offset:11696
	s_waitcnt lgkmcnt(12)
	v_pk_fma_f32 v[216:217], v[32:33], v[188:189], v[216:217] op_sel_hi:[1,0,1] neg_lo:[1,0,0] neg_hi:[1,0,0]
	v_pk_fma_f32 v[218:219], v[40:41], v[188:189], v[218:219] op_sel_hi:[1,0,1] neg_lo:[1,0,0] neg_hi:[1,0,0]
	v_pk_fma_f32 v[216:217], v[34:35], v[188:189], v[216:217] op_sel:[0,1,0] op_sel_hi:[1,1,1] neg_lo:[1,0,0] neg_hi:[1,0,0]
	v_pk_fma_f32 v[218:219], v[42:43], v[188:189], v[218:219] op_sel:[0,1,0] op_sel_hi:[1,1,1] neg_lo:[1,0,0] neg_hi:[1,0,0]
	v_pk_fma_f32 v[216:217], v[36:37], v[190:191], v[216:217] op_sel_hi:[1,0,1] neg_lo:[1,0,0] neg_hi:[1,0,0]
	v_pk_fma_f32 v[218:219], v[44:45], v[190:191], v[218:219] op_sel_hi:[1,0,1] neg_lo:[1,0,0] neg_hi:[1,0,0]
	v_pk_fma_f32 v[216:217], v[38:39], v[190:191], v[216:217] op_sel:[0,1,0] op_sel_hi:[1,1,1] neg_lo:[1,0,0] neg_hi:[1,0,0]
	v_pk_fma_f32 v[218:219], v[46:47], v[190:191], v[218:219] op_sel:[0,1,0] op_sel_hi:[1,1,1] neg_lo:[1,0,0] neg_hi:[1,0,0]
	ds_read_b128 v[32:35], v78 offset:12224
	ds_read_b128 v[36:39], v78 offset:12240
	ds_read_b128 v[40:43], v78 offset:12768
	ds_read_b128 v[44:47], v78 offset:12784
	s_waitcnt lgkmcnt(12)
	v_pk_fma_f32 v[220:221], v[48:49], v[188:189], v[220:221] op_sel_hi:[1,0,1] neg_lo:[1,0,0] neg_hi:[1,0,0]
	v_pk_fma_f32 v[222:223], v[56:57], v[188:189], v[222:223] op_sel_hi:[1,0,1] neg_lo:[1,0,0] neg_hi:[1,0,0]
	v_pk_fma_f32 v[220:221], v[50:51], v[188:189], v[220:221] op_sel:[0,1,0] op_sel_hi:[1,1,1] neg_lo:[1,0,0] neg_hi:[1,0,0]
	v_pk_fma_f32 v[222:223], v[58:59], v[188:189], v[222:223] op_sel:[0,1,0] op_sel_hi:[1,1,1] neg_lo:[1,0,0] neg_hi:[1,0,0]
	v_pk_fma_f32 v[220:221], v[52:53], v[190:191], v[220:221] op_sel_hi:[1,0,1] neg_lo:[1,0,0] neg_hi:[1,0,0]
	v_pk_fma_f32 v[222:223], v[60:61], v[190:191], v[222:223] op_sel_hi:[1,0,1] neg_lo:[1,0,0] neg_hi:[1,0,0]
	v_pk_fma_f32 v[220:221], v[54:55], v[190:191], v[220:221] op_sel:[0,1,0] op_sel_hi:[1,1,1] neg_lo:[1,0,0] neg_hi:[1,0,0]
	v_pk_fma_f32 v[222:223], v[62:63], v[190:191], v[222:223] op_sel:[0,1,0] op_sel_hi:[1,1,1] neg_lo:[1,0,0] neg_hi:[1,0,0]
	ds_read_b128 v[64:67], v78 offset:10080
	ds_read_b128 v[68:71], v78 offset:10624
	ds_read_b128 v[72:75], v78 offset:10640
	ds_read_b128 v[48:51], v78 offset:13312
	ds_read_b128 v[52:55], v78 offset:13328
	ds_read_b128 v[56:59], v78 offset:13856
	ds_read_b128 v[60:63], v78 offset:13872
	s_waitcnt lgkmcnt(15)
	v_pk_fma_f32 v[196:197], v[0:1], v[192:193], v[196:197] op_sel_hi:[1,0,1] neg_lo:[1,0,0] neg_hi:[1,0,0]
	v_pk_fma_f32 v[198:199], v[8:9], v[192:193], v[198:199] op_sel_hi:[1,0,1] neg_lo:[1,0,0] neg_hi:[1,0,0]
	v_pk_fma_f32 v[196:197], v[2:3], v[192:193], v[196:197] op_sel:[0,1,0] op_sel_hi:[1,1,1] neg_lo:[1,0,0] neg_hi:[1,0,0]
	v_pk_fma_f32 v[198:199], v[10:11], v[192:193], v[198:199] op_sel:[0,1,0] op_sel_hi:[1,1,1] neg_lo:[1,0,0] neg_hi:[1,0,0]
	v_pk_fma_f32 v[196:197], v[4:5], v[194:195], v[196:197] op_sel_hi:[1,0,1] neg_lo:[1,0,0] neg_hi:[1,0,0]
	v_pk_fma_f32 v[198:199], v[12:13], v[194:195], v[198:199] op_sel_hi:[1,0,1] neg_lo:[1,0,0] neg_hi:[1,0,0]
	v_pk_fma_f32 v[196:197], v[6:7], v[194:195], v[196:197] op_sel:[0,1,0] op_sel_hi:[1,1,1] neg_lo:[1,0,0] neg_hi:[1,0,0]
	v_pk_fma_f32 v[198:199], v[14:15], v[194:195], v[198:199] op_sel:[0,1,0] op_sel_hi:[1,1,1] neg_lo:[1,0,0] neg_hi:[1,0,0]
	ds_read_b128 v[0:3], v78 offset:14400
	ds_read_b128 v[4:7], v78 offset:14416
	ds_read_b128 v[8:11], v78 offset:14944
	ds_read_b128 v[12:15], v78 offset:14960
	s_waitcnt lgkmcnt(15)
	v_pk_fma_f32 v[200:201], v[16:17], v[192:193], v[200:201] op_sel_hi:[1,0,1] neg_lo:[1,0,0] neg_hi:[1,0,0]
	v_pk_fma_f32 v[202:203], v[24:25], v[192:193], v[202:203] op_sel_hi:[1,0,1] neg_lo:[1,0,0] neg_hi:[1,0,0]
	s_waitcnt lgkmcnt(10)
	v_pk_fma_f32 v[196:197], v[64:65], v[196:197], v[196:197] op_sel_hi:[1,0,1] neg_lo:[1,0,0] neg_hi:[1,0,0]
	v_pk_fma_f32 v[200:201], v[18:19], v[192:193], v[200:201] op_sel:[0,1,0] op_sel_hi:[1,1,1] neg_lo:[1,0,0] neg_hi:[1,0,0]
	v_pk_fma_f32 v[202:203], v[26:27], v[192:193], v[202:203] op_sel:[0,1,0] op_sel_hi:[1,1,1] neg_lo:[1,0,0] neg_hi:[1,0,0]
	s_waitcnt lgkmcnt(9)
	v_pk_fma_f32 v[198:199], v[68:69], v[196:197], v[198:199] op_sel_hi:[1,0,1] neg_lo:[1,0,0] neg_hi:[1,0,0]
	v_pk_fma_f32 v[200:201], v[20:21], v[194:195], v[200:201] op_sel_hi:[1,0,1] neg_lo:[1,0,0] neg_hi:[1,0,0]
	v_pk_fma_f32 v[202:203], v[28:29], v[194:195], v[202:203] op_sel_hi:[1,0,1] neg_lo:[1,0,0] neg_hi:[1,0,0]
	v_pk_fma_f32 v[198:199], v[70:71], v[196:197], v[198:199] op_sel:[0,1,0] op_sel_hi:[1,1,1] neg_lo:[1,0,0] neg_hi:[1,0,0]
	v_pk_fma_f32 v[200:201], v[22:23], v[194:195], v[200:201] op_sel:[0,1,0] op_sel_hi:[1,1,1] neg_lo:[1,0,0] neg_hi:[1,0,0]
	v_pk_fma_f32 v[202:203], v[30:31], v[194:195], v[202:203] op_sel:[0,1,0] op_sel_hi:[1,1,1] neg_lo:[1,0,0] neg_hi:[1,0,0]
	s_waitcnt lgkmcnt(8)
	v_pk_fma_f32 v[198:199], v[72:73], v[198:199], v[198:199] op_sel_hi:[1,0,1] neg_lo:[1,0,0] neg_hi:[1,0,0]
	ds_read_b128 v[16:19], v78 offset:15488
	ds_read_b128 v[20:23], v78 offset:15504
	ds_read_b128 v[24:27], v78 offset:16032
	ds_read_b128 v[28:31], v78 offset:16048
	s_waitcnt lgkmcnt(15)
	v_pk_fma_f32 v[204:205], v[32:33], v[192:193], v[204:205] op_sel_hi:[1,0,1] neg_lo:[1,0,0] neg_hi:[1,0,0]
	v_pk_fma_f32 v[206:207], v[40:41], v[192:193], v[206:207] op_sel_hi:[1,0,1] neg_lo:[1,0,0] neg_hi:[1,0,0]
	v_pk_fma_f32 v[204:205], v[34:35], v[192:193], v[204:205] op_sel:[0,1,0] op_sel_hi:[1,1,1] neg_lo:[1,0,0] neg_hi:[1,0,0]
	v_pk_fma_f32 v[206:207], v[42:43], v[192:193], v[206:207] op_sel:[0,1,0] op_sel_hi:[1,1,1] neg_lo:[1,0,0] neg_hi:[1,0,0]
	v_pk_fma_f32 v[204:205], v[36:37], v[194:195], v[204:205] op_sel_hi:[1,0,1] neg_lo:[1,0,0] neg_hi:[1,0,0]
	v_pk_fma_f32 v[206:207], v[44:45], v[194:195], v[206:207] op_sel_hi:[1,0,1] neg_lo:[1,0,0] neg_hi:[1,0,0]
	v_pk_fma_f32 v[204:205], v[38:39], v[194:195], v[204:205] op_sel:[0,1,0] op_sel_hi:[1,1,1] neg_lo:[1,0,0] neg_hi:[1,0,0]
	v_pk_fma_f32 v[206:207], v[46:47], v[194:195], v[206:207] op_sel:[0,1,0] op_sel_hi:[1,1,1] neg_lo:[1,0,0] neg_hi:[1,0,0]
	ds_read_b128 v[32:35], v78 offset:16576
	ds_read_b128 v[36:39], v78 offset:16592
	ds_read_b128 v[40:43], v78 offset:17120
	ds_read_b128 v[44:47], v78 offset:17136
	s_waitcnt lgkmcnt(12)
	v_pk_fma_f32 v[208:209], v[48:49], v[192:193], v[208:209] op_sel_hi:[1,0,1] neg_lo:[1,0,0] neg_hi:[1,0,0]
	v_pk_fma_f32 v[210:211], v[56:57], v[192:193], v[210:211] op_sel_hi:[1,0,1] neg_lo:[1,0,0] neg_hi:[1,0,0]
	v_pk_fma_f32 v[208:209], v[50:51], v[192:193], v[208:209] op_sel:[0,1,0] op_sel_hi:[1,1,1] neg_lo:[1,0,0] neg_hi:[1,0,0]
	v_pk_fma_f32 v[210:211], v[58:59], v[192:193], v[210:211] op_sel:[0,1,0] op_sel_hi:[1,1,1] neg_lo:[1,0,0] neg_hi:[1,0,0]
	v_pk_fma_f32 v[208:209], v[52:53], v[194:195], v[208:209] op_sel_hi:[1,0,1] neg_lo:[1,0,0] neg_hi:[1,0,0]
	v_pk_fma_f32 v[210:211], v[60:61], v[194:195], v[210:211] op_sel_hi:[1,0,1] neg_lo:[1,0,0] neg_hi:[1,0,0]
	v_pk_fma_f32 v[208:209], v[54:55], v[194:195], v[208:209] op_sel:[0,1,0] op_sel_hi:[1,1,1] neg_lo:[1,0,0] neg_hi:[1,0,0]
	v_pk_fma_f32 v[210:211], v[62:63], v[194:195], v[210:211] op_sel:[0,1,0] op_sel_hi:[1,1,1] neg_lo:[1,0,0] neg_hi:[1,0,0]
	ds_read_b128 v[48:51], v78 offset:11168
	ds_read_b128 v[52:55], v78 offset:11184
	ds_read_b128 v[56:59], v78 offset:11712
	ds_read_b128 v[60:63], v78 offset:11728
	s_waitcnt lgkmcnt(12)
	v_pk_fma_f32 v[212:213], v[0:1], v[192:193], v[212:213] op_sel_hi:[1,0,1] neg_lo:[1,0,0] neg_hi:[1,0,0]
	v_pk_fma_f32 v[214:215], v[8:9], v[192:193], v[214:215] op_sel_hi:[1,0,1] neg_lo:[1,0,0] neg_hi:[1,0,0]
	v_pk_fma_f32 v[212:213], v[2:3], v[192:193], v[212:213] op_sel:[0,1,0] op_sel_hi:[1,1,1] neg_lo:[1,0,0] neg_hi:[1,0,0]
	v_pk_fma_f32 v[214:215], v[10:11], v[192:193], v[214:215] op_sel:[0,1,0] op_sel_hi:[1,1,1] neg_lo:[1,0,0] neg_hi:[1,0,0]
	v_pk_fma_f32 v[212:213], v[4:5], v[194:195], v[212:213] op_sel_hi:[1,0,1] neg_lo:[1,0,0] neg_hi:[1,0,0]
	v_pk_fma_f32 v[214:215], v[12:13], v[194:195], v[214:215] op_sel_hi:[1,0,1] neg_lo:[1,0,0] neg_hi:[1,0,0]
	v_pk_fma_f32 v[212:213], v[6:7], v[194:195], v[212:213] op_sel:[0,1,0] op_sel_hi:[1,1,1] neg_lo:[1,0,0] neg_hi:[1,0,0]
	v_pk_fma_f32 v[214:215], v[14:15], v[194:195], v[214:215] op_sel:[0,1,0] op_sel_hi:[1,1,1] neg_lo:[1,0,0] neg_hi:[1,0,0]
	ds_read_b128 v[0:3], v78 offset:12256
	ds_read_b128 v[4:7], v78 offset:12272
	ds_read_b128 v[8:11], v78 offset:12800
	ds_read_b128 v[12:15], v78 offset:12816
	s_waitcnt lgkmcnt(12)
	v_pk_fma_f32 v[216:217], v[16:17], v[192:193], v[216:217] op_sel_hi:[1,0,1] neg_lo:[1,0,0] neg_hi:[1,0,0]
	v_pk_fma_f32 v[218:219], v[24:25], v[192:193], v[218:219] op_sel_hi:[1,0,1] neg_lo:[1,0,0] neg_hi:[1,0,0]
	v_pk_fma_f32 v[216:217], v[18:19], v[192:193], v[216:217] op_sel:[0,1,0] op_sel_hi:[1,1,1] neg_lo:[1,0,0] neg_hi:[1,0,0]
	v_pk_fma_f32 v[218:219], v[26:27], v[192:193], v[218:219] op_sel:[0,1,0] op_sel_hi:[1,1,1] neg_lo:[1,0,0] neg_hi:[1,0,0]
	v_pk_fma_f32 v[216:217], v[20:21], v[194:195], v[216:217] op_sel_hi:[1,0,1] neg_lo:[1,0,0] neg_hi:[1,0,0]
	v_pk_fma_f32 v[218:219], v[28:29], v[194:195], v[218:219] op_sel_hi:[1,0,1] neg_lo:[1,0,0] neg_hi:[1,0,0]
	v_pk_fma_f32 v[216:217], v[22:23], v[194:195], v[216:217] op_sel:[0,1,0] op_sel_hi:[1,1,1] neg_lo:[1,0,0] neg_hi:[1,0,0]
	v_pk_fma_f32 v[218:219], v[30:31], v[194:195], v[218:219] op_sel:[0,1,0] op_sel_hi:[1,1,1] neg_lo:[1,0,0] neg_hi:[1,0,0]
	ds_read_b128 v[16:19], v78 offset:13344
	ds_read_b128 v[20:23], v78 offset:13360
	ds_read_b128 v[24:27], v78 offset:13888
	ds_read_b128 v[28:31], v78 offset:13904
	s_waitcnt lgkmcnt(12)
	v_pk_fma_f32 v[220:221], v[32:33], v[192:193], v[220:221] op_sel_hi:[1,0,1] neg_lo:[1,0,0] neg_hi:[1,0,0]
	v_pk_fma_f32 v[222:223], v[40:41], v[192:193], v[222:223] op_sel_hi:[1,0,1] neg_lo:[1,0,0] neg_hi:[1,0,0]
	v_pk_fma_f32 v[220:221], v[34:35], v[192:193], v[220:221] op_sel:[0,1,0] op_sel_hi:[1,1,1] neg_lo:[1,0,0] neg_hi:[1,0,0]
	v_pk_fma_f32 v[222:223], v[42:43], v[192:193], v[222:223] op_sel:[0,1,0] op_sel_hi:[1,1,1] neg_lo:[1,0,0] neg_hi:[1,0,0]
	v_pk_fma_f32 v[220:221], v[36:37], v[194:195], v[220:221] op_sel_hi:[1,0,1] neg_lo:[1,0,0] neg_hi:[1,0,0]
	v_pk_fma_f32 v[222:223], v[44:45], v[194:195], v[222:223] op_sel_hi:[1,0,1] neg_lo:[1,0,0] neg_hi:[1,0,0]
	v_pk_fma_f32 v[220:221], v[38:39], v[194:195], v[220:221] op_sel:[0,1,0] op_sel_hi:[1,1,1] neg_lo:[1,0,0] neg_hi:[1,0,0]
	v_pk_fma_f32 v[222:223], v[46:47], v[194:195], v[222:223] op_sel:[0,1,0] op_sel_hi:[1,1,1] neg_lo:[1,0,0] neg_hi:[1,0,0]
	ds_read_b128 v[64:67], v78 offset:11200
	ds_read_b128 v[68:71], v78 offset:11744
	ds_read_b128 v[72:75], v78 offset:11760
	ds_read_b128 v[32:35], v78 offset:14432
	ds_read_b128 v[36:39], v78 offset:14448
	ds_read_b128 v[40:43], v78 offset:14976
	ds_read_b128 v[44:47], v78 offset:14992
	s_waitcnt lgkmcnt(15)
	v_pk_fma_f32 v[200:201], v[48:49], v[196:197], v[200:201] op_sel_hi:[1,0,1] neg_lo:[1,0,0] neg_hi:[1,0,0]
	v_pk_fma_f32 v[202:203], v[56:57], v[196:197], v[202:203] op_sel_hi:[1,0,1] neg_lo:[1,0,0] neg_hi:[1,0,0]
	v_pk_fma_f32 v[200:201], v[50:51], v[196:197], v[200:201] op_sel:[0,1,0] op_sel_hi:[1,1,1] neg_lo:[1,0,0] neg_hi:[1,0,0]
	v_pk_fma_f32 v[202:203], v[58:59], v[196:197], v[202:203] op_sel:[0,1,0] op_sel_hi:[1,1,1] neg_lo:[1,0,0] neg_hi:[1,0,0]
	v_pk_fma_f32 v[200:201], v[52:53], v[198:199], v[200:201] op_sel_hi:[1,0,1] neg_lo:[1,0,0] neg_hi:[1,0,0]
	v_pk_fma_f32 v[202:203], v[60:61], v[198:199], v[202:203] op_sel_hi:[1,0,1] neg_lo:[1,0,0] neg_hi:[1,0,0]
	v_pk_fma_f32 v[200:201], v[54:55], v[198:199], v[200:201] op_sel:[0,1,0] op_sel_hi:[1,1,1] neg_lo:[1,0,0] neg_hi:[1,0,0]
	v_pk_fma_f32 v[202:203], v[62:63], v[198:199], v[202:203] op_sel:[0,1,0] op_sel_hi:[1,1,1] neg_lo:[1,0,0] neg_hi:[1,0,0]
	ds_read_b128 v[48:51], v78 offset:15520
	ds_read_b128 v[52:55], v78 offset:15536
	ds_read_b128 v[56:59], v78 offset:16064
	ds_read_b128 v[60:63], v78 offset:16080
	s_waitcnt lgkmcnt(15)
	v_pk_fma_f32 v[204:205], v[0:1], v[196:197], v[204:205] op_sel_hi:[1,0,1] neg_lo:[1,0,0] neg_hi:[1,0,0]
	v_pk_fma_f32 v[206:207], v[8:9], v[196:197], v[206:207] op_sel_hi:[1,0,1] neg_lo:[1,0,0] neg_hi:[1,0,0]
	s_waitcnt lgkmcnt(10)
	v_pk_fma_f32 v[200:201], v[64:65], v[200:201], v[200:201] op_sel_hi:[1,0,1] neg_lo:[1,0,0] neg_hi:[1,0,0]
	v_pk_fma_f32 v[204:205], v[2:3], v[196:197], v[204:205] op_sel:[0,1,0] op_sel_hi:[1,1,1] neg_lo:[1,0,0] neg_hi:[1,0,0]
	v_pk_fma_f32 v[206:207], v[10:11], v[196:197], v[206:207] op_sel:[0,1,0] op_sel_hi:[1,1,1] neg_lo:[1,0,0] neg_hi:[1,0,0]
	s_waitcnt lgkmcnt(9)
	v_pk_fma_f32 v[202:203], v[68:69], v[200:201], v[202:203] op_sel_hi:[1,0,1] neg_lo:[1,0,0] neg_hi:[1,0,0]
	v_pk_fma_f32 v[204:205], v[4:5], v[198:199], v[204:205] op_sel_hi:[1,0,1] neg_lo:[1,0,0] neg_hi:[1,0,0]
	v_pk_fma_f32 v[206:207], v[12:13], v[198:199], v[206:207] op_sel_hi:[1,0,1] neg_lo:[1,0,0] neg_hi:[1,0,0]
	v_pk_fma_f32 v[202:203], v[70:71], v[200:201], v[202:203] op_sel:[0,1,0] op_sel_hi:[1,1,1] neg_lo:[1,0,0] neg_hi:[1,0,0]
	v_pk_fma_f32 v[204:205], v[6:7], v[198:199], v[204:205] op_sel:[0,1,0] op_sel_hi:[1,1,1] neg_lo:[1,0,0] neg_hi:[1,0,0]
	v_pk_fma_f32 v[206:207], v[14:15], v[198:199], v[206:207] op_sel:[0,1,0] op_sel_hi:[1,1,1] neg_lo:[1,0,0] neg_hi:[1,0,0]
	s_waitcnt lgkmcnt(8)
	v_pk_fma_f32 v[202:203], v[72:73], v[202:203], v[202:203] op_sel_hi:[1,0,1] neg_lo:[1,0,0] neg_hi:[1,0,0]
	ds_read_b128 v[0:3], v78 offset:16608
	ds_read_b128 v[4:7], v78 offset:16624
	ds_read_b128 v[8:11], v78 offset:17152
	ds_read_b128 v[12:15], v78 offset:17168
	s_waitcnt lgkmcnt(15)
	v_pk_fma_f32 v[208:209], v[16:17], v[196:197], v[208:209] op_sel_hi:[1,0,1] neg_lo:[1,0,0] neg_hi:[1,0,0]
	v_pk_fma_f32 v[210:211], v[24:25], v[196:197], v[210:211] op_sel_hi:[1,0,1] neg_lo:[1,0,0] neg_hi:[1,0,0]
	v_pk_fma_f32 v[208:209], v[18:19], v[196:197], v[208:209] op_sel:[0,1,0] op_sel_hi:[1,1,1] neg_lo:[1,0,0] neg_hi:[1,0,0]
	v_pk_fma_f32 v[210:211], v[26:27], v[196:197], v[210:211] op_sel:[0,1,0] op_sel_hi:[1,1,1] neg_lo:[1,0,0] neg_hi:[1,0,0]
	v_pk_fma_f32 v[208:209], v[20:21], v[198:199], v[208:209] op_sel_hi:[1,0,1] neg_lo:[1,0,0] neg_hi:[1,0,0]
	v_pk_fma_f32 v[210:211], v[28:29], v[198:199], v[210:211] op_sel_hi:[1,0,1] neg_lo:[1,0,0] neg_hi:[1,0,0]
	v_pk_fma_f32 v[208:209], v[22:23], v[198:199], v[208:209] op_sel:[0,1,0] op_sel_hi:[1,1,1] neg_lo:[1,0,0] neg_hi:[1,0,0]
	v_pk_fma_f32 v[210:211], v[30:31], v[198:199], v[210:211] op_sel:[0,1,0] op_sel_hi:[1,1,1] neg_lo:[1,0,0] neg_hi:[1,0,0]
	ds_read_b128 v[16:19], v78 offset:12288
	ds_read_b128 v[20:23], v78 offset:12304
	ds_read_b128 v[24:27], v78 offset:12832
	ds_read_b128 v[28:31], v78 offset:12848
	s_waitcnt lgkmcnt(12)
	v_pk_fma_f32 v[212:213], v[32:33], v[196:197], v[212:213] op_sel_hi:[1,0,1] neg_lo:[1,0,0] neg_hi:[1,0,0]
	v_pk_fma_f32 v[214:215], v[40:41], v[196:197], v[214:215] op_sel_hi:[1,0,1] neg_lo:[1,0,0] neg_hi:[1,0,0]
	v_pk_fma_f32 v[212:213], v[34:35], v[196:197], v[212:213] op_sel:[0,1,0] op_sel_hi:[1,1,1] neg_lo:[1,0,0] neg_hi:[1,0,0]
	v_pk_fma_f32 v[214:215], v[42:43], v[196:197], v[214:215] op_sel:[0,1,0] op_sel_hi:[1,1,1] neg_lo:[1,0,0] neg_hi:[1,0,0]
	v_pk_fma_f32 v[212:213], v[36:37], v[198:199], v[212:213] op_sel_hi:[1,0,1] neg_lo:[1,0,0] neg_hi:[1,0,0]
	v_pk_fma_f32 v[214:215], v[44:45], v[198:199], v[214:215] op_sel_hi:[1,0,1] neg_lo:[1,0,0] neg_hi:[1,0,0]
	v_pk_fma_f32 v[212:213], v[38:39], v[198:199], v[212:213] op_sel:[0,1,0] op_sel_hi:[1,1,1] neg_lo:[1,0,0] neg_hi:[1,0,0]
	v_pk_fma_f32 v[214:215], v[46:47], v[198:199], v[214:215] op_sel:[0,1,0] op_sel_hi:[1,1,1] neg_lo:[1,0,0] neg_hi:[1,0,0]
	ds_read_b128 v[32:35], v78 offset:13376
	ds_read_b128 v[36:39], v78 offset:13392
	ds_read_b128 v[40:43], v78 offset:13920
	ds_read_b128 v[44:47], v78 offset:13936
	s_waitcnt lgkmcnt(12)
	v_pk_fma_f32 v[216:217], v[48:49], v[196:197], v[216:217] op_sel_hi:[1,0,1] neg_lo:[1,0,0] neg_hi:[1,0,0]
	v_pk_fma_f32 v[218:219], v[56:57], v[196:197], v[218:219] op_sel_hi:[1,0,1] neg_lo:[1,0,0] neg_hi:[1,0,0]
	v_pk_fma_f32 v[216:217], v[50:51], v[196:197], v[216:217] op_sel:[0,1,0] op_sel_hi:[1,1,1] neg_lo:[1,0,0] neg_hi:[1,0,0]
	v_pk_fma_f32 v[218:219], v[58:59], v[196:197], v[218:219] op_sel:[0,1,0] op_sel_hi:[1,1,1] neg_lo:[1,0,0] neg_hi:[1,0,0]
	v_pk_fma_f32 v[216:217], v[52:53], v[198:199], v[216:217] op_sel_hi:[1,0,1] neg_lo:[1,0,0] neg_hi:[1,0,0]
	v_pk_fma_f32 v[218:219], v[60:61], v[198:199], v[218:219] op_sel_hi:[1,0,1] neg_lo:[1,0,0] neg_hi:[1,0,0]
	v_pk_fma_f32 v[216:217], v[54:55], v[198:199], v[216:217] op_sel:[0,1,0] op_sel_hi:[1,1,1] neg_lo:[1,0,0] neg_hi:[1,0,0]
	v_pk_fma_f32 v[218:219], v[62:63], v[198:199], v[218:219] op_sel:[0,1,0] op_sel_hi:[1,1,1] neg_lo:[1,0,0] neg_hi:[1,0,0]
	ds_read_b128 v[48:51], v78 offset:14464
	ds_read_b128 v[52:55], v78 offset:14480
	ds_read_b128 v[56:59], v78 offset:15008
	ds_read_b128 v[60:63], v78 offset:15024
	s_waitcnt lgkmcnt(12)
	v_pk_fma_f32 v[220:221], v[0:1], v[196:197], v[220:221] op_sel_hi:[1,0,1] neg_lo:[1,0,0] neg_hi:[1,0,0]
	v_pk_fma_f32 v[222:223], v[8:9], v[196:197], v[222:223] op_sel_hi:[1,0,1] neg_lo:[1,0,0] neg_hi:[1,0,0]
	v_pk_fma_f32 v[220:221], v[2:3], v[196:197], v[220:221] op_sel:[0,1,0] op_sel_hi:[1,1,1] neg_lo:[1,0,0] neg_hi:[1,0,0]
	v_pk_fma_f32 v[222:223], v[10:11], v[196:197], v[222:223] op_sel:[0,1,0] op_sel_hi:[1,1,1] neg_lo:[1,0,0] neg_hi:[1,0,0]
	v_pk_fma_f32 v[220:221], v[4:5], v[198:199], v[220:221] op_sel_hi:[1,0,1] neg_lo:[1,0,0] neg_hi:[1,0,0]
	v_pk_fma_f32 v[222:223], v[12:13], v[198:199], v[222:223] op_sel_hi:[1,0,1] neg_lo:[1,0,0] neg_hi:[1,0,0]
	v_pk_fma_f32 v[220:221], v[6:7], v[198:199], v[220:221] op_sel:[0,1,0] op_sel_hi:[1,1,1] neg_lo:[1,0,0] neg_hi:[1,0,0]
	v_pk_fma_f32 v[222:223], v[14:15], v[198:199], v[222:223] op_sel:[0,1,0] op_sel_hi:[1,1,1] neg_lo:[1,0,0] neg_hi:[1,0,0]
	ds_read_b128 v[64:67], v78 offset:12320
	ds_read_b128 v[68:71], v78 offset:12864
	ds_read_b128 v[72:75], v78 offset:12880
	ds_read_b128 v[0:3], v78 offset:15552
	ds_read_b128 v[4:7], v78 offset:15568
	ds_read_b128 v[8:11], v78 offset:16096
	ds_read_b128 v[12:15], v78 offset:16112
	s_waitcnt lgkmcnt(15)
	v_pk_fma_f32 v[204:205], v[16:17], v[200:201], v[204:205] op_sel_hi:[1,0,1] neg_lo:[1,0,0] neg_hi:[1,0,0]
	v_pk_fma_f32 v[206:207], v[24:25], v[200:201], v[206:207] op_sel_hi:[1,0,1] neg_lo:[1,0,0] neg_hi:[1,0,0]
	v_pk_fma_f32 v[204:205], v[18:19], v[200:201], v[204:205] op_sel:[0,1,0] op_sel_hi:[1,1,1] neg_lo:[1,0,0] neg_hi:[1,0,0]
	v_pk_fma_f32 v[206:207], v[26:27], v[200:201], v[206:207] op_sel:[0,1,0] op_sel_hi:[1,1,1] neg_lo:[1,0,0] neg_hi:[1,0,0]
	v_pk_fma_f32 v[204:205], v[20:21], v[202:203], v[204:205] op_sel_hi:[1,0,1] neg_lo:[1,0,0] neg_hi:[1,0,0]
	v_pk_fma_f32 v[206:207], v[28:29], v[202:203], v[206:207] op_sel_hi:[1,0,1] neg_lo:[1,0,0] neg_hi:[1,0,0]
	v_pk_fma_f32 v[204:205], v[22:23], v[202:203], v[204:205] op_sel:[0,1,0] op_sel_hi:[1,1,1] neg_lo:[1,0,0] neg_hi:[1,0,0]
	v_pk_fma_f32 v[206:207], v[30:31], v[202:203], v[206:207] op_sel:[0,1,0] op_sel_hi:[1,1,1] neg_lo:[1,0,0] neg_hi:[1,0,0]
	ds_read_b128 v[16:19], v78 offset:16640
	ds_read_b128 v[20:23], v78 offset:16656
	ds_read_b128 v[24:27], v78 offset:17184
	ds_read_b128 v[28:31], v78 offset:17200
	s_waitcnt lgkmcnt(15)
	v_pk_fma_f32 v[208:209], v[32:33], v[200:201], v[208:209] op_sel_hi:[1,0,1] neg_lo:[1,0,0] neg_hi:[1,0,0]
	v_pk_fma_f32 v[210:211], v[40:41], v[200:201], v[210:211] op_sel_hi:[1,0,1] neg_lo:[1,0,0] neg_hi:[1,0,0]
	s_waitcnt lgkmcnt(10)
	v_pk_fma_f32 v[204:205], v[64:65], v[204:205], v[204:205] op_sel_hi:[1,0,1] neg_lo:[1,0,0] neg_hi:[1,0,0]
	v_pk_fma_f32 v[208:209], v[34:35], v[200:201], v[208:209] op_sel:[0,1,0] op_sel_hi:[1,1,1] neg_lo:[1,0,0] neg_hi:[1,0,0]
	v_pk_fma_f32 v[210:211], v[42:43], v[200:201], v[210:211] op_sel:[0,1,0] op_sel_hi:[1,1,1] neg_lo:[1,0,0] neg_hi:[1,0,0]
	s_waitcnt lgkmcnt(9)
	v_pk_fma_f32 v[206:207], v[68:69], v[204:205], v[206:207] op_sel_hi:[1,0,1] neg_lo:[1,0,0] neg_hi:[1,0,0]
	v_pk_fma_f32 v[208:209], v[36:37], v[202:203], v[208:209] op_sel_hi:[1,0,1] neg_lo:[1,0,0] neg_hi:[1,0,0]
	v_pk_fma_f32 v[210:211], v[44:45], v[202:203], v[210:211] op_sel_hi:[1,0,1] neg_lo:[1,0,0] neg_hi:[1,0,0]
	v_pk_fma_f32 v[206:207], v[70:71], v[204:205], v[206:207] op_sel:[0,1,0] op_sel_hi:[1,1,1] neg_lo:[1,0,0] neg_hi:[1,0,0]
	v_pk_fma_f32 v[208:209], v[38:39], v[202:203], v[208:209] op_sel:[0,1,0] op_sel_hi:[1,1,1] neg_lo:[1,0,0] neg_hi:[1,0,0]
	v_pk_fma_f32 v[210:211], v[46:47], v[202:203], v[210:211] op_sel:[0,1,0] op_sel_hi:[1,1,1] neg_lo:[1,0,0] neg_hi:[1,0,0]
	s_waitcnt lgkmcnt(8)
	v_pk_fma_f32 v[206:207], v[72:73], v[206:207], v[206:207] op_sel_hi:[1,0,1] neg_lo:[1,0,0] neg_hi:[1,0,0]
	ds_read_b128 v[32:35], v78 offset:13408
	ds_read_b128 v[36:39], v78 offset:13424
	ds_read_b128 v[40:43], v78 offset:13952
	ds_read_b128 v[44:47], v78 offset:13968
	s_waitcnt lgkmcnt(15)
	v_pk_fma_f32 v[212:213], v[48:49], v[200:201], v[212:213] op_sel_hi:[1,0,1] neg_lo:[1,0,0] neg_hi:[1,0,0]
	v_pk_fma_f32 v[214:215], v[56:57], v[200:201], v[214:215] op_sel_hi:[1,0,1] neg_lo:[1,0,0] neg_hi:[1,0,0]
	v_pk_fma_f32 v[212:213], v[50:51], v[200:201], v[212:213] op_sel:[0,1,0] op_sel_hi:[1,1,1] neg_lo:[1,0,0] neg_hi:[1,0,0]
	v_pk_fma_f32 v[214:215], v[58:59], v[200:201], v[214:215] op_sel:[0,1,0] op_sel_hi:[1,1,1] neg_lo:[1,0,0] neg_hi:[1,0,0]
	v_pk_fma_f32 v[212:213], v[52:53], v[202:203], v[212:213] op_sel_hi:[1,0,1] neg_lo:[1,0,0] neg_hi:[1,0,0]
	v_pk_fma_f32 v[214:215], v[60:61], v[202:203], v[214:215] op_sel_hi:[1,0,1] neg_lo:[1,0,0] neg_hi:[1,0,0]
	v_pk_fma_f32 v[212:213], v[54:55], v[202:203], v[212:213] op_sel:[0,1,0] op_sel_hi:[1,1,1] neg_lo:[1,0,0] neg_hi:[1,0,0]
	v_pk_fma_f32 v[214:215], v[62:63], v[202:203], v[214:215] op_sel:[0,1,0] op_sel_hi:[1,1,1] neg_lo:[1,0,0] neg_hi:[1,0,0]
	ds_read_b128 v[48:51], v78 offset:14496
	ds_read_b128 v[52:55], v78 offset:14512
	ds_read_b128 v[56:59], v78 offset:15040
	ds_read_b128 v[60:63], v78 offset:15056
	s_waitcnt lgkmcnt(12)
	v_pk_fma_f32 v[216:217], v[0:1], v[200:201], v[216:217] op_sel_hi:[1,0,1] neg_lo:[1,0,0] neg_hi:[1,0,0]
	v_pk_fma_f32 v[218:219], v[8:9], v[200:201], v[218:219] op_sel_hi:[1,0,1] neg_lo:[1,0,0] neg_hi:[1,0,0]
	v_pk_fma_f32 v[216:217], v[2:3], v[200:201], v[216:217] op_sel:[0,1,0] op_sel_hi:[1,1,1] neg_lo:[1,0,0] neg_hi:[1,0,0]
	v_pk_fma_f32 v[218:219], v[10:11], v[200:201], v[218:219] op_sel:[0,1,0] op_sel_hi:[1,1,1] neg_lo:[1,0,0] neg_hi:[1,0,0]
	v_pk_fma_f32 v[216:217], v[4:5], v[202:203], v[216:217] op_sel_hi:[1,0,1] neg_lo:[1,0,0] neg_hi:[1,0,0]
	v_pk_fma_f32 v[218:219], v[12:13], v[202:203], v[218:219] op_sel_hi:[1,0,1] neg_lo:[1,0,0] neg_hi:[1,0,0]
	v_pk_fma_f32 v[216:217], v[6:7], v[202:203], v[216:217] op_sel:[0,1,0] op_sel_hi:[1,1,1] neg_lo:[1,0,0] neg_hi:[1,0,0]
	v_pk_fma_f32 v[218:219], v[14:15], v[202:203], v[218:219] op_sel:[0,1,0] op_sel_hi:[1,1,1] neg_lo:[1,0,0] neg_hi:[1,0,0]
	ds_read_b128 v[0:3], v78 offset:15584
	ds_read_b128 v[4:7], v78 offset:15600
	ds_read_b128 v[8:11], v78 offset:16128
	ds_read_b128 v[12:15], v78 offset:16144
	s_waitcnt lgkmcnt(12)
	v_pk_fma_f32 v[220:221], v[16:17], v[200:201], v[220:221] op_sel_hi:[1,0,1] neg_lo:[1,0,0] neg_hi:[1,0,0]
	v_pk_fma_f32 v[222:223], v[24:25], v[200:201], v[222:223] op_sel_hi:[1,0,1] neg_lo:[1,0,0] neg_hi:[1,0,0]
	v_pk_fma_f32 v[220:221], v[18:19], v[200:201], v[220:221] op_sel:[0,1,0] op_sel_hi:[1,1,1] neg_lo:[1,0,0] neg_hi:[1,0,0]
	v_pk_fma_f32 v[222:223], v[26:27], v[200:201], v[222:223] op_sel:[0,1,0] op_sel_hi:[1,1,1] neg_lo:[1,0,0] neg_hi:[1,0,0]
	v_pk_fma_f32 v[220:221], v[20:21], v[202:203], v[220:221] op_sel_hi:[1,0,1] neg_lo:[1,0,0] neg_hi:[1,0,0]
	v_pk_fma_f32 v[222:223], v[28:29], v[202:203], v[222:223] op_sel_hi:[1,0,1] neg_lo:[1,0,0] neg_hi:[1,0,0]
	v_pk_fma_f32 v[220:221], v[22:23], v[202:203], v[220:221] op_sel:[0,1,0] op_sel_hi:[1,1,1] neg_lo:[1,0,0] neg_hi:[1,0,0]
	v_pk_fma_f32 v[222:223], v[30:31], v[202:203], v[222:223] op_sel:[0,1,0] op_sel_hi:[1,1,1] neg_lo:[1,0,0] neg_hi:[1,0,0]
	ds_read_b128 v[64:67], v78 offset:13440
	ds_read_b128 v[68:71], v78 offset:13984
	ds_read_b128 v[72:75], v78 offset:14000
	ds_read_b128 v[16:19], v78 offset:16672
	ds_read_b128 v[20:23], v78 offset:16688
	ds_read_b128 v[24:27], v78 offset:17216
	ds_read_b128 v[28:31], v78 offset:17232
	s_waitcnt lgkmcnt(15)
	v_pk_fma_f32 v[208:209], v[32:33], v[204:205], v[208:209] op_sel_hi:[1,0,1] neg_lo:[1,0,0] neg_hi:[1,0,0]
	v_pk_fma_f32 v[210:211], v[40:41], v[204:205], v[210:211] op_sel_hi:[1,0,1] neg_lo:[1,0,0] neg_hi:[1,0,0]
	v_pk_fma_f32 v[208:209], v[34:35], v[204:205], v[208:209] op_sel:[0,1,0] op_sel_hi:[1,1,1] neg_lo:[1,0,0] neg_hi:[1,0,0]
	v_pk_fma_f32 v[210:211], v[42:43], v[204:205], v[210:211] op_sel:[0,1,0] op_sel_hi:[1,1,1] neg_lo:[1,0,0] neg_hi:[1,0,0]
	v_pk_fma_f32 v[208:209], v[36:37], v[206:207], v[208:209] op_sel_hi:[1,0,1] neg_lo:[1,0,0] neg_hi:[1,0,0]
	v_pk_fma_f32 v[210:211], v[44:45], v[206:207], v[210:211] op_sel_hi:[1,0,1] neg_lo:[1,0,0] neg_hi:[1,0,0]
	v_pk_fma_f32 v[208:209], v[38:39], v[206:207], v[208:209] op_sel:[0,1,0] op_sel_hi:[1,1,1] neg_lo:[1,0,0] neg_hi:[1,0,0]
	v_pk_fma_f32 v[210:211], v[46:47], v[206:207], v[210:211] op_sel:[0,1,0] op_sel_hi:[1,1,1] neg_lo:[1,0,0] neg_hi:[1,0,0]
	ds_read_b128 v[32:35], v78 offset:14528
	ds_read_b128 v[36:39], v78 offset:14544
	ds_read_b128 v[40:43], v78 offset:15072
	ds_read_b128 v[44:47], v78 offset:15088
	s_waitcnt lgkmcnt(15)
	v_pk_fma_f32 v[212:213], v[48:49], v[204:205], v[212:213] op_sel_hi:[1,0,1] neg_lo:[1,0,0] neg_hi:[1,0,0]
	v_pk_fma_f32 v[214:215], v[56:57], v[204:205], v[214:215] op_sel_hi:[1,0,1] neg_lo:[1,0,0] neg_hi:[1,0,0]
	s_waitcnt lgkmcnt(10)
	v_pk_fma_f32 v[208:209], v[64:65], v[208:209], v[208:209] op_sel_hi:[1,0,1] neg_lo:[1,0,0] neg_hi:[1,0,0]
	v_pk_fma_f32 v[212:213], v[50:51], v[204:205], v[212:213] op_sel:[0,1,0] op_sel_hi:[1,1,1] neg_lo:[1,0,0] neg_hi:[1,0,0]
	v_pk_fma_f32 v[214:215], v[58:59], v[204:205], v[214:215] op_sel:[0,1,0] op_sel_hi:[1,1,1] neg_lo:[1,0,0] neg_hi:[1,0,0]
	s_waitcnt lgkmcnt(9)
	v_pk_fma_f32 v[210:211], v[68:69], v[208:209], v[210:211] op_sel_hi:[1,0,1] neg_lo:[1,0,0] neg_hi:[1,0,0]
	v_pk_fma_f32 v[212:213], v[52:53], v[206:207], v[212:213] op_sel_hi:[1,0,1] neg_lo:[1,0,0] neg_hi:[1,0,0]
	v_pk_fma_f32 v[214:215], v[60:61], v[206:207], v[214:215] op_sel_hi:[1,0,1] neg_lo:[1,0,0] neg_hi:[1,0,0]
	v_pk_fma_f32 v[210:211], v[70:71], v[208:209], v[210:211] op_sel:[0,1,0] op_sel_hi:[1,1,1] neg_lo:[1,0,0] neg_hi:[1,0,0]
	v_pk_fma_f32 v[212:213], v[54:55], v[206:207], v[212:213] op_sel:[0,1,0] op_sel_hi:[1,1,1] neg_lo:[1,0,0] neg_hi:[1,0,0]
	v_pk_fma_f32 v[214:215], v[62:63], v[206:207], v[214:215] op_sel:[0,1,0] op_sel_hi:[1,1,1] neg_lo:[1,0,0] neg_hi:[1,0,0]
	s_waitcnt lgkmcnt(8)
	v_pk_fma_f32 v[210:211], v[72:73], v[210:211], v[210:211] op_sel_hi:[1,0,1] neg_lo:[1,0,0] neg_hi:[1,0,0]
	ds_read_b128 v[48:51], v78 offset:15616
	ds_read_b128 v[52:55], v78 offset:15632
	ds_read_b128 v[56:59], v78 offset:16160
	ds_read_b128 v[60:63], v78 offset:16176
	s_waitcnt lgkmcnt(15)
	v_pk_fma_f32 v[216:217], v[0:1], v[204:205], v[216:217] op_sel_hi:[1,0,1] neg_lo:[1,0,0] neg_hi:[1,0,0]
	v_pk_fma_f32 v[218:219], v[8:9], v[204:205], v[218:219] op_sel_hi:[1,0,1] neg_lo:[1,0,0] neg_hi:[1,0,0]
	v_pk_fma_f32 v[216:217], v[2:3], v[204:205], v[216:217] op_sel:[0,1,0] op_sel_hi:[1,1,1] neg_lo:[1,0,0] neg_hi:[1,0,0]
	v_pk_fma_f32 v[218:219], v[10:11], v[204:205], v[218:219] op_sel:[0,1,0] op_sel_hi:[1,1,1] neg_lo:[1,0,0] neg_hi:[1,0,0]
	v_pk_fma_f32 v[216:217], v[4:5], v[206:207], v[216:217] op_sel_hi:[1,0,1] neg_lo:[1,0,0] neg_hi:[1,0,0]
	v_pk_fma_f32 v[218:219], v[12:13], v[206:207], v[218:219] op_sel_hi:[1,0,1] neg_lo:[1,0,0] neg_hi:[1,0,0]
	v_pk_fma_f32 v[216:217], v[6:7], v[206:207], v[216:217] op_sel:[0,1,0] op_sel_hi:[1,1,1] neg_lo:[1,0,0] neg_hi:[1,0,0]
	v_pk_fma_f32 v[218:219], v[14:15], v[206:207], v[218:219] op_sel:[0,1,0] op_sel_hi:[1,1,1] neg_lo:[1,0,0] neg_hi:[1,0,0]
	ds_read_b128 v[0:3], v78 offset:16704
	ds_read_b128 v[4:7], v78 offset:16720
	ds_read_b128 v[8:11], v78 offset:17248
	ds_read_b128 v[12:15], v78 offset:17264
	s_waitcnt lgkmcnt(12)
	v_pk_fma_f32 v[220:221], v[16:17], v[204:205], v[220:221] op_sel_hi:[1,0,1] neg_lo:[1,0,0] neg_hi:[1,0,0]
	v_pk_fma_f32 v[222:223], v[24:25], v[204:205], v[222:223] op_sel_hi:[1,0,1] neg_lo:[1,0,0] neg_hi:[1,0,0]
	v_pk_fma_f32 v[220:221], v[18:19], v[204:205], v[220:221] op_sel:[0,1,0] op_sel_hi:[1,1,1] neg_lo:[1,0,0] neg_hi:[1,0,0]
	v_pk_fma_f32 v[222:223], v[26:27], v[204:205], v[222:223] op_sel:[0,1,0] op_sel_hi:[1,1,1] neg_lo:[1,0,0] neg_hi:[1,0,0]
	v_pk_fma_f32 v[220:221], v[20:21], v[206:207], v[220:221] op_sel_hi:[1,0,1] neg_lo:[1,0,0] neg_hi:[1,0,0]
	v_pk_fma_f32 v[222:223], v[28:29], v[206:207], v[222:223] op_sel_hi:[1,0,1] neg_lo:[1,0,0] neg_hi:[1,0,0]
	v_pk_fma_f32 v[220:221], v[22:23], v[206:207], v[220:221] op_sel:[0,1,0] op_sel_hi:[1,1,1] neg_lo:[1,0,0] neg_hi:[1,0,0]
	v_pk_fma_f32 v[222:223], v[30:31], v[206:207], v[222:223] op_sel:[0,1,0] op_sel_hi:[1,1,1] neg_lo:[1,0,0] neg_hi:[1,0,0]
	ds_read_b128 v[64:67], v78 offset:14560
	ds_read_b128 v[68:71], v78 offset:15104
	ds_read_b128 v[72:75], v78 offset:15120
	ds_read_b128 v[16:19], v78 offset:15648
	ds_read_b128 v[20:23], v78 offset:15664
	ds_read_b128 v[24:27], v78 offset:16192
	ds_read_b128 v[28:31], v78 offset:16208
	s_waitcnt lgkmcnt(15)
	v_pk_fma_f32 v[212:213], v[32:33], v[208:209], v[212:213] op_sel_hi:[1,0,1] neg_lo:[1,0,0] neg_hi:[1,0,0]
	v_pk_fma_f32 v[214:215], v[40:41], v[208:209], v[214:215] op_sel_hi:[1,0,1] neg_lo:[1,0,0] neg_hi:[1,0,0]
	v_pk_fma_f32 v[212:213], v[34:35], v[208:209], v[212:213] op_sel:[0,1,0] op_sel_hi:[1,1,1] neg_lo:[1,0,0] neg_hi:[1,0,0]
	v_pk_fma_f32 v[214:215], v[42:43], v[208:209], v[214:215] op_sel:[0,1,0] op_sel_hi:[1,1,1] neg_lo:[1,0,0] neg_hi:[1,0,0]
	v_pk_fma_f32 v[212:213], v[36:37], v[210:211], v[212:213] op_sel_hi:[1,0,1] neg_lo:[1,0,0] neg_hi:[1,0,0]
	v_pk_fma_f32 v[214:215], v[44:45], v[210:211], v[214:215] op_sel_hi:[1,0,1] neg_lo:[1,0,0] neg_hi:[1,0,0]
	v_pk_fma_f32 v[212:213], v[38:39], v[210:211], v[212:213] op_sel:[0,1,0] op_sel_hi:[1,1,1] neg_lo:[1,0,0] neg_hi:[1,0,0]
	v_pk_fma_f32 v[214:215], v[46:47], v[210:211], v[214:215] op_sel:[0,1,0] op_sel_hi:[1,1,1] neg_lo:[1,0,0] neg_hi:[1,0,0]
	ds_read_b128 v[32:35], v78 offset:16736
	ds_read_b128 v[36:39], v78 offset:16752
	ds_read_b128 v[40:43], v78 offset:17280
	ds_read_b128 v[44:47], v78 offset:17296
	s_waitcnt lgkmcnt(15)
	v_pk_fma_f32 v[216:217], v[48:49], v[208:209], v[216:217] op_sel_hi:[1,0,1] neg_lo:[1,0,0] neg_hi:[1,0,0]
	v_pk_fma_f32 v[218:219], v[56:57], v[208:209], v[218:219] op_sel_hi:[1,0,1] neg_lo:[1,0,0] neg_hi:[1,0,0]
	s_waitcnt lgkmcnt(10)
	v_pk_fma_f32 v[212:213], v[64:65], v[212:213], v[212:213] op_sel_hi:[1,0,1] neg_lo:[1,0,0] neg_hi:[1,0,0]
	v_pk_fma_f32 v[216:217], v[50:51], v[208:209], v[216:217] op_sel:[0,1,0] op_sel_hi:[1,1,1] neg_lo:[1,0,0] neg_hi:[1,0,0]
	v_pk_fma_f32 v[218:219], v[58:59], v[208:209], v[218:219] op_sel:[0,1,0] op_sel_hi:[1,1,1] neg_lo:[1,0,0] neg_hi:[1,0,0]
	s_waitcnt lgkmcnt(9)
	v_pk_fma_f32 v[214:215], v[68:69], v[212:213], v[214:215] op_sel_hi:[1,0,1] neg_lo:[1,0,0] neg_hi:[1,0,0]
	v_pk_fma_f32 v[216:217], v[52:53], v[210:211], v[216:217] op_sel_hi:[1,0,1] neg_lo:[1,0,0] neg_hi:[1,0,0]
	v_pk_fma_f32 v[218:219], v[60:61], v[210:211], v[218:219] op_sel_hi:[1,0,1] neg_lo:[1,0,0] neg_hi:[1,0,0]
	v_pk_fma_f32 v[214:215], v[70:71], v[212:213], v[214:215] op_sel:[0,1,0] op_sel_hi:[1,1,1] neg_lo:[1,0,0] neg_hi:[1,0,0]
	v_pk_fma_f32 v[216:217], v[54:55], v[210:211], v[216:217] op_sel:[0,1,0] op_sel_hi:[1,1,1] neg_lo:[1,0,0] neg_hi:[1,0,0]
	v_pk_fma_f32 v[218:219], v[62:63], v[210:211], v[218:219] op_sel:[0,1,0] op_sel_hi:[1,1,1] neg_lo:[1,0,0] neg_hi:[1,0,0]
	s_waitcnt lgkmcnt(8)
	v_pk_fma_f32 v[214:215], v[72:73], v[214:215], v[214:215] op_sel_hi:[1,0,1] neg_lo:[1,0,0] neg_hi:[1,0,0]
	ds_read_b128 v[48:51], v78 offset:16768
	ds_read_b128 v[52:55], v78 offset:16784
	ds_read_b128 v[56:59], v78 offset:17312
	ds_read_b128 v[60:63], v78 offset:17328
	s_waitcnt lgkmcnt(15)
	v_pk_fma_f32 v[220:221], v[0:1], v[208:209], v[220:221] op_sel_hi:[1,0,1] neg_lo:[1,0,0] neg_hi:[1,0,0]
	v_pk_fma_f32 v[222:223], v[8:9], v[208:209], v[222:223] op_sel_hi:[1,0,1] neg_lo:[1,0,0] neg_hi:[1,0,0]
	v_pk_fma_f32 v[220:221], v[2:3], v[208:209], v[220:221] op_sel:[0,1,0] op_sel_hi:[1,1,1] neg_lo:[1,0,0] neg_hi:[1,0,0]
	v_pk_fma_f32 v[222:223], v[10:11], v[208:209], v[222:223] op_sel:[0,1,0] op_sel_hi:[1,1,1] neg_lo:[1,0,0] neg_hi:[1,0,0]
	v_pk_fma_f32 v[220:221], v[4:5], v[210:211], v[220:221] op_sel_hi:[1,0,1] neg_lo:[1,0,0] neg_hi:[1,0,0]
	v_pk_fma_f32 v[222:223], v[12:13], v[210:211], v[222:223] op_sel_hi:[1,0,1] neg_lo:[1,0,0] neg_hi:[1,0,0]
	v_pk_fma_f32 v[220:221], v[6:7], v[210:211], v[220:221] op_sel:[0,1,0] op_sel_hi:[1,1,1] neg_lo:[1,0,0] neg_hi:[1,0,0]
	v_pk_fma_f32 v[222:223], v[14:15], v[210:211], v[222:223] op_sel:[0,1,0] op_sel_hi:[1,1,1] neg_lo:[1,0,0] neg_hi:[1,0,0]
	ds_read_b128 v[64:67], v78 offset:15680
	ds_read_b128 v[68:71], v78 offset:16224
	ds_read_b128 v[72:75], v78 offset:16240
	s_waitcnt lgkmcnt(11)
	v_pk_fma_f32 v[216:217], v[16:17], v[212:213], v[216:217] op_sel_hi:[1,0,1] neg_lo:[1,0,0] neg_hi:[1,0,0]
	v_pk_fma_f32 v[218:219], v[24:25], v[212:213], v[218:219] op_sel_hi:[1,0,1] neg_lo:[1,0,0] neg_hi:[1,0,0]
	v_pk_fma_f32 v[216:217], v[18:19], v[212:213], v[216:217] op_sel:[0,1,0] op_sel_hi:[1,1,1] neg_lo:[1,0,0] neg_hi:[1,0,0]
	v_pk_fma_f32 v[218:219], v[26:27], v[212:213], v[218:219] op_sel:[0,1,0] op_sel_hi:[1,1,1] neg_lo:[1,0,0] neg_hi:[1,0,0]
	v_pk_fma_f32 v[216:217], v[20:21], v[214:215], v[216:217] op_sel_hi:[1,0,1] neg_lo:[1,0,0] neg_hi:[1,0,0]
	v_pk_fma_f32 v[218:219], v[28:29], v[214:215], v[218:219] op_sel_hi:[1,0,1] neg_lo:[1,0,0] neg_hi:[1,0,0]
	v_pk_fma_f32 v[216:217], v[22:23], v[214:215], v[216:217] op_sel:[0,1,0] op_sel_hi:[1,1,1] neg_lo:[1,0,0] neg_hi:[1,0,0]
	v_pk_fma_f32 v[218:219], v[30:31], v[214:215], v[218:219] op_sel:[0,1,0] op_sel_hi:[1,1,1] neg_lo:[1,0,0] neg_hi:[1,0,0]
	s_waitcnt lgkmcnt(7)
	v_pk_fma_f32 v[220:221], v[32:33], v[212:213], v[220:221] op_sel_hi:[1,0,1] neg_lo:[1,0,0] neg_hi:[1,0,0]
	v_pk_fma_f32 v[222:223], v[40:41], v[212:213], v[222:223] op_sel_hi:[1,0,1] neg_lo:[1,0,0] neg_hi:[1,0,0]
	s_waitcnt lgkmcnt(2)
	v_pk_fma_f32 v[216:217], v[64:65], v[216:217], v[216:217] op_sel_hi:[1,0,1] neg_lo:[1,0,0] neg_hi:[1,0,0]
	v_pk_fma_f32 v[220:221], v[34:35], v[212:213], v[220:221] op_sel:[0,1,0] op_sel_hi:[1,1,1] neg_lo:[1,0,0] neg_hi:[1,0,0]
	v_pk_fma_f32 v[222:223], v[42:43], v[212:213], v[222:223] op_sel:[0,1,0] op_sel_hi:[1,1,1] neg_lo:[1,0,0] neg_hi:[1,0,0]
	s_waitcnt lgkmcnt(1)
	v_pk_fma_f32 v[218:219], v[68:69], v[216:217], v[218:219] op_sel_hi:[1,0,1] neg_lo:[1,0,0] neg_hi:[1,0,0]
	v_pk_fma_f32 v[220:221], v[36:37], v[214:215], v[220:221] op_sel_hi:[1,0,1] neg_lo:[1,0,0] neg_hi:[1,0,0]
	v_pk_fma_f32 v[222:223], v[44:45], v[214:215], v[222:223] op_sel_hi:[1,0,1] neg_lo:[1,0,0] neg_hi:[1,0,0]
	v_pk_fma_f32 v[218:219], v[70:71], v[216:217], v[218:219] op_sel:[0,1,0] op_sel_hi:[1,1,1] neg_lo:[1,0,0] neg_hi:[1,0,0]
	v_pk_fma_f32 v[220:221], v[38:39], v[214:215], v[220:221] op_sel:[0,1,0] op_sel_hi:[1,1,1] neg_lo:[1,0,0] neg_hi:[1,0,0]
	v_pk_fma_f32 v[222:223], v[46:47], v[214:215], v[222:223] op_sel:[0,1,0] op_sel_hi:[1,1,1] neg_lo:[1,0,0] neg_hi:[1,0,0]
	s_waitcnt lgkmcnt(0)
	v_pk_fma_f32 v[218:219], v[72:73], v[218:219], v[218:219] op_sel_hi:[1,0,1] neg_lo:[1,0,0] neg_hi:[1,0,0]
	ds_read_b128 v[64:67], v78 offset:16800
	ds_read_b128 v[68:71], v78 offset:17344
	ds_read_b128 v[72:75], v78 offset:17360
	s_waitcnt lgkmcnt(6)
	v_pk_fma_f32 v[220:221], v[48:49], v[216:217], v[220:221] op_sel_hi:[1,0,1] neg_lo:[1,0,0] neg_hi:[1,0,0]
	v_pk_fma_f32 v[222:223], v[56:57], v[216:217], v[222:223] op_sel_hi:[1,0,1] neg_lo:[1,0,0] neg_hi:[1,0,0]
	v_pk_fma_f32 v[220:221], v[50:51], v[216:217], v[220:221] op_sel:[0,1,0] op_sel_hi:[1,1,1] neg_lo:[1,0,0] neg_hi:[1,0,0]
	v_pk_fma_f32 v[222:223], v[58:59], v[216:217], v[222:223] op_sel:[0,1,0] op_sel_hi:[1,1,1] neg_lo:[1,0,0] neg_hi:[1,0,0]
	v_pk_fma_f32 v[220:221], v[52:53], v[218:219], v[220:221] op_sel_hi:[1,0,1] neg_lo:[1,0,0] neg_hi:[1,0,0]
	v_pk_fma_f32 v[222:223], v[60:61], v[218:219], v[222:223] op_sel_hi:[1,0,1] neg_lo:[1,0,0] neg_hi:[1,0,0]
	v_pk_fma_f32 v[220:221], v[54:55], v[218:219], v[220:221] op_sel:[0,1,0] op_sel_hi:[1,1,1] neg_lo:[1,0,0] neg_hi:[1,0,0]
	v_pk_fma_f32 v[222:223], v[62:63], v[218:219], v[222:223] op_sel:[0,1,0] op_sel_hi:[1,1,1] neg_lo:[1,0,0] neg_hi:[1,0,0]
	s_waitcnt lgkmcnt(2)
	v_pk_fma_f32 v[220:221], v[64:65], v[220:221], v[220:221] op_sel_hi:[1,0,1] neg_lo:[1,0,0] neg_hi:[1,0,0]
	s_waitcnt lgkmcnt(1)
	v_pk_fma_f32 v[222:223], v[68:69], v[220:221], v[222:223] op_sel_hi:[1,0,1] neg_lo:[1,0,0] neg_hi:[1,0,0]
	v_pk_fma_f32 v[222:223], v[70:71], v[220:221], v[222:223] op_sel:[0,1,0] op_sel_hi:[1,1,1] neg_lo:[1,0,0] neg_hi:[1,0,0]
	s_waitcnt lgkmcnt(0)
	v_pk_fma_f32 v[222:223], v[72:73], v[222:223], v[222:223] op_sel_hi:[1,0,1] neg_lo:[1,0,0] neg_hi:[1,0,0]
	s_lshl_b32 s22, s6, 14
	v_cvt_pk_bf16_f32 v0, v160, v161
	v_cvt_pk_bf16_f32 v1, v162, v163
	v_cvt_pk_bf16_f32 v2, v164, v165
	v_cvt_pk_bf16_f32 v3, v166, v167
	v_cvt_pk_bf16_f32 v4, v168, v169
	v_cvt_pk_bf16_f32 v5, v170, v171
	v_cvt_pk_bf16_f32 v6, v172, v173
	v_cvt_pk_bf16_f32 v7, v174, v175
	v_cvt_pk_bf16_f32 v8, v176, v177
	v_cvt_pk_bf16_f32 v9, v178, v179
	v_cvt_pk_bf16_f32 v10, v180, v181
	v_cvt_pk_bf16_f32 v11, v182, v183
	v_cvt_pk_bf16_f32 v12, v184, v185
	v_cvt_pk_bf16_f32 v13, v186, v187
	v_cvt_pk_bf16_f32 v14, v188, v189
	v_cvt_pk_bf16_f32 v15, v190, v191
	v_cvt_pk_bf16_f32 v16, v192, v193
	v_cvt_pk_bf16_f32 v17, v194, v195
	v_cvt_pk_bf16_f32 v18, v196, v197
	v_cvt_pk_bf16_f32 v19, v198, v199
	v_cvt_pk_bf16_f32 v20, v200, v201
	v_cvt_pk_bf16_f32 v21, v202, v203
	v_cvt_pk_bf16_f32 v22, v204, v205
	v_cvt_pk_bf16_f32 v23, v206, v207
	v_cvt_pk_bf16_f32 v24, v208, v209
	v_cvt_pk_bf16_f32 v25, v210, v211
	v_cvt_pk_bf16_f32 v26, v212, v213
	v_cvt_pk_bf16_f32 v27, v214, v215
	v_cvt_pk_bf16_f32 v28, v216, v217
	v_cvt_pk_bf16_f32 v29, v218, v219
	v_cvt_pk_bf16_f32 v30, v220, v221
	v_cvt_pk_bf16_f32 v31, v222, v223
	s_cmpk_lt_u32 s7, 0x80
	s_cbranch_scc0 .Lgsolve_w_out
	v_readlane_b32 s10, v245, 10
	v_readlane_b32 s11, v245, 11
	s_add_u32 s10, s10, s22
	s_addc_u32 s11, s11, 0
	v_lshlrev_b32_e32 v76, 7, v100
	v_mov_b32_e32 v77, 0
	v_lshl_add_u64 v[76:77], s[10:11], 0, v[76:77]
	global_store_dwordx4 v[76:77], v[0:3], off
	global_store_dwordx4 v[76:77], v[4:7], off offset:16
	global_store_dwordx4 v[76:77], v[8:11], off offset:32
	global_store_dwordx4 v[76:77], v[12:15], off offset:48
	global_store_dwordx4 v[76:77], v[16:19], off offset:64
	global_store_dwordx4 v[76:77], v[20:23], off offset:80
	global_store_dwordx4 v[76:77], v[24:27], off offset:96
	global_store_dwordx4 v[76:77], v[28:31], off offset:112
	s_branch .LBB0_392
.Lgsolve_w_out:
	v_readlane_b32 s10, v245, 12
	v_readlane_b32 s11, v245, 13
	s_add_u32 s10, s10, s22
	s_addc_u32 s11, s11, 0
	v_lshlrev_b32_e32 v64, 1, v100
	v_add_u32_e32 v64, 0xffffff00, v64
	v_mov_b32_e32 v65, 0
	v_lshl_add_u64 v[64:65], s[10:11], 0, v[64:65]
	s_mov_b64 s[24:25], 0x1000
	v_lshl_add_u64 v[66:67], v[64:65], 0, s[24:25]
	v_lshl_add_u64 v[68:69], v[66:67], 0, s[24:25]
	v_lshl_add_u64 v[70:71], v[68:69], 0, s[24:25]
	global_store_short v[64:65], v0, off
	global_store_short_d16_hi v[64:65], v0, off offset:256
	global_store_short v[64:65], v1, off offset:512
	global_store_short_d16_hi v[64:65], v1, off offset:768
	global_store_short v[64:65], v2, off offset:1024
	global_store_short_d16_hi v[64:65], v2, off offset:1280
	global_store_short v[64:65], v3, off offset:1536
	global_store_short_d16_hi v[64:65], v3, off offset:1792
	global_store_short v[64:65], v4, off offset:2048
	global_store_short_d16_hi v[64:65], v4, off offset:2304
	global_store_short v[64:65], v5, off offset:2560
	global_store_short_d16_hi v[64:65], v5, off offset:2816
	global_store_short v[64:65], v6, off offset:3072
	global_store_short_d16_hi v[64:65], v6, off offset:3328
	global_store_short v[64:65], v7, off offset:3584
	global_store_short_d16_hi v[64:65], v7, off offset:3840
	global_store_short v[66:67], v8, off
	global_store_short_d16_hi v[66:67], v8, off offset:256
	global_store_short v[66:67], v9, off offset:512
	global_store_short_d16_hi v[66:67], v9, off offset:768
	global_store_short v[66:67], v10, off offset:1024
	global_store_short_d16_hi v[66:67], v10, off offset:1280
	global_store_short v[66:67], v11, off offset:1536
	global_store_short_d16_hi v[66:67], v11, off offset:1792
	global_store_short v[66:67], v12, off offset:2048
	global_store_short_d16_hi v[66:67], v12, off offset:2304
	global_store_short v[66:67], v13, off offset:2560
	global_store_short_d16_hi v[66:67], v13, off offset:2816
	global_store_short v[66:67], v14, off offset:3072
	global_store_short_d16_hi v[66:67], v14, off offset:3328
	global_store_short v[66:67], v15, off offset:3584
	global_store_short_d16_hi v[66:67], v15, off offset:3840
	global_store_short v[68:69], v16, off
	global_store_short_d16_hi v[68:69], v16, off offset:256
	global_store_short v[68:69], v17, off offset:512
	global_store_short_d16_hi v[68:69], v17, off offset:768
	global_store_short v[68:69], v18, off offset:1024
	global_store_short_d16_hi v[68:69], v18, off offset:1280
	global_store_short v[68:69], v19, off offset:1536
	global_store_short_d16_hi v[68:69], v19, off offset:1792
	global_store_short v[68:69], v20, off offset:2048
	global_store_short_d16_hi v[68:69], v20, off offset:2304
	global_store_short v[68:69], v21, off offset:2560
	global_store_short_d16_hi v[68:69], v21, off offset:2816
	global_store_short v[68:69], v22, off offset:3072
	global_store_short_d16_hi v[68:69], v22, off offset:3328
	global_store_short v[68:69], v23, off offset:3584
	global_store_short_d16_hi v[68:69], v23, off offset:3840
	global_store_short v[70:71], v24, off
	global_store_short_d16_hi v[70:71], v24, off offset:256
	global_store_short v[70:71], v25, off offset:512
	global_store_short_d16_hi v[70:71], v25, off offset:768
	global_store_short v[70:71], v26, off offset:1024
	global_store_short_d16_hi v[70:71], v26, off offset:1280
	global_store_short v[70:71], v27, off offset:1536
	global_store_short_d16_hi v[70:71], v27, off offset:1792
	global_store_short v[70:71], v28, off offset:2048
	global_store_short_d16_hi v[70:71], v28, off offset:2304
	global_store_short v[70:71], v29, off offset:2560
	global_store_short_d16_hi v[70:71], v29, off offset:2816
	global_store_short v[70:71], v30, off offset:3072
	global_store_short_d16_hi v[70:71], v30, off offset:3328
	global_store_short v[70:71], v31, off offset:3584
	global_store_short_d16_hi v[70:71], v31, off offset:3840
	s_branch .LBB0_392

.LBB0_648:
	s_add_i32 s6, s55, 0x400
	s_cmpk_gt_i32 s6, 0xff
	s_mov_b64 s[4:5], -1
	s_cbranch_scc0 .LBB0_701
	s_cmpk_gt_u32 s6, 0x1ff
	s_cbranch_scc0 .LBB0_658
	s_cmpk_gt_u32 s6, 0x3ff
	s_cbranch_scc0 .LBB0_652
	v_mov_b32_e32 v79, v156
	s_lshr_b32 s7, s55, 6
	s_and_b32 s4, s43, 0x180
	s_lshl_b32 s48, s7, 8
	s_lshl_b32 s4, s4, 1
	v_lshlrev_b32_e32 v0, 3, v79
	s_add_u32 s8, s3, s4
	v_and_b32_e32 v40, 0x78, v0
	s_addc_u32 s9, s10, 0
	v_lshlrev_b32_e32 v64, 1, v40
	v_ashrrev_i32_e32 v48, 4, v79
	v_lshl_add_u64 v[56:57], s[8:9], 0, v[64:65]
	s_add_u32 s8, s11, s4
	v_ashrrev_i32_e32 v49, 31, v48
	s_addc_u32 s9, s27, 0
	v_lshl_add_u64 v[0:1], v[48:49], 0, s[48:49]
	v_lshl_add_u64 v[58:59], s[8:9], 0, v[64:65]
	v_lshlrev_b64 v[0:1], 10, v[0:1]
	v_lshl_add_u64 v[2:3], v[56:57], 0, v[0:1]
	v_lshl_add_u64 v[4:5], v[58:59], 0, v[0:1]
	global_load_dwordx4 v[0:3], v[2:3], off
	s_nop 0
	global_load_dwordx4 v[4:7], v[4:5], off
	v_add_u32_e32 v8, 0x200, v79
	v_add_u32_e32 v16, 0x400, v79
	s_waitcnt vmcnt(9)
	v_add_u32_e32 v24, 0x600, v79
	v_add_u32_e32 v32, 0x800, v79
	v_add_u32_e32 v42, 0xa00, v79
	v_add_u32_e32 v43, 0xc00, v79
	v_ashrrev_i32_e32 v60, 4, v8
	v_ashrrev_i32_e32 v62, 4, v16
	v_ashrrev_i32_e32 v68, 4, v24
	v_ashrrev_i32_e32 v80, 4, v32
	v_ashrrev_i32_e32 v82, 4, v42
	v_ashrrev_i32_e32 v84, 4, v43
	v_ashrrev_i32_e32 v61, 31, v60
	v_ashrrev_i32_e32 v63, 31, v62
	v_ashrrev_i32_e32 v69, 31, v68
	v_mov_b32_e32 v41, s68
	v_ashrrev_i32_e32 v81, 31, v80
	v_ashrrev_i32_e32 v83, 31, v82
	v_ashrrev_i32_e32 v85, 31, v84
	v_lshl_add_u64 v[8:9], v[60:61], 0, s[48:49]
	v_lshl_add_u64 v[16:17], v[62:63], 0, s[48:49]
	s_waitcnt vmcnt(8)
	v_lshl_add_u64 v[24:25], v[68:69], 0, s[48:49]
	v_lshl_add_u64 v[32:33], v[80:81], 0, s[48:49]
	v_mad_u32_u24 v61, v40, s69, v41
	v_add_u32_e32 v61, v61, v40
	v_add_u32_e32 v64, 0, v64
	v_lshl_add_u64 v[40:41], v[82:83], 0, s[48:49]
	v_lshl_add_u64 v[50:51], v[84:85], 0, s[48:49]
	v_lshlrev_b64 v[12:13], 10, v[8:9]
	v_lshlrev_b64 v[20:21], 10, v[16:17]
	s_waitcnt vmcnt(4)
	v_lshlrev_b64 v[28:29], 10, v[24:25]
	v_lshlrev_b64 v[36:37], 10, v[32:33]
	v_lshlrev_b64 v[44:45], 10, v[40:41]
	v_lshl_add_u32 v63, v48, 1, v61
	v_mad_u64_u32 v[86:87], s[8:9], v48, s70, v[64:65]
	v_lshlrev_b64 v[48:49], 10, v[50:51]
	v_lshl_add_u64 v[8:9], v[56:57], 0, v[12:13]
	v_lshl_add_u64 v[12:13], v[58:59], 0, v[12:13]
	v_lshl_add_u64 v[16:17], v[56:57], 0, v[20:21]
	v_lshl_add_u64 v[20:21], v[58:59], 0, v[20:21]
	v_lshl_add_u64 v[24:25], v[56:57], 0, v[28:29]
	v_lshl_add_u64 v[28:29], v[58:59], 0, v[28:29]
	v_lshl_add_u64 v[32:33], v[56:57], 0, v[36:37]
	v_lshl_add_u64 v[36:37], v[58:59], 0, v[36:37]
	v_lshl_add_u64 v[40:41], v[56:57], 0, v[44:45]
	v_lshl_add_u64 v[44:45], v[58:59], 0, v[44:45]
	v_lshl_add_u64 v[50:51], v[56:57], 0, v[48:49]
	v_lshl_add_u64 v[52:53], v[58:59], 0, v[48:49]
	global_load_dwordx4 v[8:11], v[8:9], off
	s_lshl_b32 s7, s7, 11
	global_load_dwordx4 v[12:15], v[12:13], off
	v_and_b32_e32 v67, 15, v79
	global_load_dwordx4 v[16:19], v[16:17], off
	s_mov_b32 s5, s49
	global_load_dwordx4 v[20:23], v[20:21], off
	s_nop 0
	global_load_dwordx4 v[24:27], v[24:25], off
	s_nop 0
	global_load_dwordx4 v[28:31], v[28:29], off
	s_nop 0
	global_load_dwordx4 v[32:35], v[32:33], off
	s_nop 0
	global_load_dwordx4 v[36:39], v[36:37], off
	s_nop 0
	global_load_dwordx4 v[40:43], v[40:41], off
	s_nop 0
	global_load_dwordx4 v[44:47], v[44:45], off
	s_nop 0
	global_load_dwordx4 v[48:51], v[50:51], off
	s_nop 0
	global_load_dwordx4 v[52:55], v[52:53], off
	s_waitcnt vmcnt(13)
	ds_write_b128 v86, v[0:3]
	s_waitcnt vmcnt(12)
	ds_write_b16 v63, v4
	ds_write_b16_d16_hi v63, v4 offset:528
	ds_write_b16 v63, v5 offset:1056
	ds_write_b16_d16_hi v63, v5 offset:1584
	ds_write_b16 v63, v6 offset:2112
	v_add_u32_e32 v0, 0xe00, v79
	v_ashrrev_i32_e32 v4, 4, v0
	v_ashrrev_i32_e32 v5, 31, v4
	v_lshl_add_u64 v[0:1], v[4:5], 0, s[48:49]
	v_lshlrev_b64 v[86:87], 10, v[0:1]
	v_lshl_add_u64 v[0:1], v[56:57], 0, v[86:87]
	global_load_dwordx4 v[0:3], v[0:1], off
	v_lshl_add_u64 v[56:57], v[58:59], 0, v[86:87]
	global_load_dwordx4 v[56:59], v[56:57], off
	ds_write_b16_d16_hi v63, v6 offset:2640
	ds_write_b16 v63, v7 offset:3168
	ds_write_b16_d16_hi v63, v7 offset:3696
	v_mad_u64_u32 v[6:7], s[8:9], v60, s70, v[64:65]
	v_lshl_add_u32 v5, v60, 1, v61
	s_waitcnt vmcnt(13)
	ds_write_b128 v6, v[8:11]
	v_mad_u64_u32 v[6:7], s[8:9], v62, s70, v[64:65]
	s_waitcnt vmcnt(12)
	ds_write_b16 v5, v12
	ds_write_b16_d16_hi v5, v12 offset:528
	ds_write_b16 v5, v13 offset:1056
	ds_write_b16_d16_hi v5, v13 offset:1584
	ds_write_b16 v5, v14 offset:2112
	ds_write_b16_d16_hi v5, v14 offset:2640
	ds_write_b16 v5, v15 offset:3168
	ds_write_b16_d16_hi v5, v15 offset:3696
	s_waitcnt vmcnt(11)
	ds_write_b128 v6, v[16:19]
	v_lshl_add_u32 v5, v62, 1, v61
	v_mad_u64_u32 v[6:7], s[8:9], v68, s70, v[64:65]
	s_waitcnt vmcnt(10)
	ds_write_b16 v5, v20
	ds_write_b16_d16_hi v5, v20 offset:528
	ds_write_b16 v5, v21 offset:1056
	ds_write_b16_d16_hi v5, v21 offset:1584
	ds_write_b16 v5, v22 offset:2112
	ds_write_b16_d16_hi v5, v22 offset:2640
	ds_write_b16 v5, v23 offset:3168
	ds_write_b16_d16_hi v5, v23 offset:3696
	s_waitcnt vmcnt(9)
	ds_write_b128 v6, v[24:27]
	v_lshl_add_u32 v5, v68, 1, v61
	v_mad_u64_u32 v[6:7], s[8:9], v80, s70, v[64:65]
	s_waitcnt vmcnt(8)
	ds_write_b16 v5, v28
	ds_write_b16_d16_hi v5, v28 offset:528
	ds_write_b16 v5, v29 offset:1056
	ds_write_b16_d16_hi v5, v29 offset:1584
	ds_write_b16 v5, v30 offset:2112
	ds_write_b16_d16_hi v5, v30 offset:2640
	ds_write_b16 v5, v31 offset:3168
	ds_write_b16_d16_hi v5, v31 offset:3696
	s_waitcnt vmcnt(7)
	ds_write_b128 v6, v[32:35]
	v_lshl_add_u32 v5, v80, 1, v61
	v_mad_u64_u32 v[6:7], s[8:9], v82, s70, v[64:65]
	s_waitcnt vmcnt(6)
	ds_write_b16 v5, v36
	ds_write_b16_d16_hi v5, v36 offset:528
	ds_write_b16 v5, v37 offset:1056
	ds_write_b16_d16_hi v5, v37 offset:1584
	ds_write_b16 v5, v38 offset:2112
	ds_write_b16_d16_hi v5, v38 offset:2640
	ds_write_b16 v5, v39 offset:3168
	ds_write_b16_d16_hi v5, v39 offset:3696
	s_waitcnt vmcnt(5)
	ds_write_b128 v6, v[40:43]
	v_lshl_add_u32 v5, v82, 1, v61
	v_mad_u64_u32 v[6:7], s[8:9], v84, s70, v[64:65]
	s_waitcnt vmcnt(4)
	ds_write_b16 v5, v44
	ds_write_b16_d16_hi v5, v44 offset:528
	ds_write_b16 v5, v45 offset:1056
	ds_write_b16_d16_hi v5, v45 offset:1584
	ds_write_b16 v5, v46 offset:2112
	ds_write_b16_d16_hi v5, v46 offset:2640
	ds_write_b16 v5, v47 offset:3168
	ds_write_b16_d16_hi v5, v47 offset:3696
	s_waitcnt vmcnt(3)
	ds_write_b128 v6, v[48:51]
	v_lshl_add_u32 v5, v84, 1, v61
	v_mad_u64_u32 v[6:7], s[8:9], v4, s70, v[64:65]
	s_waitcnt vmcnt(2)
	ds_write_b16 v5, v52
	ds_write_b16_d16_hi v5, v52 offset:528
	ds_write_b16 v5, v53 offset:1056
	ds_write_b16_d16_hi v5, v53 offset:1584
	ds_write_b16 v5, v54 offset:2112
	ds_write_b16_d16_hi v5, v54 offset:2640
	ds_write_b16 v5, v55 offset:3168
	ds_write_b16_d16_hi v5, v55 offset:3696
	s_and_b32 s8, s33, 0x780
	s_or_b32 s48, s7, s8
	v_bfe_u32 v16, v79, 4, 2
	v_mov_b32_e32 v5, v65
	v_lshlrev_b32_e32 v64, 3, v16
	s_waitcnt vmcnt(1)
	ds_write_b128 v6, v[0:3]
	v_lshl_add_u32 v0, v4, 1, v61
	s_waitcnt vmcnt(0)
	ds_write_b16 v0, v56
	ds_write_b16_d16_hi v0, v56 offset:528
	ds_write_b16 v0, v57 offset:1056
	ds_write_b16_d16_hi v0, v57 offset:1584
	ds_write_b16 v0, v58 offset:2112
	ds_write_b16_d16_hi v0, v58 offset:2640
	ds_write_b16 v0, v59 offset:3168
	ds_write_b16_d16_hi v0, v59 offset:3696
	v_ashrrev_i32_e32 v0, 2, v79
	v_and_b32_e32 v0, -16, v0
	v_ashrrev_i32_e32 v1, 31, v0
	v_lshl_add_u64 v[0:1], v[0:1], 0, s[48:49]
	v_or_b32_e32 v0, v0, v67
	v_mov_b64_e32 v[2:3], s[30:31]
	v_mad_u64_u32 v[2:3], s[8:9], v0, s71, v[2:3]
	v_mad_i32_i24 v3, v1, s71, v3
	v_lshl_add_u64 v[0:1], v[2:3], 0, s[4:5]
	s_mov_b64 s[4:5], 0x2000
	v_lshl_add_u64 v[68:69], v[0:1], 0, s[4:5]
	v_lshlrev_b32_e32 v4, 4, v16
	v_lshl_add_u64 v[6:7], v[68:69], 0, v[4:5]
	s_waitcnt lgkmcnt(0)
	s_barrier
	global_load_dwordx4 v[0:3], v[6:7], off
	global_load_dwordx4 v[80:83], v[6:7], off offset:64
	global_load_dwordx4 v[84:87], v[6:7], off offset:128
	global_load_dwordx4 v[88:91], v[6:7], off offset:192
	v_mul_u32_u24_e32 v5, 0x110, v67
	v_add3_u32 v79, 0, v4, v5
	ds_read_b128 v[4:7], v79
	ds_read_b128 v[8:11], v79 offset:64
	ds_read_b128 v[12:15], v79 offset:128
	s_waitcnt vmcnt(3) lgkmcnt(2)
	v_mfma_f32_16x16x32_bf16 v[4:7], v[4:7], v[0:3], 0
	s_waitcnt vmcnt(2) lgkmcnt(1)
	v_mfma_f32_16x16x32_bf16 v[4:7], v[8:11], v[80:83], v[4:7]
	ds_read_b128 v[8:11], v79 offset:192
	s_waitcnt vmcnt(1) lgkmcnt(1)
	v_mfma_f32_16x16x32_bf16 v[4:7], v[12:15], v[84:87], v[4:7]
	s_waitcnt vmcnt(0) lgkmcnt(0)
	v_mfma_f32_16x16x32_bf16 v[60:63], v[8:11], v[88:91], v[4:7]
	s_nop 5
	ds_read_b128 v[4:7], v79 offset:4352
	ds_read_b128 v[8:11], v79 offset:4416
	ds_read_b128 v[12:15], v79 offset:4480
	s_waitcnt lgkmcnt(2)
	v_mfma_f32_16x16x32_bf16 v[4:7], v[4:7], v[0:3], 0
	s_waitcnt lgkmcnt(1)
	v_mfma_f32_16x16x32_bf16 v[4:7], v[8:11], v[80:83], v[4:7]
	ds_read_b128 v[8:11], v79 offset:4544
	s_waitcnt lgkmcnt(1)
	v_mfma_f32_16x16x32_bf16 v[4:7], v[12:15], v[84:87], v[4:7]
	s_waitcnt lgkmcnt(0)
	v_mfma_f32_16x16x32_bf16 v[56:59], v[8:11], v[88:91], v[4:7]
	s_nop 5
	ds_read_b128 v[4:7], v79 offset:8704
	ds_read_b128 v[8:11], v79 offset:8768
	ds_read_b128 v[12:15], v79 offset:8832
	s_waitcnt lgkmcnt(2)
	v_mfma_f32_16x16x32_bf16 v[4:7], v[4:7], v[0:3], 0
	s_waitcnt lgkmcnt(1)
	v_mfma_f32_16x16x32_bf16 v[4:7], v[8:11], v[80:83], v[4:7]
	ds_read_b128 v[8:11], v79 offset:8896
	s_waitcnt lgkmcnt(1)
	v_mfma_f32_16x16x32_bf16 v[4:7], v[12:15], v[84:87], v[4:7]
	s_waitcnt lgkmcnt(0)
	v_mfma_f32_16x16x32_bf16 v[52:55], v[8:11], v[88:91], v[4:7]
	s_nop 5
	ds_read_b128 v[4:7], v79 offset:13056
	ds_read_b128 v[8:11], v79 offset:13120
	ds_read_b128 v[12:15], v79 offset:13184
	s_waitcnt lgkmcnt(2)
	v_mfma_f32_16x16x32_bf16 v[4:7], v[4:7], v[0:3], 0
	s_waitcnt lgkmcnt(1)
	v_mfma_f32_16x16x32_bf16 v[4:7], v[8:11], v[80:83], v[4:7]
	ds_read_b128 v[8:11], v79 offset:13248
	s_waitcnt lgkmcnt(1)
	v_mfma_f32_16x16x32_bf16 v[4:7], v[12:15], v[84:87], v[4:7]
	s_waitcnt lgkmcnt(0)
	v_mfma_f32_16x16x32_bf16 v[48:51], v[8:11], v[88:91], v[4:7]
	s_nop 5
	ds_read_b128 v[4:7], v79 offset:17408
	ds_read_b128 v[8:11], v79 offset:17472
	ds_read_b128 v[12:15], v79 offset:17536
	s_waitcnt lgkmcnt(2)
	v_mfma_f32_16x16x32_bf16 v[4:7], v[4:7], v[0:3], 0
	s_waitcnt lgkmcnt(1)
	v_mfma_f32_16x16x32_bf16 v[4:7], v[8:11], v[80:83], v[4:7]
	ds_read_b128 v[8:11], v79 offset:17600
	s_waitcnt lgkmcnt(1)
	v_mfma_f32_16x16x32_bf16 v[4:7], v[12:15], v[84:87], v[4:7]
	s_waitcnt lgkmcnt(0)
	v_mfma_f32_16x16x32_bf16 v[44:47], v[8:11], v[88:91], v[4:7]
	s_nop 5
	ds_read_b128 v[4:7], v79 offset:21760
	ds_read_b128 v[8:11], v79 offset:21824
	ds_read_b128 v[12:15], v79 offset:21888
	s_waitcnt lgkmcnt(2)
	v_mfma_f32_16x16x32_bf16 v[4:7], v[4:7], v[0:3], 0
	s_waitcnt lgkmcnt(1)
	v_mfma_f32_16x16x32_bf16 v[4:7], v[8:11], v[80:83], v[4:7]
	ds_read_b128 v[8:11], v79 offset:21952
	s_waitcnt lgkmcnt(1)
	v_mfma_f32_16x16x32_bf16 v[4:7], v[12:15], v[84:87], v[4:7]
	s_waitcnt lgkmcnt(0)
	v_mfma_f32_16x16x32_bf16 v[40:43], v[8:11], v[88:91], v[4:7]
	s_nop 5
	ds_read_b128 v[4:7], v79 offset:26112
	ds_read_b128 v[8:11], v79 offset:26176
	ds_read_b128 v[12:15], v79 offset:26240
	s_waitcnt lgkmcnt(2)
	v_mfma_f32_16x16x32_bf16 v[4:7], v[4:7], v[0:3], 0
	s_waitcnt lgkmcnt(1)
	v_mfma_f32_16x16x32_bf16 v[4:7], v[8:11], v[80:83], v[4:7]
	ds_read_b128 v[8:11], v79 offset:26304
	s_waitcnt lgkmcnt(1)
	v_mfma_f32_16x16x32_bf16 v[4:7], v[12:15], v[84:87], v[4:7]
	s_waitcnt lgkmcnt(0)
	v_mfma_f32_16x16x32_bf16 v[36:39], v[8:11], v[88:91], v[4:7]
	s_nop 5
	ds_read_b128 v[4:7], v79 offset:30464
	ds_read_b128 v[8:11], v79 offset:30528
	ds_read_b128 v[12:15], v79 offset:30592
	s_waitcnt lgkmcnt(2)
	v_mfma_f32_16x16x32_bf16 v[4:7], v[4:7], v[0:3], 0
	s_waitcnt lgkmcnt(1)
	v_mfma_f32_16x16x32_bf16 v[4:7], v[8:11], v[80:83], v[4:7]
	ds_read_b128 v[8:11], v79 offset:30656
	s_waitcnt lgkmcnt(1)
	v_mfma_f32_16x16x32_bf16 v[4:7], v[12:15], v[84:87], v[4:7]
	s_waitcnt lgkmcnt(0)
	v_mfma_f32_16x16x32_bf16 v[32:35], v[8:11], v[88:91], v[4:7]
	s_nop 5
	ds_read_b128 v[4:7], v79 offset:34816
	ds_read_b128 v[8:11], v79 offset:34880
	ds_read_b128 v[12:15], v79 offset:34944
	s_waitcnt lgkmcnt(2)
	v_mfma_f32_16x16x32_bf16 v[4:7], v[4:7], v[0:3], 0
	s_waitcnt lgkmcnt(1)
	v_mfma_f32_16x16x32_bf16 v[4:7], v[8:11], v[80:83], v[4:7]
	ds_read_b128 v[8:11], v79 offset:35008
	s_waitcnt lgkmcnt(1)
	v_mfma_f32_16x16x32_bf16 v[4:7], v[12:15], v[84:87], v[4:7]
	s_waitcnt lgkmcnt(0)
	v_mfma_f32_16x16x32_bf16 v[28:31], v[8:11], v[88:91], v[4:7]
	s_nop 5
	ds_read_b128 v[4:7], v79 offset:39168
	ds_read_b128 v[8:11], v79 offset:39232
	ds_read_b128 v[12:15], v79 offset:39296
	s_waitcnt lgkmcnt(2)
	v_mfma_f32_16x16x32_bf16 v[4:7], v[4:7], v[0:3], 0
	s_waitcnt lgkmcnt(1)
	v_mfma_f32_16x16x32_bf16 v[4:7], v[8:11], v[80:83], v[4:7]
	ds_read_b128 v[8:11], v79 offset:39360
	s_waitcnt lgkmcnt(1)
	v_mfma_f32_16x16x32_bf16 v[4:7], v[12:15], v[84:87], v[4:7]
	s_waitcnt lgkmcnt(0)
	v_mfma_f32_16x16x32_bf16 v[24:27], v[8:11], v[88:91], v[4:7]
	s_nop 5
	ds_read_b128 v[4:7], v79 offset:43520
	ds_read_b128 v[8:11], v79 offset:43584
	ds_read_b128 v[12:15], v79 offset:43648
	s_waitcnt lgkmcnt(2)
	v_mfma_f32_16x16x32_bf16 v[4:7], v[4:7], v[0:3], 0
	s_waitcnt lgkmcnt(1)
	v_mfma_f32_16x16x32_bf16 v[4:7], v[8:11], v[80:83], v[4:7]
	ds_read_b128 v[8:11], v79 offset:43712
	s_waitcnt lgkmcnt(1)
	v_mfma_f32_16x16x32_bf16 v[4:7], v[12:15], v[84:87], v[4:7]
	s_waitcnt lgkmcnt(0)
	v_mfma_f32_16x16x32_bf16 v[20:23], v[8:11], v[88:91], v[4:7]
	s_nop 5
	ds_read_b128 v[4:7], v79 offset:47872
	ds_read_b128 v[8:11], v79 offset:47936
	ds_read_b128 v[12:15], v79 offset:48000
	s_waitcnt lgkmcnt(2)
	v_mfma_f32_16x16x32_bf16 v[4:7], v[4:7], v[0:3], 0
	s_waitcnt lgkmcnt(1)
	v_mfma_f32_16x16x32_bf16 v[4:7], v[8:11], v[80:83], v[4:7]
	ds_read_b128 v[8:11], v79 offset:48064
	s_waitcnt lgkmcnt(1)
	v_mfma_f32_16x16x32_bf16 v[4:7], v[12:15], v[84:87], v[4:7]
	s_waitcnt lgkmcnt(0)
	v_mfma_f32_16x16x32_bf16 v[16:19], v[8:11], v[88:91], v[4:7]
	s_nop 5
	ds_read_b128 v[4:7], v79 offset:52224
	ds_read_b128 v[8:11], v79 offset:52288
	ds_read_b128 v[12:15], v79 offset:52352
	s_waitcnt lgkmcnt(2)
	v_mfma_f32_16x16x32_bf16 v[4:7], v[4:7], v[0:3], 0
	s_waitcnt lgkmcnt(1)
	v_mfma_f32_16x16x32_bf16 v[4:7], v[8:11], v[80:83], v[4:7]
	ds_read_b128 v[8:11], v79 offset:52416
	s_waitcnt lgkmcnt(1)
	v_mfma_f32_16x16x32_bf16 v[4:7], v[12:15], v[84:87], v[4:7]
	s_waitcnt lgkmcnt(0)
	v_mfma_f32_16x16x32_bf16 v[12:15], v[8:11], v[88:91], v[4:7]
	s_nop 5
	ds_read_b128 v[4:7], v79 offset:56576
	ds_read_b128 v[8:11], v79 offset:56640
	ds_read_b128 v[92:95], v79 offset:56704
	s_waitcnt lgkmcnt(2)
	v_mfma_f32_16x16x32_bf16 v[4:7], v[4:7], v[0:3], 0
	s_waitcnt lgkmcnt(1)
	v_mfma_f32_16x16x32_bf16 v[4:7], v[8:11], v[80:83], v[4:7]
	ds_read_b128 v[8:11], v79 offset:56768
	s_waitcnt lgkmcnt(1)
	v_mfma_f32_16x16x32_bf16 v[4:7], v[92:95], v[84:87], v[4:7]
	s_waitcnt lgkmcnt(0)
	v_mfma_f32_16x16x32_bf16 v[8:11], v[8:11], v[88:91], v[4:7]
	s_nop 5
	ds_read_b128 v[4:7], v79 offset:60928
	ds_read_b128 v[92:95], v79 offset:60992
	ds_read_b128 v[96:99], v79 offset:61056
	s_waitcnt lgkmcnt(2)
	v_mfma_f32_16x16x32_bf16 v[4:7], v[4:7], v[0:3], 0
	s_waitcnt lgkmcnt(1)
	v_mfma_f32_16x16x32_bf16 v[4:7], v[92:95], v[80:83], v[4:7]
	ds_read_b128 v[92:95], v79 offset:61120
	s_waitcnt lgkmcnt(1)
	v_mfma_f32_16x16x32_bf16 v[4:7], v[96:99], v[84:87], v[4:7]
	s_waitcnt lgkmcnt(0)
	v_mfma_f32_16x16x32_bf16 v[4:7], v[92:95], v[88:91], v[4:7]
	ds_read_b128 v[92:95], v79 offset:65280
	ds_read_b128 v[96:99], v79 offset:65344
	s_waitcnt lgkmcnt(1)
	v_mfma_f32_16x16x32_bf16 v[0:3], v[92:95], v[0:3], 0
	ds_read_b128 v[92:95], v79 offset:65408
	s_waitcnt lgkmcnt(1)
	v_mfma_f32_16x16x32_bf16 v[0:3], v[96:99], v[80:83], v[0:3]
	ds_read_b128 v[80:83], v79 offset:65472
	s_waitcnt lgkmcnt(1)
	v_mfma_f32_16x16x32_bf16 v[0:3], v[92:95], v[84:87], v[0:3]
	s_waitcnt lgkmcnt(0)
	v_mfma_f32_16x16x32_bf16 v[0:3], v[80:83], v[88:91], v[0:3]
	v_max_f32_e32 v79, v63, v63
	v_max_f32_e32 v80, v62, v62
	v_max_f32_e32 v79, v80, v79
	v_max_f32_e32 v80, v59, v59
	v_max_f32_e32 v81, v58, v58
	v_max_f32_e32 v80, v81, v80
	v_max3_f32 v79, v60, v61, v79
	v_max3_f32 v80, v56, v57, v80
	s_mov_b32 s4, 0xf149f2ca
	v_max3_f32 v79, v79, s4, v80
	v_max_f32_e32 v80, v55, v55
	v_max_f32_e32 v81, v54, v54
	v_max_f32_e32 v80, v81, v80
	v_max_f32_e32 v81, v51, v51
	v_max_f32_e32 v82, v50, v50
	v_max_f32_e32 v81, v82, v81
	v_max3_f32 v80, v52, v53, v80
	v_max3_f32 v81, v48, v49, v81
	v_max3_f32 v79, v79, v80, v81
	v_max_f32_e32 v80, v47, v47
	v_max_f32_e32 v81, v46, v46
	v_max_f32_e32 v80, v81, v80
	v_max_f32_e32 v81, v43, v43
	v_max_f32_e32 v82, v42, v42
	v_max_f32_e32 v81, v82, v81
	v_max3_f32 v80, v44, v45, v80
	v_max3_f32 v81, v40, v41, v81
	v_max3_f32 v79, v79, v80, v81
	v_max_f32_e32 v80, v39, v39
	v_max_f32_e32 v81, v38, v38
	v_max_f32_e32 v80, v81, v80
	v_max_f32_e32 v81, v35, v35
	v_max_f32_e32 v82, v34, v34
	v_max_f32_e32 v81, v82, v81
	v_max3_f32 v80, v36, v37, v80
	v_max3_f32 v81, v32, v33, v81
	v_max3_f32 v79, v79, v80, v81
	v_max_f32_e32 v80, v31, v31
	v_max_f32_e32 v81, v30, v30
	v_max_f32_e32 v80, v81, v80
	v_max_f32_e32 v81, v27, v27
	v_max_f32_e32 v82, v26, v26
	v_max_f32_e32 v81, v82, v81
	v_max3_f32 v80, v28, v29, v80
	v_max3_f32 v81, v24, v25, v81
	v_max3_f32 v79, v79, v80, v81
	v_max_f32_e32 v80, v23, v23
	v_max_f32_e32 v81, v22, v22
	v_max_f32_e32 v80, v81, v80
	v_max_f32_e32 v81, v19, v19
	v_max_f32_e32 v82, v18, v18
	v_max_f32_e32 v81, v82, v81
	v_max3_f32 v80, v20, v21, v80
	v_max3_f32 v81, v16, v17, v81
	v_max3_f32 v79, v79, v80, v81
	v_max_f32_e32 v80, v15, v15
	v_max_f32_e32 v81, v14, v14
	v_max_f32_e32 v80, v81, v80
	v_max_f32_e32 v81, v11, v11
	v_max_f32_e32 v82, v10, v10
	v_max_f32_e32 v81, v82, v81
	v_max3_f32 v80, v12, v13, v80
	v_max3_f32 v81, v8, v9, v81
	v_max3_f32 v79, v79, v80, v81
	v_max_f32_e32 v80, v7, v7
	v_max_f32_e32 v81, v6, v6
	v_max_f32_e32 v80, v81, v80
	v_max_f32_e32 v81, v3, v3
	v_max_f32_e32 v82, v2, v2
	v_max_f32_e32 v81, v82, v81
	v_max3_f32 v80, v4, v5, v80
	v_max3_f32 v81, v0, v1, v81
	v_cmp_lt_i32_e32 vcc, v72, v73
	v_max3_f32 v79, v79, v80, v81
	s_nop 0
	v_cndmask_b32_e32 v80, v71, v72, vcc
	v_lshlrev_b32_e32 v104, 2, v80
	ds_bpermute_b32 v80, v104, v79
	v_cmp_lt_i32_e32 vcc, v74, v73
	s_waitcnt lgkmcnt(0)
	v_max_f32_e32 v80, v80, v80
	v_max_f32_e32 v79, v79, v80
	v_cndmask_b32_e32 v80, v71, v74, vcc
	v_lshlrev_b32_e32 v105, 2, v80
	ds_bpermute_b32 v80, v105, v79
	s_waitcnt lgkmcnt(0)
	v_max_f32_e32 v80, v80, v80
	v_max_f32_e32 v79, v79, v80
	v_sub_f32_e32 v60, v60, v79
	v_mul_f32_e32 v60, 0x3db504f3, v60
	v_sub_f32_e32 v61, v61, v79
	v_mul_f32_e32 v60, 0x3fb8aa3b, v60
	v_mul_f32_e32 v61, 0x3db504f3, v61
	v_sub_f32_e32 v62, v62, v79
	v_exp_f32_e32 v60, v60
	v_mul_f32_e32 v61, 0x3fb8aa3b, v61
	v_mul_f32_e32 v62, 0x3db504f3, v62
	v_sub_f32_e32 v63, v63, v79
	v_exp_f32_e32 v61, v61
	v_mul_f32_e32 v62, 0x3fb8aa3b, v62
	v_mul_f32_e32 v63, 0x3db504f3, v63
	v_sub_f32_e32 v56, v56, v79
	v_exp_f32_e32 v62, v62
	v_mul_f32_e32 v63, 0x3fb8aa3b, v63
	v_mul_f32_e32 v56, 0x3db504f3, v56
	v_sub_f32_e32 v57, v57, v79
	v_sub_f32_e32 v53, v53, v79
	v_exp_f32_e32 v63, v63
	v_mul_f32_e32 v56, 0x3fb8aa3b, v56
	v_mul_f32_e32 v57, 0x3db504f3, v57
	v_sub_f32_e32 v58, v58, v79
	v_mul_f32_e32 v53, 0x3db504f3, v53
	v_add_f32_e32 v80, 0, v60
	v_exp_f32_e32 v56, v56
	v_mul_f32_e32 v57, 0x3fb8aa3b, v57
	v_mul_f32_e32 v58, 0x3db504f3, v58
	v_sub_f32_e32 v59, v59, v79
	v_mul_f32_e32 v53, 0x3fb8aa3b, v53
	v_add_f32_e32 v80, v61, v80
	v_exp_f32_e32 v57, v57
	v_mul_f32_e32 v58, 0x3fb8aa3b, v58
	v_mul_f32_e32 v59, 0x3db504f3, v59
	v_sub_f32_e32 v52, v52, v79
	v_exp_f32_e32 v107, v53
	v_sub_f32_e32 v53, v54, v79
	v_add_f32_e32 v80, v62, v80
	v_exp_f32_e32 v58, v58
	v_mul_f32_e32 v59, 0x3fb8aa3b, v59
	v_mul_f32_e32 v52, 0x3db504f3, v52
	v_mul_f32_e32 v53, 0x3db504f3, v53
	v_sub_f32_e32 v49, v49, v79
	v_add_f32_e32 v80, v63, v80
	v_exp_f32_e32 v59, v59
	v_mul_f32_e32 v52, 0x3fb8aa3b, v52
	v_mul_f32_e32 v53, 0x3fb8aa3b, v53
	v_mul_f32_e32 v49, 0x3db504f3, v49
	v_add_f32_e32 v80, v56, v80
	v_exp_f32_e32 v106, v52
	v_exp_f32_e32 v108, v53
	v_sub_f32_e32 v53, v55, v79
	v_mul_f32_e32 v49, 0x3fb8aa3b, v49
	v_add_f32_e32 v52, v57, v80
	v_mul_f32_e32 v53, 0x3db504f3, v53
	v_sub_f32_e32 v48, v48, v79
	v_exp_f32_e32 v111, v49
	v_sub_f32_e32 v49, v50, v79
	v_add_f32_e32 v52, v58, v52
	v_mul_f32_e32 v53, 0x3fb8aa3b, v53
	v_mul_f32_e32 v48, 0x3db504f3, v48
	v_mul_f32_e32 v49, 0x3db504f3, v49
	v_sub_f32_e32 v45, v45, v79
	v_add_f32_e32 v52, v59, v52
	v_exp_f32_e32 v109, v53
	v_mul_f32_e32 v48, 0x3fb8aa3b, v48
	v_mul_f32_e32 v49, 0x3fb8aa3b, v49
	v_mul_f32_e32 v45, 0x3db504f3, v45
	v_add_f32_e32 v52, v106, v52
	v_exp_f32_e32 v110, v48
	v_exp_f32_e32 v112, v49
	v_sub_f32_e32 v49, v51, v79
	v_mul_f32_e32 v45, 0x3fb8aa3b, v45
	v_add_f32_e32 v48, v107, v52
	v_mul_f32_e32 v49, 0x3db504f3, v49
	v_sub_f32_e32 v44, v44, v79
	v_exp_f32_e32 v51, v45
	v_sub_f32_e32 v45, v46, v79
	v_add_f32_e32 v48, v108, v48
	v_mul_f32_e32 v49, 0x3fb8aa3b, v49
	v_mul_f32_e32 v44, 0x3db504f3, v44
	v_mul_f32_e32 v45, 0x3db504f3, v45
	v_sub_f32_e32 v41, v41, v79
	v_add_f32_e32 v48, v109, v48
	v_exp_f32_e32 v113, v49
	v_mul_f32_e32 v44, 0x3fb8aa3b, v44
	v_mul_f32_e32 v45, 0x3fb8aa3b, v45
	v_mul_f32_e32 v41, 0x3db504f3, v41
	v_add_f32_e32 v48, v110, v48
	v_exp_f32_e32 v49, v44
	v_exp_f32_e32 v50, v45
	v_sub_f32_e32 v45, v47, v79
	v_mul_f32_e32 v41, 0x3fb8aa3b, v41
	v_add_f32_e32 v44, v111, v48
	v_mul_f32_e32 v45, 0x3db504f3, v45
	v_sub_f32_e32 v40, v40, v79
	v_exp_f32_e32 v116, v41
	v_sub_f32_e32 v41, v42, v79
	v_add_f32_e32 v44, v112, v44
	v_mul_f32_e32 v45, 0x3fb8aa3b, v45
	v_mul_f32_e32 v40, 0x3db504f3, v40
	v_mul_f32_e32 v41, 0x3db504f3, v41
	v_sub_f32_e32 v37, v37, v79
	v_add_f32_e32 v44, v113, v44
	v_exp_f32_e32 v114, v45
	v_mul_f32_e32 v40, 0x3fb8aa3b, v40
	v_mul_f32_e32 v41, 0x3fb8aa3b, v41
	v_mul_f32_e32 v37, 0x3db504f3, v37
	v_add_f32_e32 v44, v49, v44
	v_exp_f32_e32 v115, v40
	v_exp_f32_e32 v117, v41
	v_sub_f32_e32 v41, v43, v79
	v_mul_f32_e32 v37, 0x3fb8aa3b, v37
	v_add_f32_e32 v40, v51, v44
	v_mul_f32_e32 v41, 0x3db504f3, v41
	v_sub_f32_e32 v36, v36, v79
	v_exp_f32_e32 v43, v37
	v_sub_f32_e32 v37, v38, v79
	v_add_f32_e32 v40, v50, v40
	v_mul_f32_e32 v41, 0x3fb8aa3b, v41
	v_mul_f32_e32 v36, 0x3db504f3, v36
	v_mul_f32_e32 v37, 0x3db504f3, v37
	v_sub_f32_e32 v33, v33, v79
	v_add_f32_e32 v40, v114, v40
	v_exp_f32_e32 v118, v41
	v_mul_f32_e32 v36, 0x3fb8aa3b, v36
	v_mul_f32_e32 v37, 0x3fb8aa3b, v37
	v_mul_f32_e32 v33, 0x3db504f3, v33
	v_add_f32_e32 v40, v115, v40
	v_exp_f32_e32 v41, v36
	v_exp_f32_e32 v42, v37
	v_sub_f32_e32 v37, v39, v79
	v_mul_f32_e32 v33, 0x3fb8aa3b, v33
	v_add_f32_e32 v36, v116, v40
	v_mul_f32_e32 v37, 0x3db504f3, v37
	v_sub_f32_e32 v32, v32, v79
	v_exp_f32_e32 v47, v33
	v_sub_f32_e32 v33, v34, v79
	v_add_f32_e32 v36, v117, v36
	v_mul_f32_e32 v37, 0x3fb8aa3b, v37
	v_mul_f32_e32 v32, 0x3db504f3, v32
	v_mul_f32_e32 v33, 0x3db504f3, v33
	v_sub_f32_e32 v29, v29, v79
	v_add_f32_e32 v36, v118, v36
	v_exp_f32_e32 v45, v37
	v_mul_f32_e32 v32, 0x3fb8aa3b, v32
	v_mul_f32_e32 v33, 0x3fb8aa3b, v33
	v_mul_f32_e32 v29, 0x3db504f3, v29
	v_add_f32_e32 v36, v41, v36
	v_exp_f32_e32 v44, v32
	v_exp_f32_e32 v46, v33
	v_sub_f32_e32 v33, v35, v79
	v_mul_f32_e32 v29, 0x3fb8aa3b, v29
	v_add_f32_e32 v32, v43, v36
	v_mul_f32_e32 v33, 0x3db504f3, v33
	v_sub_f32_e32 v28, v28, v79
	v_exp_f32_e32 v35, v29
	v_sub_f32_e32 v29, v30, v79
	v_add_f32_e32 v32, v42, v32
	v_mul_f32_e32 v33, 0x3fb8aa3b, v33
	v_mul_f32_e32 v28, 0x3db504f3, v28
	v_mul_f32_e32 v29, 0x3db504f3, v29
	v_add_f32_e32 v32, v45, v32
	v_exp_f32_e32 v48, v33
	v_mul_f32_e32 v28, 0x3fb8aa3b, v28
	v_mul_f32_e32 v29, 0x3fb8aa3b, v29
	v_add_f32_e32 v32, v44, v32
	v_exp_f32_e32 v33, v28
	v_exp_f32_e32 v34, v29
	v_sub_f32_e32 v29, v31, v79
	v_add_f32_e32 v28, v47, v32
	v_mul_f32_e32 v29, 0x3db504f3, v29
	v_sub_f32_e32 v24, v24, v79
	v_add_f32_e32 v28, v46, v28
	v_mul_f32_e32 v29, 0x3fb8aa3b, v29
	v_mul_f32_e32 v24, 0x3db504f3, v24
	v_add_f32_e32 v28, v48, v28
	v_exp_f32_e32 v37, v29
	v_mul_f32_e32 v24, 0x3fb8aa3b, v24
	v_add_f32_e32 v28, v33, v28
	v_exp_f32_e32 v36, v24
	v_add_f32_e32 v24, v35, v28
	v_add_f32_e32 v24, v34, v24
	v_add_f32_e32 v24, v37, v24
	v_add_f32_e32 v28, v36, v24
	v_sub_f32_e32 v24, v25, v79
	v_mul_f32_e32 v24, 0x3db504f3, v24
	v_mul_f32_e32 v24, 0x3fb8aa3b, v24
	v_exp_f32_e32 v39, v24
	v_sub_f32_e32 v24, v26, v79
	v_mul_f32_e32 v24, 0x3db504f3, v24
	v_sub_f32_e32 v21, v21, v79
	v_mul_f32_e32 v24, 0x3fb8aa3b, v24
	v_mul_f32_e32 v21, 0x3db504f3, v21
	v_exp_f32_e32 v38, v24
	v_sub_f32_e32 v24, v27, v79
	v_mul_f32_e32 v21, 0x3fb8aa3b, v21
	v_mul_f32_e32 v24, 0x3db504f3, v24
	v_sub_f32_e32 v20, v20, v79
	v_exp_f32_e32 v26, v21
	v_sub_f32_e32 v21, v22, v79
	v_mul_f32_e32 v24, 0x3fb8aa3b, v24
	v_mul_f32_e32 v20, 0x3db504f3, v20
	v_mul_f32_e32 v21, 0x3db504f3, v21
	v_sub_f32_e32 v17, v17, v79
	v_exp_f32_e32 v40, v24
	v_mul_f32_e32 v20, 0x3fb8aa3b, v20
	v_mul_f32_e32 v21, 0x3fb8aa3b, v21
	v_mul_f32_e32 v17, 0x3db504f3, v17
	v_exp_f32_e32 v24, v20
	v_exp_f32_e32 v25, v21
	v_sub_f32_e32 v21, v23, v79
	v_mul_f32_e32 v17, 0x3fb8aa3b, v17
	v_add_f32_e32 v20, v39, v28
	v_mul_f32_e32 v21, 0x3db504f3, v21
	v_sub_f32_e32 v16, v16, v79
	v_exp_f32_e32 v30, v17
	v_sub_f32_e32 v17, v18, v79
	v_add_f32_e32 v20, v38, v20
	v_mul_f32_e32 v21, 0x3fb8aa3b, v21
	v_mul_f32_e32 v16, 0x3db504f3, v16
	v_mul_f32_e32 v17, 0x3db504f3, v17
	v_add_f32_e32 v20, v40, v20
	v_exp_f32_e32 v28, v21
	v_mul_f32_e32 v16, 0x3fb8aa3b, v16
	v_mul_f32_e32 v17, 0x3fb8aa3b, v17
	v_add_f32_e32 v20, v24, v20
	v_exp_f32_e32 v27, v16
	v_exp_f32_e32 v29, v17
	v_sub_f32_e32 v17, v19, v79
	v_add_f32_e32 v16, v26, v20
	v_mul_f32_e32 v17, 0x3db504f3, v17
	v_sub_f32_e32 v12, v12, v79
	v_add_f32_e32 v16, v25, v16
	v_mul_f32_e32 v17, 0x3fb8aa3b, v17
	v_mul_f32_e32 v12, 0x3db504f3, v12
	v_add_f32_e32 v16, v28, v16
	v_exp_f32_e32 v32, v17
	v_mul_f32_e32 v12, 0x3fb8aa3b, v12
	v_add_f32_e32 v16, v27, v16
	v_exp_f32_e32 v12, v12
	v_add_f32_e32 v16, v30, v16
	v_sub_f32_e32 v13, v13, v79
	v_add_f32_e32 v16, v29, v16
	v_mul_f32_e32 v13, 0x3db504f3, v13
	v_add_f32_e32 v16, v32, v16
	v_mul_f32_e32 v13, 0x3fb8aa3b, v13
	v_sub_f32_e32 v9, v9, v79
	v_add_f32_e32 v17, v12, v16
	v_exp_f32_e32 v16, v13
	v_sub_f32_e32 v13, v14, v79
	v_mul_f32_e32 v9, 0x3db504f3, v9
	v_mul_f32_e32 v13, 0x3db504f3, v13
	v_sub_f32_e32 v14, v15, v79
	v_mul_f32_e32 v9, 0x3fb8aa3b, v9
	v_mul_f32_e32 v13, 0x3fb8aa3b, v13
	v_mul_f32_e32 v14, 0x3db504f3, v14
	v_sub_f32_e32 v8, v8, v79
	v_exp_f32_e32 v21, v9
	v_sub_f32_e32 v9, v10, v79
	v_exp_f32_e32 v13, v13
	v_mul_f32_e32 v14, 0x3fb8aa3b, v14
	v_mul_f32_e32 v8, 0x3db504f3, v8
	v_mul_f32_e32 v9, 0x3db504f3, v9
	v_exp_f32_e32 v19, v14
	v_mul_f32_e32 v8, 0x3fb8aa3b, v8
	v_mul_f32_e32 v9, 0x3fb8aa3b, v9
	v_exp_f32_e32 v18, v8
	v_exp_f32_e32 v20, v9
	v_sub_f32_e32 v9, v11, v79
	v_add_f32_e32 v8, v16, v17
	v_mul_f32_e32 v9, 0x3db504f3, v9
	v_sub_f32_e32 v4, v4, v79
	v_add_f32_e32 v8, v13, v8
	v_mul_f32_e32 v9, 0x3fb8aa3b, v9
	v_mul_f32_e32 v4, 0x3db504f3, v4
	v_add_f32_e32 v8, v19, v8
	v_exp_f32_e32 v23, v9
	v_mul_f32_e32 v4, 0x3fb8aa3b, v4
	v_add_f32_e32 v8, v18, v8
	v_exp_f32_e32 v4, v4
	v_add_f32_e32 v8, v21, v8
	v_sub_f32_e32 v5, v5, v79
	v_add_f32_e32 v8, v20, v8
	v_mul_f32_e32 v5, 0x3db504f3, v5
	v_add_f32_e32 v8, v23, v8
	v_mul_f32_e32 v5, 0x3fb8aa3b, v5
	v_add_f32_e32 v9, v4, v8
	v_exp_f32_e32 v8, v5
	v_sub_f32_e32 v5, v6, v79
	v_mul_f32_e32 v5, 0x3db504f3, v5
	v_sub_f32_e32 v6, v7, v79
	v_mul_f32_e32 v5, 0x3fb8aa3b, v5
	v_mul_f32_e32 v6, 0x3db504f3, v6
	v_sub_f32_e32 v0, v0, v79
	v_exp_f32_e32 v5, v5
	v_mul_f32_e32 v6, 0x3fb8aa3b, v6
	v_mul_f32_e32 v0, 0x3db504f3, v0
	v_exp_f32_e32 v6, v6
	v_mul_f32_e32 v0, 0x3fb8aa3b, v0
	v_exp_f32_e32 v0, v0
	v_add_f32_e32 v7, v8, v9
	v_add_f32_e32 v7, v5, v7
	v_add_f32_e32 v7, v6, v7
	v_bfe_u32 v9, v57, 16, 1
	v_bfe_u32 v22, v62, 16, 1
	v_bfe_u32 v52, v58, 16, 1
	v_add_f32_e32 v15, v0, v7
	v_sub_f32_e32 v1, v1, v79
	v_bfe_u32 v7, v59, 16, 1
	v_bfe_u32 v11, v63, 16, 1
	v_add3_u32 v17, v57, v9, s73
	v_bfe_u32 v9, v60, 16, 1
	v_add3_u32 v52, v58, v52, s73
	v_add3_u32 v22, v62, v22, s73
	v_mul_f32_e32 v1, 0x3db504f3, v1
	v_sub_f32_e32 v2, v2, v79
	v_bfe_u32 v14, v61, 16, 1
	v_add3_u32 v11, v63, v11, s73
	v_add3_u32 v7, v59, v7, s73
	v_bfe_u32 v31, v56, 16, 1
	v_add3_u32 v9, v60, v9, s73
	v_lshrrev_b32_e32 v22, 16, v22
	v_lshrrev_b32_e32 v57, 16, v52
	v_mul_f32_e32 v1, 0x3fb8aa3b, v1
	v_mul_f32_e32 v2, 0x3db504f3, v2
	v_add3_u32 v14, v61, v14, s73
	v_add3_u32 v31, v56, v31, s73
	v_lshrrev_b32_e32 v56, 16, v9
	v_and_or_b32 v59, v7, s74, v57
	v_and_or_b32 v57, v11, s74, v22
	v_sub_f32_e32 v11, v3, v79
	v_exp_f32_e32 v1, v1
	v_mul_f32_e32 v10, 0x3fb8aa3b, v2
	v_lshrrev_b32_e32 v31, 16, v31
	v_and_or_b32 v56, v14, s74, v56
	v_mul_f32_e32 v14, 0x3db504f3, v11
	v_mul_u32_u24_e32 v2, 0x210, v67
	v_and_or_b32 v58, v17, s74, v31
	v_exp_f32_e32 v22, v10
	v_mul_f32_e32 v17, 0x3fb8aa3b, v14
	v_add3_u32 v9, s68, v64, v2
	v_and_b32_e32 v2, 8, v67
	v_add_u32_e32 v9, v9, v2
	v_exp_f32_e32 v31, v17
	v_add_u32_e32 v2, 0x2010, v9
	v_add_u32_e32 v7, 0x4020, v9
	v_add_u32_e32 v10, 0x6030, v9
	v_add_u32_e32 v3, 0x8040, v9
	v_add_u32_e32 v11, 0xa050, v9
	v_add_u32_e32 v14, 0xc060, v9
	v_add_u32_e32 v67, 0xe070, v9
	ds_read2_b64 v[52:55], v9 offset1:4
	ds_read2_b64 v[60:63], v2 offset0:32 offset1:36
	ds_read2_b64 v[80:83], v7 offset0:64 offset1:68
	ds_read2_b64 v[84:87], v10 offset0:96 offset1:100
	ds_read2_b64 v[88:91], v3 offset0:128 offset1:132
	ds_read2_b64 v[92:95], v11 offset0:160 offset1:164
	ds_read2_b64 v[96:99], v14 offset0:192 offset1:196
	v_add_f32_e32 v15, v1, v15
	ds_read2_b64 v[100:103], v67 offset0:224 offset1:228
	v_add_f32_e32 v15, v22, v15
	v_add_f32_e32 v15, v31, v15
	ds_bpermute_b32 v17, v104, v15
	s_waitcnt lgkmcnt(8)
	v_mfma_f32_16x16x32_bf16 v[52:55], v[52:55], v[56:59], 0
	s_waitcnt lgkmcnt(0)
	v_add_f32_e32 v15, v15, v17
	v_mfma_f32_16x16x32_bf16 v[60:63], v[60:63], v[56:59], 0
	ds_bpermute_b32 v17, v105, v15
	v_mfma_f32_16x16x32_bf16 v[80:83], v[80:83], v[56:59], 0
	v_mfma_f32_16x16x32_bf16 v[84:87], v[84:87], v[56:59], 0
	v_mfma_f32_16x16x32_bf16 v[88:91], v[88:91], v[56:59], 0
	v_mfma_f32_16x16x32_bf16 v[92:95], v[92:95], v[56:59], 0
	v_mfma_f32_16x16x32_bf16 v[96:99], v[96:99], v[56:59], 0
	v_mfma_f32_16x16x32_bf16 v[56:59], v[100:103], v[56:59], 0
	v_bfe_u32 v100, v111, 16, 1
	v_bfe_u32 v101, v109, 16, 1
	v_bfe_u32 v102, v107, 16, 1
	v_add3_u32 v104, v107, v102, s73
	v_add3_u32 v105, v109, v101, s73
	v_add3_u32 v109, v111, v100, s73
	v_bfe_u32 v100, v106, 16, 1
	v_bfe_u32 v101, v108, 16, 1
	v_bfe_u32 v102, v110, 16, 1
	v_bfe_u32 v103, v112, 16, 1
	v_add3_u32 v107, v112, v103, s73
	v_add3_u32 v110, v110, v102, s73
	v_add3_u32 v108, v108, v101, s73
	v_add3_u32 v106, v106, v100, s73
	ds_read2_b64 v[100:103], v9 offset0:8 offset1:12
	v_bfe_u32 v79, v113, 16, 1
	v_add3_u32 v79, v113, v79, s73
	v_lshrrev_b32_e32 v111, 16, v106
	v_lshrrev_b32_e32 v108, 16, v108
	v_lshrrev_b32_e32 v106, 16, v110
	v_lshrrev_b32_e32 v107, 16, v107
	v_and_or_b32 v107, v79, s74, v107
	v_and_or_b32 v106, v109, s74, v106
	v_and_or_b32 v105, v105, s74, v108
	v_and_or_b32 v104, v104, s74, v111
	s_waitcnt lgkmcnt(0)
	s_nop 0
	v_mfma_f32_16x16x32_bf16 v[52:55], v[100:103], v[104:107], v[52:55]
	ds_read2_b64 v[100:103], v2 offset0:40 offset1:44
	s_waitcnt lgkmcnt(0)
	v_mfma_f32_16x16x32_bf16 v[60:63], v[100:103], v[104:107], v[60:63]
	ds_read2_b64 v[100:103], v7 offset0:72 offset1:76
	s_waitcnt lgkmcnt(0)
	v_mfma_f32_16x16x32_bf16 v[80:83], v[100:103], v[104:107], v[80:83]
	ds_read2_b64 v[100:103], v10 offset0:104 offset1:108
	s_waitcnt lgkmcnt(0)
	v_mfma_f32_16x16x32_bf16 v[84:87], v[100:103], v[104:107], v[84:87]
	ds_read2_b64 v[100:103], v3 offset0:136 offset1:140
	s_waitcnt lgkmcnt(0)
	v_mfma_f32_16x16x32_bf16 v[88:91], v[100:103], v[104:107], v[88:91]
	ds_read2_b64 v[100:103], v11 offset0:168 offset1:172
	s_waitcnt lgkmcnt(0)
	v_mfma_f32_16x16x32_bf16 v[92:95], v[100:103], v[104:107], v[92:95]
	ds_read2_b64 v[100:103], v14 offset0:200 offset1:204
	s_waitcnt lgkmcnt(0)
	v_mfma_f32_16x16x32_bf16 v[96:99], v[100:103], v[104:107], v[96:99]
	ds_read2_b64 v[100:103], v67 offset0:232 offset1:236
	s_waitcnt lgkmcnt(0)
	v_mfma_f32_16x16x32_bf16 v[56:59], v[100:103], v[104:107], v[56:59]
	v_bfe_u32 v100, v116, 16, 1
	v_bfe_u32 v101, v114, 16, 1
	v_bfe_u32 v102, v51, 16, 1
	v_add3_u32 v51, v51, v102, s73
	v_add3_u32 v104, v114, v101, s73
	v_add3_u32 v105, v116, v100, s73
	v_bfe_u32 v100, v49, 16, 1
	v_bfe_u32 v101, v50, 16, 1
	v_bfe_u32 v102, v115, 16, 1
	v_bfe_u32 v103, v117, 16, 1
	v_add3_u32 v106, v117, v103, s73
	v_add3_u32 v107, v115, v102, s73
	v_add3_u32 v50, v50, v101, s73
	v_add3_u32 v49, v49, v100, s73
	ds_read2_b64 v[100:103], v9 offset0:16 offset1:20
	v_bfe_u32 v79, v118, 16, 1
	v_add3_u32 v79, v118, v79, s73
	v_lshrrev_b32_e32 v49, 16, v49
	v_lshrrev_b32_e32 v50, 16, v50
	v_lshrrev_b32_e32 v108, 16, v107
	v_lshrrev_b32_e32 v106, 16, v106
	v_and_or_b32 v107, v79, s74, v106
	v_and_or_b32 v106, v105, s74, v108
	v_and_or_b32 v105, v104, s74, v50
	v_and_or_b32 v104, v51, s74, v49
	s_waitcnt lgkmcnt(0)
	s_nop 0
	v_mfma_f32_16x16x32_bf16 v[50:53], v[100:103], v[104:107], v[52:55]
	ds_read2_b64 v[100:103], v2 offset0:48 offset1:52
	s_waitcnt lgkmcnt(0)
	v_mfma_f32_16x16x32_bf16 v[60:63], v[100:103], v[104:107], v[60:63]
	ds_read2_b64 v[100:103], v7 offset0:80 offset1:84
	s_waitcnt lgkmcnt(0)
	v_mfma_f32_16x16x32_bf16 v[80:83], v[100:103], v[104:107], v[80:83]
	ds_read2_b64 v[100:103], v10 offset0:112 offset1:116
	s_waitcnt lgkmcnt(0)
	v_mfma_f32_16x16x32_bf16 v[84:87], v[100:103], v[104:107], v[84:87]
	ds_read2_b64 v[100:103], v3 offset0:144 offset1:148
	s_waitcnt lgkmcnt(0)
	v_mfma_f32_16x16x32_bf16 v[88:91], v[100:103], v[104:107], v[88:91]
	ds_read2_b64 v[100:103], v11 offset0:176 offset1:180
	s_waitcnt lgkmcnt(0)
	v_mfma_f32_16x16x32_bf16 v[92:95], v[100:103], v[104:107], v[92:95]
	ds_read2_b64 v[100:103], v14 offset0:208 offset1:212
	s_waitcnt lgkmcnt(0)
	v_mfma_f32_16x16x32_bf16 v[96:99], v[100:103], v[104:107], v[96:99]
	ds_read2_b64 v[100:103], v67 offset0:240 offset1:244
	s_waitcnt lgkmcnt(0)
	v_mfma_f32_16x16x32_bf16 v[54:57], v[100:103], v[104:107], v[56:59]
	v_bfe_u32 v49, v48, 16, 1
	s_nop 1
	v_bfe_u32 v58, v47, 16, 1
	v_bfe_u32 v59, v45, 16, 1
	v_bfe_u32 v79, v43, 16, 1
	v_add3_u32 v79, v43, v79, s73
	v_add3_u32 v59, v45, v59, s73
	v_add3_u32 v47, v47, v58, s73
	v_add3_u32 v48, v48, v49, s73
	v_bfe_u32 v43, v41, 16, 1
	v_bfe_u32 v45, v42, 16, 1
	v_bfe_u32 v49, v44, 16, 1
	v_bfe_u32 v58, v46, 16, 1
	v_add3_u32 v46, v46, v58, s73
	v_add3_u32 v49, v44, v49, s73
	v_add3_u32 v58, v42, v45, s73
	v_add3_u32 v41, v41, v43, s73
	ds_read2_b64 v[42:45], v9 offset0:24 offset1:28
	v_lshrrev_b32_e32 v41, 16, v41
	v_lshrrev_b32_e32 v58, 16, v58
	v_lshrrev_b32_e32 v100, 16, v49
	v_lshrrev_b32_e32 v46, 16, v46
	v_and_or_b32 v49, v48, s74, v46
	v_and_or_b32 v48, v47, s74, v100
	v_and_or_b32 v47, v59, s74, v58
	v_and_or_b32 v46, v79, s74, v41
	s_waitcnt lgkmcnt(0)
	s_nop 0
	v_mfma_f32_16x16x32_bf16 v[42:45], v[42:45], v[46:49], v[50:53]
	s_nop 2
	ds_read2_b64 v[50:53], v2 offset0:56 offset1:60
	s_waitcnt lgkmcnt(0)
	v_mfma_f32_16x16x32_bf16 v[50:53], v[50:53], v[46:49], v[60:63]
	s_nop 2
	ds_read2_b64 v[58:61], v7 offset0:88 offset1:92
	s_waitcnt lgkmcnt(0)
	v_mfma_f32_16x16x32_bf16 v[58:61], v[58:61], v[46:49], v[80:83]
	s_nop 2
	ds_read2_b64 v[80:83], v10 offset0:120 offset1:124
	s_waitcnt lgkmcnt(0)
	v_mfma_f32_16x16x32_bf16 v[80:83], v[80:83], v[46:49], v[84:87]
	s_nop 2
	ds_read2_b64 v[84:87], v3 offset0:152 offset1:156
	s_waitcnt lgkmcnt(0)
	v_mfma_f32_16x16x32_bf16 v[84:87], v[84:87], v[46:49], v[88:91]
	s_nop 2
	ds_read2_b64 v[88:91], v11 offset0:184 offset1:188
	s_waitcnt lgkmcnt(0)
	v_mfma_f32_16x16x32_bf16 v[88:91], v[88:91], v[46:49], v[92:95]
	s_nop 2
	ds_read2_b64 v[92:95], v14 offset0:216 offset1:220
	s_waitcnt lgkmcnt(0)
	v_mfma_f32_16x16x32_bf16 v[92:95], v[92:95], v[46:49], v[96:99]
	s_nop 2
	ds_read2_b64 v[96:99], v67 offset0:248 offset1:252
	s_waitcnt lgkmcnt(0)
	v_mfma_f32_16x16x32_bf16 v[46:49], v[96:99], v[46:49], v[54:57]
	v_bfe_u32 v41, v40, 16, 1
	s_nop 1
	v_bfe_u32 v54, v39, 16, 1
	v_bfe_u32 v55, v37, 16, 1
	v_bfe_u32 v56, v35, 16, 1
	v_add3_u32 v56, v35, v56, s73
	v_add3_u32 v55, v37, v55, s73
	v_add3_u32 v39, v39, v54, s73
	v_add3_u32 v40, v40, v41, s73
	v_bfe_u32 v35, v33, 16, 1
	v_bfe_u32 v37, v34, 16, 1
	v_bfe_u32 v41, v36, 16, 1
	v_bfe_u32 v54, v38, 16, 1
	v_add3_u32 v38, v38, v54, s73
	v_add3_u32 v41, v36, v41, s73
	v_add3_u32 v54, v34, v37, s73
	v_add3_u32 v33, v33, v35, s73
	ds_read2_b64 v[34:37], v9 offset0:32 offset1:36
	v_lshrrev_b32_e32 v33, 16, v33
	v_lshrrev_b32_e32 v54, 16, v54
	v_lshrrev_b32_e32 v57, 16, v41
	v_lshrrev_b32_e32 v38, 16, v38
	v_and_or_b32 v41, v40, s74, v38
	v_and_or_b32 v40, v39, s74, v57
	v_and_or_b32 v39, v55, s74, v54
	v_and_or_b32 v38, v56, s74, v33
	ds_read2_b64 v[54:57], v10 offset0:128 offset1:132
	v_add_u32_e32 v62, 0xe870, v9
	s_waitcnt lgkmcnt(1)
	v_mfma_f32_16x16x32_bf16 v[34:37], v[34:37], v[38:41], v[42:45]
	s_nop 2
	ds_read2_b64 v[42:45], v2 offset0:64 offset1:68
	s_waitcnt lgkmcnt(0)
	v_mfma_f32_16x16x32_bf16 v[42:45], v[42:45], v[38:41], v[50:53]
	s_nop 2
	ds_read2_b64 v[50:53], v7 offset0:96 offset1:100
	s_waitcnt lgkmcnt(0)
	v_mfma_f32_16x16x32_bf16 v[50:53], v[50:53], v[38:41], v[58:61]
	s_nop 2
	ds_read2_b64 v[58:61], v3 offset0:160 offset1:164
	v_mfma_f32_16x16x32_bf16 v[54:57], v[54:57], v[38:41], v[80:83]
	s_nop 2
	ds_read2_b64 v[80:83], v11 offset0:192 offset1:196
	s_waitcnt lgkmcnt(1)
	v_mfma_f32_16x16x32_bf16 v[58:61], v[58:61], v[38:41], v[84:87]
	s_nop 2
	ds_read2_b64 v[84:87], v14 offset0:224 offset1:228
	s_waitcnt lgkmcnt(1)
	v_mfma_f32_16x16x32_bf16 v[80:83], v[80:83], v[38:41], v[88:91]
	s_nop 2
	ds_read2_b64 v[88:91], v62 offset1:4
	s_waitcnt lgkmcnt(1)
	v_mfma_f32_16x16x32_bf16 v[84:87], v[84:87], v[38:41], v[92:95]
	s_waitcnt lgkmcnt(0)
	v_mfma_f32_16x16x32_bf16 v[38:41], v[88:91], v[38:41], v[46:49]
	v_bfe_u32 v33, v32, 16, 1
	s_nop 1
	v_bfe_u32 v46, v30, 16, 1
	v_bfe_u32 v47, v28, 16, 1
	v_bfe_u32 v48, v26, 16, 1
	v_add3_u32 v63, v26, v48, s73
	v_add3_u32 v28, v28, v47, s73
	v_add3_u32 v30, v30, v46, s73
	v_add3_u32 v32, v32, v33, s73
	v_bfe_u32 v26, v24, 16, 1
	v_bfe_u32 v33, v25, 16, 1
	v_bfe_u32 v46, v27, 16, 1
	v_bfe_u32 v47, v29, 16, 1
	v_add3_u32 v29, v29, v47, s73
	v_add3_u32 v46, v27, v46, s73
	v_add3_u32 v33, v25, v33, s73
	v_add3_u32 v47, v24, v26, s73
	ds_read2_b64 v[24:27], v9 offset0:40 offset1:44
	v_lshrrev_b32_e32 v67, 16, v47
	v_lshrrev_b32_e32 v33, 16, v33
	v_lshrrev_b32_e32 v46, 16, v46
	v_lshrrev_b32_e32 v29, 16, v29
	v_and_or_b32 v49, v32, s74, v29
	v_and_or_b32 v48, v30, s74, v46
	v_and_or_b32 v47, v28, s74, v33
	v_and_or_b32 v46, v63, s74, v67
	s_waitcnt lgkmcnt(0)
	s_nop 0
	v_mfma_f32_16x16x32_bf16 v[24:27], v[24:27], v[46:49], v[34:37]
	s_nop 2
	ds_read2_b64 v[32:35], v2 offset0:72 offset1:76
	s_waitcnt lgkmcnt(0)
	v_mfma_f32_16x16x32_bf16 v[32:35], v[32:35], v[46:49], v[42:45]
	s_nop 2
	ds_read2_b64 v[42:45], v7 offset0:104 offset1:108
	s_waitcnt lgkmcnt(0)
	v_mfma_f32_16x16x32_bf16 v[42:45], v[42:45], v[46:49], v[50:53]
	s_nop 2
	ds_read2_b64 v[50:53], v10 offset0:136 offset1:140
	s_waitcnt lgkmcnt(0)
	v_mfma_f32_16x16x32_bf16 v[50:53], v[50:53], v[46:49], v[54:57]
	s_nop 2
	ds_read2_b64 v[54:57], v3 offset0:168 offset1:172
	s_waitcnt lgkmcnt(0)
	v_mfma_f32_16x16x32_bf16 v[54:57], v[54:57], v[46:49], v[58:61]
	s_nop 2
	ds_read2_b64 v[58:61], v11 offset0:200 offset1:204
	s_waitcnt lgkmcnt(0)
	v_mfma_f32_16x16x32_bf16 v[58:61], v[58:61], v[46:49], v[80:83]
	s_nop 2
	ds_read2_b64 v[80:83], v14 offset0:232 offset1:236
	s_waitcnt lgkmcnt(0)
	v_mfma_f32_16x16x32_bf16 v[80:83], v[80:83], v[46:49], v[84:87]
	s_nop 2
	ds_read2_b64 v[84:87], v62 offset0:8 offset1:12
	s_waitcnt lgkmcnt(0)
	v_mfma_f32_16x16x32_bf16 v[36:39], v[84:87], v[46:49], v[38:41]
	v_bfe_u32 v28, v23, 16, 1
	v_bfe_u32 v29, v21, 16, 1
	v_bfe_u32 v30, v19, 16, 1
	v_bfe_u32 v40, v16, 16, 1
	v_add3_u32 v16, v16, v40, s73
	v_add3_u32 v30, v19, v30, s73
	v_add3_u32 v29, v21, v29, s73
	v_add3_u32 v23, v23, v28, s73
	v_bfe_u32 v19, v12, 16, 1
	v_bfe_u32 v21, v13, 16, 1
	v_bfe_u32 v28, v18, 16, 1
	v_bfe_u32 v40, v20, 16, 1
	v_add3_u32 v40, v20, v40, s73
	v_add3_u32 v28, v18, v28, s73
	v_add3_u32 v13, v13, v21, s73
	v_add3_u32 v12, v12, v19, s73
	ds_read2_b64 v[18:21], v9 offset0:48 offset1:52
	v_lshrrev_b32_e32 v12, 16, v12
	v_lshrrev_b32_e32 v13, 16, v13
	v_lshrrev_b32_e32 v28, 16, v28
	v_lshrrev_b32_e32 v40, 16, v40
	v_and_or_b32 v49, v23, s74, v40
	v_and_or_b32 v48, v29, s74, v28
	v_and_or_b32 v47, v30, s74, v13
	v_and_or_b32 v46, v16, s74, v12
	s_waitcnt lgkmcnt(0)
	s_nop 0
	v_mfma_f32_16x16x32_bf16 v[18:21], v[18:21], v[46:49], v[24:27]
	s_nop 2
	ds_read2_b64 v[24:27], v2 offset0:80 offset1:84
	s_waitcnt lgkmcnt(0)
	v_mfma_f32_16x16x32_bf16 v[24:27], v[24:27], v[46:49], v[32:35]
	s_nop 2
	ds_read2_b64 v[32:35], v7 offset0:112 offset1:116
	s_waitcnt lgkmcnt(0)
	v_mfma_f32_16x16x32_bf16 v[32:35], v[32:35], v[46:49], v[42:45]
	s_nop 2
	ds_read2_b64 v[40:43], v10 offset0:144 offset1:148
	s_waitcnt lgkmcnt(0)
	v_mfma_f32_16x16x32_bf16 v[40:43], v[40:43], v[46:49], v[50:53]
	s_nop 2
	ds_read2_b64 v[50:53], v3 offset0:176 offset1:180
	s_waitcnt lgkmcnt(0)
	v_mfma_f32_16x16x32_bf16 v[50:53], v[50:53], v[46:49], v[54:57]
	s_nop 2
	ds_read2_b64 v[54:57], v11 offset0:208 offset1:212
	s_waitcnt lgkmcnt(0)
	v_mfma_f32_16x16x32_bf16 v[54:57], v[54:57], v[46:49], v[58:61]
	s_nop 2
	ds_read2_b64 v[58:61], v14 offset0:240 offset1:244
	s_waitcnt lgkmcnt(0)
	v_mfma_f32_16x16x32_bf16 v[58:61], v[58:61], v[46:49], v[80:83]
	s_nop 2
	ds_read2_b64 v[80:83], v62 offset0:16 offset1:20
	s_waitcnt lgkmcnt(0)
	v_mfma_f32_16x16x32_bf16 v[36:39], v[80:83], v[46:49], v[36:39]
	v_bfe_u32 v12, v31, 16, 1
	v_bfe_u32 v28, v22, 16, 1
	v_add3_u32 v12, v31, v12, s73
	v_add3_u32 v22, v22, v28, s73
	ds_read2_b64 v[28:31], v9 offset0:56 offset1:60
	v_bfe_u32 v13, v1, 16, 1
	v_bfe_u32 v16, v6, 16, 1
	v_bfe_u32 v23, v8, 16, 1
	v_add3_u32 v8, v8, v23, s73
	v_add3_u32 v6, v6, v16, s73
	v_add3_u32 v1, v1, v13, s73
	v_bfe_u32 v13, v4, 16, 1
	v_bfe_u32 v16, v5, 16, 1
	v_bfe_u32 v23, v0, 16, 1
	v_add3_u32 v0, v0, v23, s73
	v_add3_u32 v5, v5, v16, s73
	v_add3_u32 v4, v4, v13, s73
	v_lshrrev_b32_e32 v4, 16, v4
	v_lshrrev_b32_e32 v5, 16, v5
	v_lshrrev_b32_e32 v0, 16, v0
	v_lshrrev_b32_e32 v9, 16, v22
	v_and_or_b32 v47, v12, s74, v9
	v_and_or_b32 v46, v1, s74, v0
	v_and_or_b32 v45, v6, s74, v5
	v_and_or_b32 v44, v8, s74, v4
	ds_read2_b64 v[4:7], v7 offset0:120 offset1:124
	s_waitcnt lgkmcnt(1)
	v_mfma_f32_16x16x32_bf16 v[18:21], v[28:31], v[44:47], v[18:21]
	ds_read2_b64 v[28:31], v2 offset0:88 offset1:92
	ds_read2_b64 v[0:3], v3 offset0:184 offset1:188
	s_waitcnt lgkmcnt(1)
	v_mfma_f32_16x16x32_bf16 v[22:25], v[28:31], v[44:47], v[24:27]
	s_nop 2
	ds_read2_b64 v[26:29], v10 offset0:152 offset1:156
	ds_read2_b64 v[8:11], v11 offset0:216 offset1:220
	v_mfma_f32_16x16x32_bf16 v[4:7], v[4:7], v[44:47], v[32:35]
	s_waitcnt lgkmcnt(1)
	v_mfma_f32_16x16x32_bf16 v[26:29], v[26:29], v[44:47], v[40:43]
	s_nop 0
	ds_read2_b64 v[30:33], v14 offset0:248 offset1:252
	s_nop 0
	ds_read2_b64 v[40:43], v62 offset0:24 offset1:28
	v_mfma_f32_16x16x32_bf16 v[0:3], v[0:3], v[44:47], v[50:53]
	s_waitcnt lgkmcnt(2)
	v_mfma_f32_16x16x32_bf16 v[8:11], v[8:11], v[44:47], v[54:57]
	s_waitcnt lgkmcnt(1)
	v_mfma_f32_16x16x32_bf16 v[30:33], v[30:33], v[44:47], v[58:61]
	s_waitcnt lgkmcnt(0)
	v_mfma_f32_16x16x32_bf16 v[34:37], v[40:43], v[44:47], v[36:39]
	v_add_f32_e32 v12, v15, v17
	v_div_scale_f32 v13, s[4:5], v12, v12, 1.0
	v_rcp_f32_e32 v14, v13
	v_div_scale_f32 v15, vcc, 1.0, v12, 1.0
	s_mov_b64 s[4:5], 0
	v_fma_f32 v16, -v13, v14, 1.0
	v_fmac_f32_e32 v14, v16, v14
	v_mul_f32_e32 v16, v15, v14
	v_fma_f32 v17, -v13, v16, v15
	v_fmac_f32_e32 v16, v17, v14
	v_fma_f32 v13, -v13, v16, v15
	v_div_fmas_f32 v13, v13, v14, v16
	v_div_fixup_f32 v12, v13, v12, 1.0
	v_mov_b32_e32 v16, v18
	v_mov_b32_e32 v17, v20
	v_pk_mul_f32 v[16:17], v[12:13], v[16:17] op_sel_hi:[0,1]
	v_mov_b32_e32 v20, v19
	v_pk_mul_f32 v[18:19], v[12:13], v[20:21] op_sel_hi:[0,1]
	v_and_b32_sdwa v13, v17, v75 dst_sel:DWORD dst_unused:UNUSED_PAD src0_sel:WORD_1 src1_sel:DWORD
	v_and_b32_sdwa v20, v16, v75 dst_sel:DWORD dst_unused:UNUSED_PAD src0_sel:WORD_1 src1_sel:DWORD
	v_add3_u32 v16, v16, v20, s73
	v_add3_u32 v13, v17, v13, s73
	v_and_b32_sdwa v17, v19, v75 dst_sel:DWORD dst_unused:UNUSED_PAD src0_sel:WORD_1 src1_sel:DWORD
	v_and_b32_sdwa v20, v18, v75 dst_sel:DWORD dst_unused:UNUSED_PAD src0_sel:WORD_1 src1_sel:DWORD
	v_add3_u32 v17, v19, v17, s73
	v_add3_u32 v18, v18, v20, s73
	v_and_b32_e32 v17, 0xffff0000, v17
	v_and_b32_e32 v18, 0xffff0000, v18
	v_lshl_add_u64 v[14:15], v[68:69], 0, v[64:65]
	v_or_b32_sdwa v17, v17, v13 dst_sel:DWORD dst_unused:UNUSED_PAD src0_sel:DWORD src1_sel:WORD_1
	v_or_b32_sdwa v16, v18, v16 dst_sel:DWORD dst_unused:UNUSED_PAD src0_sel:DWORD src1_sel:WORD_1
	global_store_dwordx2 v[14:15], v[16:17], off
	v_mov_b32_e32 v16, v22
	v_mov_b32_e32 v17, v24
	v_pk_mul_f32 v[16:17], v[12:13], v[16:17] op_sel_hi:[0,1]
	v_mov_b32_e32 v24, v23
	v_pk_mul_f32 v[18:19], v[12:13], v[24:25] op_sel_hi:[0,1]
	v_and_b32_sdwa v13, v17, v75 dst_sel:DWORD dst_unused:UNUSED_PAD src0_sel:WORD_1 src1_sel:DWORD
	v_and_b32_sdwa v20, v16, v75 dst_sel:DWORD dst_unused:UNUSED_PAD src0_sel:WORD_1 src1_sel:DWORD
	v_add3_u32 v16, v16, v20, s73
	v_add3_u32 v13, v17, v13, s73
	v_and_b32_sdwa v17, v19, v75 dst_sel:DWORD dst_unused:UNUSED_PAD src0_sel:WORD_1 src1_sel:DWORD
	v_and_b32_sdwa v20, v18, v75 dst_sel:DWORD dst_unused:UNUSED_PAD src0_sel:WORD_1 src1_sel:DWORD
	v_add3_u32 v17, v19, v17, s73
	v_add3_u32 v18, v18, v20, s73
	v_and_b32_e32 v17, 0xffff0000, v17
	v_and_b32_e32 v18, 0xffff0000, v18
	v_or_b32_sdwa v17, v17, v13 dst_sel:DWORD dst_unused:UNUSED_PAD src0_sel:DWORD src1_sel:WORD_1
	v_or_b32_sdwa v16, v18, v16 dst_sel:DWORD dst_unused:UNUSED_PAD src0_sel:DWORD src1_sel:WORD_1
	global_store_dwordx2 v[14:15], v[16:17], off offset:32
	v_mov_b32_e32 v16, v4
	v_mov_b32_e32 v17, v6
	v_pk_mul_f32 v[16:17], v[12:13], v[16:17] op_sel_hi:[0,1]
	v_mov_b32_e32 v6, v5
	v_pk_mul_f32 v[4:5], v[12:13], v[6:7] op_sel_hi:[0,1]
	v_and_b32_sdwa v7, v16, v75 dst_sel:DWORD dst_unused:UNUSED_PAD src0_sel:WORD_1 src1_sel:DWORD
	v_add3_u32 v7, v16, v7, s73
	v_and_b32_sdwa v13, v5, v75 dst_sel:DWORD dst_unused:UNUSED_PAD src0_sel:WORD_1 src1_sel:DWORD
	v_and_b32_sdwa v16, v4, v75 dst_sel:DWORD dst_unused:UNUSED_PAD src0_sel:WORD_1 src1_sel:DWORD
	v_and_b32_sdwa v6, v17, v75 dst_sel:DWORD dst_unused:UNUSED_PAD src0_sel:WORD_1 src1_sel:DWORD
	v_add3_u32 v5, v5, v13, s73
	v_add3_u32 v4, v4, v16, s73
	v_add3_u32 v6, v17, v6, s73
	v_and_b32_e32 v5, 0xffff0000, v5
	v_and_b32_e32 v4, 0xffff0000, v4
	v_or_b32_sdwa v5, v5, v6 dst_sel:DWORD dst_unused:UNUSED_PAD src0_sel:DWORD src1_sel:WORD_1
	v_or_b32_sdwa v4, v4, v7 dst_sel:DWORD dst_unused:UNUSED_PAD src0_sel:DWORD src1_sel:WORD_1
	global_store_dwordx2 v[14:15], v[4:5], off offset:64
	v_mov_b32_e32 v4, v26
	v_mov_b32_e32 v5, v28
	v_pk_mul_f32 v[4:5], v[12:13], v[4:5] op_sel_hi:[0,1]
	v_mov_b32_e32 v28, v27
	v_pk_mul_f32 v[6:7], v[12:13], v[28:29] op_sel_hi:[0,1]
	v_and_b32_sdwa v13, v5, v75 dst_sel:DWORD dst_unused:UNUSED_PAD src0_sel:WORD_1 src1_sel:DWORD
	v_and_b32_sdwa v16, v4, v75 dst_sel:DWORD dst_unused:UNUSED_PAD src0_sel:WORD_1 src1_sel:DWORD
	v_add3_u32 v4, v4, v16, s73
	v_add3_u32 v5, v5, v13, s73
	v_and_b32_sdwa v13, v7, v75 dst_sel:DWORD dst_unused:UNUSED_PAD src0_sel:WORD_1 src1_sel:DWORD
	v_and_b32_sdwa v16, v6, v75 dst_sel:DWORD dst_unused:UNUSED_PAD src0_sel:WORD_1 src1_sel:DWORD
	v_add3_u32 v7, v7, v13, s73
	v_add3_u32 v6, v6, v16, s73
	v_and_b32_e32 v7, 0xffff0000, v7
	v_and_b32_e32 v6, 0xffff0000, v6
	v_or_b32_sdwa v5, v7, v5 dst_sel:DWORD dst_unused:UNUSED_PAD src0_sel:DWORD src1_sel:WORD_1
	v_or_b32_sdwa v4, v6, v4 dst_sel:DWORD dst_unused:UNUSED_PAD src0_sel:DWORD src1_sel:WORD_1
	global_store_dwordx2 v[14:15], v[4:5], off offset:96
	v_mov_b32_e32 v4, v0
	v_mov_b32_e32 v5, v2
	v_pk_mul_f32 v[4:5], v[12:13], v[4:5] op_sel_hi:[0,1]
	v_mov_b32_e32 v2, v1
	v_pk_mul_f32 v[0:1], v[12:13], v[2:3] op_sel_hi:[0,1]
	v_and_b32_sdwa v2, v5, v75 dst_sel:DWORD dst_unused:UNUSED_PAD src0_sel:WORD_1 src1_sel:DWORD
	v_and_b32_sdwa v3, v4, v75 dst_sel:DWORD dst_unused:UNUSED_PAD src0_sel:WORD_1 src1_sel:DWORD
	v_add3_u32 v3, v4, v3, s73
	v_add3_u32 v2, v5, v2, s73
	v_and_b32_sdwa v4, v1, v75 dst_sel:DWORD dst_unused:UNUSED_PAD src0_sel:WORD_1 src1_sel:DWORD
	v_and_b32_sdwa v5, v0, v75 dst_sel:DWORD dst_unused:UNUSED_PAD src0_sel:WORD_1 src1_sel:DWORD
	v_add3_u32 v1, v1, v4, s73
	v_add3_u32 v0, v0, v5, s73
	v_and_b32_e32 v1, 0xffff0000, v1
	v_and_b32_e32 v0, 0xffff0000, v0
	v_or_b32_sdwa v1, v1, v2 dst_sel:DWORD dst_unused:UNUSED_PAD src0_sel:DWORD src1_sel:WORD_1
	v_or_b32_sdwa v0, v0, v3 dst_sel:DWORD dst_unused:UNUSED_PAD src0_sel:DWORD src1_sel:WORD_1
	global_store_dwordx2 v[14:15], v[0:1], off offset:128
	v_mov_b32_e32 v0, v8
	v_mov_b32_e32 v1, v10
	v_pk_mul_f32 v[0:1], v[12:13], v[0:1] op_sel_hi:[0,1]
	v_mov_b32_e32 v10, v9
	v_pk_mul_f32 v[2:3], v[12:13], v[10:11] op_sel_hi:[0,1]
	v_and_b32_sdwa v4, v1, v75 dst_sel:DWORD dst_unused:UNUSED_PAD src0_sel:WORD_1 src1_sel:DWORD
	v_and_b32_sdwa v5, v0, v75 dst_sel:DWORD dst_unused:UNUSED_PAD src0_sel:WORD_1 src1_sel:DWORD
	v_add3_u32 v0, v0, v5, s73
	v_add3_u32 v1, v1, v4, s73
	v_and_b32_sdwa v4, v3, v75 dst_sel:DWORD dst_unused:UNUSED_PAD src0_sel:WORD_1 src1_sel:DWORD
	v_and_b32_sdwa v5, v2, v75 dst_sel:DWORD dst_unused:UNUSED_PAD src0_sel:WORD_1 src1_sel:DWORD
	v_add3_u32 v3, v3, v4, s73
	v_add3_u32 v2, v2, v5, s73
	v_and_b32_e32 v3, 0xffff0000, v3
	v_and_b32_e32 v2, 0xffff0000, v2
	v_or_b32_sdwa v1, v3, v1 dst_sel:DWORD dst_unused:UNUSED_PAD src0_sel:DWORD src1_sel:WORD_1
	v_or_b32_sdwa v0, v2, v0 dst_sel:DWORD dst_unused:UNUSED_PAD src0_sel:DWORD src1_sel:WORD_1
	global_store_dwordx2 v[14:15], v[0:1], off offset:160
	v_mov_b32_e32 v0, v30
	v_mov_b32_e32 v1, v32
	v_pk_mul_f32 v[0:1], v[12:13], v[0:1] op_sel_hi:[0,1]
	v_mov_b32_e32 v32, v31
	v_pk_mul_f32 v[2:3], v[12:13], v[32:33] op_sel_hi:[0,1]
	v_and_b32_sdwa v4, v1, v75 dst_sel:DWORD dst_unused:UNUSED_PAD src0_sel:WORD_1 src1_sel:DWORD
	v_and_b32_sdwa v5, v0, v75 dst_sel:DWORD dst_unused:UNUSED_PAD src0_sel:WORD_1 src1_sel:DWORD
	v_add3_u32 v0, v0, v5, s73
	v_add3_u32 v1, v1, v4, s73
	v_and_b32_sdwa v4, v3, v75 dst_sel:DWORD dst_unused:UNUSED_PAD src0_sel:WORD_1 src1_sel:DWORD
	v_and_b32_sdwa v5, v2, v75 dst_sel:DWORD dst_unused:UNUSED_PAD src0_sel:WORD_1 src1_sel:DWORD
	v_add3_u32 v3, v3, v4, s73
	v_add3_u32 v2, v2, v5, s73
	v_and_b32_e32 v3, 0xffff0000, v3
	v_and_b32_e32 v2, 0xffff0000, v2
	v_or_b32_sdwa v1, v3, v1 dst_sel:DWORD dst_unused:UNUSED_PAD src0_sel:DWORD src1_sel:WORD_1
	v_or_b32_sdwa v0, v2, v0 dst_sel:DWORD dst_unused:UNUSED_PAD src0_sel:DWORD src1_sel:WORD_1
	global_store_dwordx2 v[14:15], v[0:1], off offset:192
	v_mov_b32_e32 v0, v34
	v_mov_b32_e32 v1, v36
	v_pk_mul_f32 v[0:1], v[12:13], v[0:1] op_sel_hi:[0,1]
	v_mov_b32_e32 v36, v35
	v_pk_mul_f32 v[2:3], v[12:13], v[36:37] op_sel_hi:[0,1]
	v_and_b32_sdwa v4, v1, v75 dst_sel:DWORD dst_unused:UNUSED_PAD src0_sel:WORD_1 src1_sel:DWORD
	v_and_b32_sdwa v5, v0, v75 dst_sel:DWORD dst_unused:UNUSED_PAD src0_sel:WORD_1 src1_sel:DWORD
	v_add3_u32 v0, v0, v5, s73
	v_add3_u32 v1, v1, v4, s73
	v_and_b32_sdwa v4, v3, v75 dst_sel:DWORD dst_unused:UNUSED_PAD src0_sel:WORD_1 src1_sel:DWORD
	v_and_b32_sdwa v5, v2, v75 dst_sel:DWORD dst_unused:UNUSED_PAD src0_sel:WORD_1 src1_sel:DWORD
	v_add3_u32 v3, v3, v4, s73
	v_add3_u32 v2, v2, v5, s73
	v_and_b32_e32 v3, 0xffff0000, v3
	v_and_b32_e32 v2, 0xffff0000, v2
	v_or_b32_sdwa v1, v3, v1 dst_sel:DWORD dst_unused:UNUSED_PAD src0_sel:DWORD src1_sel:WORD_1
	v_or_b32_sdwa v0, v2, v0 dst_sel:DWORD dst_unused:UNUSED_PAD src0_sel:DWORD src1_sel:WORD_1
	global_store_dwordx2 v[14:15], v[0:1], off offset:224
	s_barrier
.LBB0_652:
	s_andn2_b64 vcc, exec, s[4:5]
	s_cbranch_vccnz .LBB0_657
	s_load_dwordx4 s[16:19], s[28:29], 0x18
	v_mov_b32_e32 v68, v156
	s_and_b32 s48, s64, 0x7f00
	v_ashrrev_i32_e32 v8, 4, v68
	s_add_i32 s4, s33, 0x10000
	v_lshlrev_b32_e32 v0, 3, v68
	v_ashrrev_i32_e32 v9, 31, v8
	s_and_b32 s7, s4, 0x180
	s_waitcnt vmcnt(1)
	v_and_b32_e32 v7, 0x78, v0
	v_lshl_add_u64 v[0:1], v[8:9], 0, s[48:49]
	v_lshlrev_b32_e32 v64, 2, v7
	v_lshlrev_b64 v[4:5], 11, v[0:1]
	s_lshl_b32 s4, s7, 2
	s_waitcnt lgkmcnt(0)
	v_lshl_add_u64 v[2:3], s[16:17], 0, v[64:65]
	v_or_b32_e32 v4, s4, v4
	v_lshl_add_u64 v[0:1], v[2:3], 0, v[4:5]
	global_load_dwordx4 v[12:15], v[0:1], off nt
	global_load_dwordx4 v[16:19], v[0:1], off offset:16 nt
	v_lshl_add_u64 v[0:1], s[18:19], 0, v[64:65]
	v_lshl_add_u64 v[4:5], v[0:1], 0, v[4:5]
	global_load_dwordx4 v[20:23], v[4:5], off nt
	global_load_dwordx4 v[24:27], v[4:5], off offset:16 nt
	v_add_u32_e32 v4, 0x200, v68
	v_ashrrev_i32_e32 v10, 4, v4
	v_ashrrev_i32_e32 v11, 31, v10
	v_lshl_add_u64 v[4:5], v[10:11], 0, s[48:49]
	v_lshlrev_b64 v[36:37], 11, v[4:5]
	v_or_b32_e32 v36, s4, v36
	v_lshl_add_u64 v[4:5], v[2:3], 0, v[36:37]
	global_load_dwordx4 v[28:31], v[4:5], off nt
	global_load_dwordx4 v[32:35], v[4:5], off offset:16 nt
	v_lshl_add_u64 v[40:41], v[0:1], 0, v[36:37]
	global_load_dwordx4 v[36:39], v[40:41], off offset:16 nt
	s_nop 0
	global_load_dwordx4 v[40:43], v[40:41], off nt
	v_add_u32_e32 v6, 0x400, v68
	v_mov_b32_e32 v9, s68
	v_ashrrev_i32_e32 v6, 4, v6
	v_lshl_add_u32 v4, v7, 1, 0
	v_mad_u32_u24 v5, v7, s69, v9
	v_add_u32_e32 v5, v5, v7
	v_ashrrev_i32_e32 v7, 31, v6
	v_mad_u64_u32 v[52:53], s[8:9], v8, s70, v[4:5]
	v_lshl_add_u32 v11, v8, 1, v5
	v_lshl_add_u64 v[8:9], v[6:7], 0, s[48:49]
	v_lshlrev_b64 v[8:9], 11, v[8:9]
	v_or_b32_e32 v8, s4, v8
	v_lshl_add_u64 v[48:49], v[2:3], 0, v[8:9]
	global_load_dwordx4 v[44:47], v[48:49], off offset:16 nt
	s_nop 0
	global_load_dwordx4 v[48:51], v[48:49], off nt
	v_lshl_add_u64 v[8:9], v[0:1], 0, v[8:9]
	v_cmp_gt_u32_e32 vcc, 64, v68
	s_waitcnt vmcnt(9)
	v_bfe_u32 v7, v12, 16, 1
	v_bfe_u32 v53, v13, 16, 1
	v_bfe_u32 v54, v14, 16, 1
	v_bfe_u32 v55, v15, 16, 1
	s_waitcnt vmcnt(8)
	v_bfe_u32 v56, v16, 16, 1
	v_bfe_u32 v57, v17, 16, 1
	v_bfe_u32 v58, v18, 16, 1
	v_bfe_u32 v59, v19, 16, 1
	v_add3_u32 v7, v12, v7, s73
	v_add3_u32 v12, v13, v53, s73
	v_add3_u32 v13, v14, v54, s73
	v_add3_u32 v14, v15, v55, s73
	v_add3_u32 v15, v16, v56, s73
	v_add3_u32 v16, v17, v57, s73
	v_add3_u32 v17, v18, v58, s73
	v_add3_u32 v18, v19, v59, s73
	v_lshrrev_b32_e32 v7, 16, v7
	v_lshrrev_b32_e32 v13, 16, v13
	v_lshrrev_b32_e32 v15, 16, v15
	v_lshrrev_b32_e32 v17, 16, v17
	s_waitcnt vmcnt(7)
	v_bfe_u32 v60, v20, 16, 1
	v_bfe_u32 v61, v21, 16, 1
	v_bfe_u32 v62, v22, 16, 1
	v_bfe_u32 v63, v23, 16, 1
	s_waitcnt vmcnt(6)
	v_bfe_u32 v64, v24, 16, 1
	v_bfe_u32 v67, v25, 16, 1
	v_bfe_u32 v69, v26, 16, 1
	v_bfe_u32 v79, v27, 16, 1
	v_and_or_b32 v12, v12, s74, v7
	v_and_or_b32 v13, v14, s74, v13
	v_and_or_b32 v14, v16, s74, v15
	v_and_or_b32 v15, v18, s74, v17
	v_add3_u32 v19, v20, v60, s73
	v_add3_u32 v20, v21, v61, s73
	v_add3_u32 v21, v22, v62, s73
	v_add3_u32 v22, v23, v63, s73
	v_add3_u32 v23, v24, v64, s73
	v_add3_u32 v24, v25, v67, s73
	v_add3_u32 v25, v26, v69, s73
	v_add3_u32 v26, v27, v79, s73
	ds_write_b128 v52, v[12:15]
	ds_write_b16_d16_hi v11, v19
	ds_write_b16_d16_hi v11, v20 offset:528
	ds_write_b16_d16_hi v11, v21 offset:1056
	ds_write_b16_d16_hi v11, v22 offset:1584
	ds_write_b16_d16_hi v11, v23 offset:2112
	ds_write_b16_d16_hi v11, v24 offset:2640
	ds_write_b16_d16_hi v11, v25 offset:3168
	ds_write_b16_d16_hi v11, v26 offset:3696
	global_load_dwordx4 v[16:19], v[8:9], off offset:16 nt
	global_load_dwordx4 v[20:23], v[8:9], off nt
	s_waitcnt vmcnt(7)
	v_bfe_u32 v7, v28, 16, 1
	v_add3_u32 v7, v28, v7, s73
	v_bfe_u32 v11, v29, 16, 1
	v_lshrrev_b32_e32 v7, 16, v7
	v_add3_u32 v11, v29, v11, s73
	v_and_or_b32 v12, v11, s74, v7
	v_bfe_u32 v7, v30, 16, 1
	v_add3_u32 v7, v30, v7, s73
	v_bfe_u32 v8, v31, 16, 1
	v_lshrrev_b32_e32 v7, 16, v7
	v_add3_u32 v8, v31, v8, s73
	v_and_or_b32 v13, v8, s74, v7
	s_waitcnt vmcnt(6)
	v_bfe_u32 v7, v32, 16, 1
	v_add3_u32 v7, v32, v7, s73
	v_bfe_u32 v8, v33, 16, 1
	v_lshrrev_b32_e32 v7, 16, v7
	v_add3_u32 v8, v33, v8, s73
	v_and_or_b32 v14, v8, s74, v7
	v_bfe_u32 v7, v34, 16, 1
	v_add3_u32 v7, v34, v7, s73
	v_bfe_u32 v8, v35, 16, 1
	v_lshrrev_b32_e32 v7, 16, v7
	v_add3_u32 v8, v35, v8, s73
	v_and_or_b32 v15, v8, s74, v7
	s_waitcnt vmcnt(4)
	v_bfe_u32 v8, v41, 16, 1
	v_bfe_u32 v7, v40, 16, 1
	v_add3_u32 v11, v41, v8, s73
	v_bfe_u32 v8, v42, 16, 1
	v_add3_u32 v7, v40, v7, s73
	v_add3_u32 v40, v42, v8, s73
	v_bfe_u32 v8, v43, 16, 1
	v_add3_u32 v41, v43, v8, s73
	v_bfe_u32 v8, v36, 16, 1
	v_add3_u32 v36, v36, v8, s73
	v_bfe_u32 v8, v37, 16, 1
	v_add3_u32 v37, v37, v8, s73
	v_add_u32_e32 v8, 0x600, v68
	v_ashrrev_i32_e32 v8, 4, v8
	v_ashrrev_i32_e32 v9, 31, v8
	v_lshl_add_u64 v[24:25], v[8:9], 0, s[48:49]
	v_lshlrev_b64 v[32:33], 11, v[24:25]
	v_or_b32_e32 v32, s4, v32
	v_lshl_add_u64 v[28:29], v[2:3], 0, v[32:33]
	global_load_dwordx4 v[24:27], v[28:29], off offset:16 nt
	s_nop 0
	global_load_dwordx4 v[28:31], v[28:29], off nt
	v_bfe_u32 v34, v38, 16, 1
	v_add3_u32 v9, v38, v34, s73
	v_bfe_u32 v34, v39, 16, 1
	v_add3_u32 v38, v39, v34, s73
	v_mad_u64_u32 v[34:35], s[8:9], v10, s70, v[4:5]
	v_lshl_add_u32 v10, v10, 1, v5
	ds_write_b128 v34, v[12:15]
	ds_write_b16_d16_hi v10, v7
	ds_write_b16_d16_hi v10, v11 offset:528
	ds_write_b16_d16_hi v10, v40 offset:1056
	ds_write_b16_d16_hi v10, v41 offset:1584
	ds_write_b16_d16_hi v10, v36 offset:2112
	ds_write_b16_d16_hi v10, v37 offset:2640
	ds_write_b16_d16_hi v10, v9 offset:3168
	ds_write_b16_d16_hi v10, v38 offset:3696
	v_lshl_add_u64 v[10:11], v[0:1], 0, v[32:33]
	global_load_dwordx4 v[32:35], v[10:11], off offset:16 nt
	global_load_dwordx4 v[36:39], v[10:11], off nt
	s_waitcnt vmcnt(6)
	v_bfe_u32 v7, v48, 16, 1
	v_add3_u32 v7, v48, v7, s73
	v_bfe_u32 v9, v49, 16, 1
	v_lshrrev_b32_e32 v7, 16, v7
	v_add3_u32 v9, v49, v9, s73
	v_and_or_b32 v12, v9, s74, v7
	v_bfe_u32 v7, v50, 16, 1
	v_add3_u32 v7, v50, v7, s73
	v_bfe_u32 v9, v51, 16, 1
	v_lshrrev_b32_e32 v7, 16, v7
	v_add3_u32 v9, v51, v9, s73
	v_and_or_b32 v13, v9, s74, v7
	v_bfe_u32 v7, v44, 16, 1
	v_add3_u32 v7, v44, v7, s73
	v_bfe_u32 v9, v45, 16, 1
	v_lshrrev_b32_e32 v7, 16, v7
	v_add3_u32 v9, v45, v9, s73
	v_and_or_b32 v14, v9, s74, v7
	v_bfe_u32 v7, v46, 16, 1
	v_add3_u32 v7, v46, v7, s73
	v_bfe_u32 v9, v47, 16, 1
	v_add3_u32 v9, v47, v9, s73
	v_lshrrev_b32_e32 v7, 16, v7
	v_and_or_b32 v15, v9, s74, v7
	s_waitcnt vmcnt(4)
	v_bfe_u32 v10, v22, 16, 1
	v_add3_u32 v44, v22, v10, s73
	v_bfe_u32 v10, v23, 16, 1
	v_add3_u32 v45, v23, v10, s73
	v_bfe_u32 v10, v16, 16, 1
	v_add3_u32 v46, v16, v10, s73
	v_bfe_u32 v10, v17, 16, 1
	v_add3_u32 v47, v17, v10, s73
	v_add_u32_e32 v10, 0x800, v68
	v_ashrrev_i32_e32 v10, 4, v10
	v_ashrrev_i32_e32 v11, 31, v10
	v_lshl_add_u64 v[16:17], v[10:11], 0, s[48:49]
	v_lshlrev_b64 v[16:17], 11, v[16:17]
	v_or_b32_e32 v16, s4, v16
	v_bfe_u32 v7, v20, 16, 1
	v_bfe_u32 v9, v21, 16, 1
	v_lshl_add_u64 v[40:41], v[2:3], 0, v[16:17]
	v_add3_u32 v7, v20, v7, s73
	v_add3_u32 v9, v21, v9, s73
	global_load_dwordx4 v[20:23], v[40:41], off offset:16 nt
	s_nop 0
	global_load_dwordx4 v[40:43], v[40:41], off nt
	v_bfe_u32 v48, v18, 16, 1
	v_add3_u32 v11, v18, v48, s73
	v_bfe_u32 v18, v19, 16, 1
	v_add3_u32 v48, v19, v18, s73
	v_mad_u64_u32 v[18:19], s[8:9], v6, s70, v[4:5]
	v_lshl_add_u32 v6, v6, 1, v5
	ds_write_b128 v18, v[12:15]
	ds_write_b16_d16_hi v6, v7
	ds_write_b16_d16_hi v6, v9 offset:528
	ds_write_b16_d16_hi v6, v44 offset:1056
	ds_write_b16_d16_hi v6, v45 offset:1584
	ds_write_b16_d16_hi v6, v46 offset:2112
	ds_write_b16_d16_hi v6, v47 offset:2640
	ds_write_b16_d16_hi v6, v11 offset:3168
	ds_write_b16_d16_hi v6, v48 offset:3696
	s_waitcnt vmcnt(4)
	v_bfe_u32 v6, v28, 16, 1
	v_add3_u32 v6, v28, v6, s73
	v_bfe_u32 v7, v29, 16, 1
	v_lshrrev_b32_e32 v6, 16, v6
	v_add3_u32 v7, v29, v7, s73
	v_and_or_b32 v12, v7, s74, v6
	v_bfe_u32 v6, v30, 16, 1
	v_add3_u32 v6, v30, v6, s73
	v_lshrrev_b32_e32 v9, 16, v6
	v_lshl_add_u64 v[6:7], v[0:1], 0, v[16:17]
	global_load_dwordx4 v[16:19], v[6:7], off offset:16 nt
	global_load_dwordx4 v[44:47], v[6:7], off nt
	v_bfe_u32 v6, v31, 16, 1
	v_add3_u32 v6, v31, v6, s73
	v_and_or_b32 v13, v6, s74, v9
	v_bfe_u32 v6, v24, 16, 1
	v_add3_u32 v6, v24, v6, s73
	v_bfe_u32 v7, v25, 16, 1
	v_lshrrev_b32_e32 v6, 16, v6
	v_add3_u32 v7, v25, v7, s73
	v_and_or_b32 v14, v7, s74, v6
	v_bfe_u32 v6, v26, 16, 1
	v_add3_u32 v6, v26, v6, s73
	v_bfe_u32 v7, v27, 16, 1
	v_lshrrev_b32_e32 v6, 16, v6
	v_add3_u32 v7, v27, v7, s73
	v_and_or_b32 v15, v7, s74, v6
	s_waitcnt vmcnt(4)
	v_bfe_u32 v6, v36, 16, 1
	v_add3_u32 v9, v36, v6, s73
	v_bfe_u32 v6, v37, 16, 1
	v_add3_u32 v11, v37, v6, s73
	v_bfe_u32 v6, v38, 16, 1
	v_add3_u32 v36, v38, v6, s73
	v_bfe_u32 v6, v39, 16, 1
	v_add3_u32 v37, v39, v6, s73
	v_bfe_u32 v6, v32, 16, 1
	v_add3_u32 v38, v32, v6, s73
	v_bfe_u32 v6, v33, 16, 1
	v_add3_u32 v39, v33, v6, s73
	v_add_u32_e32 v6, 0xa00, v68
	v_ashrrev_i32_e32 v6, 4, v6
	v_ashrrev_i32_e32 v7, 31, v6
	v_lshl_add_u64 v[24:25], v[6:7], 0, s[48:49]
	v_lshlrev_b64 v[32:33], 11, v[24:25]
	v_or_b32_e32 v32, s4, v32
	v_lshl_add_u64 v[28:29], v[2:3], 0, v[32:33]
	global_load_dwordx4 v[24:27], v[28:29], off offset:16 nt
	s_nop 0
	global_load_dwordx4 v[28:31], v[28:29], off nt
	v_bfe_u32 v48, v34, 16, 1
	v_add3_u32 v7, v34, v48, s73
	v_bfe_u32 v34, v35, 16, 1
	v_add3_u32 v48, v35, v34, s73
	v_mad_u64_u32 v[34:35], s[8:9], v8, s70, v[4:5]
	v_lshl_add_u32 v8, v8, 1, v5
	ds_write_b128 v34, v[12:15]
	ds_write_b16_d16_hi v8, v9
	ds_write_b16_d16_hi v8, v11 offset:528
	ds_write_b16_d16_hi v8, v36 offset:1056
	ds_write_b16_d16_hi v8, v37 offset:1584
	ds_write_b16_d16_hi v8, v38 offset:2112
	ds_write_b16_d16_hi v8, v39 offset:2640
	ds_write_b16_d16_hi v8, v7 offset:3168
	ds_write_b16_d16_hi v8, v48 offset:3696
	s_waitcnt vmcnt(4)
	v_bfe_u32 v7, v40, 16, 1
	v_add3_u32 v7, v40, v7, s73
	v_bfe_u32 v8, v41, 16, 1
	v_lshrrev_b32_e32 v7, 16, v7
	v_add3_u32 v8, v41, v8, s73
	v_and_or_b32 v12, v8, s74, v7
	v_lshl_add_u64 v[8:9], v[0:1], 0, v[32:33]
	global_load_dwordx4 v[32:35], v[8:9], off offset:16 nt
	global_load_dwordx4 v[36:39], v[8:9], off nt
	v_bfe_u32 v7, v42, 16, 1
	v_add3_u32 v7, v42, v7, s73
	v_bfe_u32 v8, v43, 16, 1
	v_lshrrev_b32_e32 v7, 16, v7
	v_add3_u32 v8, v43, v8, s73
	v_and_or_b32 v13, v8, s74, v7
	v_bfe_u32 v7, v20, 16, 1
	v_add3_u32 v7, v20, v7, s73
	v_bfe_u32 v8, v21, 16, 1
	v_lshrrev_b32_e32 v7, 16, v7
	v_add3_u32 v8, v21, v8, s73
	v_and_or_b32 v14, v8, s74, v7
	v_bfe_u32 v7, v22, 16, 1
	v_add3_u32 v7, v22, v7, s73
	v_bfe_u32 v8, v23, 16, 1
	v_lshrrev_b32_e32 v7, 16, v7
	v_add3_u32 v8, v23, v8, s73
	v_and_or_b32 v15, v8, s74, v7
	s_waitcnt vmcnt(4)
	v_bfe_u32 v8, v45, 16, 1
	v_add3_u32 v11, v45, v8, s73
	v_bfe_u32 v8, v46, 16, 1
	v_add3_u32 v42, v46, v8, s73
	v_bfe_u32 v8, v47, 16, 1
	v_add3_u32 v43, v47, v8, s73
	v_bfe_u32 v8, v16, 16, 1
	v_add3_u32 v46, v16, v8, s73
	v_bfe_u32 v8, v17, 16, 1
	v_add3_u32 v47, v17, v8, s73
	v_bfe_u32 v8, v18, 16, 1
	v_add3_u32 v48, v18, v8, s73
	v_bfe_u32 v8, v19, 16, 1
	v_bfe_u32 v7, v44, 16, 1
	v_add3_u32 v49, v19, v8, s73
	v_add_u32_e32 v8, 0xc00, v68
	v_add3_u32 v7, v44, v7, s73
	v_ashrrev_i32_e32 v44, 4, v8
	v_ashrrev_i32_e32 v45, 31, v44
	v_lshl_add_u64 v[8:9], v[44:45], 0, s[48:49]
	v_lshlrev_b64 v[40:41], 11, v[8:9]
	v_or_b32_e32 v40, s4, v40
	v_lshl_add_u64 v[8:9], v[2:3], 0, v[40:41]
	global_load_dwordx4 v[16:19], v[8:9], off offset:16 nt
	global_load_dwordx4 v[20:23], v[8:9], off nt
	v_mad_u64_u32 v[8:9], s[8:9], v10, s70, v[4:5]
	ds_write_b128 v8, v[12:15]
	v_lshl_add_u32 v8, v10, 1, v5
	ds_write_b16_d16_hi v8, v7
	ds_write_b16_d16_hi v8, v11 offset:528
	ds_write_b16_d16_hi v8, v42 offset:1056
	ds_write_b16_d16_hi v8, v43 offset:1584
	ds_write_b16_d16_hi v8, v46 offset:2112
	ds_write_b16_d16_hi v8, v47 offset:2640
	ds_write_b16_d16_hi v8, v48 offset:3168
	ds_write_b16_d16_hi v8, v49 offset:3696
	v_lshl_add_u64 v[10:11], v[0:1], 0, v[40:41]
	global_load_dwordx4 v[12:15], v[10:11], off offset:16 nt
	global_load_dwordx4 v[40:43], v[10:11], off nt
	s_waitcnt vmcnt(7)
	v_bfe_u32 v10, v25, 16, 1
	s_waitcnt vmcnt(6)
	v_bfe_u32 v7, v28, 16, 1
	v_add3_u32 v7, v28, v7, s73
	v_bfe_u32 v8, v29, 16, 1
	v_lshrrev_b32_e32 v7, 16, v7
	v_add3_u32 v8, v29, v8, s73
	v_and_or_b32 v8, v8, s74, v7
	v_bfe_u32 v7, v30, 16, 1
	v_add3_u32 v7, v30, v7, s73
	v_bfe_u32 v9, v31, 16, 1
	v_lshrrev_b32_e32 v7, 16, v7
	v_add3_u32 v9, v31, v9, s73
	v_and_or_b32 v9, v9, s74, v7
	v_bfe_u32 v7, v24, 16, 1
	v_add3_u32 v7, v24, v7, s73
	v_lshrrev_b32_e32 v7, 16, v7
	v_add3_u32 v10, v25, v10, s73
	v_and_or_b32 v10, v10, s74, v7
	v_bfe_u32 v7, v26, 16, 1
	v_add3_u32 v7, v26, v7, s73
	v_bfe_u32 v11, v27, 16, 1
	v_lshrrev_b32_e32 v7, 16, v7
	v_add3_u32 v11, v27, v11, s73
	s_waitcnt vmcnt(4)
	v_bfe_u32 v24, v37, 16, 1
	v_and_or_b32 v11, v11, s74, v7
	v_bfe_u32 v7, v36, 16, 1
	v_add3_u32 v45, v37, v24, s73
	v_add_u32_e32 v24, 0xe00, v68
	v_add3_u32 v7, v36, v7, s73
	v_ashrrev_i32_e32 v36, 4, v24
	v_ashrrev_i32_e32 v37, 31, v36
	v_lshl_add_u64 v[24:25], v[36:37], 0, s[48:49]
	v_lshlrev_b64 v[46:47], 11, v[24:25]
	v_or_b32_e32 v46, s4, v46
	v_lshl_add_u64 v[2:3], v[2:3], 0, v[46:47]
	global_load_dwordx4 v[24:27], v[2:3], off offset:16 nt
	global_load_dwordx4 v[28:31], v[2:3], off nt
	v_bfe_u32 v2, v38, 16, 1
	v_add3_u32 v37, v38, v2, s73
	v_bfe_u32 v2, v39, 16, 1
	v_add3_u32 v38, v39, v2, s73
	v_bfe_u32 v2, v32, 16, 1
	v_add3_u32 v32, v32, v2, s73
	v_bfe_u32 v2, v33, 16, 1
	v_add3_u32 v33, v33, v2, s73
	v_bfe_u32 v2, v34, 16, 1
	v_add3_u32 v34, v34, v2, s73
	v_bfe_u32 v2, v35, 16, 1
	v_add3_u32 v35, v35, v2, s73
	v_mad_u64_u32 v[2:3], s[4:5], v6, s70, v[4:5]
	ds_write_b128 v2, v[8:11]
	v_lshl_add_u32 v10, v6, 1, v5
	ds_write_b16_d16_hi v10, v7
	ds_write_b16_d16_hi v10, v45 offset:528
	ds_write_b16_d16_hi v10, v37 offset:1056
	ds_write_b16_d16_hi v10, v38 offset:1584
	ds_write_b16_d16_hi v10, v32 offset:2112
	v_lshl_add_u64 v[6:7], v[0:1], 0, v[46:47]
	global_load_dwordx4 v[0:3], v[6:7], off offset:16 nt
	s_nop 0
	global_load_dwordx4 v[6:9], v[6:7], off nt
	ds_write_b16_d16_hi v10, v33 offset:2640
	ds_write_b16_d16_hi v10, v34 offset:3168
	ds_write_b16_d16_hi v10, v35 offset:3696
	s_waitcnt vmcnt(6)
	v_bfe_u32 v10, v20, 16, 1
	v_add3_u32 v10, v20, v10, s73
	v_bfe_u32 v11, v21, 16, 1
	v_lshrrev_b32_e32 v10, 16, v10
	v_add3_u32 v11, v21, v11, s73
	v_and_or_b32 v20, v11, s74, v10
	v_bfe_u32 v10, v22, 16, 1
	v_add3_u32 v10, v22, v10, s73
	v_bfe_u32 v11, v23, 16, 1
	v_lshrrev_b32_e32 v10, 16, v10
	v_add3_u32 v11, v23, v11, s73
	v_and_or_b32 v21, v11, s74, v10
	v_bfe_u32 v10, v16, 16, 1
	v_add3_u32 v10, v16, v10, s73
	v_bfe_u32 v11, v17, 16, 1
	v_lshrrev_b32_e32 v10, 16, v10
	v_add3_u32 v11, v17, v11, s73
	v_and_or_b32 v22, v11, s74, v10
	v_bfe_u32 v10, v18, 16, 1
	v_add3_u32 v10, v18, v10, s73
	v_bfe_u32 v11, v19, 16, 1
	v_lshrrev_b32_e32 v10, 16, v10
	v_add3_u32 v11, v19, v11, s73
	v_and_or_b32 v23, v11, s74, v10
	s_waitcnt vmcnt(4)
	v_bfe_u32 v10, v40, 16, 1
	v_add3_u32 v16, v40, v10, s73
	v_bfe_u32 v10, v41, 16, 1
	v_add3_u32 v17, v41, v10, s73
	v_bfe_u32 v10, v42, 16, 1
	v_add3_u32 v18, v42, v10, s73
	v_bfe_u32 v10, v43, 16, 1
	v_add3_u32 v19, v43, v10, s73
	v_bfe_u32 v10, v12, 16, 1
	v_add3_u32 v12, v12, v10, s73
	v_bfe_u32 v10, v13, 16, 1
	v_add3_u32 v13, v13, v10, s73
	v_bfe_u32 v10, v14, 16, 1
	v_add3_u32 v14, v14, v10, s73
	v_bfe_u32 v10, v15, 16, 1
	v_add3_u32 v15, v15, v10, s73
	v_mad_u64_u32 v[10:11], s[4:5], v44, s70, v[4:5]
	ds_write_b128 v10, v[20:23]
	v_lshl_add_u32 v10, v44, 1, v5
	ds_write_b16_d16_hi v10, v16
	ds_write_b16_d16_hi v10, v17 offset:528
	ds_write_b16_d16_hi v10, v18 offset:1056
	ds_write_b16_d16_hi v10, v19 offset:1584
	ds_write_b16_d16_hi v10, v12 offset:2112
	ds_write_b16_d16_hi v10, v13 offset:2640
	ds_write_b16_d16_hi v10, v14 offset:3168
	ds_write_b16_d16_hi v10, v15 offset:3696
	s_waitcnt vmcnt(3)
	v_bfe_u32 v13, v25, 16, 1
	s_waitcnt vmcnt(2)
	v_bfe_u32 v10, v28, 16, 1
	v_add3_u32 v10, v28, v10, s73
	v_bfe_u32 v11, v29, 16, 1
	v_lshrrev_b32_e32 v10, 16, v10
	v_add3_u32 v11, v29, v11, s73
	v_and_or_b32 v10, v11, s74, v10
	v_bfe_u32 v11, v30, 16, 1
	v_add3_u32 v11, v30, v11, s73
	v_bfe_u32 v12, v31, 16, 1
	v_lshrrev_b32_e32 v11, 16, v11
	v_add3_u32 v12, v31, v12, s73
	v_and_or_b32 v11, v12, s74, v11
	v_bfe_u32 v12, v24, 16, 1
	v_add3_u32 v12, v24, v12, s73
	v_lshrrev_b32_e32 v12, 16, v12
	v_add3_u32 v13, v25, v13, s73
	v_and_or_b32 v12, v13, s74, v12
	v_bfe_u32 v13, v26, 16, 1
	v_add3_u32 v13, v26, v13, s73
	v_bfe_u32 v14, v27, 16, 1
	v_lshrrev_b32_e32 v13, 16, v13
	v_add3_u32 v14, v27, v14, s73
	v_and_or_b32 v13, v14, s74, v13
	s_waitcnt vmcnt(0)
	v_bfe_u32 v14, v6, 16, 1
	v_add3_u32 v6, v6, v14, s73
	v_bfe_u32 v14, v7, 16, 1
	v_add3_u32 v7, v7, v14, s73
	v_bfe_u32 v14, v8, 16, 1
	v_add3_u32 v8, v8, v14, s73
	v_bfe_u32 v14, v9, 16, 1
	v_add3_u32 v9, v9, v14, s73
	v_bfe_u32 v14, v0, 16, 1
	v_add3_u32 v14, v0, v14, s73
	v_bfe_u32 v0, v1, 16, 1
	v_add3_u32 v15, v1, v0, s73
	v_bfe_u32 v0, v2, 16, 1
	v_add3_u32 v2, v2, v0, s73
	v_bfe_u32 v0, v3, 16, 1
	v_add3_u32 v3, v3, v0, s73
	v_mad_u64_u32 v[0:1], s[4:5], v36, s70, v[4:5]
	ds_write_b128 v0, v[10:13]
	v_lshl_add_u32 v0, v36, 1, v5
	ds_write_b16_d16_hi v0, v6
	ds_write_b16_d16_hi v0, v7 offset:528
	ds_write_b16_d16_hi v0, v8 offset:1056
	ds_write_b16_d16_hi v0, v9 offset:1584
	ds_write_b16_d16_hi v0, v14 offset:2112
	ds_write_b16_d16_hi v0, v15 offset:2640
	ds_write_b16_d16_hi v0, v2 offset:3168
	ds_write_b16_d16_hi v0, v3 offset:3696
	s_waitcnt lgkmcnt(0)
	s_barrier
	s_and_saveexec_b64 s[4:5], vcc
	s_cbranch_execz .LBB0_656
	s_and_b32 s6, s6, 0x1fc
	s_bitset1_b32 s6, 14
	v_and_or_b32 v0, v68, 3, s6
	v_mul_u32_u24_e32 v0, 0x1e00, v0
	v_lshlrev_b32_e32 v64, 1, v0
	v_lshl_add_u64 v[0:1], s[30:31], 0, v[64:65]
	s_lshl_b32 s48, s7, 1
	v_lshl_add_u64 v[0:1], v[0:1], 0, s[48:49]
	v_and_b32_e32 v64, -16, v68
	v_lshl_add_u64 v[4:5], v[0:1], 0, v[64:65]
	v_add_co_u32_e32 v0, vcc, s76, v4
	s_mov_b64 s[8:9], 0x2000
	s_nop 0
	v_addc_co_u32_e32 v1, vcc, 0, v5, vcc
	global_load_dwordx4 v[0:3], v[0:1], off
	v_lshl_add_u64 v[4:5], v[4:5], 0, s[8:9]
	global_load_dwordx4 v[80:83], v[4:5], off offset:64
	global_load_dwordx4 v[84:87], v[4:5], off offset:128
	global_load_dwordx4 v[88:91], v[4:5], off offset:192
	v_and_b32_e32 v4, 48, v68
	v_and_b32_e32 v64, 15, v68
	v_add_u32_e32 v100, 0, v4
	v_mad_u32_u24 v101, v64, s70, v100
	ds_read_b128 v[4:7], v101
	ds_read_b128 v[8:11], v101 offset:64
	ds_read_b128 v[12:15], v101 offset:128
	v_lshrrev_b32_e32 v67, 4, v68
	s_waitcnt vmcnt(3) lgkmcnt(2)
	v_mfma_f32_16x16x32_bf16 v[4:7], v[4:7], v[0:3], 0
	s_waitcnt vmcnt(2) lgkmcnt(1)
	v_mfma_f32_16x16x32_bf16 v[4:7], v[8:11], v[80:83], v[4:7]
	ds_read_b128 v[8:11], v101 offset:192
	s_waitcnt vmcnt(1) lgkmcnt(1)
	v_mfma_f32_16x16x32_bf16 v[4:7], v[12:15], v[84:87], v[4:7]
	s_waitcnt vmcnt(0) lgkmcnt(0)
	v_mfma_f32_16x16x32_bf16 v[60:63], v[8:11], v[88:91], v[4:7]
	s_nop 5
	ds_read_b128 v[4:7], v101 offset:4352
	ds_read_b128 v[8:11], v101 offset:4416
	ds_read_b128 v[12:15], v101 offset:4480
	s_waitcnt lgkmcnt(2)
	v_mfma_f32_16x16x32_bf16 v[4:7], v[4:7], v[0:3], 0
	s_waitcnt lgkmcnt(1)
	v_mfma_f32_16x16x32_bf16 v[4:7], v[8:11], v[80:83], v[4:7]
	ds_read_b128 v[8:11], v101 offset:4544
	s_waitcnt lgkmcnt(1)
	v_mfma_f32_16x16x32_bf16 v[4:7], v[12:15], v[84:87], v[4:7]
	s_waitcnt lgkmcnt(0)
	v_mfma_f32_16x16x32_bf16 v[56:59], v[8:11], v[88:91], v[4:7]
	s_nop 5
	ds_read_b128 v[4:7], v101 offset:8704
	ds_read_b128 v[8:11], v101 offset:8768
	ds_read_b128 v[12:15], v101 offset:8832
	s_waitcnt lgkmcnt(2)
	v_mfma_f32_16x16x32_bf16 v[4:7], v[4:7], v[0:3], 0
	s_waitcnt lgkmcnt(1)
	v_mfma_f32_16x16x32_bf16 v[4:7], v[8:11], v[80:83], v[4:7]
	ds_read_b128 v[8:11], v101 offset:8896
	s_waitcnt lgkmcnt(1)
	v_mfma_f32_16x16x32_bf16 v[4:7], v[12:15], v[84:87], v[4:7]
	s_waitcnt lgkmcnt(0)
	v_mfma_f32_16x16x32_bf16 v[52:55], v[8:11], v[88:91], v[4:7]
	v_or_b32_e32 v69, 48, v68
	v_mad_u64_u32 v[16:17], s[8:9], v69, s70, v[100:101]
	s_nop 3
	ds_read_b128 v[4:7], v16
	ds_read_b128 v[8:11], v16 offset:64
	ds_read_b128 v[12:15], v16 offset:128
	s_waitcnt lgkmcnt(2)
	v_mfma_f32_16x16x32_bf16 v[4:7], v[4:7], v[0:3], 0
	s_waitcnt lgkmcnt(1)
	v_mfma_f32_16x16x32_bf16 v[4:7], v[8:11], v[80:83], v[4:7]
	ds_read_b128 v[8:11], v16 offset:192
	s_waitcnt lgkmcnt(1)
	v_mfma_f32_16x16x32_bf16 v[4:7], v[12:15], v[84:87], v[4:7]
	s_waitcnt lgkmcnt(0)
	v_mfma_f32_16x16x32_bf16 v[48:51], v[8:11], v[88:91], v[4:7]
	s_nop 5
	ds_read_b128 v[4:7], v101 offset:17408
	ds_read_b128 v[8:11], v101 offset:17472
	ds_read_b128 v[12:15], v101 offset:17536
	s_waitcnt lgkmcnt(2)
	v_mfma_f32_16x16x32_bf16 v[4:7], v[4:7], v[0:3], 0
	s_waitcnt lgkmcnt(1)
	v_mfma_f32_16x16x32_bf16 v[4:7], v[8:11], v[80:83], v[4:7]
	ds_read_b128 v[8:11], v101 offset:17600
	s_waitcnt lgkmcnt(1)
	v_mfma_f32_16x16x32_bf16 v[4:7], v[12:15], v[84:87], v[4:7]
	s_waitcnt lgkmcnt(0)
	v_mfma_f32_16x16x32_bf16 v[44:47], v[8:11], v[88:91], v[4:7]
	s_nop 5
	ds_read_b128 v[4:7], v101 offset:21760
	ds_read_b128 v[8:11], v101 offset:21824
	ds_read_b128 v[12:15], v101 offset:21888
	s_waitcnt lgkmcnt(2)
	v_mfma_f32_16x16x32_bf16 v[4:7], v[4:7], v[0:3], 0
	s_waitcnt lgkmcnt(1)
	v_mfma_f32_16x16x32_bf16 v[4:7], v[8:11], v[80:83], v[4:7]
	ds_read_b128 v[8:11], v101 offset:21952
	s_waitcnt lgkmcnt(1)
	v_mfma_f32_16x16x32_bf16 v[4:7], v[12:15], v[84:87], v[4:7]
	s_waitcnt lgkmcnt(0)
	v_mfma_f32_16x16x32_bf16 v[40:43], v[8:11], v[88:91], v[4:7]
	s_nop 5
	ds_read_b128 v[4:7], v101 offset:26112
	ds_read_b128 v[8:11], v101 offset:26176
	ds_read_b128 v[12:15], v101 offset:26240
	s_waitcnt lgkmcnt(2)
	v_mfma_f32_16x16x32_bf16 v[4:7], v[4:7], v[0:3], 0
	s_waitcnt lgkmcnt(1)
	v_mfma_f32_16x16x32_bf16 v[4:7], v[8:11], v[80:83], v[4:7]
	ds_read_b128 v[8:11], v101 offset:26304
	s_waitcnt lgkmcnt(1)
	v_mfma_f32_16x16x32_bf16 v[4:7], v[12:15], v[84:87], v[4:7]
	s_waitcnt lgkmcnt(0)
	v_mfma_f32_16x16x32_bf16 v[36:39], v[8:11], v[88:91], v[4:7]
	v_or_b32_e32 v79, 0x70, v68
	v_mad_u64_u32 v[16:17], s[8:9], v79, s70, v[100:101]
	s_nop 3
	ds_read_b128 v[4:7], v16
	ds_read_b128 v[8:11], v16 offset:64
	ds_read_b128 v[12:15], v16 offset:128
	s_waitcnt lgkmcnt(2)
	v_mfma_f32_16x16x32_bf16 v[4:7], v[4:7], v[0:3], 0
	s_waitcnt lgkmcnt(1)
	v_mfma_f32_16x16x32_bf16 v[4:7], v[8:11], v[80:83], v[4:7]
	ds_read_b128 v[8:11], v16 offset:192
	s_waitcnt lgkmcnt(1)
	v_mfma_f32_16x16x32_bf16 v[4:7], v[12:15], v[84:87], v[4:7]
	s_waitcnt lgkmcnt(0)
	v_mfma_f32_16x16x32_bf16 v[32:35], v[8:11], v[88:91], v[4:7]
	s_nop 5
	ds_read_b128 v[4:7], v101 offset:34816
	ds_read_b128 v[8:11], v101 offset:34880
	ds_read_b128 v[12:15], v101 offset:34944
	s_waitcnt lgkmcnt(2)
	v_mfma_f32_16x16x32_bf16 v[4:7], v[4:7], v[0:3], 0
	s_waitcnt lgkmcnt(1)
	v_mfma_f32_16x16x32_bf16 v[4:7], v[8:11], v[80:83], v[4:7]
	ds_read_b128 v[8:11], v101 offset:35008
	s_waitcnt lgkmcnt(1)
	v_mfma_f32_16x16x32_bf16 v[4:7], v[12:15], v[84:87], v[4:7]
	s_waitcnt lgkmcnt(0)
	v_mfma_f32_16x16x32_bf16 v[28:31], v[8:11], v[88:91], v[4:7]
	s_nop 5
	ds_read_b128 v[4:7], v101 offset:39168
	ds_read_b128 v[8:11], v101 offset:39232
	ds_read_b128 v[12:15], v101 offset:39296
	s_waitcnt lgkmcnt(2)
	v_mfma_f32_16x16x32_bf16 v[4:7], v[4:7], v[0:3], 0
	s_waitcnt lgkmcnt(1)
	v_mfma_f32_16x16x32_bf16 v[4:7], v[8:11], v[80:83], v[4:7]
	ds_read_b128 v[8:11], v101 offset:39360
	s_waitcnt lgkmcnt(1)
	v_mfma_f32_16x16x32_bf16 v[4:7], v[12:15], v[84:87], v[4:7]
	s_waitcnt lgkmcnt(0)
	v_mfma_f32_16x16x32_bf16 v[24:27], v[8:11], v[88:91], v[4:7]
	s_nop 5
	ds_read_b128 v[4:7], v101 offset:43520
	ds_read_b128 v[8:11], v101 offset:43584
	ds_read_b128 v[12:15], v101 offset:43648
	s_waitcnt lgkmcnt(2)
	v_mfma_f32_16x16x32_bf16 v[4:7], v[4:7], v[0:3], 0
	s_waitcnt lgkmcnt(1)
	v_mfma_f32_16x16x32_bf16 v[4:7], v[8:11], v[80:83], v[4:7]
	ds_read_b128 v[8:11], v101 offset:43712
	s_waitcnt lgkmcnt(1)
	v_mfma_f32_16x16x32_bf16 v[4:7], v[12:15], v[84:87], v[4:7]
	s_waitcnt lgkmcnt(0)
	v_mfma_f32_16x16x32_bf16 v[20:23], v[8:11], v[88:91], v[4:7]
	s_nop 5
	v_or_b32_e32 v4, 0xb0, v68
	v_mad_u64_u32 v[16:17], s[8:9], v4, s70, v[100:101]
	ds_read_b128 v[4:7], v16
	ds_read_b128 v[8:11], v16 offset:64
	ds_read_b128 v[12:15], v16 offset:128
	s_waitcnt lgkmcnt(2)
	v_mfma_f32_16x16x32_bf16 v[4:7], v[4:7], v[0:3], 0
	s_waitcnt lgkmcnt(1)
	v_mfma_f32_16x16x32_bf16 v[4:7], v[8:11], v[80:83], v[4:7]
	ds_read_b128 v[8:11], v16 offset:192
	s_waitcnt lgkmcnt(1)
	v_mfma_f32_16x16x32_bf16 v[4:7], v[12:15], v[84:87], v[4:7]
	s_waitcnt lgkmcnt(0)
	v_mfma_f32_16x16x32_bf16 v[16:19], v[8:11], v[88:91], v[4:7]
	s_nop 5
	ds_read_b128 v[4:7], v101 offset:52224
	ds_read_b128 v[8:11], v101 offset:52288
	ds_read_b128 v[12:15], v101 offset:52352
	s_waitcnt lgkmcnt(2)
	v_mfma_f32_16x16x32_bf16 v[4:7], v[4:7], v[0:3], 0
	s_waitcnt lgkmcnt(1)
	v_mfma_f32_16x16x32_bf16 v[4:7], v[8:11], v[80:83], v[4:7]
	ds_read_b128 v[8:11], v101 offset:52416
	s_waitcnt lgkmcnt(1)
	v_mfma_f32_16x16x32_bf16 v[4:7], v[12:15], v[84:87], v[4:7]
	s_waitcnt lgkmcnt(0)
	v_mfma_f32_16x16x32_bf16 v[12:15], v[8:11], v[88:91], v[4:7]
	s_nop 5
	ds_read_b128 v[4:7], v101 offset:56576
	ds_read_b128 v[8:11], v101 offset:56640
	ds_read_b128 v[92:95], v101 offset:56704
	s_waitcnt lgkmcnt(2)
	v_mfma_f32_16x16x32_bf16 v[4:7], v[4:7], v[0:3], 0
	s_waitcnt lgkmcnt(1)
	v_mfma_f32_16x16x32_bf16 v[4:7], v[8:11], v[80:83], v[4:7]
	ds_read_b128 v[8:11], v101 offset:56768
	s_waitcnt lgkmcnt(1)
	v_mfma_f32_16x16x32_bf16 v[4:7], v[92:95], v[84:87], v[4:7]
	s_waitcnt lgkmcnt(0)
	v_mfma_f32_16x16x32_bf16 v[8:11], v[8:11], v[88:91], v[4:7]
	s_nop 5
	ds_read_b128 v[4:7], v101 offset:60928
	ds_read_b128 v[92:95], v101 offset:60992
	ds_read_b128 v[96:99], v101 offset:61056
	s_waitcnt lgkmcnt(2)
	v_mfma_f32_16x16x32_bf16 v[4:7], v[4:7], v[0:3], 0
	s_waitcnt lgkmcnt(1)
	v_mfma_f32_16x16x32_bf16 v[4:7], v[92:95], v[80:83], v[4:7]
	ds_read_b128 v[92:95], v101 offset:61120
	s_waitcnt lgkmcnt(1)
	v_mfma_f32_16x16x32_bf16 v[4:7], v[96:99], v[84:87], v[4:7]
	s_waitcnt lgkmcnt(0)
	v_mfma_f32_16x16x32_bf16 v[4:7], v[92:95], v[88:91], v[4:7]
	v_or_b32_e32 v68, 0xf0, v68
	v_mad_u64_u32 v[100:101], s[8:9], v68, s70, v[100:101]
	ds_read_b128 v[92:95], v100
	ds_read_b128 v[96:99], v100 offset:64
	s_waitcnt lgkmcnt(1)
	v_mfma_f32_16x16x32_bf16 v[0:3], v[92:95], v[0:3], 0
	ds_read_b128 v[92:95], v100 offset:128
	s_waitcnt lgkmcnt(1)
	v_mfma_f32_16x16x32_bf16 v[0:3], v[96:99], v[80:83], v[0:3]
	ds_read_b128 v[80:83], v100 offset:192
	s_waitcnt lgkmcnt(1)
	v_mfma_f32_16x16x32_bf16 v[0:3], v[92:95], v[84:87], v[0:3]
	s_waitcnt lgkmcnt(0)
	v_mfma_f32_16x16x32_bf16 v[0:3], v[80:83], v[88:91], v[0:3]
	v_max_f32_e32 v68, v63, v63
	v_max_f32_e32 v80, v62, v62
	v_max_f32_e32 v68, v80, v68
	v_max_f32_e32 v80, v59, v59
	v_max_f32_e32 v81, v58, v58
	v_max_f32_e32 v80, v81, v80
	v_max3_f32 v68, v60, v61, v68
	v_max3_f32 v80, v56, v57, v80
	s_mov_b32 s7, 0xf149f2ca
	v_max3_f32 v68, v68, s7, v80
	v_max_f32_e32 v80, v55, v55
	v_max_f32_e32 v81, v54, v54
	v_max_f32_e32 v80, v81, v80
	v_max_f32_e32 v81, v51, v51
	v_max_f32_e32 v82, v50, v50
	v_max_f32_e32 v81, v82, v81
	v_max3_f32 v80, v52, v53, v80
	v_max3_f32 v81, v48, v49, v81
	v_max3_f32 v68, v68, v80, v81
	v_max_f32_e32 v80, v47, v47
	v_max_f32_e32 v81, v46, v46
	v_max_f32_e32 v80, v81, v80
	v_max_f32_e32 v81, v43, v43
	v_max_f32_e32 v82, v42, v42
	v_max_f32_e32 v81, v82, v81
	v_max3_f32 v80, v44, v45, v80
	v_max3_f32 v81, v40, v41, v81
	v_max3_f32 v68, v68, v80, v81
	v_max_f32_e32 v80, v39, v39
	v_max_f32_e32 v81, v38, v38
	v_max_f32_e32 v80, v81, v80
	v_max_f32_e32 v81, v35, v35
	v_max_f32_e32 v82, v34, v34
	v_max_f32_e32 v81, v82, v81
	v_max3_f32 v80, v36, v37, v80
	v_max3_f32 v81, v32, v33, v81
	v_max3_f32 v68, v68, v80, v81
	v_max_f32_e32 v80, v31, v31
	v_max_f32_e32 v81, v30, v30
	v_max_f32_e32 v80, v81, v80
	v_max_f32_e32 v81, v27, v27
	v_max_f32_e32 v82, v26, v26
	v_max_f32_e32 v81, v82, v81
	v_max3_f32 v80, v28, v29, v80
	v_max3_f32 v81, v24, v25, v81
	v_max3_f32 v68, v68, v80, v81
	v_max_f32_e32 v80, v23, v23
	v_max_f32_e32 v81, v22, v22
	v_max_f32_e32 v80, v81, v80
	v_max_f32_e32 v81, v19, v19
	v_max_f32_e32 v82, v18, v18
	v_max_f32_e32 v81, v82, v81
	v_max3_f32 v80, v20, v21, v80
	v_max3_f32 v81, v16, v17, v81
	v_max3_f32 v68, v68, v80, v81
	v_max_f32_e32 v80, v15, v15
	v_max_f32_e32 v81, v14, v14
	v_max_f32_e32 v80, v81, v80
	v_max_f32_e32 v81, v11, v11
	v_max_f32_e32 v82, v10, v10
	v_max_f32_e32 v81, v82, v81
	v_max3_f32 v80, v12, v13, v80
	v_max3_f32 v81, v8, v9, v81
	v_max3_f32 v68, v68, v80, v81
	v_max_f32_e32 v80, v7, v7
	v_max_f32_e32 v81, v6, v6
	v_max_f32_e32 v80, v81, v80
	v_max_f32_e32 v81, v3, v3
	v_max_f32_e32 v82, v2, v2
	v_max_f32_e32 v81, v82, v81
	v_max3_f32 v80, v4, v5, v80
	v_max3_f32 v81, v0, v1, v81
	v_cmp_lt_i32_e32 vcc, v72, v73
	v_max3_f32 v68, v68, v80, v81
	s_nop 0
	v_cndmask_b32_e32 v80, v71, v72, vcc
	v_lshlrev_b32_e32 v108, 2, v80
	ds_bpermute_b32 v80, v108, v68
	v_cmp_lt_i32_e32 vcc, v74, v73
	s_waitcnt lgkmcnt(0)
	v_max_f32_e32 v80, v80, v80
	v_max_f32_e32 v68, v68, v80
	v_cndmask_b32_e32 v80, v71, v74, vcc
	v_lshlrev_b32_e32 v109, 2, v80
	ds_bpermute_b32 v80, v109, v68
	s_waitcnt lgkmcnt(0)
	v_max_f32_e32 v80, v80, v80
	v_max_f32_e32 v68, v68, v80
	v_sub_f32_e32 v60, v60, v68
	v_sub_f32_e32 v62, v62, v68
	v_mul_f32_e32 v60, 0x3db504f3, v60
	v_sub_f32_e32 v61, v61, v68
	v_mul_f32_e32 v62, 0x3db504f3, v62
	v_mul_f32_e32 v60, 0x3fb8aa3b, v60
	v_mul_f32_e32 v61, 0x3db504f3, v61
	v_mul_f32_e32 v62, 0x3fb8aa3b, v62
	v_exp_f32_e32 v60, v60
	v_mul_f32_e32 v61, 0x3fb8aa3b, v61
	v_exp_f32_e32 v81, v62
	v_sub_f32_e32 v62, v63, v68
	v_exp_f32_e32 v61, v61
	v_mul_f32_e32 v62, 0x3db504f3, v62
	v_sub_f32_e32 v56, v56, v68
	v_mul_f32_e32 v62, 0x3fb8aa3b, v62
	v_mul_f32_e32 v56, 0x3db504f3, v56
	v_sub_f32_e32 v57, v57, v68
	v_sub_f32_e32 v53, v53, v68
	v_exp_f32_e32 v63, v62
	v_mul_f32_e32 v56, 0x3fb8aa3b, v56
	v_mul_f32_e32 v57, 0x3db504f3, v57
	v_sub_f32_e32 v58, v58, v68
	v_mul_f32_e32 v53, 0x3db504f3, v53
	v_add_f32_e32 v80, 0, v60
	v_exp_f32_e32 v56, v56
	v_mul_f32_e32 v57, 0x3fb8aa3b, v57
	v_mul_f32_e32 v58, 0x3db504f3, v58
	v_sub_f32_e32 v59, v59, v68
	v_mul_f32_e32 v53, 0x3fb8aa3b, v53
	v_add_f32_e32 v62, v61, v80
	v_exp_f32_e32 v57, v57
	v_mul_f32_e32 v58, 0x3fb8aa3b, v58
	v_mul_f32_e32 v59, 0x3db504f3, v59
	v_sub_f32_e32 v52, v52, v68
	v_exp_f32_e32 v111, v53
	v_sub_f32_e32 v53, v54, v68
	v_add_f32_e32 v62, v81, v62
	v_exp_f32_e32 v58, v58
	v_mul_f32_e32 v59, 0x3fb8aa3b, v59
	v_mul_f32_e32 v52, 0x3db504f3, v52
	v_mul_f32_e32 v53, 0x3db504f3, v53
	v_sub_f32_e32 v49, v49, v68
	v_add_f32_e32 v62, v63, v62
	v_exp_f32_e32 v59, v59
	v_mul_f32_e32 v52, 0x3fb8aa3b, v52
	v_mul_f32_e32 v53, 0x3fb8aa3b, v53
	v_mul_f32_e32 v49, 0x3db504f3, v49
	v_add_f32_e32 v62, v56, v62
	v_exp_f32_e32 v110, v52
	v_exp_f32_e32 v112, v53
	v_sub_f32_e32 v53, v55, v68
	v_mul_f32_e32 v49, 0x3fb8aa3b, v49
	v_add_f32_e32 v52, v57, v62
	v_mul_f32_e32 v53, 0x3db504f3, v53
	v_sub_f32_e32 v48, v48, v68
	v_exp_f32_e32 v115, v49
	v_sub_f32_e32 v49, v50, v68
	v_add_f32_e32 v52, v58, v52
	v_mul_f32_e32 v53, 0x3fb8aa3b, v53
	v_mul_f32_e32 v48, 0x3db504f3, v48
	v_mul_f32_e32 v49, 0x3db504f3, v49
	v_sub_f32_e32 v45, v45, v68
	v_add_f32_e32 v52, v59, v52
	v_exp_f32_e32 v113, v53
	v_mul_f32_e32 v48, 0x3fb8aa3b, v48
	v_mul_f32_e32 v49, 0x3fb8aa3b, v49
	v_mul_f32_e32 v45, 0x3db504f3, v45
	v_add_f32_e32 v52, v110, v52
	v_exp_f32_e32 v114, v48
	v_exp_f32_e32 v116, v49
	v_sub_f32_e32 v49, v51, v68
	v_mul_f32_e32 v45, 0x3fb8aa3b, v45
	v_add_f32_e32 v48, v111, v52
	v_mul_f32_e32 v49, 0x3db504f3, v49
	v_sub_f32_e32 v44, v44, v68
	v_exp_f32_e32 v53, v45
	v_sub_f32_e32 v45, v46, v68
	v_add_f32_e32 v48, v112, v48
	v_mul_f32_e32 v49, 0x3fb8aa3b, v49
	v_mul_f32_e32 v44, 0x3db504f3, v44
	v_mul_f32_e32 v45, 0x3db504f3, v45
	v_sub_f32_e32 v41, v41, v68
	v_add_f32_e32 v48, v113, v48
	v_exp_f32_e32 v117, v49
	v_mul_f32_e32 v44, 0x3fb8aa3b, v44
	v_mul_f32_e32 v45, 0x3fb8aa3b, v45
	v_mul_f32_e32 v41, 0x3db504f3, v41
	v_add_f32_e32 v48, v114, v48
	v_exp_f32_e32 v51, v44
	v_exp_f32_e32 v52, v45
	v_sub_f32_e32 v45, v47, v68
	v_mul_f32_e32 v41, 0x3fb8aa3b, v41
	v_add_f32_e32 v44, v115, v48
	v_mul_f32_e32 v45, 0x3db504f3, v45
	v_sub_f32_e32 v40, v40, v68
	v_exp_f32_e32 v120, v41
	v_sub_f32_e32 v41, v42, v68
	v_add_f32_e32 v44, v116, v44
	v_mul_f32_e32 v45, 0x3fb8aa3b, v45
	v_mul_f32_e32 v40, 0x3db504f3, v40
	v_mul_f32_e32 v41, 0x3db504f3, v41
	v_sub_f32_e32 v37, v37, v68
	v_add_f32_e32 v44, v117, v44
	v_exp_f32_e32 v118, v45
	v_mul_f32_e32 v40, 0x3fb8aa3b, v40
	v_mul_f32_e32 v41, 0x3fb8aa3b, v41
	v_mul_f32_e32 v37, 0x3db504f3, v37
	v_add_f32_e32 v44, v51, v44
	v_exp_f32_e32 v119, v40
	v_exp_f32_e32 v121, v41
	v_sub_f32_e32 v41, v43, v68
	v_mul_f32_e32 v37, 0x3fb8aa3b, v37
	v_add_f32_e32 v40, v53, v44
	v_mul_f32_e32 v41, 0x3db504f3, v41
	v_sub_f32_e32 v36, v36, v68
	v_exp_f32_e32 v45, v37
	v_sub_f32_e32 v37, v38, v68
	v_add_f32_e32 v40, v52, v40
	v_mul_f32_e32 v41, 0x3fb8aa3b, v41
	v_mul_f32_e32 v36, 0x3db504f3, v36
	v_mul_f32_e32 v37, 0x3db504f3, v37
	v_sub_f32_e32 v33, v33, v68
	v_add_f32_e32 v40, v118, v40
	v_exp_f32_e32 v122, v41
	v_mul_f32_e32 v36, 0x3fb8aa3b, v36
	v_mul_f32_e32 v37, 0x3fb8aa3b, v37
	v_mul_f32_e32 v33, 0x3db504f3, v33
	v_add_f32_e32 v40, v119, v40
	v_exp_f32_e32 v43, v36
	v_exp_f32_e32 v44, v37
	v_sub_f32_e32 v37, v39, v68
	v_mul_f32_e32 v33, 0x3fb8aa3b, v33
	v_add_f32_e32 v36, v120, v40
	v_mul_f32_e32 v37, 0x3db504f3, v37
	v_sub_f32_e32 v32, v32, v68
	v_exp_f32_e32 v49, v33
	v_sub_f32_e32 v33, v34, v68
	v_add_f32_e32 v36, v121, v36
	v_mul_f32_e32 v37, 0x3fb8aa3b, v37
	v_mul_f32_e32 v32, 0x3db504f3, v32
	v_mul_f32_e32 v33, 0x3db504f3, v33
	v_sub_f32_e32 v29, v29, v68
	v_add_f32_e32 v36, v122, v36
	v_exp_f32_e32 v47, v37
	v_mul_f32_e32 v32, 0x3fb8aa3b, v32
	v_mul_f32_e32 v33, 0x3fb8aa3b, v33
	v_mul_f32_e32 v29, 0x3db504f3, v29
	v_add_f32_e32 v36, v43, v36
	v_exp_f32_e32 v46, v32
	v_exp_f32_e32 v48, v33
	v_sub_f32_e32 v33, v35, v68
	v_mul_f32_e32 v29, 0x3fb8aa3b, v29
	v_add_f32_e32 v32, v45, v36
	v_mul_f32_e32 v33, 0x3db504f3, v33
	v_sub_f32_e32 v28, v28, v68
	v_exp_f32_e32 v38, v29
	v_sub_f32_e32 v29, v30, v68
	v_add_f32_e32 v32, v44, v32
	v_mul_f32_e32 v33, 0x3fb8aa3b, v33
	v_mul_f32_e32 v28, 0x3db504f3, v28
	v_mul_f32_e32 v29, 0x3db504f3, v29
	v_add_f32_e32 v32, v47, v32
	v_exp_f32_e32 v50, v33
	v_mul_f32_e32 v28, 0x3fb8aa3b, v28
	v_mul_f32_e32 v29, 0x3fb8aa3b, v29
	v_add_f32_e32 v32, v46, v32
	v_exp_f32_e32 v36, v28
	v_exp_f32_e32 v37, v29
	v_sub_f32_e32 v29, v31, v68
	v_add_f32_e32 v28, v49, v32
	v_mul_f32_e32 v29, 0x3db504f3, v29
	v_sub_f32_e32 v24, v24, v68
	v_add_f32_e32 v28, v48, v28
	v_mul_f32_e32 v29, 0x3fb8aa3b, v29
	v_mul_f32_e32 v24, 0x3db504f3, v24
	v_add_f32_e32 v28, v50, v28
	v_exp_f32_e32 v39, v29
	v_mul_f32_e32 v24, 0x3fb8aa3b, v24
	v_add_f32_e32 v28, v36, v28
	v_exp_f32_e32 v31, v24
	v_add_f32_e32 v24, v38, v28
	v_add_f32_e32 v24, v37, v24
	v_add_f32_e32 v24, v39, v24
	v_add_f32_e32 v28, v31, v24
	v_sub_f32_e32 v24, v25, v68
	v_mul_f32_e32 v24, 0x3db504f3, v24
	v_mul_f32_e32 v24, 0x3fb8aa3b, v24
	v_exp_f32_e32 v41, v24
	v_sub_f32_e32 v24, v26, v68
	v_mul_f32_e32 v24, 0x3db504f3, v24
	v_sub_f32_e32 v21, v21, v68
	v_mul_f32_e32 v24, 0x3fb8aa3b, v24
	v_mul_f32_e32 v21, 0x3db504f3, v21
	v_exp_f32_e32 v40, v24
	v_sub_f32_e32 v24, v27, v68
	v_mul_f32_e32 v21, 0x3fb8aa3b, v21
	v_mul_f32_e32 v24, 0x3db504f3, v24
	v_sub_f32_e32 v20, v20, v68
	v_exp_f32_e32 v25, v21
	v_sub_f32_e32 v21, v22, v68
	v_mul_f32_e32 v24, 0x3fb8aa3b, v24
	v_mul_f32_e32 v20, 0x3db504f3, v20
	v_mul_f32_e32 v21, 0x3db504f3, v21
	v_sub_f32_e32 v17, v17, v68
	v_exp_f32_e32 v42, v24
	v_mul_f32_e32 v20, 0x3fb8aa3b, v20
	v_mul_f32_e32 v21, 0x3fb8aa3b, v21
	v_mul_f32_e32 v17, 0x3db504f3, v17
	v_exp_f32_e32 v24, v20
	v_exp_f32_e32 v22, v21
	v_sub_f32_e32 v21, v23, v68
	v_mul_f32_e32 v17, 0x3fb8aa3b, v17
	v_add_f32_e32 v20, v41, v28
	v_mul_f32_e32 v21, 0x3db504f3, v21
	v_sub_f32_e32 v16, v16, v68
	v_exp_f32_e32 v29, v17
	v_sub_f32_e32 v17, v18, v68
	v_add_f32_e32 v20, v40, v20
	v_mul_f32_e32 v21, 0x3fb8aa3b, v21
	v_mul_f32_e32 v16, 0x3db504f3, v16
	v_mul_f32_e32 v17, 0x3db504f3, v17
	v_add_f32_e32 v20, v42, v20
	v_exp_f32_e32 v26, v21
	v_mul_f32_e32 v16, 0x3fb8aa3b, v16
	v_mul_f32_e32 v17, 0x3fb8aa3b, v17
	v_add_f32_e32 v20, v24, v20
	v_exp_f32_e32 v23, v16
	v_exp_f32_e32 v28, v17
	v_sub_f32_e32 v17, v19, v68
	v_add_f32_e32 v16, v25, v20
	v_mul_f32_e32 v17, 0x3db504f3, v17
	v_sub_f32_e32 v12, v12, v68
	v_add_f32_e32 v16, v22, v16
	v_mul_f32_e32 v17, 0x3fb8aa3b, v17
	v_mul_f32_e32 v12, 0x3db504f3, v12
	v_sub_f32_e32 v13, v13, v68
	v_add_f32_e32 v16, v26, v16
	v_exp_f32_e32 v30, v17
	v_mul_f32_e32 v12, 0x3fb8aa3b, v12
	v_mul_f32_e32 v13, 0x3db504f3, v13
	v_add_f32_e32 v16, v23, v16
	v_exp_f32_e32 v12, v12
	v_mul_f32_e32 v13, 0x3fb8aa3b, v13
	v_add_f32_e32 v16, v29, v16
	v_exp_f32_e32 v17, v13
	v_sub_f32_e32 v13, v14, v68
	v_add_f32_e32 v16, v28, v16
	v_mul_f32_e32 v13, 0x3db504f3, v13
	v_sub_f32_e32 v9, v9, v68
	v_add_f32_e32 v16, v30, v16
	v_mul_f32_e32 v13, 0x3fb8aa3b, v13
	v_mul_f32_e32 v9, 0x3db504f3, v9
	v_add_f32_e32 v19, v12, v16
	v_exp_f32_e32 v16, v13
	v_sub_f32_e32 v13, v15, v68
	v_mul_f32_e32 v9, 0x3fb8aa3b, v9
	v_mul_f32_e32 v13, 0x3db504f3, v13
	v_sub_f32_e32 v8, v8, v68
	v_exp_f32_e32 v20, v9
	v_sub_f32_e32 v9, v10, v68
	v_mul_f32_e32 v13, 0x3fb8aa3b, v13
	v_mul_f32_e32 v8, 0x3db504f3, v8
	v_mul_f32_e32 v9, 0x3db504f3, v9
	v_exp_f32_e32 v18, v13
	v_mul_f32_e32 v8, 0x3fb8aa3b, v8
	v_mul_f32_e32 v9, 0x3fb8aa3b, v9
	v_exp_f32_e32 v15, v8
	v_add_f32_e32 v8, v17, v19
	v_exp_f32_e32 v19, v9
	v_sub_f32_e32 v9, v11, v68
	v_mul_f32_e32 v9, 0x3db504f3, v9
	v_sub_f32_e32 v4, v4, v68
	v_add_f32_e32 v8, v16, v8
	v_mul_f32_e32 v9, 0x3fb8aa3b, v9
	v_mul_f32_e32 v4, 0x3db504f3, v4
	v_add_f32_e32 v8, v18, v8
	v_exp_f32_e32 v21, v9
	v_mul_f32_e32 v4, 0x3fb8aa3b, v4
	v_add_f32_e32 v8, v15, v8
	v_exp_f32_e32 v4, v4
	v_add_f32_e32 v8, v20, v8
	v_sub_f32_e32 v5, v5, v68
	v_add_f32_e32 v8, v19, v8
	v_mul_f32_e32 v5, 0x3db504f3, v5
	v_add_f32_e32 v8, v21, v8
	v_mul_f32_e32 v5, 0x3fb8aa3b, v5
	v_add_f32_e32 v9, v4, v8
	v_exp_f32_e32 v8, v5
	v_sub_f32_e32 v5, v6, v68
	v_mul_f32_e32 v5, 0x3db504f3, v5
	v_sub_f32_e32 v6, v7, v68
	v_mul_f32_e32 v5, 0x3fb8aa3b, v5
	v_mul_f32_e32 v6, 0x3db504f3, v6
	v_sub_f32_e32 v0, v0, v68
	v_exp_f32_e32 v5, v5
	v_mul_f32_e32 v6, 0x3fb8aa3b, v6
	v_mul_f32_e32 v0, 0x3db504f3, v0
	v_exp_f32_e32 v7, v6
	v_mul_f32_e32 v0, 0x3fb8aa3b, v0
	v_exp_f32_e32 v6, v0
	v_add_f32_e32 v0, v8, v9
	v_add_f32_e32 v0, v5, v0
	v_add_f32_e32 v0, v7, v0
	v_add_f32_e32 v104, v6, v0
	v_sub_f32_e32 v0, v1, v68
	v_mul_f32_e32 v0, 0x3db504f3, v0
	v_mul_f32_e32 v0, 0x3fb8aa3b, v0
	v_exp_f32_e32 v10, v0
	v_sub_f32_e32 v0, v2, v68
	v_mul_f32_e32 v0, 0x3db504f3, v0
	v_mul_f32_e32 v0, 0x3fb8aa3b, v0
	v_exp_f32_e32 v9, v0
	v_sub_f32_e32 v27, v3, v68
	v_bfe_u32 v0, v59, 16, 1
	v_bfe_u32 v1, v57, 16, 1
	v_bfe_u32 v2, v63, 16, 1
	v_bfe_u32 v3, v61, 16, 1
	v_lshl_add_u32 v62, v67, 3, s68
	v_add3_u32 v13, v61, v3, s73
	v_add3_u32 v54, v63, v2, s73
	v_add3_u32 v11, v57, v1, s73
	v_add3_u32 v32, v59, v0, s73
	v_bfe_u32 v0, v60, 16, 1
	v_bfe_u32 v1, v81, 16, 1
	v_bfe_u32 v2, v56, 16, 1
	v_bfe_u32 v3, v58, 16, 1
	v_add3_u32 v3, v58, v3, s73
	v_add3_u32 v2, v56, v2, s73
	v_add3_u32 v1, v81, v1, s73
	v_add3_u32 v0, v60, v0, s73
	v_mad_u32_u24 v14, v64, s69, v62
	v_and_b32_e32 v140, 8, v64
	v_add_u32_e32 v14, v14, v140
	v_lshrrev_b32_e32 v58, 16, v0
	v_lshrrev_b32_e32 v55, 16, v1
	v_lshrrev_b32_e32 v33, 16, v2
	v_lshrrev_b32_e32 v34, 16, v3
	ds_read2_b64 v[0:3], v14 offset1:4
	v_and_or_b32 v56, v11, s74, v33
	v_add_u32_e32 v11, 0x2010, v14
	v_and_or_b32 v57, v32, s74, v34
	ds_read2_b64 v[32:35], v11 offset0:32 offset1:36
	v_and_or_b32 v55, v54, s74, v55
	v_and_or_b32 v54, v13, s74, v58
	v_add_u32_e32 v13, 0x4020, v14
	ds_read2_b64 v[58:61], v13 offset0:64 offset1:68
	s_waitcnt lgkmcnt(2)
	v_mfma_f32_16x16x32_bf16 v[80:83], v[0:3], v[54:57], 0
	v_mul_f32_e32 v2, 0x3db504f3, v27
	v_mul_f32_e32 v2, 0x3fb8aa3b, v2
	v_exp_f32_e32 v27, v2
	v_add_f32_e32 v2, v10, v104
	v_add_f32_e32 v2, v9, v2
	s_waitcnt lgkmcnt(1)
	v_mfma_f32_16x16x32_bf16 v[88:91], v[32:35], v[54:57], 0
	v_add_f32_e32 v32, v27, v2
	v_mad_u64_u32 v[2:3], s[8:9], v79, s69, v[62:63]
	v_mad_u64_u32 v[0:1], s[8:9], v69, s69, v[62:63]
	v_and_b32_e32 v140, 0x78, v79
	v_and_b32_e32 v141, 0x78, v69
	v_add_u32_e32 v2, v2, v140
	v_add_u32_e32 v0, v0, v141
	ds_bpermute_b32 v3, v108, v32
	v_add_u32_e32 v1, 0x8040, v14
	v_add_u32_e32 v34, 0xa050, v14
	v_add_u32_e32 v35, 0xc060, v14
	ds_read2_b64 v[84:87], v0 offset1:4
	ds_read2_b64 v[92:95], v1 offset0:128 offset1:132
	ds_read2_b64 v[96:99], v34 offset0:160 offset1:164
	ds_read2_b64 v[100:103], v35 offset0:192 offset1:196
	ds_read2_b64 v[104:107], v2 offset1:4
	s_waitcnt lgkmcnt(5)
	v_add_f32_e32 v32, v32, v3
	ds_bpermute_b32 v33, v109, v32
	v_mfma_f32_16x16x32_bf16 v[58:61], v[58:61], v[54:57], 0
	s_waitcnt lgkmcnt(5)
	v_mfma_f32_16x16x32_bf16 v[84:87], v[84:87], v[54:57], 0
	s_waitcnt lgkmcnt(4)
	v_mfma_f32_16x16x32_bf16 v[92:95], v[92:95], v[54:57], 0
	s_waitcnt lgkmcnt(3)
	v_mfma_f32_16x16x32_bf16 v[96:99], v[96:99], v[54:57], 0
	s_waitcnt lgkmcnt(2)
	v_mfma_f32_16x16x32_bf16 v[100:103], v[100:103], v[54:57], 0
	s_waitcnt lgkmcnt(1)
	v_mfma_f32_16x16x32_bf16 v[54:57], v[104:107], v[54:57], 0
	v_bfe_u32 v104, v114, 16, 1
	v_bfe_u32 v105, v116, 16, 1
	v_add3_u32 v108, v116, v105, s73
	v_add3_u32 v109, v114, v104, s73
	ds_read2_b64 v[104:107], v14 offset0:8 offset1:12
	v_bfe_u32 v69, v110, 16, 1
	v_bfe_u32 v79, v112, 16, 1
	v_bfe_u32 v3, v117, 16, 1
	v_bfe_u32 v62, v115, 16, 1
	v_bfe_u32 v63, v113, 16, 1
	v_bfe_u32 v68, v111, 16, 1
	v_add3_u32 v79, v112, v79, s73
	v_add3_u32 v69, v110, v69, s73
	v_add3_u32 v68, v111, v68, s73
	v_add3_u32 v63, v113, v63, s73
	v_add3_u32 v62, v115, v62, s73
	v_add3_u32 v3, v117, v3, s73
	v_lshrrev_b32_e32 v69, 16, v69
	v_lshrrev_b32_e32 v79, 16, v79
	v_lshrrev_b32_e32 v109, 16, v109
	v_lshrrev_b32_e32 v108, 16, v108
	v_and_or_b32 v111, v3, s74, v108
	v_and_or_b32 v110, v62, s74, v109
	v_and_or_b32 v109, v63, s74, v79
	v_and_or_b32 v108, v68, s74, v69
	s_waitcnt lgkmcnt(0)
	s_nop 0
	v_mfma_f32_16x16x32_bf16 v[80:83], v[104:107], v[108:111], v[80:83]
	ds_read2_b64 v[104:107], v11 offset0:40 offset1:44
	s_waitcnt lgkmcnt(0)
	v_mfma_f32_16x16x32_bf16 v[88:91], v[104:107], v[108:111], v[88:91]
	ds_read2_b64 v[104:107], v13 offset0:72 offset1:76
	s_waitcnt lgkmcnt(0)
	v_mfma_f32_16x16x32_bf16 v[58:61], v[104:107], v[108:111], v[58:61]
	ds_read2_b64 v[104:107], v0 offset0:8 offset1:12
	s_waitcnt lgkmcnt(0)
	v_mfma_f32_16x16x32_bf16 v[84:87], v[104:107], v[108:111], v[84:87]
	ds_read2_b64 v[104:107], v1 offset0:136 offset1:140
	s_waitcnt lgkmcnt(0)
	v_mfma_f32_16x16x32_bf16 v[92:95], v[104:107], v[108:111], v[92:95]
	ds_read2_b64 v[104:107], v34 offset0:168 offset1:172
	s_waitcnt lgkmcnt(0)
	v_mfma_f32_16x16x32_bf16 v[96:99], v[104:107], v[108:111], v[96:99]
	ds_read2_b64 v[104:107], v35 offset0:200 offset1:204
	s_waitcnt lgkmcnt(0)
	v_mfma_f32_16x16x32_bf16 v[100:103], v[104:107], v[108:111], v[100:103]
	ds_read2_b64 v[104:107], v2 offset0:8 offset1:12
	s_waitcnt lgkmcnt(0)
	v_mfma_f32_16x16x32_bf16 v[54:57], v[104:107], v[108:111], v[54:57]
	v_bfe_u32 v104, v121, 16, 1
	v_add3_u32 v108, v121, v104, s73
	ds_read2_b64 v[104:107], v14 offset0:16 offset1:20
	v_bfe_u32 v68, v53, 16, 1
	v_add3_u32 v53, v53, v68, s73
	v_bfe_u32 v68, v51, 16, 1
	v_bfe_u32 v69, v52, 16, 1
	v_bfe_u32 v79, v119, 16, 1
	v_bfe_u32 v3, v122, 16, 1
	v_bfe_u32 v62, v120, 16, 1
	v_bfe_u32 v63, v118, 16, 1
	v_add3_u32 v79, v119, v79, s73
	v_add3_u32 v52, v52, v69, s73
	v_add3_u32 v51, v51, v68, s73
	v_add3_u32 v63, v118, v63, s73
	v_add3_u32 v62, v120, v62, s73
	v_add3_u32 v3, v122, v3, s73
	v_lshrrev_b32_e32 v51, 16, v51
	v_lshrrev_b32_e32 v52, 16, v52
	v_lshrrev_b32_e32 v68, 16, v79
	v_lshrrev_b32_e32 v69, 16, v108
	v_and_or_b32 v111, v3, s74, v69
	v_and_or_b32 v110, v62, s74, v68
	v_and_or_b32 v109, v63, s74, v52
	v_and_or_b32 v108, v53, s74, v51
	s_waitcnt lgkmcnt(0)
	s_nop 0
	v_mfma_f32_16x16x32_bf16 v[80:83], v[104:107], v[108:111], v[80:83]
	ds_read2_b64 v[104:107], v11 offset0:48 offset1:52
	s_waitcnt lgkmcnt(0)
	v_mfma_f32_16x16x32_bf16 v[88:91], v[104:107], v[108:111], v[88:91]
	ds_read2_b64 v[104:107], v13 offset0:80 offset1:84
	s_waitcnt lgkmcnt(0)
	v_mfma_f32_16x16x32_bf16 v[58:61], v[104:107], v[108:111], v[58:61]
	ds_read2_b64 v[104:107], v0 offset0:16 offset1:20
	s_waitcnt lgkmcnt(0)
	v_mfma_f32_16x16x32_bf16 v[84:87], v[104:107], v[108:111], v[84:87]
	ds_read2_b64 v[104:107], v1 offset0:144 offset1:148
	s_waitcnt lgkmcnt(0)
	v_mfma_f32_16x16x32_bf16 v[92:95], v[104:107], v[108:111], v[92:95]
	ds_read2_b64 v[104:107], v34 offset0:176 offset1:180
	s_waitcnt lgkmcnt(0)
	v_mfma_f32_16x16x32_bf16 v[96:99], v[104:107], v[108:111], v[96:99]
	ds_read2_b64 v[104:107], v35 offset0:208 offset1:212
	s_waitcnt lgkmcnt(0)
	v_mfma_f32_16x16x32_bf16 v[100:103], v[104:107], v[108:111], v[100:103]
	ds_read2_b64 v[104:107], v2 offset0:16 offset1:20
	s_waitcnt lgkmcnt(0)
	v_mfma_f32_16x16x32_bf16 v[52:55], v[104:107], v[108:111], v[54:57]
	v_bfe_u32 v3, v50, 16, 1
	v_bfe_u32 v51, v49, 16, 1
	s_nop 0
	v_bfe_u32 v56, v47, 16, 1
	v_bfe_u32 v57, v45, 16, 1
	v_add3_u32 v57, v45, v57, s73
	v_add3_u32 v56, v47, v56, s73
	v_add3_u32 v49, v49, v51, s73
	v_add3_u32 v3, v50, v3, s73
	v_bfe_u32 v45, v43, 16, 1
	v_bfe_u32 v47, v44, 16, 1
	v_bfe_u32 v50, v46, 16, 1
	v_bfe_u32 v51, v48, 16, 1
	v_add3_u32 v48, v48, v51, s73
	v_add3_u32 v50, v46, v50, s73
	v_add3_u32 v51, v44, v47, s73
	v_add3_u32 v43, v43, v45, s73
	ds_read2_b64 v[44:47], v14 offset0:24 offset1:28
	v_lshrrev_b32_e32 v43, 16, v43
	v_lshrrev_b32_e32 v62, 16, v51
	v_lshrrev_b32_e32 v50, 16, v50
	v_lshrrev_b32_e32 v48, 16, v48
	v_and_or_b32 v51, v3, s74, v48
	v_and_or_b32 v50, v49, s74, v50
	v_and_or_b32 v49, v56, s74, v62
	v_and_or_b32 v48, v57, s74, v43
	s_waitcnt lgkmcnt(0)
	s_nop 0
	v_mfma_f32_16x16x32_bf16 v[44:47], v[44:47], v[48:51], v[80:83]
	s_nop 2
	ds_read2_b64 v[80:83], v11 offset0:56 offset1:60
	s_waitcnt lgkmcnt(0)
	v_mfma_f32_16x16x32_bf16 v[80:83], v[80:83], v[48:51], v[88:91]
	s_nop 2
	ds_read2_b64 v[88:91], v13 offset0:88 offset1:92
	s_waitcnt lgkmcnt(0)
	v_mfma_f32_16x16x32_bf16 v[56:59], v[88:91], v[48:51], v[58:61]
	s_nop 2
	ds_read2_b64 v[60:63], v0 offset0:24 offset1:28
	ds_read2_b64 v[88:91], v34 offset0:184 offset1:188
	s_waitcnt lgkmcnt(1)
	v_mfma_f32_16x16x32_bf16 v[60:63], v[60:63], v[48:51], v[84:87]
	s_nop 2
	ds_read2_b64 v[84:87], v1 offset0:152 offset1:156
	s_waitcnt lgkmcnt(0)
	v_mfma_f32_16x16x32_bf16 v[84:87], v[84:87], v[48:51], v[92:95]
	s_nop 2
	ds_read2_b64 v[92:95], v35 offset0:216 offset1:220
	v_mfma_f32_16x16x32_bf16 v[88:91], v[88:91], v[48:51], v[96:99]
	s_nop 2
	ds_read2_b64 v[96:99], v2 offset0:24 offset1:28
	s_waitcnt lgkmcnt(1)
	v_mfma_f32_16x16x32_bf16 v[92:95], v[92:95], v[48:51], v[100:103]
	s_waitcnt lgkmcnt(0)
	v_mfma_f32_16x16x32_bf16 v[48:51], v[96:99], v[48:51], v[52:55]
	v_bfe_u32 v3, v42, 16, 1
	v_bfe_u32 v43, v41, 16, 1
	s_nop 0
	v_bfe_u32 v52, v39, 16, 1
	v_bfe_u32 v53, v38, 16, 1
	v_add3_u32 v53, v38, v53, s73
	v_add3_u32 v52, v39, v52, s73
	v_add3_u32 v41, v41, v43, s73
	v_add3_u32 v3, v42, v3, s73
	v_bfe_u32 v38, v36, 16, 1
	v_bfe_u32 v39, v37, 16, 1
	v_bfe_u32 v42, v31, 16, 1
	v_bfe_u32 v43, v40, 16, 1
	v_add3_u32 v40, v40, v43, s73
	v_add3_u32 v31, v31, v42, s73
	v_add3_u32 v42, v37, v39, s73
	v_add3_u32 v43, v36, v38, s73
	v_lshrrev_b32_e32 v54, 16, v43
	v_lshrrev_b32_e32 v55, 16, v42
	v_lshrrev_b32_e32 v31, 16, v31
	v_lshrrev_b32_e32 v40, 16, v40
	ds_read2_b64 v[36:39], v14 offset0:32 offset1:36
	v_and_or_b32 v43, v3, s74, v40
	v_and_or_b32 v42, v41, s74, v31
	v_and_or_b32 v41, v52, s74, v55
	v_and_or_b32 v40, v53, s74, v54
	ds_read2_b64 v[52:55], v13 offset0:96 offset1:100
	s_waitcnt lgkmcnt(1)
	v_mfma_f32_16x16x32_bf16 v[36:39], v[36:39], v[40:43], v[44:47]
	s_nop 2
	ds_read2_b64 v[44:47], v11 offset0:64 offset1:68
	s_waitcnt lgkmcnt(1)
	v_mfma_f32_16x16x32_bf16 v[52:55], v[52:55], v[40:43], v[56:59]
	s_nop 2
	ds_read2_b64 v[56:59], v0 offset0:32 offset1:36
	s_waitcnt lgkmcnt(1)
	v_mfma_f32_16x16x32_bf16 v[44:47], v[44:47], v[40:43], v[80:83]
	s_nop 2
	ds_read2_b64 v[80:83], v34 offset0:192 offset1:196
	s_waitcnt lgkmcnt(1)
	v_mfma_f32_16x16x32_bf16 v[56:59], v[56:59], v[40:43], v[60:63]
	s_nop 2
	ds_read2_b64 v[60:63], v1 offset0:160 offset1:164
	s_waitcnt lgkmcnt(0)
	v_mfma_f32_16x16x32_bf16 v[60:63], v[60:63], v[40:43], v[84:87]
	s_nop 2
	ds_read2_b64 v[84:87], v35 offset0:224 offset1:228
	v_mfma_f32_16x16x32_bf16 v[80:83], v[80:83], v[40:43], v[88:91]
	s_nop 2
	ds_read2_b64 v[88:91], v2 offset0:32 offset1:36
	s_waitcnt lgkmcnt(1)
	v_mfma_f32_16x16x32_bf16 v[84:87], v[84:87], v[40:43], v[92:95]
	s_waitcnt lgkmcnt(0)
	v_mfma_f32_16x16x32_bf16 v[40:43], v[88:91], v[40:43], v[48:51]
	v_bfe_u32 v3, v30, 16, 1
	v_bfe_u32 v31, v29, 16, 1
	s_nop 0
	v_bfe_u32 v48, v26, 16, 1
	v_bfe_u32 v49, v25, 16, 1
	v_add3_u32 v49, v25, v49, s73
	v_add3_u32 v26, v26, v48, s73
	v_add3_u32 v29, v29, v31, s73
	v_add3_u32 v3, v30, v3, s73
	v_bfe_u32 v25, v24, 16, 1
	v_bfe_u32 v30, v22, 16, 1
	v_bfe_u32 v31, v23, 16, 1
	v_bfe_u32 v48, v28, 16, 1
	v_add3_u32 v28, v28, v48, s73
	v_add3_u32 v31, v23, v31, s73
	v_add3_u32 v30, v22, v30, s73
	v_add3_u32 v48, v24, v25, s73
	ds_read2_b64 v[22:25], v14 offset0:40 offset1:44
	v_lshrrev_b32_e32 v48, 16, v48
	v_lshrrev_b32_e32 v50, 16, v30
	v_lshrrev_b32_e32 v30, 16, v31
	v_lshrrev_b32_e32 v28, 16, v28
	v_and_or_b32 v31, v3, s74, v28
	v_and_or_b32 v30, v29, s74, v30
	v_and_or_b32 v29, v26, s74, v50
	v_and_or_b32 v28, v49, s74, v48
	ds_read2_b64 v[48:51], v0 offset0:40 offset1:44
	s_waitcnt lgkmcnt(1)
	v_mfma_f32_16x16x32_bf16 v[22:25], v[22:25], v[28:31], v[36:39]
	s_nop 2
	ds_read2_b64 v[36:39], v11 offset0:72 offset1:76
	s_waitcnt lgkmcnt(0)
	v_mfma_f32_16x16x32_bf16 v[36:39], v[36:39], v[28:31], v[44:47]
	s_nop 2
	ds_read2_b64 v[44:47], v13 offset0:104 offset1:108
	s_waitcnt lgkmcnt(0)
	v_mfma_f32_16x16x32_bf16 v[44:47], v[44:47], v[28:31], v[52:55]
	s_nop 2
	ds_read2_b64 v[52:55], v1 offset0:168 offset1:172
	v_mfma_f32_16x16x32_bf16 v[48:51], v[48:51], v[28:31], v[56:59]
	s_nop 2
	ds_read2_b64 v[56:59], v34 offset0:200 offset1:204
	s_waitcnt lgkmcnt(1)
	v_mfma_f32_16x16x32_bf16 v[52:55], v[52:55], v[28:31], v[60:63]
	s_nop 2
	ds_read2_b64 v[60:63], v35 offset0:232 offset1:236
	s_waitcnt lgkmcnt(1)
	v_mfma_f32_16x16x32_bf16 v[56:59], v[56:59], v[28:31], v[80:83]
	s_nop 2
	ds_read2_b64 v[80:83], v2 offset0:40 offset1:44
	s_waitcnt lgkmcnt(1)
	v_mfma_f32_16x16x32_bf16 v[60:63], v[60:63], v[28:31], v[84:87]
	s_waitcnt lgkmcnt(0)
	v_mfma_f32_16x16x32_bf16 v[28:31], v[80:83], v[28:31], v[40:43]
	v_bfe_u32 v3, v21, 16, 1
	v_bfe_u32 v26, v20, 16, 1
	s_nop 0
	v_bfe_u32 v40, v18, 16, 1
	v_bfe_u32 v41, v17, 16, 1
	v_add3_u32 v68, v17, v41, s73
	v_add3_u32 v40, v18, v40, s73
	v_add3_u32 v20, v20, v26, s73
	v_add3_u32 v3, v21, v3, s73
	v_bfe_u32 v17, v12, 16, 1
	v_bfe_u32 v18, v16, 16, 1
	v_bfe_u32 v21, v15, 16, 1
	v_bfe_u32 v26, v19, 16, 1
	v_add3_u32 v26, v19, v26, s73
	v_add3_u32 v15, v15, v21, s73
	v_add3_u32 v21, v16, v18, s73
	v_add3_u32 v12, v12, v17, s73
	ds_read2_b64 v[16:19], v14 offset0:48 offset1:52
	v_lshrrev_b32_e32 v12, 16, v12
	v_lshrrev_b32_e32 v21, 16, v21
	v_lshrrev_b32_e32 v15, 16, v15
	v_lshrrev_b32_e32 v26, 16, v26
	v_and_or_b32 v43, v3, s74, v26
	v_and_or_b32 v42, v20, s74, v15
	v_and_or_b32 v41, v40, s74, v21
	v_and_or_b32 v40, v68, s74, v12
	s_waitcnt lgkmcnt(0)
	s_nop 0
	v_mfma_f32_16x16x32_bf16 v[16:19], v[16:19], v[40:43], v[22:25]
	s_nop 2
	ds_read2_b64 v[20:23], v11 offset0:80 offset1:84
	s_waitcnt lgkmcnt(0)
	v_mfma_f32_16x16x32_bf16 v[20:23], v[20:23], v[40:43], v[36:39]
	s_nop 2
	ds_read2_b64 v[36:39], v13 offset0:112 offset1:116
	s_waitcnt lgkmcnt(0)
	v_mfma_f32_16x16x32_bf16 v[36:39], v[36:39], v[40:43], v[44:47]
	s_nop 2
	ds_read2_b64 v[44:47], v0 offset0:48 offset1:52
	s_waitcnt lgkmcnt(0)
	v_mfma_f32_16x16x32_bf16 v[44:47], v[44:47], v[40:43], v[48:51]
	s_nop 2
	ds_read2_b64 v[48:51], v1 offset0:176 offset1:180
	s_waitcnt lgkmcnt(0)
	v_mfma_f32_16x16x32_bf16 v[48:51], v[48:51], v[40:43], v[52:55]
	s_nop 2
	ds_read2_b64 v[52:55], v34 offset0:208 offset1:212
	s_waitcnt lgkmcnt(0)
	v_mfma_f32_16x16x32_bf16 v[52:55], v[52:55], v[40:43], v[56:59]
	s_nop 2
	ds_read2_b64 v[56:59], v35 offset0:240 offset1:244
	s_waitcnt lgkmcnt(0)
	v_mfma_f32_16x16x32_bf16 v[56:59], v[56:59], v[40:43], v[60:63]
	s_nop 2
	ds_read2_b64 v[60:63], v2 offset0:48 offset1:52
	s_waitcnt lgkmcnt(0)
	v_mfma_f32_16x16x32_bf16 v[40:43], v[60:63], v[40:43], v[28:31]
	v_bfe_u32 v12, v10, 16, 1
	v_bfe_u32 v15, v7, 16, 1
	v_bfe_u32 v24, v8, 16, 1
	v_add3_u32 v8, v8, v24, s73
	v_add3_u32 v15, v7, v15, s73
	v_add3_u32 v10, v10, v12, s73
	v_bfe_u32 v7, v4, 16, 1
	v_bfe_u32 v12, v5, 16, 1
	v_bfe_u32 v24, v6, 16, 1
	v_bfe_u32 v25, v9, 16, 1
	v_add3_u32 v9, v9, v25, s73
	v_add3_u32 v24, v6, v24, s73
	v_add3_u32 v12, v5, v12, s73
	v_add3_u32 v25, v4, v7, s73
	ds_read2_b64 v[4:7], v14 offset0:56 offset1:60
	v_bfe_u32 v3, v27, 16, 1
	v_add3_u32 v3, v27, v3, s73
	v_lshrrev_b32_e32 v14, 16, v25
	v_lshrrev_b32_e32 v12, 16, v12
	v_lshrrev_b32_e32 v24, 16, v24
	v_lshrrev_b32_e32 v9, 16, v9
	v_and_or_b32 v63, v3, s74, v9
	v_and_or_b32 v62, v10, s74, v24
	v_and_or_b32 v61, v15, s74, v12
	v_and_or_b32 v60, v8, s74, v14
	s_waitcnt lgkmcnt(0)
	s_nop 0
	v_mfma_f32_16x16x32_bf16 v[28:31], v[4:7], v[60:63], v[16:19]
	ds_read2_b64 v[4:7], v11 offset0:88 offset1:92
	s_waitcnt lgkmcnt(0)
	v_mfma_f32_16x16x32_bf16 v[24:27], v[4:7], v[60:63], v[20:23]
	ds_read2_b64 v[4:7], v13 offset0:120 offset1:124
	s_waitcnt lgkmcnt(0)
	v_mfma_f32_16x16x32_bf16 v[20:23], v[4:7], v[60:63], v[36:39]
	ds_read2_b64 v[4:7], v0 offset0:56 offset1:60
	s_waitcnt lgkmcnt(0)
	v_mfma_f32_16x16x32_bf16 v[16:19], v[4:7], v[60:63], v[44:47]
	ds_read2_b64 v[4:7], v1 offset0:184 offset1:188
	ds_read2_b64 v[0:3], v2 offset0:56 offset1:60
	s_waitcnt lgkmcnt(1)
	v_mfma_f32_16x16x32_bf16 v[12:15], v[4:7], v[60:63], v[48:51]
	ds_read2_b64 v[4:7], v34 offset0:216 offset1:220
	s_waitcnt lgkmcnt(0)
	v_mfma_f32_16x16x32_bf16 v[8:11], v[4:7], v[60:63], v[52:55]
	ds_read2_b64 v[4:7], v35 offset0:248 offset1:252
	s_waitcnt lgkmcnt(0)
	v_mfma_f32_16x16x32_bf16 v[4:7], v[4:7], v[60:63], v[56:59]
	v_mfma_f32_16x16x32_bf16 v[0:3], v[0:3], v[60:63], v[40:43]
	v_cmp_gt_u32_e32 vcc, 4, v64
	s_and_b64 exec, exec, vcc
	s_cbranch_execz .LBB0_656
	v_add_f32_e32 v32, v32, v33
	v_div_scale_f32 v33, s[8:9], v32, v32, 1.0
	v_rcp_f32_e32 v34, v33
	v_div_scale_f32 v35, vcc, 1.0, v32, 1.0
	v_mov_b32_e32 v38, v28
	v_fma_f32 v36, -v33, v34, 1.0
	v_fmac_f32_e32 v34, v36, v34
	v_mul_f32_e32 v36, v35, v34
	v_fma_f32 v37, -v33, v36, v35
	v_fmac_f32_e32 v36, v37, v34
	v_fma_f32 v33, -v33, v36, v35
	v_div_fmas_f32 v33, v33, v34, v36
	v_div_fixup_f32 v32, v33, v32, 1.0
	v_or_b32_e32 v33, s6, v64
	v_mul_u32_u24_e32 v33, 0x1e00, v33
	v_mov_b32_e32 v39, v30
	v_mov_b32_e32 v30, v29
	v_lshlrev_b32_e32 v64, 1, v33
	v_pk_mul_f32 v[38:39], v[32:33], v[38:39] op_sel_hi:[0,1]
	v_pk_mul_f32 v[28:29], v[32:33], v[30:31] op_sel_hi:[0,1]
	v_lshl_add_u64 v[34:35], s[30:31], 0, v[64:65]
	v_and_b32_sdwa v31, v38, v75 dst_sel:DWORD dst_unused:UNUSED_PAD src0_sel:WORD_1 src1_sel:DWORD
	v_and_b32_sdwa v33, v29, v75 dst_sel:DWORD dst_unused:UNUSED_PAD src0_sel:WORD_1 src1_sel:DWORD
	v_lshl_add_u64 v[34:35], v[34:35], 0, s[48:49]
	v_lshlrev_b32_e32 v64, 3, v67
	v_and_b32_sdwa v30, v39, v75 dst_sel:DWORD dst_unused:UNUSED_PAD src0_sel:WORD_1 src1_sel:DWORD
	v_add3_u32 v31, v38, v31, s73
	v_and_b32_sdwa v38, v28, v75 dst_sel:DWORD dst_unused:UNUSED_PAD src0_sel:WORD_1 src1_sel:DWORD
	v_add3_u32 v29, v29, v33, s73
	v_lshl_add_u64 v[34:35], v[34:35], 0, v[64:65]
	v_add3_u32 v30, v39, v30, s73
	v_add3_u32 v28, v28, v38, s73
	v_and_b32_e32 v29, 0xffff0000, v29
	v_and_b32_e32 v28, 0xffff0000, v28
	v_or_b32_sdwa v29, v29, v30 dst_sel:DWORD dst_unused:UNUSED_PAD src0_sel:DWORD src1_sel:WORD_1
	v_add_co_u32_e32 v30, vcc, s76, v34
	v_or_b32_sdwa v28, v28, v31 dst_sel:DWORD dst_unused:UNUSED_PAD src0_sel:DWORD src1_sel:WORD_1
	s_nop 0
	v_addc_co_u32_e32 v31, vcc, 0, v35, vcc
	global_store_dwordx2 v[30:31], v[28:29], off
	v_mov_b32_e32 v28, v24
	v_mov_b32_e32 v29, v26
	v_pk_mul_f32 v[28:29], v[32:33], v[28:29] op_sel_hi:[0,1]
	v_mov_b32_e32 v26, v25
	v_pk_mul_f32 v[24:25], v[32:33], v[26:27] op_sel_hi:[0,1]
	v_and_b32_sdwa v26, v29, v75 dst_sel:DWORD dst_unused:UNUSED_PAD src0_sel:WORD_1 src1_sel:DWORD
	v_and_b32_sdwa v27, v28, v75 dst_sel:DWORD dst_unused:UNUSED_PAD src0_sel:WORD_1 src1_sel:DWORD
	v_add3_u32 v27, v28, v27, s73
	v_add3_u32 v26, v29, v26, s73
	v_and_b32_sdwa v28, v25, v75 dst_sel:DWORD dst_unused:UNUSED_PAD src0_sel:WORD_1 src1_sel:DWORD
	v_and_b32_sdwa v29, v24, v75 dst_sel:DWORD dst_unused:UNUSED_PAD src0_sel:WORD_1 src1_sel:DWORD
	v_add3_u32 v25, v25, v28, s73
	v_add3_u32 v24, v24, v29, s73
	s_mov_b64 s[6:7], 0x2000
	v_and_b32_e32 v25, 0xffff0000, v25
	v_and_b32_e32 v24, 0xffff0000, v24
	v_lshl_add_u64 v[36:37], v[34:35], 0, s[6:7]
	v_or_b32_sdwa v25, v25, v26 dst_sel:DWORD dst_unused:UNUSED_PAD src0_sel:DWORD src1_sel:WORD_1
	v_or_b32_sdwa v24, v24, v27 dst_sel:DWORD dst_unused:UNUSED_PAD src0_sel:DWORD src1_sel:WORD_1
	global_store_dwordx2 v[36:37], v[24:25], off offset:32
	v_mov_b32_e32 v24, v20
	v_mov_b32_e32 v25, v22
	v_pk_mul_f32 v[24:25], v[32:33], v[24:25] op_sel_hi:[0,1]
	v_mov_b32_e32 v22, v21
	v_pk_mul_f32 v[20:21], v[32:33], v[22:23] op_sel_hi:[0,1]
	v_and_b32_sdwa v22, v25, v75 dst_sel:DWORD dst_unused:UNUSED_PAD src0_sel:WORD_1 src1_sel:DWORD
	v_and_b32_sdwa v23, v24, v75 dst_sel:DWORD dst_unused:UNUSED_PAD src0_sel:WORD_1 src1_sel:DWORD
	v_add3_u32 v23, v24, v23, s73
	v_add3_u32 v22, v25, v22, s73
	v_and_b32_sdwa v24, v21, v75 dst_sel:DWORD dst_unused:UNUSED_PAD src0_sel:WORD_1 src1_sel:DWORD
	v_and_b32_sdwa v25, v20, v75 dst_sel:DWORD dst_unused:UNUSED_PAD src0_sel:WORD_1 src1_sel:DWORD
	v_add3_u32 v21, v21, v24, s73
	v_add3_u32 v20, v20, v25, s73
	v_and_b32_e32 v21, 0xffff0000, v21
	v_and_b32_e32 v20, 0xffff0000, v20
	v_or_b32_sdwa v21, v21, v22 dst_sel:DWORD dst_unused:UNUSED_PAD src0_sel:DWORD src1_sel:WORD_1
	v_or_b32_sdwa v20, v20, v23 dst_sel:DWORD dst_unused:UNUSED_PAD src0_sel:DWORD src1_sel:WORD_1
	global_store_dwordx2 v[36:37], v[20:21], off offset:64
	v_mov_b32_e32 v20, v16
	v_mov_b32_e32 v21, v18
	v_pk_mul_f32 v[20:21], v[32:33], v[20:21] op_sel_hi:[0,1]
	v_mov_b32_e32 v18, v17
	v_pk_mul_f32 v[16:17], v[32:33], v[18:19] op_sel_hi:[0,1]
	v_and_b32_sdwa v18, v21, v75 dst_sel:DWORD dst_unused:UNUSED_PAD src0_sel:WORD_1 src1_sel:DWORD
	v_and_b32_sdwa v19, v20, v75 dst_sel:DWORD dst_unused:UNUSED_PAD src0_sel:WORD_1 src1_sel:DWORD
	v_add3_u32 v19, v20, v19, s73
	v_add3_u32 v18, v21, v18, s73
	v_and_b32_sdwa v20, v17, v75 dst_sel:DWORD dst_unused:UNUSED_PAD src0_sel:WORD_1 src1_sel:DWORD
	v_and_b32_sdwa v21, v16, v75 dst_sel:DWORD dst_unused:UNUSED_PAD src0_sel:WORD_1 src1_sel:DWORD
	v_add3_u32 v17, v17, v20, s73
	v_add3_u32 v16, v16, v21, s73
	v_and_b32_e32 v17, 0xffff0000, v17
	v_and_b32_e32 v16, 0xffff0000, v16
	v_or_b32_sdwa v17, v17, v18 dst_sel:DWORD dst_unused:UNUSED_PAD src0_sel:DWORD src1_sel:WORD_1
	v_or_b32_sdwa v16, v16, v19 dst_sel:DWORD dst_unused:UNUSED_PAD src0_sel:DWORD src1_sel:WORD_1
	global_store_dwordx2 v[36:37], v[16:17], off offset:96
	v_mov_b32_e32 v16, v12
	v_mov_b32_e32 v17, v14
	v_pk_mul_f32 v[16:17], v[32:33], v[16:17] op_sel_hi:[0,1]
	v_mov_b32_e32 v14, v13
	v_pk_mul_f32 v[12:13], v[32:33], v[14:15] op_sel_hi:[0,1]
	v_and_b32_sdwa v14, v17, v75 dst_sel:DWORD dst_unused:UNUSED_PAD src0_sel:WORD_1 src1_sel:DWORD
	v_and_b32_sdwa v15, v16, v75 dst_sel:DWORD dst_unused:UNUSED_PAD src0_sel:WORD_1 src1_sel:DWORD
	v_add3_u32 v15, v16, v15, s73
	v_add3_u32 v14, v17, v14, s73
	v_and_b32_sdwa v16, v13, v75 dst_sel:DWORD dst_unused:UNUSED_PAD src0_sel:WORD_1 src1_sel:DWORD
	v_and_b32_sdwa v17, v12, v75 dst_sel:DWORD dst_unused:UNUSED_PAD src0_sel:WORD_1 src1_sel:DWORD
	v_add3_u32 v13, v13, v16, s73
	v_add3_u32 v12, v12, v17, s73
	v_and_b32_e32 v13, 0xffff0000, v13
	v_and_b32_e32 v12, 0xffff0000, v12
	v_or_b32_sdwa v13, v13, v14 dst_sel:DWORD dst_unused:UNUSED_PAD src0_sel:DWORD src1_sel:WORD_1
	v_or_b32_sdwa v12, v12, v15 dst_sel:DWORD dst_unused:UNUSED_PAD src0_sel:DWORD src1_sel:WORD_1
	global_store_dwordx2 v[36:37], v[12:13], off offset:128
	v_mov_b32_e32 v12, v8
	v_mov_b32_e32 v13, v10
	v_pk_mul_f32 v[12:13], v[32:33], v[12:13] op_sel_hi:[0,1]
	v_mov_b32_e32 v10, v9
	v_pk_mul_f32 v[8:9], v[32:33], v[10:11] op_sel_hi:[0,1]
	v_and_b32_sdwa v10, v13, v75 dst_sel:DWORD dst_unused:UNUSED_PAD src0_sel:WORD_1 src1_sel:DWORD
	v_and_b32_sdwa v11, v12, v75 dst_sel:DWORD dst_unused:UNUSED_PAD src0_sel:WORD_1 src1_sel:DWORD
	v_add3_u32 v11, v12, v11, s73
	v_add3_u32 v10, v13, v10, s73
	v_and_b32_sdwa v12, v9, v75 dst_sel:DWORD dst_unused:UNUSED_PAD src0_sel:WORD_1 src1_sel:DWORD
	v_and_b32_sdwa v13, v8, v75 dst_sel:DWORD dst_unused:UNUSED_PAD src0_sel:WORD_1 src1_sel:DWORD
	v_add3_u32 v9, v9, v12, s73
	v_add3_u32 v8, v8, v13, s73
	v_and_b32_e32 v9, 0xffff0000, v9
	v_and_b32_e32 v8, 0xffff0000, v8
	v_or_b32_sdwa v9, v9, v10 dst_sel:DWORD dst_unused:UNUSED_PAD src0_sel:DWORD src1_sel:WORD_1
	v_or_b32_sdwa v8, v8, v11 dst_sel:DWORD dst_unused:UNUSED_PAD src0_sel:DWORD src1_sel:WORD_1
	global_store_dwordx2 v[36:37], v[8:9], off offset:160
	v_mov_b32_e32 v8, v4
	v_mov_b32_e32 v9, v6
	v_pk_mul_f32 v[8:9], v[32:33], v[8:9] op_sel_hi:[0,1]
	v_mov_b32_e32 v6, v5
	v_pk_mul_f32 v[4:5], v[32:33], v[6:7] op_sel_hi:[0,1]
	v_and_b32_sdwa v6, v9, v75 dst_sel:DWORD dst_unused:UNUSED_PAD src0_sel:WORD_1 src1_sel:DWORD
	v_and_b32_sdwa v7, v8, v75 dst_sel:DWORD dst_unused:UNUSED_PAD src0_sel:WORD_1 src1_sel:DWORD
	v_add3_u32 v7, v8, v7, s73
	v_add3_u32 v6, v9, v6, s73
	v_and_b32_sdwa v8, v5, v75 dst_sel:DWORD dst_unused:UNUSED_PAD src0_sel:WORD_1 src1_sel:DWORD
	v_and_b32_sdwa v9, v4, v75 dst_sel:DWORD dst_unused:UNUSED_PAD src0_sel:WORD_1 src1_sel:DWORD
	v_add3_u32 v5, v5, v8, s73
	v_add3_u32 v4, v4, v9, s73
	v_and_b32_e32 v5, 0xffff0000, v5
	v_and_b32_e32 v4, 0xffff0000, v4
	v_or_b32_sdwa v5, v5, v6 dst_sel:DWORD dst_unused:UNUSED_PAD src0_sel:DWORD src1_sel:WORD_1
	v_or_b32_sdwa v4, v4, v7 dst_sel:DWORD dst_unused:UNUSED_PAD src0_sel:DWORD src1_sel:WORD_1
	global_store_dwordx2 v[36:37], v[4:5], off offset:192
	v_mov_b32_e32 v4, v0
	v_mov_b32_e32 v5, v2
	v_pk_mul_f32 v[4:5], v[32:33], v[4:5] op_sel_hi:[0,1]
	v_mov_b32_e32 v2, v1
	v_pk_mul_f32 v[0:1], v[32:33], v[2:3] op_sel_hi:[0,1]
	v_and_b32_sdwa v2, v5, v75 dst_sel:DWORD dst_unused:UNUSED_PAD src0_sel:WORD_1 src1_sel:DWORD
	v_and_b32_sdwa v3, v4, v75 dst_sel:DWORD dst_unused:UNUSED_PAD src0_sel:WORD_1 src1_sel:DWORD
	v_add3_u32 v3, v4, v3, s73
	v_add3_u32 v2, v5, v2, s73
	v_and_b32_sdwa v4, v1, v75 dst_sel:DWORD dst_unused:UNUSED_PAD src0_sel:WORD_1 src1_sel:DWORD
	v_and_b32_sdwa v5, v0, v75 dst_sel:DWORD dst_unused:UNUSED_PAD src0_sel:WORD_1 src1_sel:DWORD
	v_add3_u32 v1, v1, v4, s73
	v_add3_u32 v0, v0, v5, s73
	v_and_b32_e32 v1, 0xffff0000, v1
	v_and_b32_e32 v0, 0xffff0000, v0
	v_or_b32_sdwa v1, v1, v2 dst_sel:DWORD dst_unused:UNUSED_PAD src0_sel:DWORD src1_sel:WORD_1
	v_or_b32_sdwa v0, v0, v3 dst_sel:DWORD dst_unused:UNUSED_PAD src0_sel:DWORD src1_sel:WORD_1
	global_store_dwordx2 v[36:37], v[0:1], off offset:224
